# first K-loop iteration of each GEMM unit after an epilogue peeled: its first two vmcnt waits relaxed by the epilogue store count so the first K-tile overlaps the store drain
# speedup vs baseline: 1.0169x; 1.0011x over previous
.LBB0_272:
	s_add_u32 s6, s4, 0x186a0000
	s_addc_u32 s7, s5, 0
	s_lshl_b32 s2, s2, 5
	s_mov_b64 s[8:9], 0x80
	s_and_b32 s14, s2, 0x60
	s_add_i32 m0, s21, 0x18000
	v_lshl_add_u64 v[6:7], v[6:7], 0, s[8:9]
	s_lshl_b32 s13, s12, 13
	s_lshl_b32 s15, s14, 7
	s_waitcnt vmcnt(2)
	s_barrier
	global_load_lds_dwordx4 v[6:7], off
	v_lshl_add_u64 v[4:5], v[4:5], 0, s[8:9]
	s_add_i32 m0, s21, 0x1a000
	s_add_i32 s39, s21, 0x8000
	s_add_i32 s40, s21, 0xa000
	global_load_lds_dwordx4 v[4:5], off
	v_lshl_add_u64 v[0:1], v[0:1], 0, s[8:9]
	s_mov_b32 m0, s39
	s_add_u32 s4, s24, 0x40080
	global_load_lds_dwordx4 v[0:1], off
	v_lshl_add_u64 v[0:1], v[2:3], 0, s[8:9]
	s_mov_b32 m0, s40
	s_addc_u32 s5, s25, 0
	global_load_lds_dwordx4 v[0:1], off
	s_add_i32 m0, s21, 0x1c000
	v_lshl_add_u64 v[0:1], s[4:5], 0, v[132:133]
	global_load_lds_dwordx4 v[0:1], off
	v_lshl_add_u64 v[0:1], s[4:5], 0, v[128:129]
	s_add_i32 m0, s21, 0x1e000
	s_cmpk_lt_u32 s11, 0x100
	global_load_lds_dwordx4 v[0:1], off
	v_lshrrev_b32_e32 v1, 1, v8
	v_and_b32_e32 v1, 24, v1
	v_and_b32_e32 v0, 15, v8
	v_lshlrev_b32_e32 v2, 1, v1
	v_lshl_or_b32 v146, s12, 6, v0
	v_lshl_or_b32 v0, v0, 6, v2
	v_lshlrev_b32_e32 v2, 2, v8
	v_and_b32_e32 v2, 32, v2
	v_bitop3_b32 v3, v0, s13, v2 bitop3:0xde
	v_bitop3_b32 v147, v0, s15, v2 bitop3:0xde
	v_lshlrev_b32_e32 v0, 14, v13
	v_and_b32_e32 v0, 0xffff8000, v0
	v_or_b32_e32 v148, s14, v1
	v_lshl_add_u32 v0, v12, 11, v0
	v_and_b32_e32 v1, 1, v13
	v_lshl_or_b32 v0, v1, 6, v0
	v_lshl_add_u32 v136, v14, 1, v0
	v_lshlrev_b32_e32 v0, 14, v9
	v_and_b32_e32 v0, 0xffff8000, v0
	s_waitcnt vmcnt(6)
	v_lshl_add_u32 v0, v10, 11, v0
	v_and_b32_e32 v1, 1, v9
	s_sext_i32_i16 s2, s10
	s_cselect_b64 s[10:11], -1, 0
	v_lshl_or_b32 v0, v1, 6, v0
	s_add_i32 s43, 0, 0x10000
	s_add_i32 s44, 0, 0x14000
	s_ashr_i32 s41, s90, 31
	s_mov_b32 s42, s90
	v_mov_b32_e32 v137, v133
	v_lshl_add_u32 v138, v11, 1, v0
	v_mov_b32_e32 v139, v133
	v_mov_b64_e32 v[140:141], 0x1600
	v_mov_b64_e32 v[142:143], 0x15ff
	v_add_u32_e32 v149, s43, v147
	v_add_u32_e32 v150, s44, v147
	v_add_u32_e32 v151, 0, v3
	s_movk_i32 s45, 0x1600
	s_barrier
	s_mov_b32 s98, 0
	s_branch .LBB0_275

.LBB0_277:
	s_ashr_i32 s15, s14, 31
	s_lshl_b64 s[16:17], s[14:15], 19
	s_add_u32 s16, s3, s16
	s_addc_u32 s17, s28, s17
	s_and_b64 s[18:19], s[4:5], exec
	s_cselect_b32 s15, s17, s23
	s_cselect_b32 s46, s16, s22
	s_ashr_i32 s13, s12, 31
	s_lshl_b64 s[18:19], s[12:13], 19
	s_add_u32 s18, s29, s18
	s_addc_u32 s19, s30, s19
	s_and_b64 s[26:27], s[4:5], exec
	s_cselect_b32 s13, s19, s25
	s_cselect_b32 s47, s18, s24
	s_add_u32 s22, s22, 0x40080
	s_addc_u32 s23, s23, 0
	s_add_u32 s48, s24, 0x100
	v_mov_b32_e32 v0, 0
	s_addc_u32 s49, s25, 0
	s_mov_b32 s50, -2
	v_mov_b32_e32 v1, v0
	v_mov_b32_e32 v2, v0
	v_mov_b32_e32 v3, v0
	v_mov_b32_e32 v4, v0
	v_mov_b32_e32 v5, v0
	v_mov_b32_e32 v6, v0
	v_mov_b32_e32 v7, v0
	v_mov_b32_e32 v16, v0
	v_mov_b32_e32 v17, v0
	v_mov_b32_e32 v18, v0
	v_mov_b32_e32 v19, v0
	v_mov_b32_e32 v20, v0
	v_mov_b32_e32 v21, v0
	v_mov_b32_e32 v22, v0
	v_mov_b32_e32 v23, v0
	v_mov_b32_e32 v32, v0
	v_mov_b32_e32 v33, v0
	v_mov_b32_e32 v34, v0
	v_mov_b32_e32 v35, v0
	v_mov_b32_e32 v36, v0
	v_mov_b32_e32 v37, v0
	v_mov_b32_e32 v38, v0
	v_mov_b32_e32 v39, v0
	v_mov_b32_e32 v48, v0
	v_mov_b32_e32 v49, v0
	v_mov_b32_e32 v50, v0
	v_mov_b32_e32 v51, v0
	v_mov_b32_e32 v52, v0
	v_mov_b32_e32 v53, v0
	v_mov_b32_e32 v54, v0
	v_mov_b32_e32 v55, v0
	v_mov_b32_e32 v8, v0
	v_mov_b32_e32 v9, v0
	v_mov_b32_e32 v10, v0
	v_mov_b32_e32 v11, v0
	v_mov_b32_e32 v12, v0
	v_mov_b32_e32 v13, v0
	v_mov_b32_e32 v14, v0
	v_mov_b32_e32 v15, v0
	v_mov_b32_e32 v24, v0
	v_mov_b32_e32 v25, v0
	v_mov_b32_e32 v26, v0
	v_mov_b32_e32 v27, v0
	v_mov_b32_e32 v28, v0
	v_mov_b32_e32 v29, v0
	v_mov_b32_e32 v30, v0
	v_mov_b32_e32 v31, v0
	v_mov_b32_e32 v40, v0
	v_mov_b32_e32 v41, v0
	v_mov_b32_e32 v42, v0
	v_mov_b32_e32 v43, v0
	v_mov_b32_e32 v44, v0
	v_mov_b32_e32 v45, v0
	v_mov_b32_e32 v46, v0
	v_mov_b32_e32 v47, v0
	v_mov_b32_e32 v56, v0
	v_mov_b32_e32 v57, v0
	v_mov_b32_e32 v58, v0
	v_mov_b32_e32 v59, v0
	v_mov_b32_e32 v60, v0
	v_mov_b32_e32 v61, v0
	v_mov_b32_e32 v62, v0
	v_mov_b32_e32 v63, v0
	v_mov_b32_e32 v64, v0
	v_mov_b32_e32 v65, v0
	v_mov_b32_e32 v66, v0
	v_mov_b32_e32 v67, v0
	v_mov_b32_e32 v68, v0
	v_mov_b32_e32 v69, v0
	v_mov_b32_e32 v70, v0
	v_mov_b32_e32 v71, v0
	v_mov_b32_e32 v80, v0
	v_mov_b32_e32 v81, v0
	v_mov_b32_e32 v82, v0
	v_mov_b32_e32 v83, v0
	v_mov_b32_e32 v84, v0
	v_mov_b32_e32 v85, v0
	v_mov_b32_e32 v86, v0
	v_mov_b32_e32 v87, v0
	v_mov_b32_e32 v96, v0
	v_mov_b32_e32 v97, v0
	v_mov_b32_e32 v98, v0
	v_mov_b32_e32 v99, v0
	v_mov_b32_e32 v100, v0
	v_mov_b32_e32 v101, v0
	v_mov_b32_e32 v102, v0
	v_mov_b32_e32 v103, v0
	v_mov_b32_e32 v112, v0
	v_mov_b32_e32 v113, v0
	v_mov_b32_e32 v114, v0
	v_mov_b32_e32 v115, v0
	v_mov_b32_e32 v116, v0
	v_mov_b32_e32 v117, v0
	v_mov_b32_e32 v118, v0
	v_mov_b32_e32 v119, v0
	v_mov_b32_e32 v72, v0
	v_mov_b32_e32 v73, v0
	v_mov_b32_e32 v74, v0
	v_mov_b32_e32 v75, v0
	v_mov_b32_e32 v76, v0
	v_mov_b32_e32 v77, v0
	v_mov_b32_e32 v78, v0
	v_mov_b32_e32 v79, v0
	v_mov_b32_e32 v88, v0
	v_mov_b32_e32 v89, v0
	v_mov_b32_e32 v90, v0
	v_mov_b32_e32 v91, v0
	v_mov_b32_e32 v92, v0
	v_mov_b32_e32 v93, v0
	v_mov_b32_e32 v94, v0
	v_mov_b32_e32 v95, v0
	v_mov_b32_e32 v104, v0
	v_mov_b32_e32 v105, v0
	v_mov_b32_e32 v106, v0
	v_mov_b32_e32 v107, v0
	v_mov_b32_e32 v108, v0
	v_mov_b32_e32 v109, v0
	v_mov_b32_e32 v110, v0
	v_mov_b32_e32 v111, v0
	v_mov_b32_e32 v120, v0
	v_mov_b32_e32 v121, v0
	v_mov_b32_e32 v122, v0
	v_mov_b32_e32 v123, v0
	v_mov_b32_e32 v124, v0
	v_mov_b32_e32 v125, v0
	v_mov_b32_e32 v126, v0
	v_mov_b32_e32 v127, v0
	s_cmp_eq_u32 s98, 0
	s_cbranch_scc1 .LBB0_278
	ds_read_b128 v[152:155], v149
	ds_read_b128 v[156:159], v149 offset:1024
	ds_read_b128 v[160:163], v149 offset:2048
	ds_read_b128 v[164:167], v149 offset:3072
	ds_read_b128 v[168:171], v150
	ds_read_b128 v[172:175], v150 offset:1024
	ds_read_b128 v[176:179], v150 offset:2048
	ds_read_b128 v[180:183], v150 offset:3072
	s_add_u32 s24, s22, 0xfffc0080
	s_addc_u32 s25, s23, -1
	s_cmp_eq_u32 s50, 12
	s_cselect_b32 s27, s15, s25
	s_cselect_b32 s26, s46, s24
	s_cselect_b32 s25, s13, s49
	s_cselect_b32 s24, s47, s48
	v_lshl_add_u64 v[144:145], s[22:23], 0, v[136:137]
	s_add_i32 m0, s21, 0xc000
	ds_read_b128 v[184:187], v151
	ds_read_b128 v[188:191], v151 offset:1024
	ds_read_b128 v[192:195], v151 offset:2048
	ds_read_b128 v[196:199], v151 offset:3072
	ds_read_b128 v[200:203], v151 offset:4096
	ds_read_b128 v[204:207], v151 offset:5120
	ds_read_b128 v[208:211], v151 offset:6144
	ds_read_b128 v[212:215], v151 offset:7168
	global_load_lds_dwordx4 v[144:145], off
	v_lshl_add_u64 v[144:145], s[22:23], 0, v[138:139]
	s_add_i32 m0, s21, 0xe000
	s_nop 0
	global_load_lds_dwordx4 v[144:145], off
	s_waitcnt vmcnt(16)
	s_waitcnt lgkmcnt(0)
	s_barrier
	s_setprio 1
	s_waitcnt lgkmcnt(0)
	v_mfma_f32_16x16x32_bf16 v[124:127], v[152:155], v[184:187], v[124:127]
	v_mfma_f32_16x16x32_bf16 v[120:123], v[160:163], v[184:187], v[120:123]
	v_mfma_f32_16x16x32_bf16 v[108:111], v[152:155], v[192:195], v[108:111]
	v_mfma_f32_16x16x32_bf16 v[104:107], v[160:163], v[192:195], v[104:107]
	v_mfma_f32_16x16x32_bf16 v[92:95], v[152:155], v[200:203], v[92:95]
	v_mfma_f32_16x16x32_bf16 v[88:91], v[160:163], v[200:203], v[88:91]
	v_mfma_f32_16x16x32_bf16 v[76:79], v[152:155], v[208:211], v[76:79]
	v_mfma_f32_16x16x32_bf16 v[72:75], v[160:163], v[208:211], v[72:75]
	v_mfma_f32_16x16x32_bf16 v[124:127], v[156:159], v[188:191], v[124:127]
	v_mfma_f32_16x16x32_bf16 v[120:123], v[164:167], v[188:191], v[120:123]
	v_mfma_f32_16x16x32_bf16 v[108:111], v[156:159], v[196:199], v[108:111]
	v_mfma_f32_16x16x32_bf16 v[104:107], v[164:167], v[196:199], v[104:107]
	v_mfma_f32_16x16x32_bf16 v[92:95], v[156:159], v[204:207], v[92:95]
	v_mfma_f32_16x16x32_bf16 v[88:91], v[164:167], v[204:207], v[88:91]
	v_mfma_f32_16x16x32_bf16 v[76:79], v[156:159], v[212:215], v[76:79]
	v_mfma_f32_16x16x32_bf16 v[72:75], v[164:167], v[212:215], v[72:75]
	s_setprio 0
	s_setprio 1
	v_mfma_f32_16x16x32_bf16 v[116:119], v[168:171], v[184:187], v[116:119]
	v_mfma_f32_16x16x32_bf16 v[112:115], v[176:179], v[184:187], v[112:115]
	v_mfma_f32_16x16x32_bf16 v[100:103], v[168:171], v[192:195], v[100:103]
	v_mfma_f32_16x16x32_bf16 v[96:99], v[176:179], v[192:195], v[96:99]
	v_mfma_f32_16x16x32_bf16 v[84:87], v[168:171], v[200:203], v[84:87]
	v_mfma_f32_16x16x32_bf16 v[80:83], v[176:179], v[200:203], v[80:83]
	v_mfma_f32_16x16x32_bf16 v[68:71], v[168:171], v[208:211], v[68:71]
	v_mfma_f32_16x16x32_bf16 v[64:67], v[176:179], v[208:211], v[64:67]
	v_mfma_f32_16x16x32_bf16 v[116:119], v[172:175], v[188:191], v[116:119]
	v_mfma_f32_16x16x32_bf16 v[112:115], v[180:183], v[188:191], v[112:115]
	v_mfma_f32_16x16x32_bf16 v[100:103], v[172:175], v[196:199], v[100:103]
	v_mfma_f32_16x16x32_bf16 v[96:99], v[180:183], v[196:199], v[96:99]
	v_mfma_f32_16x16x32_bf16 v[84:87], v[172:175], v[204:207], v[84:87]
	v_mfma_f32_16x16x32_bf16 v[80:83], v[180:183], v[204:207], v[80:83]
	v_mfma_f32_16x16x32_bf16 v[68:71], v[172:175], v[212:215], v[68:71]
	v_mfma_f32_16x16x32_bf16 v[64:67], v[180:183], v[212:215], v[64:67]
	s_setprio 0
	s_barrier
	s_add_i32 s51, s43, s31
	v_lshl_add_u64 v[144:145], s[24:25], 0, v[132:133]
	s_mov_b32 m0, s51
	ds_read_b128 v[184:187], v151 offset:16384
	ds_read_b128 v[188:191], v151 offset:17408
	ds_read_b128 v[192:195], v151 offset:18432
	ds_read_b128 v[196:199], v151 offset:19456
	ds_read_b128 v[200:203], v151 offset:20480
	ds_read_b128 v[204:207], v151 offset:21504
	ds_read_b128 v[208:211], v151 offset:22528
	ds_read_b128 v[212:215], v151 offset:23552
	global_load_lds_dwordx4 v[144:145], off
	s_add_i32 m0, s51, 0x2000
	s_add_u32 s52, s24, 0x40000
	v_lshl_add_u64 v[216:217], s[24:25], 0, v[128:129]
	s_addc_u32 s53, s25, 0
	s_add_i32 s51, s44, s31
	global_load_lds_dwordx4 v[216:217], off
	v_lshl_add_u64 v[218:219], s[52:53], 0, v[132:133]
	s_mov_b32 m0, s51
	v_lshl_add_u64 v[222:223], s[26:27], 0, v[130:131]
	global_load_lds_dwordx4 v[218:219], off
	v_lshl_add_u64 v[218:219], s[52:53], 0, v[128:129]
	s_add_i32 m0, s51, 0x2000
	s_nop 0
	global_load_lds_dwordx4 v[218:219], off
	v_lshl_add_u64 v[218:219], s[26:27], 0, v[134:135]
	s_mov_b32 m0, s21
	s_nop 0
	global_load_lds_dwordx4 v[218:219], off
	s_mov_b32 m0, s35
	s_nop 0
	global_load_lds_dwordx4 v[222:223], off
	s_waitcnt vmcnt(16)
	s_waitcnt lgkmcnt(0)
	s_barrier
	s_setprio 1
	s_waitcnt lgkmcnt(0)
	v_mfma_f32_16x16x32_bf16 v[60:63], v[152:155], v[184:187], v[60:63]
	v_mfma_f32_16x16x32_bf16 v[56:59], v[160:163], v[184:187], v[56:59]
	v_mfma_f32_16x16x32_bf16 v[44:47], v[152:155], v[192:195], v[44:47]
	v_mfma_f32_16x16x32_bf16 v[40:43], v[160:163], v[192:195], v[40:43]
	v_mfma_f32_16x16x32_bf16 v[28:31], v[152:155], v[200:203], v[28:31]
	v_mfma_f32_16x16x32_bf16 v[24:27], v[160:163], v[200:203], v[24:27]
	v_mfma_f32_16x16x32_bf16 v[12:15], v[152:155], v[208:211], v[12:15]
	v_mfma_f32_16x16x32_bf16 v[8:11], v[160:163], v[208:211], v[8:11]
	v_mfma_f32_16x16x32_bf16 v[60:63], v[156:159], v[188:191], v[60:63]
	v_mfma_f32_16x16x32_bf16 v[56:59], v[164:167], v[188:191], v[56:59]
	v_mfma_f32_16x16x32_bf16 v[44:47], v[156:159], v[196:199], v[44:47]
	v_mfma_f32_16x16x32_bf16 v[40:43], v[164:167], v[196:199], v[40:43]
	v_mfma_f32_16x16x32_bf16 v[28:31], v[156:159], v[204:207], v[28:31]
	v_mfma_f32_16x16x32_bf16 v[24:27], v[164:167], v[204:207], v[24:27]
	v_mfma_f32_16x16x32_bf16 v[12:15], v[156:159], v[212:215], v[12:15]
	v_mfma_f32_16x16x32_bf16 v[8:11], v[164:167], v[212:215], v[8:11]
	s_setprio 0
	s_setprio 1
	v_mfma_f32_16x16x32_bf16 v[52:55], v[168:171], v[184:187], v[52:55]
	v_mfma_f32_16x16x32_bf16 v[48:51], v[176:179], v[184:187], v[48:51]
	v_mfma_f32_16x16x32_bf16 v[36:39], v[168:171], v[192:195], v[36:39]
	v_mfma_f32_16x16x32_bf16 v[32:35], v[176:179], v[192:195], v[32:35]
	v_mfma_f32_16x16x32_bf16 v[20:23], v[168:171], v[200:203], v[20:23]
	v_mfma_f32_16x16x32_bf16 v[16:19], v[176:179], v[200:203], v[16:19]
	v_mfma_f32_16x16x32_bf16 v[4:7], v[168:171], v[208:211], v[4:7]
	v_mfma_f32_16x16x32_bf16 v[0:3], v[176:179], v[208:211], v[0:3]
	v_mfma_f32_16x16x32_bf16 v[52:55], v[172:175], v[188:191], v[52:55]
	v_mfma_f32_16x16x32_bf16 v[48:51], v[180:183], v[188:191], v[48:51]
	v_mfma_f32_16x16x32_bf16 v[36:39], v[172:175], v[196:199], v[36:39]
	v_mfma_f32_16x16x32_bf16 v[32:35], v[180:183], v[196:199], v[32:35]
	v_mfma_f32_16x16x32_bf16 v[20:23], v[172:175], v[204:207], v[20:23]
	v_mfma_f32_16x16x32_bf16 v[16:19], v[180:183], v[204:207], v[16:19]
	v_mfma_f32_16x16x32_bf16 v[4:7], v[172:175], v[212:215], v[4:7]
	v_mfma_f32_16x16x32_bf16 v[0:3], v[180:183], v[212:215], v[0:3]
	s_setprio 0
	s_barrier
	s_add_i32 s51, 0, 0x18000
	s_add_i32 s52, 0, 0x1c000
	v_add_u32_e32 v164, s51, v147
	v_add_u32_e32 v180, s52, v147
	ds_read_b128 v[152:155], v164
	ds_read_b128 v[156:159], v164 offset:1024
	ds_read_b128 v[160:163], v164 offset:2048
	ds_read_b128 v[164:167], v164 offset:3072
	ds_read_b128 v[168:171], v180
	ds_read_b128 v[172:175], v180 offset:1024
	ds_read_b128 v[176:179], v180 offset:2048
	ds_read_b128 v[180:183], v180 offset:3072
	s_add_u32 s26, s26, 0x40000
	s_addc_u32 s27, s27, 0
	s_mov_b32 m0, s36
	v_lshl_add_u64 v[224:225], s[26:27], 0, v[134:135]
	ds_read_b128 v[184:187], v151 offset:32768
	ds_read_b128 v[188:191], v151 offset:33792
	ds_read_b128 v[192:195], v151 offset:34816
	ds_read_b128 v[196:199], v151 offset:35840
	ds_read_b128 v[200:203], v151 offset:36864
	ds_read_b128 v[204:207], v151 offset:37888
	ds_read_b128 v[208:211], v151 offset:38912
	ds_read_b128 v[212:215], v151 offset:39936
	global_load_lds_dwordx4 v[224:225], off
	v_lshl_add_u64 v[224:225], s[26:27], 0, v[130:131]
	s_mov_b32 m0, s37
	s_nop 0
	global_load_lds_dwordx4 v[224:225], off
	s_waitcnt vmcnt(8)
	s_waitcnt lgkmcnt(0)
	s_barrier
	s_setprio 1
	s_waitcnt lgkmcnt(0)
	v_mfma_f32_16x16x32_bf16 v[124:127], v[152:155], v[184:187], v[124:127]
	v_mfma_f32_16x16x32_bf16 v[120:123], v[160:163], v[184:187], v[120:123]
	v_mfma_f32_16x16x32_bf16 v[108:111], v[152:155], v[192:195], v[108:111]
	v_mfma_f32_16x16x32_bf16 v[104:107], v[160:163], v[192:195], v[104:107]
	v_mfma_f32_16x16x32_bf16 v[92:95], v[152:155], v[200:203], v[92:95]
	v_mfma_f32_16x16x32_bf16 v[88:91], v[160:163], v[200:203], v[88:91]
	v_mfma_f32_16x16x32_bf16 v[76:79], v[152:155], v[208:211], v[76:79]
	v_mfma_f32_16x16x32_bf16 v[72:75], v[160:163], v[208:211], v[72:75]
	v_mfma_f32_16x16x32_bf16 v[124:127], v[156:159], v[188:191], v[124:127]
	v_mfma_f32_16x16x32_bf16 v[120:123], v[164:167], v[188:191], v[120:123]
	v_mfma_f32_16x16x32_bf16 v[108:111], v[156:159], v[196:199], v[108:111]
	v_mfma_f32_16x16x32_bf16 v[104:107], v[164:167], v[196:199], v[104:107]
	v_mfma_f32_16x16x32_bf16 v[92:95], v[156:159], v[204:207], v[92:95]
	v_mfma_f32_16x16x32_bf16 v[88:91], v[164:167], v[204:207], v[88:91]
	v_mfma_f32_16x16x32_bf16 v[76:79], v[156:159], v[212:215], v[76:79]
	v_mfma_f32_16x16x32_bf16 v[72:75], v[164:167], v[212:215], v[72:75]
	s_setprio 0
	s_setprio 1
	v_mfma_f32_16x16x32_bf16 v[116:119], v[168:171], v[184:187], v[116:119]
	v_mfma_f32_16x16x32_bf16 v[112:115], v[176:179], v[184:187], v[112:115]
	v_mfma_f32_16x16x32_bf16 v[100:103], v[168:171], v[192:195], v[100:103]
	v_mfma_f32_16x16x32_bf16 v[96:99], v[176:179], v[192:195], v[96:99]
	v_mfma_f32_16x16x32_bf16 v[84:87], v[168:171], v[200:203], v[84:87]
	v_mfma_f32_16x16x32_bf16 v[80:83], v[176:179], v[200:203], v[80:83]
	v_mfma_f32_16x16x32_bf16 v[68:71], v[168:171], v[208:211], v[68:71]
	v_mfma_f32_16x16x32_bf16 v[64:67], v[176:179], v[208:211], v[64:67]
	v_mfma_f32_16x16x32_bf16 v[116:119], v[172:175], v[188:191], v[116:119]
	v_mfma_f32_16x16x32_bf16 v[112:115], v[180:183], v[188:191], v[112:115]
	v_mfma_f32_16x16x32_bf16 v[100:103], v[172:175], v[196:199], v[100:103]
	v_mfma_f32_16x16x32_bf16 v[96:99], v[180:183], v[196:199], v[96:99]
	v_mfma_f32_16x16x32_bf16 v[84:87], v[172:175], v[204:207], v[84:87]
	v_mfma_f32_16x16x32_bf16 v[80:83], v[180:183], v[204:207], v[80:83]
	v_mfma_f32_16x16x32_bf16 v[68:71], v[172:175], v[212:215], v[68:71]
	v_mfma_f32_16x16x32_bf16 v[64:67], v[180:183], v[212:215], v[64:67]
	s_setprio 0
	s_barrier
	s_add_i32 s26, s51, s31
	v_lshl_add_u64 v[144:145], v[144:145], 0, s[8:9]
	s_mov_b32 m0, s26
	ds_read_b128 v[184:187], v151 offset:49152
	ds_read_b128 v[188:191], v151 offset:50176
	ds_read_b128 v[192:195], v151 offset:51200
	ds_read_b128 v[196:199], v151 offset:52224
	ds_read_b128 v[200:203], v151 offset:53248
	ds_read_b128 v[204:207], v151 offset:54272
	ds_read_b128 v[208:211], v151 offset:55296
	ds_read_b128 v[212:215], v151 offset:56320
	global_load_lds_dwordx4 v[144:145], off
	s_add_i32 m0, s26, 0x2000
	s_add_u32 s24, s24, 0x40080
	v_lshl_add_u64 v[144:145], v[216:217], 0, s[8:9]
	s_addc_u32 s25, s25, 0
	s_add_i32 s26, s52, s31
	global_load_lds_dwordx4 v[144:145], off
	v_lshl_add_u64 v[144:145], s[24:25], 0, v[132:133]
	s_mov_b32 m0, s26
	s_nop 0
	global_load_lds_dwordx4 v[144:145], off
	v_lshl_add_u64 v[144:145], s[24:25], 0, v[128:129]
	s_add_i32 m0, s26, 0x2000
	s_nop 0
	global_load_lds_dwordx4 v[144:145], off
	v_lshl_add_u64 v[144:145], v[218:219], 0, s[8:9]
	s_mov_b32 m0, s39
	s_nop 0
	global_load_lds_dwordx4 v[144:145], off
	v_lshl_add_u64 v[144:145], v[222:223], 0, s[8:9]
	s_mov_b32 m0, s40
	s_nop 0
	global_load_lds_dwordx4 v[144:145], off
	s_waitcnt vmcnt(8)
	s_waitcnt lgkmcnt(0)
	s_barrier
	s_setprio 1
	s_waitcnt lgkmcnt(0)
	v_mfma_f32_16x16x32_bf16 v[60:63], v[152:155], v[184:187], v[60:63]
	v_mfma_f32_16x16x32_bf16 v[56:59], v[160:163], v[184:187], v[56:59]
	v_mfma_f32_16x16x32_bf16 v[44:47], v[152:155], v[192:195], v[44:47]
	v_mfma_f32_16x16x32_bf16 v[40:43], v[160:163], v[192:195], v[40:43]
	v_mfma_f32_16x16x32_bf16 v[28:31], v[152:155], v[200:203], v[28:31]
	v_mfma_f32_16x16x32_bf16 v[24:27], v[160:163], v[200:203], v[24:27]
	v_mfma_f32_16x16x32_bf16 v[12:15], v[152:155], v[208:211], v[12:15]
	v_mfma_f32_16x16x32_bf16 v[8:11], v[160:163], v[208:211], v[8:11]
	v_mfma_f32_16x16x32_bf16 v[60:63], v[156:159], v[188:191], v[60:63]
	v_mfma_f32_16x16x32_bf16 v[56:59], v[164:167], v[188:191], v[56:59]
	v_mfma_f32_16x16x32_bf16 v[44:47], v[156:159], v[196:199], v[44:47]
	v_mfma_f32_16x16x32_bf16 v[40:43], v[164:167], v[196:199], v[40:43]
	v_mfma_f32_16x16x32_bf16 v[28:31], v[156:159], v[204:207], v[28:31]
	v_mfma_f32_16x16x32_bf16 v[24:27], v[164:167], v[204:207], v[24:27]
	v_mfma_f32_16x16x32_bf16 v[12:15], v[156:159], v[212:215], v[12:15]
	v_mfma_f32_16x16x32_bf16 v[8:11], v[164:167], v[212:215], v[8:11]
	s_setprio 0
	s_setprio 1
	v_mfma_f32_16x16x32_bf16 v[52:55], v[168:171], v[184:187], v[52:55]
	v_mfma_f32_16x16x32_bf16 v[48:51], v[176:179], v[184:187], v[48:51]
	v_mfma_f32_16x16x32_bf16 v[36:39], v[168:171], v[192:195], v[36:39]
	v_mfma_f32_16x16x32_bf16 v[32:35], v[176:179], v[192:195], v[32:35]
	v_mfma_f32_16x16x32_bf16 v[20:23], v[168:171], v[200:203], v[20:23]
	v_mfma_f32_16x16x32_bf16 v[16:19], v[176:179], v[200:203], v[16:19]
	v_mfma_f32_16x16x32_bf16 v[4:7], v[168:171], v[208:211], v[4:7]
	v_mfma_f32_16x16x32_bf16 v[0:3], v[176:179], v[208:211], v[0:3]
	v_mfma_f32_16x16x32_bf16 v[52:55], v[172:175], v[188:191], v[52:55]
	v_mfma_f32_16x16x32_bf16 v[48:51], v[180:183], v[188:191], v[48:51]
	v_mfma_f32_16x16x32_bf16 v[36:39], v[172:175], v[196:199], v[36:39]
	v_mfma_f32_16x16x32_bf16 v[32:35], v[180:183], v[196:199], v[32:35]
	v_mfma_f32_16x16x32_bf16 v[20:23], v[172:175], v[204:207], v[20:23]
	v_mfma_f32_16x16x32_bf16 v[16:19], v[180:183], v[204:207], v[16:19]
	v_mfma_f32_16x16x32_bf16 v[4:7], v[172:175], v[212:215], v[4:7]
	v_mfma_f32_16x16x32_bf16 v[0:3], v[180:183], v[212:215], v[0:3]
	s_setprio 0
	s_barrier
	s_add_i32 s50, s50, 2
	s_add_u32 s22, s22, 0x100
	s_addc_u32 s23, s23, 0
	s_add_u32 s48, s48, 0x100
	s_addc_u32 s49, s49, 0
	s_cmp_gt_u32 s50, 13
	s_cbranch_scc0 .LBB0_278
	s_branch .Lpeel_exit_P1

.Lpeel_exit_P1:
	s_mov_b32 s98, 0
	s_and_b64 vcc, exec, s[10:11]
	s_cbranch_vccz .LBB0_281
	s_barrier
.LBB0_281:
	v_mul_f32_e32 v144, 0xbfb8aa3b, v124
	v_exp_f32_e32 v144, v144
	v_mul_f32_e32 v145, 0xbfb8aa3b, v125
	v_exp_f32_e32 v145, v145
	v_mul_f32_e32 v153, 0xbfb8aa3b, v126
	v_add_f32_e32 v144, 1.0, v144
	v_rcp_f32_e32 v156, v144
	v_add_f32_e32 v144, 1.0, v145
	v_rcp_f32_e32 v157, v144
	v_exp_f32_e32 v153, v153
	v_lshl_or_b32 v154, s2, 7, v148
	v_lshl_add_u32 v152, s20, 8, v146
	v_pk_mul_f32 v[124:125], v[124:125], v[156:157]
	v_mul_f32_e32 v156, 0xbfb8aa3b, v127
	v_exp_f32_e32 v156, v156
	v_pk_mul_f32 v[116:117], v[124:125], v[116:117]
	v_add_f32_e32 v124, 1.0, v153
	v_mul_f32_e32 v153, 0xbfb8aa3b, v120
	v_add_f32_e32 v125, 1.0, v156
	v_rcp_f32_e32 v124, v124
	v_rcp_f32_e32 v125, v125
	v_exp_f32_e32 v153, v153
	v_mul_f32_e32 v156, 0xbfb8aa3b, v121
	v_exp_f32_e32 v156, v156
	v_pk_mul_f32 v[124:125], v[126:127], v[124:125]
	v_add_f32_e32 v126, 1.0, v153
	v_mul_f32_e32 v153, 0xbfb8aa3b, v122
	v_add_f32_e32 v127, 1.0, v156
	v_exp_f32_e32 v153, v153
	v_mul_f32_e32 v156, 0xbfb8aa3b, v123
	v_exp_f32_e32 v157, v156
	v_rcp_f32_e32 v126, v126
	v_add_f32_e32 v153, 1.0, v153
	v_rcp_f32_e32 v127, v127
	v_rcp_f32_e32 v156, v153
	v_add_f32_e32 v153, 1.0, v157
	v_rcp_f32_e32 v157, v153
	v_pk_mul_f32 v[120:121], v[120:121], v[126:127]
	v_pk_mul_f32 v[118:119], v[124:125], v[118:119]
	v_pk_mul_f32 v[120:121], v[120:121], v[112:113]
	v_pk_mul_f32 v[112:113], v[122:123], v[156:157]
	v_ashrrev_i32_e32 v155, 31, v154
	v_pk_mul_f32 v[122:123], v[112:113], v[114:115]
	v_cvt_pk_bf16_f32 v115, v118, v119
	v_mul_f32_e32 v118, 0xbfb8aa3b, v108
	v_mul_f32_e32 v119, 0xbfb8aa3b, v109
	v_exp_f32_e32 v118, v118
	v_exp_f32_e32 v119, v119
	v_mov_b64_e32 v[144:145], s[6:7]
	v_mad_i64_i32 v[158:159], s[22:23], v152, s45, v[144:145]
	v_lshlrev_b64 v[112:113], 1, v[154:155]
	v_lshl_add_u64 v[124:125], v[158:159], 0, v[112:113]
	v_cvt_pk_bf16_f32 v114, v116, v117
	v_cvt_pk_bf16_f32 v116, v120, v121
	v_cvt_pk_bf16_f32 v117, v122, v123
	global_store_dwordx4 v[124:125], v[114:117], off
	s_andn2_b64 vcc, exec, s[4:5]
	s_mov_b64 s[4:5], -1
	v_add_f32_e32 v114, 1.0, v118
	v_add_f32_e32 v115, 1.0, v119
	v_rcp_f32_e32 v114, v114
	v_rcp_f32_e32 v115, v115
	v_or_b32_e32 v116, 16, v152
	v_mad_i64_i32 v[116:117], s[22:23], v116, s45, v[144:145]
	v_pk_mul_f32 v[108:109], v[108:109], v[114:115]
	v_mul_f32_e32 v114, 0xbfb8aa3b, v110
	v_mul_f32_e32 v115, 0xbfb8aa3b, v111
	v_exp_f32_e32 v114, v114
	v_exp_f32_e32 v115, v115
	v_pk_mul_f32 v[100:101], v[108:109], v[100:101]
	v_add_f32_e32 v108, 1.0, v114
	v_add_f32_e32 v109, 1.0, v115
	v_mul_f32_e32 v114, 0xbfb8aa3b, v104
	v_mul_f32_e32 v115, 0xbfb8aa3b, v105
	v_rcp_f32_e32 v108, v108
	v_rcp_f32_e32 v109, v109
	v_exp_f32_e32 v114, v114
	v_exp_f32_e32 v115, v115
	v_pk_mul_f32 v[108:109], v[110:111], v[108:109]
	v_add_f32_e32 v110, 1.0, v114
	v_add_f32_e32 v111, 1.0, v115
	v_mul_f32_e32 v114, 0xbfb8aa3b, v106
	v_mul_f32_e32 v115, 0xbfb8aa3b, v107
	v_exp_f32_e32 v114, v114
	v_exp_f32_e32 v115, v115
	v_rcp_f32_e32 v110, v110
	v_rcp_f32_e32 v111, v111
	v_add_f32_e32 v114, 1.0, v114
	v_add_f32_e32 v115, 1.0, v115
	v_rcp_f32_e32 v114, v114
	v_rcp_f32_e32 v115, v115
	v_pk_mul_f32 v[104:105], v[104:105], v[110:111]
	v_pk_mul_f32 v[102:103], v[108:109], v[102:103]
	v_pk_mul_f32 v[104:105], v[104:105], v[96:97]
	v_pk_mul_f32 v[96:97], v[106:107], v[114:115]
	v_lshl_add_u64 v[108:109], v[116:117], 0, v[112:113]
	v_pk_mul_f32 v[106:107], v[96:97], v[98:99]
	v_cvt_pk_bf16_f32 v96, v100, v101
	v_mul_f32_e32 v100, 0xbfb8aa3b, v92
	v_mul_f32_e32 v101, 0xbfb8aa3b, v93
	v_exp_f32_e32 v100, v100
	v_exp_f32_e32 v101, v101
	v_cvt_pk_bf16_f32 v97, v102, v103
	v_cvt_pk_bf16_f32 v98, v104, v105
	v_cvt_pk_bf16_f32 v99, v106, v107
	global_store_dwordx4 v[108:109], v[96:99], off
	s_nop 1
	v_add_f32_e32 v96, 1.0, v100
	v_add_f32_e32 v97, 1.0, v101
	v_rcp_f32_e32 v96, v96
	v_rcp_f32_e32 v97, v97
	v_or_b32_e32 v98, 32, v152
	v_mad_i64_i32 v[98:99], s[22:23], v98, s45, v[144:145]
	v_pk_mul_f32 v[92:93], v[92:93], v[96:97]
	v_mul_f32_e32 v96, 0xbfb8aa3b, v94
	v_mul_f32_e32 v97, 0xbfb8aa3b, v95
	v_exp_f32_e32 v96, v96
	v_exp_f32_e32 v97, v97
	v_pk_mul_f32 v[84:85], v[92:93], v[84:85]
	v_add_f32_e32 v92, 1.0, v96
	v_add_f32_e32 v93, 1.0, v97
	v_mul_f32_e32 v96, 0xbfb8aa3b, v88
	v_mul_f32_e32 v97, 0xbfb8aa3b, v89
	v_rcp_f32_e32 v92, v92
	v_rcp_f32_e32 v93, v93
	v_exp_f32_e32 v96, v96
	v_exp_f32_e32 v97, v97
	v_pk_mul_f32 v[92:93], v[94:95], v[92:93]
	v_add_f32_e32 v94, 1.0, v96
	v_add_f32_e32 v95, 1.0, v97
	v_mul_f32_e32 v96, 0xbfb8aa3b, v90
	v_mul_f32_e32 v97, 0xbfb8aa3b, v91
	v_exp_f32_e32 v96, v96
	v_exp_f32_e32 v97, v97
	v_rcp_f32_e32 v94, v94
	v_rcp_f32_e32 v95, v95
	v_add_f32_e32 v96, 1.0, v96
	v_add_f32_e32 v97, 1.0, v97
	v_rcp_f32_e32 v96, v96
	v_rcp_f32_e32 v97, v97
	v_pk_mul_f32 v[88:89], v[88:89], v[94:95]
	v_pk_mul_f32 v[86:87], v[92:93], v[86:87]
	v_pk_mul_f32 v[88:89], v[88:89], v[80:81]
	v_pk_mul_f32 v[80:81], v[90:91], v[96:97]
	v_lshl_add_u64 v[92:93], v[98:99], 0, v[112:113]
	v_pk_mul_f32 v[90:91], v[80:81], v[82:83]
	v_cvt_pk_bf16_f32 v80, v84, v85
	v_mul_f32_e32 v84, 0xbfb8aa3b, v76
	v_mul_f32_e32 v85, 0xbfb8aa3b, v77
	v_exp_f32_e32 v84, v84
	v_exp_f32_e32 v85, v85
	v_cvt_pk_bf16_f32 v81, v86, v87
	v_cvt_pk_bf16_f32 v82, v88, v89
	v_cvt_pk_bf16_f32 v83, v90, v91
	global_store_dwordx4 v[92:93], v[80:83], off
	s_nop 1
	v_add_f32_e32 v80, 1.0, v84
	v_add_f32_e32 v81, 1.0, v85
	v_rcp_f32_e32 v80, v80
	v_rcp_f32_e32 v81, v81
	v_or_b32_e32 v82, 48, v152
	v_mad_i64_i32 v[82:83], s[22:23], v82, s45, v[144:145]
	v_pk_mul_f32 v[76:77], v[76:77], v[80:81]
	v_mul_f32_e32 v80, 0xbfb8aa3b, v78
	v_mul_f32_e32 v81, 0xbfb8aa3b, v79
	v_exp_f32_e32 v80, v80
	v_exp_f32_e32 v81, v81
	v_pk_mul_f32 v[68:69], v[76:77], v[68:69]
	v_add_f32_e32 v76, 1.0, v80
	v_add_f32_e32 v77, 1.0, v81
	v_mul_f32_e32 v80, 0xbfb8aa3b, v72
	v_mul_f32_e32 v81, 0xbfb8aa3b, v73
	v_rcp_f32_e32 v76, v76
	v_rcp_f32_e32 v77, v77
	v_exp_f32_e32 v80, v80
	v_exp_f32_e32 v81, v81
	v_pk_mul_f32 v[76:77], v[78:79], v[76:77]
	v_add_f32_e32 v78, 1.0, v80
	v_add_f32_e32 v79, 1.0, v81
	v_mul_f32_e32 v80, 0xbfb8aa3b, v74
	v_mul_f32_e32 v81, 0xbfb8aa3b, v75
	v_exp_f32_e32 v80, v80
	v_exp_f32_e32 v81, v81
	v_rcp_f32_e32 v78, v78
	v_rcp_f32_e32 v79, v79
	v_add_f32_e32 v80, 1.0, v80
	v_add_f32_e32 v81, 1.0, v81
	v_rcp_f32_e32 v80, v80
	v_rcp_f32_e32 v81, v81
	v_pk_mul_f32 v[72:73], v[72:73], v[78:79]
	v_pk_mul_f32 v[70:71], v[76:77], v[70:71]
	v_pk_mul_f32 v[72:73], v[72:73], v[64:65]
	v_pk_mul_f32 v[64:65], v[74:75], v[80:81]
	v_lshl_add_u64 v[76:77], v[82:83], 0, v[112:113]
	v_pk_mul_f32 v[74:75], v[64:65], v[66:67]
	v_cvt_pk_bf16_f32 v64, v68, v69
	v_mul_f32_e32 v68, 0xbfb8aa3b, v60
	v_mul_f32_e32 v69, 0xbfb8aa3b, v61
	v_exp_f32_e32 v68, v68
	v_exp_f32_e32 v69, v69
	v_cvt_pk_bf16_f32 v65, v70, v71
	v_cvt_pk_bf16_f32 v66, v72, v73
	v_cvt_pk_bf16_f32 v67, v74, v75
	global_store_dwordx4 v[76:77], v[64:67], off
	s_nop 1
	v_add_f32_e32 v64, 1.0, v68
	v_add_f32_e32 v65, 1.0, v69
	v_rcp_f32_e32 v64, v64
	v_rcp_f32_e32 v65, v65
	v_add_u32_e32 v66, 0x80, v152
	v_mad_i64_i32 v[66:67], s[22:23], v66, s45, v[144:145]
	v_pk_mul_f32 v[60:61], v[60:61], v[64:65]
	v_mul_f32_e32 v64, 0xbfb8aa3b, v62
	v_mul_f32_e32 v65, 0xbfb8aa3b, v63
	v_exp_f32_e32 v64, v64
	v_exp_f32_e32 v65, v65
	v_pk_mul_f32 v[52:53], v[60:61], v[52:53]
	v_add_f32_e32 v60, 1.0, v64
	v_add_f32_e32 v61, 1.0, v65
	v_mul_f32_e32 v64, 0xbfb8aa3b, v56
	v_mul_f32_e32 v65, 0xbfb8aa3b, v57
	v_rcp_f32_e32 v60, v60
	v_rcp_f32_e32 v61, v61
	v_exp_f32_e32 v64, v64
	v_exp_f32_e32 v65, v65
	v_pk_mul_f32 v[60:61], v[62:63], v[60:61]
	v_add_f32_e32 v62, 1.0, v64
	v_add_f32_e32 v63, 1.0, v65
	v_mul_f32_e32 v64, 0xbfb8aa3b, v58
	v_mul_f32_e32 v65, 0xbfb8aa3b, v59
	v_exp_f32_e32 v64, v64
	v_exp_f32_e32 v65, v65
	v_rcp_f32_e32 v62, v62
	v_rcp_f32_e32 v63, v63
	v_add_f32_e32 v64, 1.0, v64
	v_add_f32_e32 v65, 1.0, v65
	v_rcp_f32_e32 v64, v64
	v_rcp_f32_e32 v65, v65
	v_pk_mul_f32 v[56:57], v[56:57], v[62:63]
	v_pk_mul_f32 v[54:55], v[60:61], v[54:55]
	v_pk_mul_f32 v[56:57], v[56:57], v[48:49]
	v_pk_mul_f32 v[48:49], v[58:59], v[64:65]
	v_lshl_add_u64 v[60:61], v[66:67], 0, v[112:113]
	v_pk_mul_f32 v[58:59], v[48:49], v[50:51]
	v_cvt_pk_bf16_f32 v48, v52, v53
	v_mul_f32_e32 v52, 0xbfb8aa3b, v44
	v_mul_f32_e32 v53, 0xbfb8aa3b, v45
	v_exp_f32_e32 v52, v52
	v_exp_f32_e32 v53, v53
	v_cvt_pk_bf16_f32 v49, v54, v55
	v_cvt_pk_bf16_f32 v50, v56, v57
	v_cvt_pk_bf16_f32 v51, v58, v59
	global_store_dwordx4 v[60:61], v[48:51], off
	s_nop 1
	v_add_f32_e32 v48, 1.0, v52
	v_add_f32_e32 v49, 1.0, v53
	v_rcp_f32_e32 v48, v48
	v_rcp_f32_e32 v49, v49
	v_add_u32_e32 v50, 0x90, v152
	v_mad_i64_i32 v[50:51], s[22:23], v50, s45, v[144:145]
	v_pk_mul_f32 v[44:45], v[44:45], v[48:49]
	v_mul_f32_e32 v48, 0xbfb8aa3b, v46
	v_mul_f32_e32 v49, 0xbfb8aa3b, v47
	v_exp_f32_e32 v48, v48
	v_exp_f32_e32 v49, v49
	v_pk_mul_f32 v[36:37], v[44:45], v[36:37]
	v_add_f32_e32 v44, 1.0, v48
	v_add_f32_e32 v45, 1.0, v49
	v_mul_f32_e32 v48, 0xbfb8aa3b, v40
	v_mul_f32_e32 v49, 0xbfb8aa3b, v41
	v_rcp_f32_e32 v44, v44
	v_rcp_f32_e32 v45, v45
	v_exp_f32_e32 v48, v48
	v_exp_f32_e32 v49, v49
	v_pk_mul_f32 v[44:45], v[46:47], v[44:45]
	v_add_f32_e32 v46, 1.0, v48
	v_add_f32_e32 v47, 1.0, v49
	v_mul_f32_e32 v48, 0xbfb8aa3b, v42
	v_mul_f32_e32 v49, 0xbfb8aa3b, v43
	v_exp_f32_e32 v48, v48
	v_exp_f32_e32 v49, v49
	v_rcp_f32_e32 v46, v46
	v_rcp_f32_e32 v47, v47
	v_add_f32_e32 v48, 1.0, v48
	v_add_f32_e32 v49, 1.0, v49
	v_rcp_f32_e32 v48, v48
	v_rcp_f32_e32 v49, v49
	v_pk_mul_f32 v[40:41], v[40:41], v[46:47]
	v_pk_mul_f32 v[38:39], v[44:45], v[38:39]
	v_pk_mul_f32 v[40:41], v[40:41], v[32:33]
	v_pk_mul_f32 v[32:33], v[42:43], v[48:49]
	v_lshl_add_u64 v[44:45], v[50:51], 0, v[112:113]
	v_pk_mul_f32 v[42:43], v[32:33], v[34:35]
	v_cvt_pk_bf16_f32 v32, v36, v37
	v_mul_f32_e32 v36, 0xbfb8aa3b, v28
	v_mul_f32_e32 v37, 0xbfb8aa3b, v29
	v_exp_f32_e32 v36, v36
	v_exp_f32_e32 v37, v37
	v_cvt_pk_bf16_f32 v33, v38, v39
	v_cvt_pk_bf16_f32 v34, v40, v41
	v_cvt_pk_bf16_f32 v35, v42, v43
	global_store_dwordx4 v[44:45], v[32:35], off
	s_nop 1
	v_add_f32_e32 v32, 1.0, v36
	v_add_f32_e32 v33, 1.0, v37
	v_rcp_f32_e32 v32, v32
	v_rcp_f32_e32 v33, v33
	v_add_u32_e32 v34, 0xa0, v152
	v_mad_i64_i32 v[34:35], s[22:23], v34, s45, v[144:145]
	v_pk_mul_f32 v[28:29], v[28:29], v[32:33]
	v_mul_f32_e32 v32, 0xbfb8aa3b, v30
	v_mul_f32_e32 v33, 0xbfb8aa3b, v31
	v_exp_f32_e32 v32, v32
	v_exp_f32_e32 v33, v33
	v_pk_mul_f32 v[20:21], v[28:29], v[20:21]
	v_add_f32_e32 v28, 1.0, v32
	v_add_f32_e32 v29, 1.0, v33
	v_mul_f32_e32 v32, 0xbfb8aa3b, v24
	v_mul_f32_e32 v33, 0xbfb8aa3b, v25
	v_rcp_f32_e32 v28, v28
	v_rcp_f32_e32 v29, v29
	v_exp_f32_e32 v32, v32
	v_exp_f32_e32 v33, v33
	v_pk_mul_f32 v[28:29], v[30:31], v[28:29]
	v_add_f32_e32 v30, 1.0, v32
	v_add_f32_e32 v31, 1.0, v33
	v_mul_f32_e32 v32, 0xbfb8aa3b, v26
	v_mul_f32_e32 v33, 0xbfb8aa3b, v27
	v_exp_f32_e32 v32, v32
	v_exp_f32_e32 v33, v33
	v_rcp_f32_e32 v30, v30
	v_rcp_f32_e32 v31, v31
	v_add_f32_e32 v32, 1.0, v32
	v_add_f32_e32 v33, 1.0, v33
	v_rcp_f32_e32 v32, v32
	v_rcp_f32_e32 v33, v33
	v_pk_mul_f32 v[24:25], v[24:25], v[30:31]
	v_pk_mul_f32 v[22:23], v[28:29], v[22:23]
	v_pk_mul_f32 v[24:25], v[24:25], v[16:17]
	v_pk_mul_f32 v[16:17], v[26:27], v[32:33]
	v_lshl_add_u64 v[28:29], v[34:35], 0, v[112:113]
	v_pk_mul_f32 v[26:27], v[16:17], v[18:19]
	v_cvt_pk_bf16_f32 v16, v20, v21
	v_mul_f32_e32 v20, 0xbfb8aa3b, v12
	v_mul_f32_e32 v21, 0xbfb8aa3b, v13
	v_exp_f32_e32 v20, v20
	v_exp_f32_e32 v21, v21
	v_cvt_pk_bf16_f32 v17, v22, v23
	v_cvt_pk_bf16_f32 v18, v24, v25
	v_cvt_pk_bf16_f32 v19, v26, v27
	global_store_dwordx4 v[28:29], v[16:19], off
	s_nop 1
	v_add_f32_e32 v16, 1.0, v20
	v_add_f32_e32 v17, 1.0, v21
	v_rcp_f32_e32 v16, v16
	v_rcp_f32_e32 v17, v17
	v_add_u32_e32 v18, 0xb0, v152
	v_mad_i64_i32 v[18:19], s[22:23], v18, s45, v[144:145]
	v_pk_mul_f32 v[12:13], v[12:13], v[16:17]
	v_mul_f32_e32 v16, 0xbfb8aa3b, v14
	v_mul_f32_e32 v17, 0xbfb8aa3b, v15
	v_exp_f32_e32 v16, v16
	v_exp_f32_e32 v17, v17
	v_pk_mul_f32 v[4:5], v[12:13], v[4:5]
	v_add_f32_e32 v12, 1.0, v16
	v_add_f32_e32 v13, 1.0, v17
	v_mul_f32_e32 v16, 0xbfb8aa3b, v8
	v_mul_f32_e32 v17, 0xbfb8aa3b, v9
	v_rcp_f32_e32 v12, v12
	v_rcp_f32_e32 v13, v13
	v_exp_f32_e32 v16, v16
	v_exp_f32_e32 v17, v17
	v_pk_mul_f32 v[12:13], v[14:15], v[12:13]
	v_add_f32_e32 v14, 1.0, v16
	v_add_f32_e32 v15, 1.0, v17
	v_mul_f32_e32 v16, 0xbfb8aa3b, v10
	v_mul_f32_e32 v17, 0xbfb8aa3b, v11
	v_exp_f32_e32 v16, v16
	v_exp_f32_e32 v17, v17
	v_rcp_f32_e32 v14, v14
	v_rcp_f32_e32 v15, v15
	v_add_f32_e32 v16, 1.0, v16
	v_add_f32_e32 v17, 1.0, v17
	v_rcp_f32_e32 v16, v16
	v_rcp_f32_e32 v17, v17
	v_pk_mul_f32 v[8:9], v[8:9], v[14:15]
	v_pk_mul_f32 v[6:7], v[12:13], v[6:7]
	v_pk_mul_f32 v[8:9], v[8:9], v[0:1]
	v_pk_mul_f32 v[0:1], v[10:11], v[16:17]
	v_lshl_add_u64 v[12:13], v[18:19], 0, v[112:113]
	v_pk_mul_f32 v[10:11], v[0:1], v[2:3]
	v_cvt_pk_bf16_f32 v0, v4, v5
	v_cvt_pk_bf16_f32 v1, v6, v7
	v_cvt_pk_bf16_f32 v2, v8, v9
	v_cvt_pk_bf16_f32 v3, v10, v11
	global_store_dwordx4 v[12:13], v[0:3], off
	s_mov_b32 s98, 1
	s_cbranch_vccnz .LBB0_274
	s_andn2_b64 vcc, exec, s[0:1]
	s_cbranch_vccnz .LBB0_273
	s_barrier
	s_branch .LBB0_273

.LBB0_344:
	s_add_u32 s52, s10, 0x3012000
	s_addc_u32 s53, s11, 0
	s_lshl_b32 s7, s7, 5
	s_mov_b64 s[10:11], 0x80
	s_and_b32 s19, s7, 0x60
	s_add_i32 m0, s46, 0x18000
	v_lshl_add_u64 v[6:7], v[6:7], 0, s[10:11]
	s_lshl_b32 s18, s5, 13
	s_lshl_b32 s7, s19, 7
	s_waitcnt vmcnt(2)
	s_barrier
	global_load_lds_dwordx4 v[6:7], off
	v_lshl_add_u64 v[4:5], v[4:5], 0, s[10:11]
	s_add_i32 m0, s46, 0x1a000
	s_add_i32 s54, s46, 0x8000
	s_add_i32 s55, s46, 0xa000
	global_load_lds_dwordx4 v[4:5], off
	v_lshl_add_u64 v[0:1], v[0:1], 0, s[10:11]
	s_mov_b32 m0, s54
	s_add_u32 s16, s36, 0xb0080
	global_load_lds_dwordx4 v[0:1], off
	v_lshl_add_u64 v[0:1], v[2:3], 0, s[10:11]
	s_mov_b32 m0, s55
	s_addc_u32 s17, s37, 0
	global_load_lds_dwordx4 v[0:1], off
	s_add_i32 m0, s46, 0x1c000
	v_lshl_add_u64 v[0:1], s[16:17], 0, v[176:177]
	global_load_lds_dwordx4 v[0:1], off
	v_lshl_add_u64 v[0:1], s[16:17], 0, v[178:179]
	s_add_i32 m0, s46, 0x1e000
	s_cmpk_lt_u32 s2, 0x100
	global_load_lds_dwordx4 v[0:1], off
	v_bfe_u32 v0, v8, 4, 2
	v_and_b32_e32 v1, 15, v8
	v_lshlrev_b32_e32 v2, 4, v0
	v_lshl_or_b32 v221, s5, 6, v1
	v_lshl_or_b32 v1, v1, 6, v2
	v_lshlrev_b32_e32 v2, 2, v8
	v_and_b32_e32 v2, 32, v2
	v_bitop3_b32 v3, v1, s18, v2 bitop3:0xde
	v_bitop3_b32 v222, v1, s7, v2 bitop3:0xde
	v_lshl_or_b32 v223, v0, 2, s19
	v_lshrrev_b32_e32 v1, 1, v9
	v_mul_lo_u32 v0, v11, s4
	s_mov_b32 s2, 0xb000
	v_mad_u64_u32 v[0:1], s[18:19], v1, s2, v[0:1]
	v_or_b32_e32 v0, v0, v10
	s_sext_i32_i8 s70, s6
	s_mov_b64 s[6:7], 0xb0080
	v_add_lshl_u32 v0, v0, v12, 1
	v_mov_b32_e32 v1, v177
	v_lshl_add_u64 v[180:181], v[0:1], 0, s[6:7]
	v_lshrrev_b32_e32 v1, 1, v13
	v_mul_lo_u32 v0, v14, s4
	v_mad_u64_u32 v[0:1], s[4:5], v1, s2, v[0:1]
	s_waitcnt vmcnt(6)
	v_or_b32_e32 v0, v0, v15
	s_cselect_b64 s[16:17], -1, 0
	v_add_lshl_u32 v0, v0, v16, 1
	v_mov_b32_e32 v1, v177
	s_add_i32 s59, 0, 0x10000
	s_add_i32 s60, 0, 0x14000
	s_ashr_i32 s57, s90, 31
	s_mov_b32 s58, s90
	v_lshl_add_u64 v[182:183], v[0:1], 0, s[6:7]
	v_mov_b64_e32 v[184:185], 0x400
	v_mov_b64_e32 v[186:187], 0x3ff
	v_add_u32_e32 v224, s59, v222
	v_add_u32_e32 v225, s60, v222
	v_add_u32_e32 v226, 0, v3
	s_mov_b32 s61, 0x20000
	s_mov_b32 s62, 0x30000
	s_mov_b32 s63, 0x80000
	s_mov_b32 s64, 0x90000
	s_mov_b32 s65, 0xa0000
	s_mov_b32 s66, 0xb0000
	s_mov_b64 s[18:19], 0x10000
	s_mov_b64 s[20:21], 0x20000
	s_mov_b64 s[22:23], 0x30000
	s_mov_b64 s[24:25], 0x80000
	s_mov_b64 s[26:27], 0x90000
	s_mov_b64 s[28:29], 0xa0000
	s_barrier
	s_mov_b32 s98, 0
	s_branch .LBB0_347

.LBB0_357:
	s_add_u32 s2, s36, 0x100
	v_mov_b32_e32 v0, 0
	s_addc_u32 s71, s37, 0
	s_mov_b32 s72, -2
	v_mov_b32_e32 v1, v0
	v_mov_b32_e32 v2, v0
	v_mov_b32_e32 v3, v0
	v_mov_b32_e32 v16, v0
	v_mov_b32_e32 v17, v0
	v_mov_b32_e32 v18, v0
	v_mov_b32_e32 v19, v0
	v_mov_b32_e32 v4, v0
	v_mov_b32_e32 v5, v0
	v_mov_b32_e32 v6, v0
	v_mov_b32_e32 v7, v0
	v_mov_b32_e32 v24, v0
	v_mov_b32_e32 v25, v0
	v_mov_b32_e32 v26, v0
	v_mov_b32_e32 v27, v0
	v_mov_b32_e32 v8, v0
	v_mov_b32_e32 v9, v0
	v_mov_b32_e32 v10, v0
	v_mov_b32_e32 v11, v0
	v_mov_b32_e32 v32, v0
	v_mov_b32_e32 v33, v0
	v_mov_b32_e32 v34, v0
	v_mov_b32_e32 v35, v0
	v_mov_b32_e32 v12, v0
	v_mov_b32_e32 v13, v0
	v_mov_b32_e32 v14, v0
	v_mov_b32_e32 v15, v0
	v_mov_b32_e32 v40, v0
	v_mov_b32_e32 v41, v0
	v_mov_b32_e32 v42, v0
	v_mov_b32_e32 v43, v0
	v_mov_b32_e32 v56, v0
	v_mov_b32_e32 v57, v0
	v_mov_b32_e32 v58, v0
	v_mov_b32_e32 v59, v0
	v_mov_b32_e32 v84, v0
	v_mov_b32_e32 v85, v0
	v_mov_b32_e32 v86, v0
	v_mov_b32_e32 v87, v0
	v_mov_b32_e32 v60, v0
	v_mov_b32_e32 v61, v0
	v_mov_b32_e32 v62, v0
	v_mov_b32_e32 v63, v0
	v_mov_b32_e32 v92, v0
	v_mov_b32_e32 v93, v0
	v_mov_b32_e32 v94, v0
	v_mov_b32_e32 v95, v0
	v_mov_b32_e32 v72, v0
	v_mov_b32_e32 v73, v0
	v_mov_b32_e32 v74, v0
	v_mov_b32_e32 v75, v0
	v_mov_b32_e32 v100, v0
	v_mov_b32_e32 v101, v0
	v_mov_b32_e32 v102, v0
	v_mov_b32_e32 v103, v0
	v_mov_b32_e32 v76, v0
	v_mov_b32_e32 v77, v0
	v_mov_b32_e32 v78, v0
	v_mov_b32_e32 v79, v0
	v_mov_b32_e32 v108, v0
	v_mov_b32_e32 v109, v0
	v_mov_b32_e32 v110, v0
	v_mov_b32_e32 v111, v0
	v_mov_b32_e32 v20, v0
	v_mov_b32_e32 v21, v0
	v_mov_b32_e32 v22, v0
	v_mov_b32_e32 v23, v0
	v_mov_b32_e32 v48, v0
	v_mov_b32_e32 v49, v0
	v_mov_b32_e32 v50, v0
	v_mov_b32_e32 v51, v0
	v_mov_b32_e32 v28, v0
	v_mov_b32_e32 v29, v0
	v_mov_b32_e32 v30, v0
	v_mov_b32_e32 v31, v0
	v_mov_b32_e32 v52, v0
	v_mov_b32_e32 v53, v0
	v_mov_b32_e32 v54, v0
	v_mov_b32_e32 v55, v0
	v_mov_b32_e32 v36, v0
	v_mov_b32_e32 v37, v0
	v_mov_b32_e32 v38, v0
	v_mov_b32_e32 v39, v0
	v_mov_b32_e32 v64, v0
	v_mov_b32_e32 v65, v0
	v_mov_b32_e32 v66, v0
	v_mov_b32_e32 v67, v0
	v_mov_b32_e32 v44, v0
	v_mov_b32_e32 v45, v0
	v_mov_b32_e32 v46, v0
	v_mov_b32_e32 v47, v0
	v_mov_b32_e32 v68, v0
	v_mov_b32_e32 v69, v0
	v_mov_b32_e32 v70, v0
	v_mov_b32_e32 v71, v0
	v_mov_b32_e32 v80, v0
	v_mov_b32_e32 v81, v0
	v_mov_b32_e32 v82, v0
	v_mov_b32_e32 v83, v0
	v_mov_b32_e32 v112, v0
	v_mov_b32_e32 v113, v0
	v_mov_b32_e32 v114, v0
	v_mov_b32_e32 v115, v0
	v_mov_b32_e32 v88, v0
	v_mov_b32_e32 v89, v0
	v_mov_b32_e32 v90, v0
	v_mov_b32_e32 v91, v0
	v_mov_b32_e32 v116, v0
	v_mov_b32_e32 v117, v0
	v_mov_b32_e32 v118, v0
	v_mov_b32_e32 v119, v0
	v_mov_b32_e32 v96, v0
	v_mov_b32_e32 v97, v0
	v_mov_b32_e32 v98, v0
	v_mov_b32_e32 v99, v0
	v_mov_b32_e32 v120, v0
	v_mov_b32_e32 v121, v0
	v_mov_b32_e32 v122, v0
	v_mov_b32_e32 v123, v0
	v_mov_b32_e32 v104, v0
	v_mov_b32_e32 v105, v0
	v_mov_b32_e32 v106, v0
	v_mov_b32_e32 v107, v0
	v_mov_b32_e32 v124, v0
	v_mov_b32_e32 v125, v0
	v_mov_b32_e32 v126, v0
	v_mov_b32_e32 v127, v0
	s_cmp_eq_u32 s98, 0
	s_cbranch_scc1 .LBB0_358
	ds_read_b128 v[128:131], v224
	ds_read_b128 v[132:135], v224 offset:1024
	ds_read_b128 v[136:139], v224 offset:2048
	ds_read_b128 v[140:143], v224 offset:3072
	ds_read_b128 v[144:147], v225
	ds_read_b128 v[148:151], v225 offset:1024
	ds_read_b128 v[152:155], v225 offset:2048
	ds_read_b128 v[156:159], v225 offset:3072
	s_add_u32 s36, s34, 0x100
	s_addc_u32 s37, s35, 0
	s_cmp_eq_u32 s72, 40
	s_cselect_b32 s41, s7, s37
	s_cselect_b32 s40, s6, s36
	s_cselect_b32 s39, s31, s71
	s_cselect_b32 s38, s30, s2
	v_lshl_add_u64 v[204:205], s[34:35], 0, v[180:181]
	s_add_i32 m0, s46, 0xc000
	ds_read_b128 v[160:163], v226
	ds_read_b128 v[164:167], v226 offset:1024
	ds_read_b128 v[168:171], v226 offset:2048
	ds_read_b128 v[172:175], v226 offset:3072
	ds_read_b128 v[188:191], v226 offset:4096
	ds_read_b128 v[192:195], v226 offset:5120
	ds_read_b128 v[196:199], v226 offset:6144
	ds_read_b128 v[200:203], v226 offset:7168
	global_load_lds_dwordx4 v[204:205], off
	v_lshl_add_u64 v[204:205], s[34:35], 0, v[182:183]
	s_add_i32 m0, s46, 0xe000
	s_nop 0
	global_load_lds_dwordx4 v[204:205], off
	s_waitcnt vmcnt(30)
	s_waitcnt lgkmcnt(0)
	s_barrier
	s_setprio 1
	s_waitcnt lgkmcnt(0)
	v_mfma_f32_16x16x32_bf16 v[124:127], v[128:131], v[160:163], v[124:127]
	v_mfma_f32_16x16x32_bf16 v[104:107], v[136:139], v[160:163], v[104:107]
	v_mfma_f32_16x16x32_bf16 v[120:123], v[128:131], v[168:171], v[120:123]
	v_mfma_f32_16x16x32_bf16 v[96:99], v[136:139], v[168:171], v[96:99]
	v_mfma_f32_16x16x32_bf16 v[116:119], v[128:131], v[188:191], v[116:119]
	v_mfma_f32_16x16x32_bf16 v[88:91], v[136:139], v[188:191], v[88:91]
	v_mfma_f32_16x16x32_bf16 v[112:115], v[128:131], v[196:199], v[112:115]
	v_mfma_f32_16x16x32_bf16 v[80:83], v[136:139], v[196:199], v[80:83]
	v_mfma_f32_16x16x32_bf16 v[124:127], v[132:135], v[164:167], v[124:127]
	v_mfma_f32_16x16x32_bf16 v[104:107], v[140:143], v[164:167], v[104:107]
	v_mfma_f32_16x16x32_bf16 v[120:123], v[132:135], v[172:175], v[120:123]
	v_mfma_f32_16x16x32_bf16 v[96:99], v[140:143], v[172:175], v[96:99]
	v_mfma_f32_16x16x32_bf16 v[116:119], v[132:135], v[192:195], v[116:119]
	v_mfma_f32_16x16x32_bf16 v[88:91], v[140:143], v[192:195], v[88:91]
	v_mfma_f32_16x16x32_bf16 v[112:115], v[132:135], v[200:203], v[112:115]
	v_mfma_f32_16x16x32_bf16 v[80:83], v[140:143], v[200:203], v[80:83]
	s_setprio 0
	s_setprio 1
	v_mfma_f32_16x16x32_bf16 v[68:71], v[144:147], v[160:163], v[68:71]
	v_mfma_f32_16x16x32_bf16 v[44:47], v[152:155], v[160:163], v[44:47]
	v_mfma_f32_16x16x32_bf16 v[64:67], v[144:147], v[168:171], v[64:67]
	v_mfma_f32_16x16x32_bf16 v[36:39], v[152:155], v[168:171], v[36:39]
	v_mfma_f32_16x16x32_bf16 v[52:55], v[144:147], v[188:191], v[52:55]
	v_mfma_f32_16x16x32_bf16 v[28:31], v[152:155], v[188:191], v[28:31]
	v_mfma_f32_16x16x32_bf16 v[48:51], v[144:147], v[196:199], v[48:51]
	v_mfma_f32_16x16x32_bf16 v[20:23], v[152:155], v[196:199], v[20:23]
	v_mfma_f32_16x16x32_bf16 v[68:71], v[148:151], v[164:167], v[68:71]
	v_mfma_f32_16x16x32_bf16 v[44:47], v[156:159], v[164:167], v[44:47]
	v_mfma_f32_16x16x32_bf16 v[64:67], v[148:151], v[172:175], v[64:67]
	v_mfma_f32_16x16x32_bf16 v[36:39], v[156:159], v[172:175], v[36:39]
	v_mfma_f32_16x16x32_bf16 v[52:55], v[148:151], v[192:195], v[52:55]
	v_mfma_f32_16x16x32_bf16 v[28:31], v[156:159], v[192:195], v[28:31]
	v_mfma_f32_16x16x32_bf16 v[48:51], v[148:151], v[200:203], v[48:51]
	v_mfma_f32_16x16x32_bf16 v[20:23], v[156:159], v[200:203], v[20:23]
	s_setprio 0
	s_barrier
	s_add_i32 s34, s59, s45
	v_lshl_add_u64 v[204:205], s[38:39], 0, v[176:177]
	s_mov_b32 m0, s34
	ds_read_b128 v[160:163], v226 offset:16384
	ds_read_b128 v[164:167], v226 offset:17408
	ds_read_b128 v[168:171], v226 offset:18432
	ds_read_b128 v[172:175], v226 offset:19456
	ds_read_b128 v[188:191], v226 offset:20480
	ds_read_b128 v[192:195], v226 offset:21504
	ds_read_b128 v[196:199], v226 offset:22528
	ds_read_b128 v[200:203], v226 offset:23552
	global_load_lds_dwordx4 v[204:205], off
	s_add_i32 m0, s34, 0x2000
	s_add_u32 s34, s38, 0xb0000
	v_lshl_add_u64 v[206:207], s[38:39], 0, v[178:179]
	s_addc_u32 s35, s39, 0
	s_add_i32 s73, s60, s45
	global_load_lds_dwordx4 v[206:207], off
	v_lshl_add_u64 v[208:209], s[34:35], 0, v[176:177]
	s_mov_b32 m0, s73
	v_lshl_add_u64 v[210:211], s[40:41], 0, v[178:179]
	global_load_lds_dwordx4 v[208:209], off
	v_lshl_add_u64 v[208:209], s[34:35], 0, v[178:179]
	s_add_i32 m0, s73, 0x2000
	s_nop 0
	global_load_lds_dwordx4 v[208:209], off
	v_lshl_add_u64 v[208:209], s[40:41], 0, v[176:177]
	s_mov_b32 m0, s46
	s_nop 0
	global_load_lds_dwordx4 v[208:209], off
	s_mov_b32 m0, s47
	s_nop 0
	global_load_lds_dwordx4 v[210:211], off
	s_waitcnt vmcnt(30)
	s_waitcnt lgkmcnt(0)
	s_barrier
	s_setprio 1
	s_waitcnt lgkmcnt(0)
	v_mfma_f32_16x16x32_bf16 v[108:111], v[128:131], v[160:163], v[108:111]
	v_mfma_f32_16x16x32_bf16 v[76:79], v[136:139], v[160:163], v[76:79]
	v_mfma_f32_16x16x32_bf16 v[100:103], v[128:131], v[168:171], v[100:103]
	v_mfma_f32_16x16x32_bf16 v[72:75], v[136:139], v[168:171], v[72:75]
	v_mfma_f32_16x16x32_bf16 v[92:95], v[128:131], v[188:191], v[92:95]
	v_mfma_f32_16x16x32_bf16 v[60:63], v[136:139], v[188:191], v[60:63]
	v_mfma_f32_16x16x32_bf16 v[84:87], v[128:131], v[196:199], v[84:87]
	v_mfma_f32_16x16x32_bf16 v[56:59], v[136:139], v[196:199], v[56:59]
	v_mfma_f32_16x16x32_bf16 v[108:111], v[132:135], v[164:167], v[108:111]
	v_mfma_f32_16x16x32_bf16 v[76:79], v[140:143], v[164:167], v[76:79]
	v_mfma_f32_16x16x32_bf16 v[100:103], v[132:135], v[172:175], v[100:103]
	v_mfma_f32_16x16x32_bf16 v[72:75], v[140:143], v[172:175], v[72:75]
	v_mfma_f32_16x16x32_bf16 v[92:95], v[132:135], v[192:195], v[92:95]
	v_mfma_f32_16x16x32_bf16 v[60:63], v[140:143], v[192:195], v[60:63]
	v_mfma_f32_16x16x32_bf16 v[84:87], v[132:135], v[200:203], v[84:87]
	v_mfma_f32_16x16x32_bf16 v[56:59], v[140:143], v[200:203], v[56:59]
	s_setprio 0
	s_setprio 1
	v_mfma_f32_16x16x32_bf16 v[40:43], v[144:147], v[160:163], v[40:43]
	v_mfma_f32_16x16x32_bf16 v[12:15], v[152:155], v[160:163], v[12:15]
	v_mfma_f32_16x16x32_bf16 v[32:35], v[144:147], v[168:171], v[32:35]
	v_mfma_f32_16x16x32_bf16 v[8:11], v[152:155], v[168:171], v[8:11]
	v_mfma_f32_16x16x32_bf16 v[24:27], v[144:147], v[188:191], v[24:27]
	v_mfma_f32_16x16x32_bf16 v[4:7], v[152:155], v[188:191], v[4:7]
	v_mfma_f32_16x16x32_bf16 v[16:19], v[144:147], v[196:199], v[16:19]
	v_mfma_f32_16x16x32_bf16 v[0:3], v[152:155], v[196:199], v[0:3]
	v_mfma_f32_16x16x32_bf16 v[40:43], v[148:151], v[164:167], v[40:43]
	v_mfma_f32_16x16x32_bf16 v[12:15], v[156:159], v[164:167], v[12:15]
	v_mfma_f32_16x16x32_bf16 v[32:35], v[148:151], v[172:175], v[32:35]
	v_mfma_f32_16x16x32_bf16 v[8:11], v[156:159], v[172:175], v[8:11]
	v_mfma_f32_16x16x32_bf16 v[24:27], v[148:151], v[192:195], v[24:27]
	v_mfma_f32_16x16x32_bf16 v[4:7], v[156:159], v[192:195], v[4:7]
	v_mfma_f32_16x16x32_bf16 v[16:19], v[148:151], v[200:203], v[16:19]
	v_mfma_f32_16x16x32_bf16 v[0:3], v[156:159], v[200:203], v[0:3]
	s_setprio 0
	s_barrier
	s_add_i32 s73, 0, 0x18000
	s_add_i32 s74, 0, 0x1c000
	v_add_u32_e32 v140, s73, v222
	v_add_u32_e32 v156, s74, v222
	ds_read_b128 v[128:131], v140
	ds_read_b128 v[132:135], v140 offset:1024
	ds_read_b128 v[136:139], v140 offset:2048
	ds_read_b128 v[140:143], v140 offset:3072
	ds_read_b128 v[144:147], v156
	ds_read_b128 v[148:151], v156 offset:1024
	ds_read_b128 v[152:155], v156 offset:2048
	ds_read_b128 v[156:159], v156 offset:3072
	s_add_u32 s34, s40, 0xb0000
	s_addc_u32 s35, s41, 0
	s_mov_b32 m0, s48
	v_lshl_add_u64 v[212:213], s[34:35], 0, v[176:177]
	ds_read_b128 v[160:163], v226 offset:32768
	ds_read_b128 v[164:167], v226 offset:33792
	ds_read_b128 v[168:171], v226 offset:34816
	ds_read_b128 v[172:175], v226 offset:35840
	ds_read_b128 v[188:191], v226 offset:36864
	ds_read_b128 v[192:195], v226 offset:37888
	ds_read_b128 v[196:199], v226 offset:38912
	ds_read_b128 v[200:203], v226 offset:39936
	global_load_lds_dwordx4 v[212:213], off
	v_lshl_add_u64 v[212:213], s[34:35], 0, v[178:179]
	s_mov_b32 m0, s49
	s_nop 0
	global_load_lds_dwordx4 v[212:213], off
	s_waitcnt vmcnt(8)
	s_waitcnt lgkmcnt(0)
	s_barrier
	s_setprio 1
	s_waitcnt lgkmcnt(0)
	v_mfma_f32_16x16x32_bf16 v[124:127], v[128:131], v[160:163], v[124:127]
	v_mfma_f32_16x16x32_bf16 v[104:107], v[136:139], v[160:163], v[104:107]
	v_mfma_f32_16x16x32_bf16 v[120:123], v[128:131], v[168:171], v[120:123]
	v_mfma_f32_16x16x32_bf16 v[96:99], v[136:139], v[168:171], v[96:99]
	v_mfma_f32_16x16x32_bf16 v[116:119], v[128:131], v[188:191], v[116:119]
	v_mfma_f32_16x16x32_bf16 v[88:91], v[136:139], v[188:191], v[88:91]
	v_mfma_f32_16x16x32_bf16 v[112:115], v[128:131], v[196:199], v[112:115]
	v_mfma_f32_16x16x32_bf16 v[80:83], v[136:139], v[196:199], v[80:83]
	v_mfma_f32_16x16x32_bf16 v[124:127], v[132:135], v[164:167], v[124:127]
	v_mfma_f32_16x16x32_bf16 v[104:107], v[140:143], v[164:167], v[104:107]
	v_mfma_f32_16x16x32_bf16 v[120:123], v[132:135], v[172:175], v[120:123]
	v_mfma_f32_16x16x32_bf16 v[96:99], v[140:143], v[172:175], v[96:99]
	v_mfma_f32_16x16x32_bf16 v[116:119], v[132:135], v[192:195], v[116:119]
	v_mfma_f32_16x16x32_bf16 v[88:91], v[140:143], v[192:195], v[88:91]
	v_mfma_f32_16x16x32_bf16 v[112:115], v[132:135], v[200:203], v[112:115]
	v_mfma_f32_16x16x32_bf16 v[80:83], v[140:143], v[200:203], v[80:83]
	s_setprio 0
	s_setprio 1
	v_mfma_f32_16x16x32_bf16 v[68:71], v[144:147], v[160:163], v[68:71]
	v_mfma_f32_16x16x32_bf16 v[44:47], v[152:155], v[160:163], v[44:47]
	v_mfma_f32_16x16x32_bf16 v[64:67], v[144:147], v[168:171], v[64:67]
	v_mfma_f32_16x16x32_bf16 v[36:39], v[152:155], v[168:171], v[36:39]
	v_mfma_f32_16x16x32_bf16 v[52:55], v[144:147], v[188:191], v[52:55]
	v_mfma_f32_16x16x32_bf16 v[28:31], v[152:155], v[188:191], v[28:31]
	v_mfma_f32_16x16x32_bf16 v[48:51], v[144:147], v[196:199], v[48:51]
	v_mfma_f32_16x16x32_bf16 v[20:23], v[152:155], v[196:199], v[20:23]
	v_mfma_f32_16x16x32_bf16 v[68:71], v[148:151], v[164:167], v[68:71]
	v_mfma_f32_16x16x32_bf16 v[44:47], v[156:159], v[164:167], v[44:47]
	v_mfma_f32_16x16x32_bf16 v[64:67], v[148:151], v[172:175], v[64:67]
	v_mfma_f32_16x16x32_bf16 v[36:39], v[156:159], v[172:175], v[36:39]
	v_mfma_f32_16x16x32_bf16 v[52:55], v[148:151], v[192:195], v[52:55]
	v_mfma_f32_16x16x32_bf16 v[28:31], v[156:159], v[192:195], v[28:31]
	v_mfma_f32_16x16x32_bf16 v[48:51], v[148:151], v[200:203], v[48:51]
	v_mfma_f32_16x16x32_bf16 v[20:23], v[156:159], v[200:203], v[20:23]
	s_setprio 0
	s_barrier
	s_add_i32 s34, s73, s45
	v_lshl_add_u64 v[204:205], v[204:205], 0, s[10:11]
	s_mov_b32 m0, s34
	ds_read_b128 v[160:163], v226 offset:49152
	ds_read_b128 v[164:167], v226 offset:50176
	ds_read_b128 v[168:171], v226 offset:51200
	ds_read_b128 v[172:175], v226 offset:52224
	ds_read_b128 v[188:191], v226 offset:53248
	ds_read_b128 v[192:195], v226 offset:54272
	ds_read_b128 v[196:199], v226 offset:55296
	ds_read_b128 v[200:203], v226 offset:56320
	global_load_lds_dwordx4 v[204:205], off
	s_add_i32 m0, s34, 0x2000
	s_add_u32 s34, s38, 0xb0080
	v_lshl_add_u64 v[204:205], v[206:207], 0, s[10:11]
	s_addc_u32 s35, s39, 0
	s_add_i32 s38, s74, s45
	global_load_lds_dwordx4 v[204:205], off
	v_lshl_add_u64 v[204:205], s[34:35], 0, v[176:177]
	s_mov_b32 m0, s38
	s_nop 0
	global_load_lds_dwordx4 v[204:205], off
	v_lshl_add_u64 v[204:205], s[34:35], 0, v[178:179]
	s_add_i32 m0, s38, 0x2000
	s_nop 0
	global_load_lds_dwordx4 v[204:205], off
	v_lshl_add_u64 v[204:205], v[208:209], 0, s[10:11]
	s_mov_b32 m0, s54
	s_nop 0
	global_load_lds_dwordx4 v[204:205], off
	v_lshl_add_u64 v[204:205], v[210:211], 0, s[10:11]
	s_mov_b32 m0, s55
	s_nop 0
	global_load_lds_dwordx4 v[204:205], off
	s_waitcnt vmcnt(8)
	s_waitcnt lgkmcnt(0)
	s_barrier
	s_setprio 1
	s_waitcnt lgkmcnt(0)
	v_mfma_f32_16x16x32_bf16 v[108:111], v[128:131], v[160:163], v[108:111]
	v_mfma_f32_16x16x32_bf16 v[76:79], v[136:139], v[160:163], v[76:79]
	v_mfma_f32_16x16x32_bf16 v[100:103], v[128:131], v[168:171], v[100:103]
	v_mfma_f32_16x16x32_bf16 v[72:75], v[136:139], v[168:171], v[72:75]
	v_mfma_f32_16x16x32_bf16 v[92:95], v[128:131], v[188:191], v[92:95]
	v_mfma_f32_16x16x32_bf16 v[60:63], v[136:139], v[188:191], v[60:63]
	v_mfma_f32_16x16x32_bf16 v[84:87], v[128:131], v[196:199], v[84:87]
	v_mfma_f32_16x16x32_bf16 v[56:59], v[136:139], v[196:199], v[56:59]
	v_mfma_f32_16x16x32_bf16 v[108:111], v[132:135], v[164:167], v[108:111]
	v_mfma_f32_16x16x32_bf16 v[76:79], v[140:143], v[164:167], v[76:79]
	v_mfma_f32_16x16x32_bf16 v[100:103], v[132:135], v[172:175], v[100:103]
	v_mfma_f32_16x16x32_bf16 v[72:75], v[140:143], v[172:175], v[72:75]
	v_mfma_f32_16x16x32_bf16 v[92:95], v[132:135], v[192:195], v[92:95]
	v_mfma_f32_16x16x32_bf16 v[60:63], v[140:143], v[192:195], v[60:63]
	v_mfma_f32_16x16x32_bf16 v[84:87], v[132:135], v[200:203], v[84:87]
	v_mfma_f32_16x16x32_bf16 v[56:59], v[140:143], v[200:203], v[56:59]
	s_setprio 0
	s_setprio 1
	v_mfma_f32_16x16x32_bf16 v[40:43], v[144:147], v[160:163], v[40:43]
	v_mfma_f32_16x16x32_bf16 v[12:15], v[152:155], v[160:163], v[12:15]
	v_mfma_f32_16x16x32_bf16 v[32:35], v[144:147], v[168:171], v[32:35]
	v_mfma_f32_16x16x32_bf16 v[8:11], v[152:155], v[168:171], v[8:11]
	v_mfma_f32_16x16x32_bf16 v[24:27], v[144:147], v[188:191], v[24:27]
	v_mfma_f32_16x16x32_bf16 v[4:7], v[152:155], v[188:191], v[4:7]
	v_mfma_f32_16x16x32_bf16 v[16:19], v[144:147], v[196:199], v[16:19]
	v_mfma_f32_16x16x32_bf16 v[0:3], v[152:155], v[196:199], v[0:3]
	v_mfma_f32_16x16x32_bf16 v[40:43], v[148:151], v[164:167], v[40:43]
	v_mfma_f32_16x16x32_bf16 v[12:15], v[156:159], v[164:167], v[12:15]
	v_mfma_f32_16x16x32_bf16 v[32:35], v[148:151], v[172:175], v[32:35]
	v_mfma_f32_16x16x32_bf16 v[8:11], v[156:159], v[172:175], v[8:11]
	v_mfma_f32_16x16x32_bf16 v[24:27], v[148:151], v[192:195], v[24:27]
	v_mfma_f32_16x16x32_bf16 v[4:7], v[156:159], v[192:195], v[4:7]
	v_mfma_f32_16x16x32_bf16 v[16:19], v[148:151], v[200:203], v[16:19]
	v_mfma_f32_16x16x32_bf16 v[0:3], v[156:159], v[200:203], v[0:3]
	s_setprio 0
	s_barrier
	s_add_i32 s72, s72, 2
	s_add_u32 s2, s2, 0x100
	s_addc_u32 s71, s71, 0
	s_cmp_gt_u32 s72, 41
	s_mov_b64 s[34:35], s[36:37]
	s_cbranch_scc0 .LBB0_358
	s_branch .Lpeel_exit_P2

.Lpeel_exit_P2:
	s_mov_b32 s98, 0
	s_and_b64 vcc, exec, s[16:17]
	s_cbranch_vccz .LBB0_361
	s_barrier
.LBB0_361:
	v_lshl_add_u32 v128, s69, 8, v221
	v_lshl_or_b32 v136, s70, 8, v223
	s_ashr_i32 s2, s69, 4
	v_lshlrev_b32_e32 v136, 2, v136
	s_mul_hi_i32 s32, s2, 0x9000
	s_mul_i32 s2, s2, 0x9000
	v_lshl_add_u32 v128, v128, 12, v136
	s_add_u32 s34, s52, s2
	s_addc_u32 s35, s53, s32
	v_add_u32_e32 v129, 0x10000, v128
	v_add_u32_e32 v130, 0x20000, v128
	v_add_u32_e32 v131, 0x30000, v128
	v_add_u32_e32 v132, 0x80000, v128
	v_add_u32_e32 v133, 0x90000, v128
	v_add_u32_e32 v134, 0xa0000, v128
	v_add_u32_e32 v135, 0xb0000, v128
	global_load_dwordx4 v[140:143], v136, s[34:35]
	global_load_dwordx4 v[144:147], v136, s[34:35] offset:64
	global_load_dwordx4 v[148:151], v136, s[34:35] offset:512
	global_load_dwordx4 v[152:155], v136, s[34:35] offset:576
	global_load_dwordx4 v[188:191], v128, s[0:1]
	global_load_dwordx4 v[192:195], v128, s[0:1] offset:64
	global_load_dwordx4 v[196:199], v128, s[0:1] offset:512
	global_load_dwordx4 v[200:203], v128, s[0:1] offset:576
	global_load_dwordx4 v[204:207], v129, s[0:1]
	global_load_dwordx4 v[208:211], v129, s[0:1] offset:64
	global_load_dwordx4 v[212:215], v129, s[0:1] offset:512
	global_load_dwordx4 v[216:219], v129, s[0:1] offset:576
	global_load_dwordx4 v[156:159], v130, s[0:1]
	global_load_dwordx4 v[160:163], v130, s[0:1] offset:64
	global_load_dwordx4 v[164:167], v130, s[0:1] offset:512
	global_load_dwordx4 v[168:171], v130, s[0:1] offset:576
	global_load_dwordx4 v[236:239], v131, s[0:1]
	global_load_dwordx4 v[240:243], v131, s[0:1] offset:64
	global_load_dwordx4 v[244:247], v131, s[0:1] offset:512
	global_load_dwordx4 v[248:251], v131, s[0:1] offset:576
	s_waitcnt vmcnt(8)
	v_pk_mul_f32 v[140:141], v[140:141], 0.5 op_sel_hi:[1,0]
	v_pk_mul_f32 v[142:143], v[142:143], 0.5 op_sel_hi:[1,0]
	v_pk_mul_f32 v[144:145], v[144:145], 0.5 op_sel_hi:[1,0]
	v_pk_mul_f32 v[146:147], v[146:147], 0.5 op_sel_hi:[1,0]
	v_pk_mul_f32 v[148:149], v[148:149], 0.5 op_sel_hi:[1,0]
	v_pk_mul_f32 v[150:151], v[150:151], 0.5 op_sel_hi:[1,0]
	v_pk_mul_f32 v[152:153], v[152:153], 0.5 op_sel_hi:[1,0]
	v_pk_mul_f32 v[154:155], v[154:155], 0.5 op_sel_hi:[1,0]
	v_pk_fma_f32 v[188:189], v[124:125], v[140:141], v[188:189]
	v_pk_fma_f32 v[190:191], v[126:127], v[142:143], v[190:191]
	v_pk_fma_f32 v[192:193], v[104:105], v[144:145], v[192:193]
	v_pk_fma_f32 v[194:195], v[106:107], v[146:147], v[194:195]
	v_pk_fma_f32 v[196:197], v[68:69], v[148:149], v[196:197]
	v_pk_fma_f32 v[198:199], v[70:71], v[150:151], v[198:199]
	v_pk_fma_f32 v[200:201], v[44:45], v[152:153], v[200:201]
	v_pk_fma_f32 v[202:203], v[46:47], v[154:155], v[202:203]
	global_store_dwordx4 v128, v[188:191], s[8:9]
	global_store_dwordx4 v128, v[192:195], s[8:9] offset:64
	global_store_dwordx4 v128, v[196:199], s[8:9] offset:512
	global_store_dwordx4 v128, v[200:203], s[8:9] offset:576
	v_pk_fma_f32 v[204:205], v[120:121], v[140:141], v[204:205]
	v_pk_fma_f32 v[206:207], v[122:123], v[142:143], v[206:207]
	v_pk_fma_f32 v[208:209], v[96:97], v[144:145], v[208:209]
	v_pk_fma_f32 v[210:211], v[98:99], v[146:147], v[210:211]
	v_pk_fma_f32 v[212:213], v[64:65], v[148:149], v[212:213]
	v_pk_fma_f32 v[214:215], v[66:67], v[150:151], v[214:215]
	v_pk_fma_f32 v[216:217], v[36:37], v[152:153], v[216:217]
	v_pk_fma_f32 v[218:219], v[38:39], v[154:155], v[218:219]
	global_store_dwordx4 v129, v[204:207], s[8:9]
	global_store_dwordx4 v129, v[208:211], s[8:9] offset:64
	global_store_dwordx4 v129, v[212:215], s[8:9] offset:512
	global_store_dwordx4 v129, v[216:219], s[8:9] offset:576
	s_nop 1
	global_load_dwordx4 v[188:191], v132, s[0:1]
	global_load_dwordx4 v[192:195], v132, s[0:1] offset:64
	global_load_dwordx4 v[196:199], v132, s[0:1] offset:512
	global_load_dwordx4 v[200:203], v132, s[0:1] offset:576
	global_load_dwordx4 v[204:207], v133, s[0:1]
	global_load_dwordx4 v[208:211], v133, s[0:1] offset:64
	global_load_dwordx4 v[212:215], v133, s[0:1] offset:512
	global_load_dwordx4 v[216:219], v133, s[0:1] offset:576
	s_waitcnt vmcnt(16)
	v_pk_fma_f32 v[156:157], v[116:117], v[140:141], v[156:157]
	v_pk_fma_f32 v[158:159], v[118:119], v[142:143], v[158:159]
	v_pk_fma_f32 v[160:161], v[88:89], v[144:145], v[160:161]
	v_pk_fma_f32 v[162:163], v[90:91], v[146:147], v[162:163]
	v_pk_fma_f32 v[164:165], v[52:53], v[148:149], v[164:165]
	v_pk_fma_f32 v[166:167], v[54:55], v[150:151], v[166:167]
	v_pk_fma_f32 v[168:169], v[28:29], v[152:153], v[168:169]
	v_pk_fma_f32 v[170:171], v[30:31], v[154:155], v[170:171]
	global_store_dwordx4 v130, v[156:159], s[8:9]
	global_store_dwordx4 v130, v[160:163], s[8:9] offset:64
	global_store_dwordx4 v130, v[164:167], s[8:9] offset:512
	global_store_dwordx4 v130, v[168:171], s[8:9] offset:576
	v_pk_fma_f32 v[236:237], v[112:113], v[140:141], v[236:237]
	v_pk_fma_f32 v[238:239], v[114:115], v[142:143], v[238:239]
	v_pk_fma_f32 v[240:241], v[80:81], v[144:145], v[240:241]
	v_pk_fma_f32 v[242:243], v[82:83], v[146:147], v[242:243]
	v_pk_fma_f32 v[244:245], v[48:49], v[148:149], v[244:245]
	v_pk_fma_f32 v[246:247], v[50:51], v[150:151], v[246:247]
	v_pk_fma_f32 v[248:249], v[20:21], v[152:153], v[248:249]
	v_pk_fma_f32 v[250:251], v[22:23], v[154:155], v[250:251]
	global_store_dwordx4 v131, v[236:239], s[8:9]
	global_store_dwordx4 v131, v[240:243], s[8:9] offset:64
	global_store_dwordx4 v131, v[244:247], s[8:9] offset:512
	global_store_dwordx4 v131, v[248:251], s[8:9] offset:576
	s_nop 1
	global_load_dwordx4 v[156:159], v134, s[0:1]
	global_load_dwordx4 v[160:163], v134, s[0:1] offset:64
	global_load_dwordx4 v[164:167], v134, s[0:1] offset:512
	global_load_dwordx4 v[168:171], v134, s[0:1] offset:576
	global_load_dwordx4 v[236:239], v135, s[0:1]
	global_load_dwordx4 v[240:243], v135, s[0:1] offset:64
	global_load_dwordx4 v[244:247], v135, s[0:1] offset:512
	global_load_dwordx4 v[248:251], v135, s[0:1] offset:576
	s_waitcnt vmcnt(16)
	v_pk_fma_f32 v[188:189], v[108:109], v[140:141], v[188:189]
	v_pk_fma_f32 v[190:191], v[110:111], v[142:143], v[190:191]
	v_pk_fma_f32 v[192:193], v[76:77], v[144:145], v[192:193]
	v_pk_fma_f32 v[194:195], v[78:79], v[146:147], v[194:195]
	v_pk_fma_f32 v[196:197], v[40:41], v[148:149], v[196:197]
	v_pk_fma_f32 v[198:199], v[42:43], v[150:151], v[198:199]
	v_pk_fma_f32 v[200:201], v[12:13], v[152:153], v[200:201]
	v_pk_fma_f32 v[202:203], v[14:15], v[154:155], v[202:203]
	global_store_dwordx4 v132, v[188:191], s[8:9]
	global_store_dwordx4 v132, v[192:195], s[8:9] offset:64
	global_store_dwordx4 v132, v[196:199], s[8:9] offset:512
	global_store_dwordx4 v132, v[200:203], s[8:9] offset:576
	v_pk_fma_f32 v[204:205], v[100:101], v[140:141], v[204:205]
	v_pk_fma_f32 v[206:207], v[102:103], v[142:143], v[206:207]
	v_pk_fma_f32 v[208:209], v[72:73], v[144:145], v[208:209]
	v_pk_fma_f32 v[210:211], v[74:75], v[146:147], v[210:211]
	v_pk_fma_f32 v[212:213], v[32:33], v[148:149], v[212:213]
	v_pk_fma_f32 v[214:215], v[34:35], v[150:151], v[214:215]
	v_pk_fma_f32 v[216:217], v[8:9], v[152:153], v[216:217]
	v_pk_fma_f32 v[218:219], v[10:11], v[154:155], v[218:219]
	global_store_dwordx4 v133, v[204:207], s[8:9]
	global_store_dwordx4 v133, v[208:211], s[8:9] offset:64
	global_store_dwordx4 v133, v[212:215], s[8:9] offset:512
	global_store_dwordx4 v133, v[216:219], s[8:9] offset:576
	s_waitcnt vmcnt(8)
	v_pk_fma_f32 v[156:157], v[92:93], v[140:141], v[156:157]
	v_pk_fma_f32 v[158:159], v[94:95], v[142:143], v[158:159]
	v_pk_fma_f32 v[160:161], v[60:61], v[144:145], v[160:161]
	v_pk_fma_f32 v[162:163], v[62:63], v[146:147], v[162:163]
	v_pk_fma_f32 v[164:165], v[24:25], v[148:149], v[164:165]
	v_pk_fma_f32 v[166:167], v[26:27], v[150:151], v[166:167]
	v_pk_fma_f32 v[168:169], v[4:5], v[152:153], v[168:169]
	v_pk_fma_f32 v[170:171], v[6:7], v[154:155], v[170:171]
	global_store_dwordx4 v134, v[156:159], s[8:9]
	global_store_dwordx4 v134, v[160:163], s[8:9] offset:64
	global_store_dwordx4 v134, v[164:167], s[8:9] offset:512
	global_store_dwordx4 v134, v[168:171], s[8:9] offset:576
	v_pk_fma_f32 v[236:237], v[84:85], v[140:141], v[236:237]
	v_pk_fma_f32 v[238:239], v[86:87], v[142:143], v[238:239]
	v_pk_fma_f32 v[240:241], v[56:57], v[144:145], v[240:241]
	v_pk_fma_f32 v[242:243], v[58:59], v[146:147], v[242:243]
	v_pk_fma_f32 v[244:245], v[16:17], v[148:149], v[244:245]
	v_pk_fma_f32 v[246:247], v[18:19], v[150:151], v[246:247]
	v_pk_fma_f32 v[248:249], v[0:1], v[152:153], v[248:249]
	v_pk_fma_f32 v[250:251], v[2:3], v[154:155], v[250:251]
	global_store_dwordx4 v135, v[236:239], s[8:9]
	global_store_dwordx4 v135, v[240:243], s[8:9] offset:64
	global_store_dwordx4 v135, v[244:247], s[8:9] offset:512
	global_store_dwordx4 v135, v[248:251], s[8:9] offset:576
	s_mov_b64 s[34:35], -1
	s_and_b64 vcc, exec, s[4:5]
	s_mov_b32 s98, 1
	s_cbranch_vccnz .LBB0_346
	s_andn2_b64 vcc, exec, s[14:15]
	s_cbranch_vccnz .LBB0_345
	s_barrier
	s_branch .LBB0_345

.LBB0_485:
	s_add_u32 s8, s6, 0x186a0000
	s_addc_u32 s9, s7, 0
	s_add_u32 s10, s6, 0x3aa0000
	s_mov_b64 s[12:13], 0x80
	s_addc_u32 s11, s7, 0
	s_and_b32 s34, s4, 3
	s_add_i32 m0, s39, 0x18000
	v_lshl_add_u64 v[6:7], v[6:7], 0, s[12:13]
	s_lshl_b32 s4, s5, 13
	s_lshl_b32 s16, s34, 12
	s_waitcnt vmcnt(2)
	s_barrier
	global_load_lds_dwordx4 v[6:7], off
	v_lshl_add_u64 v[4:5], v[4:5], 0, s[12:13]
	s_add_i32 m0, s39, 0x1a000
	s_add_i32 s64, s39, 0x8000
	s_add_i32 s65, s39, 0xa000
	global_load_lds_dwordx4 v[4:5], off
	v_lshl_add_u64 v[0:1], v[0:1], 0, s[12:13]
	s_mov_b32 m0, s64
	s_add_u32 s14, s52, 0x40080
	global_load_lds_dwordx4 v[0:1], off
	v_lshl_add_u64 v[0:1], v[2:3], 0, s[12:13]
	s_mov_b32 m0, s65
	s_addc_u32 s15, s53, 0
	global_load_lds_dwordx4 v[0:1], off
	s_add_i32 m0, s39, 0x1c000
	v_lshl_add_u64 v[0:1], s[14:15], 0, v[130:131]
	global_load_lds_dwordx4 v[0:1], off
	v_lshl_add_u64 v[0:1], s[14:15], 0, v[134:135]
	s_add_i32 m0, s39, 0x1e000
	s_cmpk_lt_u32 s2, 0x100
	global_load_lds_dwordx4 v[0:1], off
	v_bfe_u32 v1, v8, 4, 2
	v_and_b32_e32 v0, 15, v8
	v_lshlrev_b32_e32 v3, 4, v1
	v_lshl_or_b32 v154, s5, 6, v0
	v_lshl_or_b32 v0, v0, 6, v3
	v_lshlrev_b32_e32 v3, 2, v8
	v_and_b32_e32 v3, 32, v3
	v_lshlrev_b32_e32 v2, 3, v1
	v_bitop3_b32 v4, v0, s4, v3 bitop3:0xde
	v_bitop3_b32 v155, v0, s16, v3 bitop3:0xde
	s_cselect_b64 s[14:15], -1, 0
	s_cmp_eq_u32 s34, 0
	v_cmp_ne_u32_e64 s[4:5], 3, v1
	v_lshlrev_b32_e32 v0, 5, v1
	v_mov_b32_e32 v1, v131
	s_cselect_b64 s[16:17], -1, 0
	s_ashr_i32 s66, s90, 31
	s_ashr_i32 s68, s87, 31
	v_lshl_add_u64 v[0:1], s[6:7], 0, v[0:1]
	s_mov_b64 s[18:19], 0x32a0000
	v_lshl_add_u64 v[136:137], v[0:1], 0, s[18:19]
	s_add_u32 s18, s6, 0x3ba0000
	s_addc_u32 s19, s7, 0
	s_add_u32 s20, s6, 0x3ae0000
	s_addc_u32 s21, s7, 0
	s_add_u32 s22, s6, 0x3be0000
	s_addc_u32 s23, s7, 0
	s_add_u32 s24, s6, 0x3b20000
	v_lshlrev_b32_e32 v0, 14, v9
	s_addc_u32 s25, s7, 0
	v_and_b32_e32 v0, 0xffff8000, v0
	s_add_u32 s26, s6, 0x3c20000
	v_lshl_add_u32 v0, v10, 11, v0
	v_and_b32_e32 v1, 1, v9
	s_addc_u32 s27, s7, 0
	v_lshl_or_b32 v0, v1, 6, v0
	s_add_u32 s28, s6, 0x3b60000
	v_lshl_add_u32 v138, v11, 1, v0
	v_lshlrev_b32_e32 v0, 14, v12
	s_addc_u32 s29, s7, 0
	v_and_b32_e32 v0, 0xffff8000, v0
	s_waitcnt vmcnt(6)
	s_add_u32 s30, s6, 0x3c60000
	v_lshl_add_u32 v0, v13, 11, v0
	v_and_b32_e32 v1, 1, v12
	s_addc_u32 s31, s7, 0
	v_lshl_or_b32 v0, v1, 6, v0
	s_add_i32 s70, 0, 0x10000
	s_add_i32 s71, 0, 0x14000
	s_mov_b32 s67, s90
	v_lshl_or_b32 v156, s34, 5, v2
	v_mov_b32_e32 v139, v131
	v_lshl_add_u32 v140, v14, 1, v0
	v_mov_b32_e32 v141, v131
	v_mov_b64_e32 v[142:143], 0x1400
	v_mov_b64_e32 v[144:145], 0x13ff
	s_movk_i32 s69, 0x281
	v_add_u32_e32 v157, s70, v155
	v_add_u32_e32 v158, s71, v155
	v_add_u32_e32 v159, 0, v4
	s_mov_b64 s[34:35], 0x4800
	s_mov_b64 s[36:37], 0x5800
	s_movk_i32 s72, 0x2600
	v_mov_b32_e32 v160, 0x3e38aa3b
	s_barrier
	s_mov_b32 s98, 0
	s_branch .LBB0_488

.LBB0_490:
	s_ashr_i32 s43, s42, 31
	s_lshl_b64 s[44:45], s[42:43], 19
	s_add_u32 s44, s3, s44
	s_addc_u32 s45, s33, s45
	s_and_b64 s[46:47], s[6:7], exec
	s_cselect_b32 s2, s45, s51
	s_cselect_b32 s43, s44, s50
	s_ashr_i32 s41, s40, 31
	s_lshl_b64 s[46:47], s[40:41], 19
	s_add_u32 s46, s57, s46
	s_addc_u32 s47, s58, s47
	s_and_b64 s[54:55], s[6:7], exec
	s_cselect_b32 s41, s47, s53
	s_cselect_b32 s49, s46, s52
	s_add_u32 s50, s50, 0x40080
	s_addc_u32 s51, s51, 0
	s_add_u32 s73, s52, 0x100
	v_mov_b32_e32 v0, 0
	s_addc_u32 s74, s53, 0
	s_mov_b32 s75, -2
	v_mov_b32_e32 v1, v0
	v_mov_b32_e32 v2, v0
	v_mov_b32_e32 v3, v0
	v_mov_b32_e32 v4, v0
	v_mov_b32_e32 v5, v0
	v_mov_b32_e32 v6, v0
	v_mov_b32_e32 v7, v0
	v_mov_b32_e32 v8, v0
	v_mov_b32_e32 v9, v0
	v_mov_b32_e32 v10, v0
	v_mov_b32_e32 v11, v0
	v_mov_b32_e32 v16, v0
	v_mov_b32_e32 v17, v0
	v_mov_b32_e32 v18, v0
	v_mov_b32_e32 v19, v0
	v_mov_b32_e32 v24, v0
	v_mov_b32_e32 v25, v0
	v_mov_b32_e32 v26, v0
	v_mov_b32_e32 v27, v0
	v_mov_b32_e32 v32, v0
	v_mov_b32_e32 v33, v0
	v_mov_b32_e32 v34, v0
	v_mov_b32_e32 v35, v0
	v_mov_b32_e32 v40, v0
	v_mov_b32_e32 v41, v0
	v_mov_b32_e32 v42, v0
	v_mov_b32_e32 v43, v0
	v_mov_b32_e32 v48, v0
	v_mov_b32_e32 v49, v0
	v_mov_b32_e32 v50, v0
	v_mov_b32_e32 v51, v0
	v_mov_b32_e32 v12, v0
	v_mov_b32_e32 v13, v0
	v_mov_b32_e32 v14, v0
	v_mov_b32_e32 v15, v0
	v_mov_b32_e32 v20, v0
	v_mov_b32_e32 v21, v0
	v_mov_b32_e32 v22, v0
	v_mov_b32_e32 v23, v0
	v_mov_b32_e32 v28, v0
	v_mov_b32_e32 v29, v0
	v_mov_b32_e32 v30, v0
	v_mov_b32_e32 v31, v0
	v_mov_b32_e32 v36, v0
	v_mov_b32_e32 v37, v0
	v_mov_b32_e32 v38, v0
	v_mov_b32_e32 v39, v0
	v_mov_b32_e32 v44, v0
	v_mov_b32_e32 v45, v0
	v_mov_b32_e32 v46, v0
	v_mov_b32_e32 v47, v0
	v_mov_b32_e32 v52, v0
	v_mov_b32_e32 v53, v0
	v_mov_b32_e32 v54, v0
	v_mov_b32_e32 v55, v0
	v_mov_b32_e32 v56, v0
	v_mov_b32_e32 v57, v0
	v_mov_b32_e32 v58, v0
	v_mov_b32_e32 v59, v0
	v_mov_b32_e32 v60, v0
	v_mov_b32_e32 v61, v0
	v_mov_b32_e32 v62, v0
	v_mov_b32_e32 v63, v0
	v_mov_b32_e32 v64, v0
	v_mov_b32_e32 v65, v0
	v_mov_b32_e32 v66, v0
	v_mov_b32_e32 v67, v0
	v_mov_b32_e32 v68, v0
	v_mov_b32_e32 v69, v0
	v_mov_b32_e32 v70, v0
	v_mov_b32_e32 v71, v0
	v_mov_b32_e32 v72, v0
	v_mov_b32_e32 v73, v0
	v_mov_b32_e32 v74, v0
	v_mov_b32_e32 v75, v0
	v_mov_b32_e32 v80, v0
	v_mov_b32_e32 v81, v0
	v_mov_b32_e32 v82, v0
	v_mov_b32_e32 v83, v0
	v_mov_b32_e32 v88, v0
	v_mov_b32_e32 v89, v0
	v_mov_b32_e32 v90, v0
	v_mov_b32_e32 v91, v0
	v_mov_b32_e32 v96, v0
	v_mov_b32_e32 v97, v0
	v_mov_b32_e32 v98, v0
	v_mov_b32_e32 v99, v0
	v_mov_b32_e32 v104, v0
	v_mov_b32_e32 v105, v0
	v_mov_b32_e32 v106, v0
	v_mov_b32_e32 v107, v0
	v_mov_b32_e32 v112, v0
	v_mov_b32_e32 v113, v0
	v_mov_b32_e32 v114, v0
	v_mov_b32_e32 v115, v0
	v_mov_b32_e32 v76, v0
	v_mov_b32_e32 v77, v0
	v_mov_b32_e32 v78, v0
	v_mov_b32_e32 v79, v0
	v_mov_b32_e32 v84, v0
	v_mov_b32_e32 v85, v0
	v_mov_b32_e32 v86, v0
	v_mov_b32_e32 v87, v0
	v_mov_b32_e32 v92, v0
	v_mov_b32_e32 v93, v0
	v_mov_b32_e32 v94, v0
	v_mov_b32_e32 v95, v0
	v_mov_b32_e32 v100, v0
	v_mov_b32_e32 v101, v0
	v_mov_b32_e32 v102, v0
	v_mov_b32_e32 v103, v0
	v_mov_b32_e32 v108, v0
	v_mov_b32_e32 v109, v0
	v_mov_b32_e32 v110, v0
	v_mov_b32_e32 v111, v0
	v_mov_b32_e32 v116, v0
	v_mov_b32_e32 v117, v0
	v_mov_b32_e32 v118, v0
	v_mov_b32_e32 v119, v0
	v_mov_b32_e32 v120, v0
	v_mov_b32_e32 v121, v0
	v_mov_b32_e32 v122, v0
	v_mov_b32_e32 v123, v0
	v_mov_b32_e32 v124, v0
	v_mov_b32_e32 v125, v0
	v_mov_b32_e32 v126, v0
	v_mov_b32_e32 v127, v0
	s_cmp_eq_u32 s98, 0
	s_cbranch_scc1 .LBB0_491
	ds_read_b128 v[146:149], v157
	ds_read_b128 v[150:153], v157 offset:1024
	ds_read_b128 v[162:165], v157 offset:2048
	ds_read_b128 v[166:169], v157 offset:3072
	ds_read_b128 v[170:173], v158
	ds_read_b128 v[174:177], v158 offset:1024
	ds_read_b128 v[178:181], v158 offset:2048
	ds_read_b128 v[182:185], v158 offset:3072
	s_add_u32 s52, s50, 0xfffc0080
	s_addc_u32 s53, s51, -1
	s_cmp_eq_u32 s75, 12
	s_cselect_b32 s55, s2, s53
	s_cselect_b32 s54, s43, s52
	s_cselect_b32 s53, s41, s74
	s_cselect_b32 s52, s49, s73
	v_lshl_add_u64 v[218:219], s[50:51], 0, v[138:139]
	s_add_i32 m0, s39, 0xc000
	ds_read_b128 v[186:189], v159
	ds_read_b128 v[190:193], v159 offset:1024
	ds_read_b128 v[194:197], v159 offset:2048
	ds_read_b128 v[198:201], v159 offset:3072
	ds_read_b128 v[202:205], v159 offset:4096
	ds_read_b128 v[206:209], v159 offset:5120
	ds_read_b128 v[210:213], v159 offset:6144
	ds_read_b128 v[214:217], v159 offset:7168
	global_load_lds_dwordx4 v[218:219], off
	v_lshl_add_u64 v[218:219], s[50:51], 0, v[140:141]
	s_add_i32 m0, s39, 0xe000
	s_nop 0
	global_load_lds_dwordx4 v[218:219], off
	s_waitcnt vmcnt(24)
	s_waitcnt lgkmcnt(0)
	s_barrier
	s_setprio 1
	s_waitcnt lgkmcnt(0)
	v_mfma_f32_16x16x32_bf16 v[124:127], v[146:149], v[186:189], v[124:127]
	v_mfma_f32_16x16x32_bf16 v[120:123], v[162:165], v[186:189], v[120:123]
	v_mfma_f32_16x16x32_bf16 v[116:119], v[146:149], v[194:197], v[116:119]
	v_mfma_f32_16x16x32_bf16 v[108:111], v[162:165], v[194:197], v[108:111]
	v_mfma_f32_16x16x32_bf16 v[100:103], v[146:149], v[202:205], v[100:103]
	v_mfma_f32_16x16x32_bf16 v[92:95], v[162:165], v[202:205], v[92:95]
	v_mfma_f32_16x16x32_bf16 v[84:87], v[146:149], v[210:213], v[84:87]
	v_mfma_f32_16x16x32_bf16 v[76:79], v[162:165], v[210:213], v[76:79]
	v_mfma_f32_16x16x32_bf16 v[124:127], v[150:153], v[190:193], v[124:127]
	v_mfma_f32_16x16x32_bf16 v[120:123], v[166:169], v[190:193], v[120:123]
	v_mfma_f32_16x16x32_bf16 v[116:119], v[150:153], v[198:201], v[116:119]
	v_mfma_f32_16x16x32_bf16 v[108:111], v[166:169], v[198:201], v[108:111]
	v_mfma_f32_16x16x32_bf16 v[100:103], v[150:153], v[206:209], v[100:103]
	v_mfma_f32_16x16x32_bf16 v[92:95], v[166:169], v[206:209], v[92:95]
	v_mfma_f32_16x16x32_bf16 v[84:87], v[150:153], v[214:217], v[84:87]
	v_mfma_f32_16x16x32_bf16 v[76:79], v[166:169], v[214:217], v[76:79]
	s_setprio 0
	s_setprio 1
	v_mfma_f32_16x16x32_bf16 v[112:115], v[170:173], v[186:189], v[112:115]
	v_mfma_f32_16x16x32_bf16 v[104:107], v[178:181], v[186:189], v[104:107]
	v_mfma_f32_16x16x32_bf16 v[96:99], v[170:173], v[194:197], v[96:99]
	v_mfma_f32_16x16x32_bf16 v[88:91], v[178:181], v[194:197], v[88:91]
	v_mfma_f32_16x16x32_bf16 v[80:83], v[170:173], v[202:205], v[80:83]
	v_mfma_f32_16x16x32_bf16 v[72:75], v[178:181], v[202:205], v[72:75]
	v_mfma_f32_16x16x32_bf16 v[68:71], v[170:173], v[210:213], v[68:71]
	v_mfma_f32_16x16x32_bf16 v[64:67], v[178:181], v[210:213], v[64:67]
	v_mfma_f32_16x16x32_bf16 v[112:115], v[174:177], v[190:193], v[112:115]
	v_mfma_f32_16x16x32_bf16 v[104:107], v[182:185], v[190:193], v[104:107]
	v_mfma_f32_16x16x32_bf16 v[96:99], v[174:177], v[198:201], v[96:99]
	v_mfma_f32_16x16x32_bf16 v[88:91], v[182:185], v[198:201], v[88:91]
	v_mfma_f32_16x16x32_bf16 v[80:83], v[174:177], v[206:209], v[80:83]
	v_mfma_f32_16x16x32_bf16 v[72:75], v[182:185], v[206:209], v[72:75]
	v_mfma_f32_16x16x32_bf16 v[68:71], v[174:177], v[214:217], v[68:71]
	v_mfma_f32_16x16x32_bf16 v[64:67], v[182:185], v[214:217], v[64:67]
	s_setprio 0
	s_barrier
	s_add_i32 s76, s70, s59
	v_lshl_add_u64 v[218:219], s[52:53], 0, v[130:131]
	s_mov_b32 m0, s76
	ds_read_b128 v[186:189], v159 offset:16384
	ds_read_b128 v[190:193], v159 offset:17408
	ds_read_b128 v[194:197], v159 offset:18432
	ds_read_b128 v[198:201], v159 offset:19456
	ds_read_b128 v[202:205], v159 offset:20480
	ds_read_b128 v[206:209], v159 offset:21504
	ds_read_b128 v[210:213], v159 offset:22528
	ds_read_b128 v[214:217], v159 offset:23552
	global_load_lds_dwordx4 v[218:219], off
	s_add_i32 m0, s76, 0x2000
	s_add_u32 s76, s52, 0x40000
	v_lshl_add_u64 v[222:223], s[52:53], 0, v[134:135]
	s_addc_u32 s77, s53, 0
	s_add_i32 s78, s71, s59
	global_load_lds_dwordx4 v[222:223], off
	v_lshl_add_u64 v[224:225], s[76:77], 0, v[130:131]
	s_mov_b32 m0, s78
	v_lshl_add_u64 v[226:227], s[54:55], 0, v[132:133]
	global_load_lds_dwordx4 v[224:225], off
	v_lshl_add_u64 v[224:225], s[76:77], 0, v[134:135]
	s_add_i32 m0, s78, 0x2000
	s_nop 0
	global_load_lds_dwordx4 v[224:225], off
	v_lshl_add_u64 v[224:225], s[54:55], 0, v[128:129]
	s_mov_b32 m0, s39
	s_nop 0
	global_load_lds_dwordx4 v[224:225], off
	s_mov_b32 m0, s60
	s_nop 0
	global_load_lds_dwordx4 v[226:227], off
	s_waitcnt vmcnt(24)
	s_waitcnt lgkmcnt(0)
	s_barrier
	s_setprio 1
	s_waitcnt lgkmcnt(0)
	v_mfma_f32_16x16x32_bf16 v[60:63], v[146:149], v[186:189], v[60:63]
	v_mfma_f32_16x16x32_bf16 v[56:59], v[162:165], v[186:189], v[56:59]
	v_mfma_f32_16x16x32_bf16 v[52:55], v[146:149], v[194:197], v[52:55]
	v_mfma_f32_16x16x32_bf16 v[44:47], v[162:165], v[194:197], v[44:47]
	v_mfma_f32_16x16x32_bf16 v[36:39], v[146:149], v[202:205], v[36:39]
	v_mfma_f32_16x16x32_bf16 v[28:31], v[162:165], v[202:205], v[28:31]
	v_mfma_f32_16x16x32_bf16 v[20:23], v[146:149], v[210:213], v[20:23]
	v_mfma_f32_16x16x32_bf16 v[12:15], v[162:165], v[210:213], v[12:15]
	v_mfma_f32_16x16x32_bf16 v[60:63], v[150:153], v[190:193], v[60:63]
	v_mfma_f32_16x16x32_bf16 v[56:59], v[166:169], v[190:193], v[56:59]
	v_mfma_f32_16x16x32_bf16 v[52:55], v[150:153], v[198:201], v[52:55]
	v_mfma_f32_16x16x32_bf16 v[44:47], v[166:169], v[198:201], v[44:47]
	v_mfma_f32_16x16x32_bf16 v[36:39], v[150:153], v[206:209], v[36:39]
	v_mfma_f32_16x16x32_bf16 v[28:31], v[166:169], v[206:209], v[28:31]
	v_mfma_f32_16x16x32_bf16 v[20:23], v[150:153], v[214:217], v[20:23]
	v_mfma_f32_16x16x32_bf16 v[12:15], v[166:169], v[214:217], v[12:15]
	s_setprio 0
	s_setprio 1
	v_mfma_f32_16x16x32_bf16 v[48:51], v[170:173], v[186:189], v[48:51]
	v_mfma_f32_16x16x32_bf16 v[40:43], v[178:181], v[186:189], v[40:43]
	v_mfma_f32_16x16x32_bf16 v[32:35], v[170:173], v[194:197], v[32:35]
	v_mfma_f32_16x16x32_bf16 v[24:27], v[178:181], v[194:197], v[24:27]
	v_mfma_f32_16x16x32_bf16 v[16:19], v[170:173], v[202:205], v[16:19]
	v_mfma_f32_16x16x32_bf16 v[8:11], v[178:181], v[202:205], v[8:11]
	v_mfma_f32_16x16x32_bf16 v[4:7], v[170:173], v[210:213], v[4:7]
	v_mfma_f32_16x16x32_bf16 v[0:3], v[178:181], v[210:213], v[0:3]
	v_mfma_f32_16x16x32_bf16 v[48:51], v[174:177], v[190:193], v[48:51]
	v_mfma_f32_16x16x32_bf16 v[40:43], v[182:185], v[190:193], v[40:43]
	v_mfma_f32_16x16x32_bf16 v[32:35], v[174:177], v[198:201], v[32:35]
	v_mfma_f32_16x16x32_bf16 v[24:27], v[182:185], v[198:201], v[24:27]
	v_mfma_f32_16x16x32_bf16 v[16:19], v[174:177], v[206:209], v[16:19]
	v_mfma_f32_16x16x32_bf16 v[8:11], v[182:185], v[206:209], v[8:11]
	v_mfma_f32_16x16x32_bf16 v[4:7], v[174:177], v[214:217], v[4:7]
	v_mfma_f32_16x16x32_bf16 v[0:3], v[182:185], v[214:217], v[0:3]
	s_setprio 0
	s_barrier
	s_add_i32 s76, 0, 0x18000
	v_add_u32_e32 v161, s76, v155
	s_add_i32 s77, 0, 0x1c000
	ds_read_b128 v[146:149], v161
	ds_read_b128 v[150:153], v161 offset:1024
	ds_read_b128 v[162:165], v161 offset:2048
	ds_read_b128 v[166:169], v161 offset:3072
	v_add_u32_e32 v161, s77, v155
	ds_read_b128 v[170:173], v161
	ds_read_b128 v[174:177], v161 offset:1024
	ds_read_b128 v[178:181], v161 offset:2048
	ds_read_b128 v[182:185], v161 offset:3072
	s_add_u32 s54, s54, 0x40000
	s_addc_u32 s55, s55, 0
	s_mov_b32 m0, s61
	v_lshl_add_u64 v[228:229], s[54:55], 0, v[128:129]
	ds_read_b128 v[186:189], v159 offset:32768
	ds_read_b128 v[190:193], v159 offset:33792
	ds_read_b128 v[194:197], v159 offset:34816
	ds_read_b128 v[198:201], v159 offset:35840
	ds_read_b128 v[202:205], v159 offset:36864
	ds_read_b128 v[206:209], v159 offset:37888
	ds_read_b128 v[210:213], v159 offset:38912
	ds_read_b128 v[214:217], v159 offset:39936
	global_load_lds_dwordx4 v[228:229], off
	v_lshl_add_u64 v[228:229], s[54:55], 0, v[132:133]
	s_mov_b32 m0, s62
	s_nop 0
	global_load_lds_dwordx4 v[228:229], off
	s_waitcnt vmcnt(8)
	s_waitcnt lgkmcnt(0)
	s_barrier
	s_setprio 1
	s_waitcnt lgkmcnt(0)
	v_mfma_f32_16x16x32_bf16 v[124:127], v[146:149], v[186:189], v[124:127]
	v_mfma_f32_16x16x32_bf16 v[120:123], v[162:165], v[186:189], v[120:123]
	v_mfma_f32_16x16x32_bf16 v[116:119], v[146:149], v[194:197], v[116:119]
	v_mfma_f32_16x16x32_bf16 v[108:111], v[162:165], v[194:197], v[108:111]
	v_mfma_f32_16x16x32_bf16 v[100:103], v[146:149], v[202:205], v[100:103]
	v_mfma_f32_16x16x32_bf16 v[92:95], v[162:165], v[202:205], v[92:95]
	v_mfma_f32_16x16x32_bf16 v[84:87], v[146:149], v[210:213], v[84:87]
	v_mfma_f32_16x16x32_bf16 v[76:79], v[162:165], v[210:213], v[76:79]
	v_mfma_f32_16x16x32_bf16 v[124:127], v[150:153], v[190:193], v[124:127]
	v_mfma_f32_16x16x32_bf16 v[120:123], v[166:169], v[190:193], v[120:123]
	v_mfma_f32_16x16x32_bf16 v[116:119], v[150:153], v[198:201], v[116:119]
	v_mfma_f32_16x16x32_bf16 v[108:111], v[166:169], v[198:201], v[108:111]
	v_mfma_f32_16x16x32_bf16 v[100:103], v[150:153], v[206:209], v[100:103]
	v_mfma_f32_16x16x32_bf16 v[92:95], v[166:169], v[206:209], v[92:95]
	v_mfma_f32_16x16x32_bf16 v[84:87], v[150:153], v[214:217], v[84:87]
	v_mfma_f32_16x16x32_bf16 v[76:79], v[166:169], v[214:217], v[76:79]
	s_setprio 0
	s_setprio 1
	v_mfma_f32_16x16x32_bf16 v[112:115], v[170:173], v[186:189], v[112:115]
	v_mfma_f32_16x16x32_bf16 v[104:107], v[178:181], v[186:189], v[104:107]
	v_mfma_f32_16x16x32_bf16 v[96:99], v[170:173], v[194:197], v[96:99]
	v_mfma_f32_16x16x32_bf16 v[88:91], v[178:181], v[194:197], v[88:91]
	v_mfma_f32_16x16x32_bf16 v[80:83], v[170:173], v[202:205], v[80:83]
	v_mfma_f32_16x16x32_bf16 v[72:75], v[178:181], v[202:205], v[72:75]
	v_mfma_f32_16x16x32_bf16 v[68:71], v[170:173], v[210:213], v[68:71]
	v_mfma_f32_16x16x32_bf16 v[64:67], v[178:181], v[210:213], v[64:67]
	v_mfma_f32_16x16x32_bf16 v[112:115], v[174:177], v[190:193], v[112:115]
	v_mfma_f32_16x16x32_bf16 v[104:107], v[182:185], v[190:193], v[104:107]
	v_mfma_f32_16x16x32_bf16 v[96:99], v[174:177], v[198:201], v[96:99]
	v_mfma_f32_16x16x32_bf16 v[88:91], v[182:185], v[198:201], v[88:91]
	v_mfma_f32_16x16x32_bf16 v[80:83], v[174:177], v[206:209], v[80:83]
	v_mfma_f32_16x16x32_bf16 v[72:75], v[182:185], v[206:209], v[72:75]
	v_mfma_f32_16x16x32_bf16 v[68:71], v[174:177], v[214:217], v[68:71]
	v_mfma_f32_16x16x32_bf16 v[64:67], v[182:185], v[214:217], v[64:67]
	s_setprio 0
	s_barrier
	s_add_i32 s54, s76, s59
	v_lshl_add_u64 v[218:219], v[218:219], 0, s[12:13]
	s_mov_b32 m0, s54
	ds_read_b128 v[186:189], v159 offset:49152
	ds_read_b128 v[190:193], v159 offset:50176
	ds_read_b128 v[194:197], v159 offset:51200
	ds_read_b128 v[198:201], v159 offset:52224
	ds_read_b128 v[202:205], v159 offset:53248
	ds_read_b128 v[206:209], v159 offset:54272
	ds_read_b128 v[210:213], v159 offset:55296
	ds_read_b128 v[214:217], v159 offset:56320
	global_load_lds_dwordx4 v[218:219], off
	s_add_i32 m0, s54, 0x2000
	s_add_u32 s52, s52, 0x40080
	v_lshl_add_u64 v[218:219], v[222:223], 0, s[12:13]
	s_addc_u32 s53, s53, 0
	s_add_i32 s54, s77, s59
	global_load_lds_dwordx4 v[218:219], off
	v_lshl_add_u64 v[218:219], s[52:53], 0, v[130:131]
	s_mov_b32 m0, s54
	s_nop 0
	global_load_lds_dwordx4 v[218:219], off
	v_lshl_add_u64 v[218:219], s[52:53], 0, v[134:135]
	s_add_i32 m0, s54, 0x2000
	s_nop 0
	global_load_lds_dwordx4 v[218:219], off
	v_lshl_add_u64 v[218:219], v[224:225], 0, s[12:13]
	s_mov_b32 m0, s64
	s_nop 0
	global_load_lds_dwordx4 v[218:219], off
	v_lshl_add_u64 v[218:219], v[226:227], 0, s[12:13]
	s_mov_b32 m0, s65
	s_nop 0
	global_load_lds_dwordx4 v[218:219], off
	s_waitcnt vmcnt(8)
	s_waitcnt lgkmcnt(0)
	s_barrier
	s_setprio 1
	s_waitcnt lgkmcnt(0)
	v_mfma_f32_16x16x32_bf16 v[60:63], v[146:149], v[186:189], v[60:63]
	v_mfma_f32_16x16x32_bf16 v[56:59], v[162:165], v[186:189], v[56:59]
	v_mfma_f32_16x16x32_bf16 v[52:55], v[146:149], v[194:197], v[52:55]
	v_mfma_f32_16x16x32_bf16 v[44:47], v[162:165], v[194:197], v[44:47]
	v_mfma_f32_16x16x32_bf16 v[36:39], v[146:149], v[202:205], v[36:39]
	v_mfma_f32_16x16x32_bf16 v[28:31], v[162:165], v[202:205], v[28:31]
	v_mfma_f32_16x16x32_bf16 v[20:23], v[146:149], v[210:213], v[20:23]
	v_mfma_f32_16x16x32_bf16 v[12:15], v[162:165], v[210:213], v[12:15]
	v_mfma_f32_16x16x32_bf16 v[60:63], v[150:153], v[190:193], v[60:63]
	v_mfma_f32_16x16x32_bf16 v[56:59], v[166:169], v[190:193], v[56:59]
	v_mfma_f32_16x16x32_bf16 v[52:55], v[150:153], v[198:201], v[52:55]
	v_mfma_f32_16x16x32_bf16 v[44:47], v[166:169], v[198:201], v[44:47]
	v_mfma_f32_16x16x32_bf16 v[36:39], v[150:153], v[206:209], v[36:39]
	v_mfma_f32_16x16x32_bf16 v[28:31], v[166:169], v[206:209], v[28:31]
	v_mfma_f32_16x16x32_bf16 v[20:23], v[150:153], v[214:217], v[20:23]
	v_mfma_f32_16x16x32_bf16 v[12:15], v[166:169], v[214:217], v[12:15]
	s_setprio 0
	s_setprio 1
	v_mfma_f32_16x16x32_bf16 v[48:51], v[170:173], v[186:189], v[48:51]
	v_mfma_f32_16x16x32_bf16 v[40:43], v[178:181], v[186:189], v[40:43]
	v_mfma_f32_16x16x32_bf16 v[32:35], v[170:173], v[194:197], v[32:35]
	v_mfma_f32_16x16x32_bf16 v[24:27], v[178:181], v[194:197], v[24:27]
	v_mfma_f32_16x16x32_bf16 v[16:19], v[170:173], v[202:205], v[16:19]
	v_mfma_f32_16x16x32_bf16 v[8:11], v[178:181], v[202:205], v[8:11]
	v_mfma_f32_16x16x32_bf16 v[4:7], v[170:173], v[210:213], v[4:7]
	v_mfma_f32_16x16x32_bf16 v[0:3], v[178:181], v[210:213], v[0:3]
	v_mfma_f32_16x16x32_bf16 v[48:51], v[174:177], v[190:193], v[48:51]
	v_mfma_f32_16x16x32_bf16 v[40:43], v[182:185], v[190:193], v[40:43]
	v_mfma_f32_16x16x32_bf16 v[32:35], v[174:177], v[198:201], v[32:35]
	v_mfma_f32_16x16x32_bf16 v[24:27], v[182:185], v[198:201], v[24:27]
	v_mfma_f32_16x16x32_bf16 v[16:19], v[174:177], v[206:209], v[16:19]
	v_mfma_f32_16x16x32_bf16 v[8:11], v[182:185], v[206:209], v[8:11]
	v_mfma_f32_16x16x32_bf16 v[4:7], v[174:177], v[214:217], v[4:7]
	v_mfma_f32_16x16x32_bf16 v[0:3], v[182:185], v[214:217], v[0:3]
	s_setprio 0
	s_barrier
	s_add_i32 s75, s75, 2
	s_add_u32 s50, s50, 0x100
	s_addc_u32 s51, s51, 0
	s_add_u32 s73, s73, 0x100
	s_addc_u32 s74, s74, 0
	s_cmp_gt_u32 s75, 13
	s_cbranch_scc0 .LBB0_491
	s_branch .Lpeel_exit_P4

.Lpeel_exit_P4:
	s_mov_b32 s98, 0
	s_and_b64 vcc, exec, s[14:15]
	s_cbranch_vccz .LBB0_496
	s_barrier
	v_lshl_add_u32 v146, s48, 8, v154
	s_cmp_gt_i32 s38, 18
	s_mov_b64 s[48:49], -1
	s_cbranch_scc1 .LBB0_497

.LBB0_495:
	s_cmp_lt_i32 s38, 2
	s_cselect_b64 s[48:49], -1, 0
	s_add_i32 s2, s38, -5
	s_cmp_lt_u32 s2, 2
	s_cselect_b64 s[50:51], -1, 0
	s_or_b64 vcc, s[48:49], s[50:51]
	v_lshl_or_b32 v152, s38, 8, v156
	v_cndmask_b32_e32 v148, 1.0, v160, vcc
	v_ashrrev_i32_e32 v153, 31, v152
	v_mov_b64_e32 v[150:151], s[8:9]
	v_mad_i64_i32 v[162:163], s[48:49], v146, s72, v[150:151]
	v_lshlrev_b64 v[152:153], 1, v[152:153]
	v_pk_mul_f32 v[126:127], v[148:149], v[126:127] op_sel_hi:[0,1]
	v_pk_mul_f32 v[124:125], v[148:149], v[124:125] op_sel_hi:[0,1]
	v_pk_mul_f32 v[164:165], v[148:149], v[122:123] op_sel_hi:[0,1]
	v_pk_mul_f32 v[122:123], v[148:149], v[120:121] op_sel_hi:[0,1]
	v_lshl_add_u64 v[162:163], v[162:163], 0, v[152:153]
	v_cvt_pk_bf16_f32 v120, v124, v125
	v_cvt_pk_bf16_f32 v121, v126, v127
	v_cvt_pk_bf16_f32 v122, v122, v123
	v_cvt_pk_bf16_f32 v123, v164, v165
	global_store_dwordx4 v[162:163], v[120:123], off
	v_pk_mul_f32 v[114:115], v[148:149], v[114:115] op_sel_hi:[0,1]
	v_pk_mul_f32 v[112:113], v[148:149], v[112:113] op_sel_hi:[0,1]
	v_pk_mul_f32 v[120:121], v[148:149], v[106:107] op_sel_hi:[0,1]
	v_pk_mul_f32 v[106:107], v[148:149], v[104:105] op_sel_hi:[0,1]
	v_cvt_pk_bf16_f32 v104, v112, v113
	v_cvt_pk_bf16_f32 v105, v114, v115
	v_cvt_pk_bf16_f32 v106, v106, v107
	v_cvt_pk_bf16_f32 v107, v120, v121
	global_store_dwordx4 v[162:163], v[104:107], off offset:256
	v_pk_mul_f32 v[110:111], v[148:149], v[110:111] op_sel_hi:[0,1]
	v_pk_mul_f32 v[108:109], v[148:149], v[108:109] op_sel_hi:[0,1]
	v_or_b32_e32 v104, 16, v146
	v_mad_i64_i32 v[104:105], s[48:49], v104, s72, v[150:151]
	v_lshl_add_u64 v[112:113], v[104:105], 0, v[152:153]
	v_pk_mul_f32 v[106:107], v[148:149], v[118:119] op_sel_hi:[0,1]
	v_pk_mul_f32 v[104:105], v[148:149], v[116:117] op_sel_hi:[0,1]
	v_cvt_pk_bf16_f32 v104, v104, v105
	v_cvt_pk_bf16_f32 v105, v106, v107
	v_cvt_pk_bf16_f32 v106, v108, v109
	v_cvt_pk_bf16_f32 v107, v110, v111
	global_store_dwordx4 v[112:113], v[104:107], off
	v_pk_mul_f32 v[98:99], v[148:149], v[98:99] op_sel_hi:[0,1]
	v_pk_mul_f32 v[96:97], v[148:149], v[96:97] op_sel_hi:[0,1]
	v_pk_mul_f32 v[104:105], v[148:149], v[90:91] op_sel_hi:[0,1]
	v_pk_mul_f32 v[90:91], v[148:149], v[88:89] op_sel_hi:[0,1]
	v_cvt_pk_bf16_f32 v88, v96, v97
	v_cvt_pk_bf16_f32 v89, v98, v99
	v_cvt_pk_bf16_f32 v90, v90, v91
	v_cvt_pk_bf16_f32 v91, v104, v105
	global_store_dwordx4 v[112:113], v[88:91], off offset:256
	v_pk_mul_f32 v[94:95], v[148:149], v[94:95] op_sel_hi:[0,1]
	v_pk_mul_f32 v[92:93], v[148:149], v[92:93] op_sel_hi:[0,1]
	v_or_b32_e32 v88, 32, v146
	v_mad_i64_i32 v[88:89], s[48:49], v88, s72, v[150:151]
	v_lshl_add_u64 v[96:97], v[88:89], 0, v[152:153]
	v_pk_mul_f32 v[90:91], v[148:149], v[102:103] op_sel_hi:[0,1]
	v_pk_mul_f32 v[88:89], v[148:149], v[100:101] op_sel_hi:[0,1]
	v_cvt_pk_bf16_f32 v88, v88, v89
	v_cvt_pk_bf16_f32 v89, v90, v91
	v_cvt_pk_bf16_f32 v90, v92, v93
	v_cvt_pk_bf16_f32 v91, v94, v95
	global_store_dwordx4 v[96:97], v[88:91], off
	v_pk_mul_f32 v[82:83], v[148:149], v[82:83] op_sel_hi:[0,1]
	v_pk_mul_f32 v[80:81], v[148:149], v[80:81] op_sel_hi:[0,1]
	v_pk_mul_f32 v[88:89], v[148:149], v[74:75] op_sel_hi:[0,1]
	v_pk_mul_f32 v[74:75], v[148:149], v[72:73] op_sel_hi:[0,1]
	v_cvt_pk_bf16_f32 v72, v80, v81
	v_cvt_pk_bf16_f32 v73, v82, v83
	v_cvt_pk_bf16_f32 v74, v74, v75
	v_cvt_pk_bf16_f32 v75, v88, v89
	global_store_dwordx4 v[96:97], v[72:75], off offset:256
	v_pk_mul_f32 v[78:79], v[148:149], v[78:79] op_sel_hi:[0,1]
	v_pk_mul_f32 v[76:77], v[148:149], v[76:77] op_sel_hi:[0,1]
	v_or_b32_e32 v72, 48, v146
	v_mad_i64_i32 v[72:73], s[48:49], v72, s72, v[150:151]
	v_lshl_add_u64 v[80:81], v[72:73], 0, v[152:153]
	v_pk_mul_f32 v[74:75], v[148:149], v[86:87] op_sel_hi:[0,1]
	v_pk_mul_f32 v[72:73], v[148:149], v[84:85] op_sel_hi:[0,1]
	v_cvt_pk_bf16_f32 v72, v72, v73
	v_cvt_pk_bf16_f32 v73, v74, v75
	v_cvt_pk_bf16_f32 v74, v76, v77
	v_cvt_pk_bf16_f32 v75, v78, v79
	global_store_dwordx4 v[80:81], v[72:75], off
	v_pk_mul_f32 v[70:71], v[148:149], v[70:71] op_sel_hi:[0,1]
	v_pk_mul_f32 v[68:69], v[148:149], v[68:69] op_sel_hi:[0,1]
	v_pk_mul_f32 v[72:73], v[148:149], v[66:67] op_sel_hi:[0,1]
	v_pk_mul_f32 v[66:67], v[148:149], v[64:65] op_sel_hi:[0,1]
	v_cvt_pk_bf16_f32 v64, v68, v69
	v_cvt_pk_bf16_f32 v65, v70, v71
	v_cvt_pk_bf16_f32 v66, v66, v67
	v_cvt_pk_bf16_f32 v67, v72, v73
	global_store_dwordx4 v[80:81], v[64:67], off offset:256
	v_pk_mul_f32 v[62:63], v[148:149], v[62:63] op_sel_hi:[0,1]
	v_pk_mul_f32 v[60:61], v[148:149], v[60:61] op_sel_hi:[0,1]
	v_add_u32_e32 v64, 0x80, v146
	v_mad_i64_i32 v[64:65], s[48:49], v64, s72, v[150:151]
	v_pk_mul_f32 v[66:67], v[148:149], v[58:59] op_sel_hi:[0,1]
	v_pk_mul_f32 v[58:59], v[148:149], v[56:57] op_sel_hi:[0,1]
	v_lshl_add_u64 v[64:65], v[64:65], 0, v[152:153]
	v_cvt_pk_bf16_f32 v56, v60, v61
	v_cvt_pk_bf16_f32 v57, v62, v63
	v_cvt_pk_bf16_f32 v58, v58, v59
	v_cvt_pk_bf16_f32 v59, v66, v67
	global_store_dwordx4 v[64:65], v[56:59], off
	v_pk_mul_f32 v[50:51], v[148:149], v[50:51] op_sel_hi:[0,1]
	v_pk_mul_f32 v[48:49], v[148:149], v[48:49] op_sel_hi:[0,1]
	v_pk_mul_f32 v[56:57], v[148:149], v[42:43] op_sel_hi:[0,1]
	v_pk_mul_f32 v[42:43], v[148:149], v[40:41] op_sel_hi:[0,1]
	v_cvt_pk_bf16_f32 v40, v48, v49
	v_cvt_pk_bf16_f32 v41, v50, v51
	v_cvt_pk_bf16_f32 v42, v42, v43
	v_cvt_pk_bf16_f32 v43, v56, v57
	global_store_dwordx4 v[64:65], v[40:43], off offset:256
	v_pk_mul_f32 v[46:47], v[148:149], v[46:47] op_sel_hi:[0,1]
	v_pk_mul_f32 v[44:45], v[148:149], v[44:45] op_sel_hi:[0,1]
	v_add_u32_e32 v40, 0x90, v146
	v_mad_i64_i32 v[40:41], s[48:49], v40, s72, v[150:151]
	v_lshl_add_u64 v[48:49], v[40:41], 0, v[152:153]
	v_pk_mul_f32 v[42:43], v[148:149], v[54:55] op_sel_hi:[0,1]
	v_pk_mul_f32 v[40:41], v[148:149], v[52:53] op_sel_hi:[0,1]
	v_cvt_pk_bf16_f32 v40, v40, v41
	v_cvt_pk_bf16_f32 v41, v42, v43
	v_cvt_pk_bf16_f32 v42, v44, v45
	v_cvt_pk_bf16_f32 v43, v46, v47
	global_store_dwordx4 v[48:49], v[40:43], off
	v_pk_mul_f32 v[34:35], v[148:149], v[34:35] op_sel_hi:[0,1]
	v_pk_mul_f32 v[32:33], v[148:149], v[32:33] op_sel_hi:[0,1]
	v_pk_mul_f32 v[40:41], v[148:149], v[26:27] op_sel_hi:[0,1]
	v_pk_mul_f32 v[26:27], v[148:149], v[24:25] op_sel_hi:[0,1]
	v_cvt_pk_bf16_f32 v24, v32, v33
	v_cvt_pk_bf16_f32 v25, v34, v35
	v_cvt_pk_bf16_f32 v26, v26, v27
	v_cvt_pk_bf16_f32 v27, v40, v41
	global_store_dwordx4 v[48:49], v[24:27], off offset:256
	v_pk_mul_f32 v[30:31], v[148:149], v[30:31] op_sel_hi:[0,1]
	v_pk_mul_f32 v[28:29], v[148:149], v[28:29] op_sel_hi:[0,1]
	v_add_u32_e32 v24, 0xa0, v146
	v_mad_i64_i32 v[24:25], s[48:49], v24, s72, v[150:151]
	v_lshl_add_u64 v[32:33], v[24:25], 0, v[152:153]
	v_pk_mul_f32 v[26:27], v[148:149], v[38:39] op_sel_hi:[0,1]
	v_pk_mul_f32 v[24:25], v[148:149], v[36:37] op_sel_hi:[0,1]
	v_cvt_pk_bf16_f32 v24, v24, v25
	v_cvt_pk_bf16_f32 v25, v26, v27
	v_cvt_pk_bf16_f32 v26, v28, v29
	v_cvt_pk_bf16_f32 v27, v30, v31
	global_store_dwordx4 v[32:33], v[24:27], off
	v_pk_mul_f32 v[18:19], v[148:149], v[18:19] op_sel_hi:[0,1]
	v_pk_mul_f32 v[16:17], v[148:149], v[16:17] op_sel_hi:[0,1]
	v_pk_mul_f32 v[24:25], v[148:149], v[10:11] op_sel_hi:[0,1]
	v_pk_mul_f32 v[10:11], v[148:149], v[8:9] op_sel_hi:[0,1]
	v_cvt_pk_bf16_f32 v8, v16, v17
	v_cvt_pk_bf16_f32 v9, v18, v19
	v_cvt_pk_bf16_f32 v10, v10, v11
	v_cvt_pk_bf16_f32 v11, v24, v25
	global_store_dwordx4 v[32:33], v[8:11], off offset:256
	v_pk_mul_f32 v[14:15], v[148:149], v[14:15] op_sel_hi:[0,1]
	v_pk_mul_f32 v[12:13], v[148:149], v[12:13] op_sel_hi:[0,1]
	v_add_u32_e32 v8, 0xb0, v146
	v_mad_i64_i32 v[8:9], s[48:49], v8, s72, v[150:151]
	v_lshl_add_u64 v[16:17], v[8:9], 0, v[152:153]
	v_pk_mul_f32 v[10:11], v[148:149], v[22:23] op_sel_hi:[0,1]
	v_pk_mul_f32 v[8:9], v[148:149], v[20:21] op_sel_hi:[0,1]
	v_cvt_pk_bf16_f32 v8, v8, v9
	v_cvt_pk_bf16_f32 v9, v10, v11
	v_cvt_pk_bf16_f32 v10, v12, v13
	v_cvt_pk_bf16_f32 v11, v14, v15
	global_store_dwordx4 v[16:17], v[8:11], off
	v_pk_mul_f32 v[6:7], v[148:149], v[6:7] op_sel_hi:[0,1]
	v_pk_mul_f32 v[4:5], v[148:149], v[4:5] op_sel_hi:[0,1]
	v_pk_mul_f32 v[8:9], v[148:149], v[2:3] op_sel_hi:[0,1]
	v_pk_mul_f32 v[2:3], v[148:149], v[0:1] op_sel_hi:[0,1]
	v_cvt_pk_bf16_f32 v0, v4, v5
	v_cvt_pk_bf16_f32 v1, v6, v7
	v_cvt_pk_bf16_f32 v2, v2, v3
	v_cvt_pk_bf16_f32 v3, v8, v9
	global_store_dwordx4 v[16:17], v[0:3], off offset:256
	s_andn2_b64 vcc, exec, s[6:7]
	s_mov_b64 s[6:7], -1
	s_mov_b32 s98, 1
	s_cbranch_vccnz .LBB0_487
	s_branch .LBB0_500

.LBB0_1090:
	s_add_u32 s8, s6, 0x86a0000
	s_addc_u32 s9, s7, 0
	s_add_u32 s10, s6, 0x186a0000
	s_addc_u32 s11, s7, 0
	s_lshl_b32 s6, s12, 5
	s_mov_b64 s[12:13], 0x80
	s_and_b32 s17, s6, 0x60
	s_add_i32 m0, s27, 0x18000
	v_lshl_add_u64 v[6:7], v[6:7], 0, s[12:13]
	s_lshl_b32 s16, s15, 13
	s_lshl_b32 s18, s17, 7
	s_waitcnt vmcnt(2)
	s_barrier
	global_load_lds_dwordx4 v[6:7], off
	v_lshl_add_u64 v[4:5], v[4:5], 0, s[12:13]
	s_add_i32 m0, s27, 0x1a000
	s_add_i32 s44, s27, 0x8000
	s_add_i32 s45, s27, 0xa000
	global_load_lds_dwordx4 v[4:5], off
	v_lshl_add_u64 v[0:1], v[0:1], 0, s[12:13]
	s_mov_b32 m0, s44
	s_add_u32 s6, s30, 0x20080
	global_load_lds_dwordx4 v[0:1], off
	v_lshl_add_u64 v[0:1], v[2:3], 0, s[12:13]
	s_mov_b32 m0, s45
	s_addc_u32 s7, s31, 0
	global_load_lds_dwordx4 v[0:1], off
	s_add_i32 m0, s27, 0x1c000
	v_lshl_add_u64 v[0:1], s[6:7], 0, v[130:131]
	global_load_lds_dwordx4 v[0:1], off
	v_lshl_add_u64 v[0:1], s[6:7], 0, v[134:135]
	s_add_i32 m0, s27, 0x1e000
	s_cmpk_lt_u32 s2, 0x100
	global_load_lds_dwordx4 v[0:1], off
	v_lshrrev_b32_e32 v1, 1, v8
	v_and_b32_e32 v1, 24, v1
	v_and_b32_e32 v0, 15, v8
	v_lshlrev_b32_e32 v2, 1, v1
	v_lshl_or_b32 v152, s15, 6, v0
	v_lshl_or_b32 v0, v0, 6, v2
	v_lshlrev_b32_e32 v2, 2, v8
	v_and_b32_e32 v2, 32, v2
	v_bitop3_b32 v3, v0, s16, v2 bitop3:0xde
	v_bitop3_b32 v153, v0, s18, v2 bitop3:0xde
	v_lshlrev_b32_e32 v0, 13, v9
	v_and_b32_e32 v0, 0xffffc000, v0
	v_or_b32_e32 v154, s17, v1
	v_lshl_add_u32 v0, v10, 10, v0
	v_and_b32_e32 v1, 1, v9
	v_lshl_or_b32 v0, v1, 6, v0
	v_lshl_add_u32 v136, v11, 1, v0
	v_lshlrev_b32_e32 v0, 13, v12
	v_and_b32_e32 v0, 0xffffc000, v0
	s_waitcnt vmcnt(6)
	v_lshl_add_u32 v0, v13, 10, v0
	v_and_b32_e32 v1, 1, v12
	s_sext_i32_i8 s51, s14
	s_cselect_b64 s[14:15], -1, 0
	v_lshl_or_b32 v0, v1, 6, v0
	s_add_i32 s48, 0, 0x10000
	s_add_i32 s49, 0, 0x14000
	s_ashr_i32 s46, s90, 31
	s_mov_b32 s47, s90
	v_mov_b32_e32 v137, v131
	v_lshl_add_u32 v138, v14, 1, v0
	v_mov_b32_e32 v139, v131
	v_mov_b64_e32 v[140:141], 0x400
	v_mov_b64_e32 v[142:143], 0x3ff
	v_add_u32_e32 v155, s48, v153
	v_add_u32_e32 v156, s49, v153
	v_add_u32_e32 v157, 0, v3
	s_movk_i32 s50, 0x2600
	s_mov_b64 s[16:17], 0x1600
	s_barrier
	s_mov_b32 s98, 0
	s_branch .LBB0_1093

.LBB0_1099:
	s_ashr_i32 s21, s20, 31
	s_lshl_b64 s[22:23], s[20:21], 18
	s_add_u32 s22, s33, s22
	s_addc_u32 s23, s36, s23
	s_and_b64 s[24:25], s[6:7], exec
	s_cselect_b32 s2, s23, s29
	s_cselect_b32 s21, s22, s28
	s_ashr_i32 s19, s18, 31
	s_lshl_b64 s[24:25], s[18:19], 18
	s_add_u32 s24, s37, s24
	s_addc_u32 s25, s38, s25
	s_and_b64 s[34:35], s[6:7], exec
	s_cselect_b32 s19, s25, s31
	s_cselect_b32 s52, s24, s30
	s_add_u32 s28, s28, 0x20080
	s_addc_u32 s29, s29, 0
	s_add_u32 s53, s30, 0x100
	v_mov_b32_e32 v0, 0
	s_addc_u32 s54, s31, 0
	s_mov_b32 s55, -2
	v_mov_b32_e32 v1, v0
	v_mov_b32_e32 v2, v0
	v_mov_b32_e32 v3, v0
	v_mov_b32_e32 v4, v0
	v_mov_b32_e32 v5, v0
	v_mov_b32_e32 v6, v0
	v_mov_b32_e32 v7, v0
	v_mov_b32_e32 v16, v0
	v_mov_b32_e32 v17, v0
	v_mov_b32_e32 v18, v0
	v_mov_b32_e32 v19, v0
	v_mov_b32_e32 v20, v0
	v_mov_b32_e32 v21, v0
	v_mov_b32_e32 v22, v0
	v_mov_b32_e32 v23, v0
	v_mov_b32_e32 v32, v0
	v_mov_b32_e32 v33, v0
	v_mov_b32_e32 v34, v0
	v_mov_b32_e32 v35, v0
	v_mov_b32_e32 v36, v0
	v_mov_b32_e32 v37, v0
	v_mov_b32_e32 v38, v0
	v_mov_b32_e32 v39, v0
	v_mov_b32_e32 v48, v0
	v_mov_b32_e32 v49, v0
	v_mov_b32_e32 v50, v0
	v_mov_b32_e32 v51, v0
	v_mov_b32_e32 v52, v0
	v_mov_b32_e32 v53, v0
	v_mov_b32_e32 v54, v0
	v_mov_b32_e32 v55, v0
	v_mov_b32_e32 v8, v0
	v_mov_b32_e32 v9, v0
	v_mov_b32_e32 v10, v0
	v_mov_b32_e32 v11, v0
	v_mov_b32_e32 v12, v0
	v_mov_b32_e32 v13, v0
	v_mov_b32_e32 v14, v0
	v_mov_b32_e32 v15, v0
	v_mov_b32_e32 v24, v0
	v_mov_b32_e32 v25, v0
	v_mov_b32_e32 v26, v0
	v_mov_b32_e32 v27, v0
	v_mov_b32_e32 v28, v0
	v_mov_b32_e32 v29, v0
	v_mov_b32_e32 v30, v0
	v_mov_b32_e32 v31, v0
	v_mov_b32_e32 v40, v0
	v_mov_b32_e32 v41, v0
	v_mov_b32_e32 v42, v0
	v_mov_b32_e32 v43, v0
	v_mov_b32_e32 v44, v0
	v_mov_b32_e32 v45, v0
	v_mov_b32_e32 v46, v0
	v_mov_b32_e32 v47, v0
	v_mov_b32_e32 v56, v0
	v_mov_b32_e32 v57, v0
	v_mov_b32_e32 v58, v0
	v_mov_b32_e32 v59, v0
	v_mov_b32_e32 v60, v0
	v_mov_b32_e32 v61, v0
	v_mov_b32_e32 v62, v0
	v_mov_b32_e32 v63, v0
	v_mov_b32_e32 v64, v0
	v_mov_b32_e32 v65, v0
	v_mov_b32_e32 v66, v0
	v_mov_b32_e32 v67, v0
	v_mov_b32_e32 v68, v0
	v_mov_b32_e32 v69, v0
	v_mov_b32_e32 v70, v0
	v_mov_b32_e32 v71, v0
	v_mov_b32_e32 v80, v0
	v_mov_b32_e32 v81, v0
	v_mov_b32_e32 v82, v0
	v_mov_b32_e32 v83, v0
	v_mov_b32_e32 v84, v0
	v_mov_b32_e32 v85, v0
	v_mov_b32_e32 v86, v0
	v_mov_b32_e32 v87, v0
	v_mov_b32_e32 v96, v0
	v_mov_b32_e32 v97, v0
	v_mov_b32_e32 v98, v0
	v_mov_b32_e32 v99, v0
	v_mov_b32_e32 v100, v0
	v_mov_b32_e32 v101, v0
	v_mov_b32_e32 v102, v0
	v_mov_b32_e32 v103, v0
	v_mov_b32_e32 v112, v0
	v_mov_b32_e32 v113, v0
	v_mov_b32_e32 v114, v0
	v_mov_b32_e32 v115, v0
	v_mov_b32_e32 v116, v0
	v_mov_b32_e32 v117, v0
	v_mov_b32_e32 v118, v0
	v_mov_b32_e32 v119, v0
	v_mov_b32_e32 v72, v0
	v_mov_b32_e32 v73, v0
	v_mov_b32_e32 v74, v0
	v_mov_b32_e32 v75, v0
	v_mov_b32_e32 v76, v0
	v_mov_b32_e32 v77, v0
	v_mov_b32_e32 v78, v0
	v_mov_b32_e32 v79, v0
	v_mov_b32_e32 v88, v0
	v_mov_b32_e32 v89, v0
	v_mov_b32_e32 v90, v0
	v_mov_b32_e32 v91, v0
	v_mov_b32_e32 v92, v0
	v_mov_b32_e32 v93, v0
	v_mov_b32_e32 v94, v0
	v_mov_b32_e32 v95, v0
	v_mov_b32_e32 v104, v0
	v_mov_b32_e32 v105, v0
	v_mov_b32_e32 v106, v0
	v_mov_b32_e32 v107, v0
	v_mov_b32_e32 v108, v0
	v_mov_b32_e32 v109, v0
	v_mov_b32_e32 v110, v0
	v_mov_b32_e32 v111, v0
	v_mov_b32_e32 v120, v0
	v_mov_b32_e32 v121, v0
	v_mov_b32_e32 v122, v0
	v_mov_b32_e32 v123, v0
	v_mov_b32_e32 v124, v0
	v_mov_b32_e32 v125, v0
	v_mov_b32_e32 v126, v0
	v_mov_b32_e32 v127, v0
	s_cmp_eq_u32 s98, 0
	s_cbranch_scc1 .LBB0_1100
	ds_read_b128 v[144:147], v155
	ds_read_b128 v[148:151], v155 offset:1024
	ds_read_b128 v[158:161], v155 offset:2048
	ds_read_b128 v[162:165], v155 offset:3072
	ds_read_b128 v[166:169], v156
	ds_read_b128 v[170:173], v156 offset:1024
	ds_read_b128 v[174:177], v156 offset:2048
	ds_read_b128 v[178:181], v156 offset:3072
	s_add_u32 s30, s28, 0xfffe0080
	s_addc_u32 s31, s29, -1
	s_cmp_eq_u32 s55, 4
	s_cselect_b32 s35, s2, s31
	s_cselect_b32 s34, s21, s30
	s_cselect_b32 s31, s19, s54
	s_cselect_b32 s30, s52, s53
	v_lshl_add_u64 v[214:215], s[28:29], 0, v[136:137]
	s_add_i32 m0, s27, 0xc000
	ds_read_b128 v[182:185], v157
	ds_read_b128 v[186:189], v157 offset:1024
	ds_read_b128 v[190:193], v157 offset:2048
	ds_read_b128 v[194:197], v157 offset:3072
	ds_read_b128 v[198:201], v157 offset:4096
	ds_read_b128 v[202:205], v157 offset:5120
	ds_read_b128 v[206:209], v157 offset:6144
	ds_read_b128 v[210:213], v157 offset:7168
	global_load_lds_dwordx4 v[214:215], off
	v_lshl_add_u64 v[214:215], s[28:29], 0, v[138:139]
	s_add_i32 m0, s27, 0xe000
	s_nop 0
	global_load_lds_dwordx4 v[214:215], off
	s_waitcnt vmcnt(30)
	s_waitcnt lgkmcnt(0)
	s_barrier
	s_setprio 1
	s_waitcnt lgkmcnt(0)
	v_mfma_f32_16x16x32_bf16 v[124:127], v[144:147], v[182:185], v[124:127]
	v_mfma_f32_16x16x32_bf16 v[120:123], v[158:161], v[182:185], v[120:123]
	v_mfma_f32_16x16x32_bf16 v[108:111], v[144:147], v[190:193], v[108:111]
	v_mfma_f32_16x16x32_bf16 v[104:107], v[158:161], v[190:193], v[104:107]
	v_mfma_f32_16x16x32_bf16 v[92:95], v[144:147], v[198:201], v[92:95]
	v_mfma_f32_16x16x32_bf16 v[88:91], v[158:161], v[198:201], v[88:91]
	v_mfma_f32_16x16x32_bf16 v[76:79], v[144:147], v[206:209], v[76:79]
	v_mfma_f32_16x16x32_bf16 v[72:75], v[158:161], v[206:209], v[72:75]
	v_mfma_f32_16x16x32_bf16 v[124:127], v[148:151], v[186:189], v[124:127]
	v_mfma_f32_16x16x32_bf16 v[120:123], v[162:165], v[186:189], v[120:123]
	v_mfma_f32_16x16x32_bf16 v[108:111], v[148:151], v[194:197], v[108:111]
	v_mfma_f32_16x16x32_bf16 v[104:107], v[162:165], v[194:197], v[104:107]
	v_mfma_f32_16x16x32_bf16 v[92:95], v[148:151], v[202:205], v[92:95]
	v_mfma_f32_16x16x32_bf16 v[88:91], v[162:165], v[202:205], v[88:91]
	v_mfma_f32_16x16x32_bf16 v[76:79], v[148:151], v[210:213], v[76:79]
	v_mfma_f32_16x16x32_bf16 v[72:75], v[162:165], v[210:213], v[72:75]
	s_setprio 0
	s_setprio 1
	v_mfma_f32_16x16x32_bf16 v[116:119], v[166:169], v[182:185], v[116:119]
	v_mfma_f32_16x16x32_bf16 v[112:115], v[174:177], v[182:185], v[112:115]
	v_mfma_f32_16x16x32_bf16 v[100:103], v[166:169], v[190:193], v[100:103]
	v_mfma_f32_16x16x32_bf16 v[96:99], v[174:177], v[190:193], v[96:99]
	v_mfma_f32_16x16x32_bf16 v[84:87], v[166:169], v[198:201], v[84:87]
	v_mfma_f32_16x16x32_bf16 v[80:83], v[174:177], v[198:201], v[80:83]
	v_mfma_f32_16x16x32_bf16 v[68:71], v[166:169], v[206:209], v[68:71]
	v_mfma_f32_16x16x32_bf16 v[64:67], v[174:177], v[206:209], v[64:67]
	v_mfma_f32_16x16x32_bf16 v[116:119], v[170:173], v[186:189], v[116:119]
	v_mfma_f32_16x16x32_bf16 v[112:115], v[178:181], v[186:189], v[112:115]
	v_mfma_f32_16x16x32_bf16 v[100:103], v[170:173], v[194:197], v[100:103]
	v_mfma_f32_16x16x32_bf16 v[96:99], v[178:181], v[194:197], v[96:99]
	v_mfma_f32_16x16x32_bf16 v[84:87], v[170:173], v[202:205], v[84:87]
	v_mfma_f32_16x16x32_bf16 v[80:83], v[178:181], v[202:205], v[80:83]
	v_mfma_f32_16x16x32_bf16 v[68:71], v[170:173], v[210:213], v[68:71]
	v_mfma_f32_16x16x32_bf16 v[64:67], v[178:181], v[210:213], v[64:67]
	s_setprio 0
	s_barrier
	s_add_i32 s56, s48, s39
	v_lshl_add_u64 v[214:215], s[30:31], 0, v[130:131]
	s_mov_b32 m0, s56
	ds_read_b128 v[182:185], v157 offset:16384
	ds_read_b128 v[186:189], v157 offset:17408
	ds_read_b128 v[190:193], v157 offset:18432
	ds_read_b128 v[194:197], v157 offset:19456
	ds_read_b128 v[198:201], v157 offset:20480
	ds_read_b128 v[202:205], v157 offset:21504
	ds_read_b128 v[206:209], v157 offset:22528
	ds_read_b128 v[210:213], v157 offset:23552
	global_load_lds_dwordx4 v[214:215], off
	s_add_i32 m0, s56, 0x2000
	s_add_u32 s56, s30, 0x20000
	v_lshl_add_u64 v[216:217], s[30:31], 0, v[134:135]
	s_addc_u32 s57, s31, 0
	s_add_i32 s58, s49, s39
	global_load_lds_dwordx4 v[216:217], off
	v_lshl_add_u64 v[218:219], s[56:57], 0, v[130:131]
	s_mov_b32 m0, s58
	v_lshl_add_u64 v[220:221], s[34:35], 0, v[132:133]
	global_load_lds_dwordx4 v[218:219], off
	v_lshl_add_u64 v[218:219], s[56:57], 0, v[134:135]
	s_add_i32 m0, s58, 0x2000
	s_nop 0
	global_load_lds_dwordx4 v[218:219], off
	v_lshl_add_u64 v[218:219], s[34:35], 0, v[128:129]
	s_mov_b32 m0, s27
	s_nop 0
	global_load_lds_dwordx4 v[218:219], off
	s_mov_b32 m0, s40
	s_nop 0
	global_load_lds_dwordx4 v[220:221], off
	s_waitcnt vmcnt(30)
	s_waitcnt lgkmcnt(0)
	s_barrier
	s_setprio 1
	s_waitcnt lgkmcnt(0)
	v_mfma_f32_16x16x32_bf16 v[60:63], v[144:147], v[182:185], v[60:63]
	v_mfma_f32_16x16x32_bf16 v[56:59], v[158:161], v[182:185], v[56:59]
	v_mfma_f32_16x16x32_bf16 v[44:47], v[144:147], v[190:193], v[44:47]
	v_mfma_f32_16x16x32_bf16 v[40:43], v[158:161], v[190:193], v[40:43]
	v_mfma_f32_16x16x32_bf16 v[28:31], v[144:147], v[198:201], v[28:31]
	v_mfma_f32_16x16x32_bf16 v[24:27], v[158:161], v[198:201], v[24:27]
	v_mfma_f32_16x16x32_bf16 v[12:15], v[144:147], v[206:209], v[12:15]
	v_mfma_f32_16x16x32_bf16 v[8:11], v[158:161], v[206:209], v[8:11]
	v_mfma_f32_16x16x32_bf16 v[60:63], v[148:151], v[186:189], v[60:63]
	v_mfma_f32_16x16x32_bf16 v[56:59], v[162:165], v[186:189], v[56:59]
	v_mfma_f32_16x16x32_bf16 v[44:47], v[148:151], v[194:197], v[44:47]
	v_mfma_f32_16x16x32_bf16 v[40:43], v[162:165], v[194:197], v[40:43]
	v_mfma_f32_16x16x32_bf16 v[28:31], v[148:151], v[202:205], v[28:31]
	v_mfma_f32_16x16x32_bf16 v[24:27], v[162:165], v[202:205], v[24:27]
	v_mfma_f32_16x16x32_bf16 v[12:15], v[148:151], v[210:213], v[12:15]
	v_mfma_f32_16x16x32_bf16 v[8:11], v[162:165], v[210:213], v[8:11]
	s_setprio 0
	s_setprio 1
	v_mfma_f32_16x16x32_bf16 v[52:55], v[166:169], v[182:185], v[52:55]
	v_mfma_f32_16x16x32_bf16 v[48:51], v[174:177], v[182:185], v[48:51]
	v_mfma_f32_16x16x32_bf16 v[36:39], v[166:169], v[190:193], v[36:39]
	v_mfma_f32_16x16x32_bf16 v[32:35], v[174:177], v[190:193], v[32:35]
	v_mfma_f32_16x16x32_bf16 v[20:23], v[166:169], v[198:201], v[20:23]
	v_mfma_f32_16x16x32_bf16 v[16:19], v[174:177], v[198:201], v[16:19]
	v_mfma_f32_16x16x32_bf16 v[4:7], v[166:169], v[206:209], v[4:7]
	v_mfma_f32_16x16x32_bf16 v[0:3], v[174:177], v[206:209], v[0:3]
	v_mfma_f32_16x16x32_bf16 v[52:55], v[170:173], v[186:189], v[52:55]
	v_mfma_f32_16x16x32_bf16 v[48:51], v[178:181], v[186:189], v[48:51]
	v_mfma_f32_16x16x32_bf16 v[36:39], v[170:173], v[194:197], v[36:39]
	v_mfma_f32_16x16x32_bf16 v[32:35], v[178:181], v[194:197], v[32:35]
	v_mfma_f32_16x16x32_bf16 v[20:23], v[170:173], v[202:205], v[20:23]
	v_mfma_f32_16x16x32_bf16 v[16:19], v[178:181], v[202:205], v[16:19]
	v_mfma_f32_16x16x32_bf16 v[4:7], v[170:173], v[210:213], v[4:7]
	v_mfma_f32_16x16x32_bf16 v[0:3], v[178:181], v[210:213], v[0:3]
	s_setprio 0
	s_barrier
	s_add_i32 s56, 0, 0x18000
	s_add_i32 s57, 0, 0x1c000
	v_add_u32_e32 v162, s56, v153
	v_add_u32_e32 v178, s57, v153
	ds_read_b128 v[144:147], v162
	ds_read_b128 v[148:151], v162 offset:1024
	ds_read_b128 v[158:161], v162 offset:2048
	ds_read_b128 v[162:165], v162 offset:3072
	ds_read_b128 v[166:169], v178
	ds_read_b128 v[170:173], v178 offset:1024
	ds_read_b128 v[174:177], v178 offset:2048
	ds_read_b128 v[178:181], v178 offset:3072
	s_add_u32 s34, s34, 0x20000
	s_addc_u32 s35, s35, 0
	s_mov_b32 m0, s41
	v_lshl_add_u64 v[222:223], s[34:35], 0, v[128:129]
	ds_read_b128 v[182:185], v157 offset:32768
	ds_read_b128 v[186:189], v157 offset:33792
	ds_read_b128 v[190:193], v157 offset:34816
	ds_read_b128 v[194:197], v157 offset:35840
	ds_read_b128 v[198:201], v157 offset:36864
	ds_read_b128 v[202:205], v157 offset:37888
	ds_read_b128 v[206:209], v157 offset:38912
	ds_read_b128 v[210:213], v157 offset:39936
	global_load_lds_dwordx4 v[222:223], off
	v_lshl_add_u64 v[222:223], s[34:35], 0, v[132:133]
	s_mov_b32 m0, s42
	s_nop 0
	global_load_lds_dwordx4 v[222:223], off
	s_waitcnt vmcnt(8)
	s_waitcnt lgkmcnt(0)
	s_barrier
	s_setprio 1
	s_waitcnt lgkmcnt(0)
	v_mfma_f32_16x16x32_bf16 v[124:127], v[144:147], v[182:185], v[124:127]
	v_mfma_f32_16x16x32_bf16 v[120:123], v[158:161], v[182:185], v[120:123]
	v_mfma_f32_16x16x32_bf16 v[108:111], v[144:147], v[190:193], v[108:111]
	v_mfma_f32_16x16x32_bf16 v[104:107], v[158:161], v[190:193], v[104:107]
	v_mfma_f32_16x16x32_bf16 v[92:95], v[144:147], v[198:201], v[92:95]
	v_mfma_f32_16x16x32_bf16 v[88:91], v[158:161], v[198:201], v[88:91]
	v_mfma_f32_16x16x32_bf16 v[76:79], v[144:147], v[206:209], v[76:79]
	v_mfma_f32_16x16x32_bf16 v[72:75], v[158:161], v[206:209], v[72:75]
	v_mfma_f32_16x16x32_bf16 v[124:127], v[148:151], v[186:189], v[124:127]
	v_mfma_f32_16x16x32_bf16 v[120:123], v[162:165], v[186:189], v[120:123]
	v_mfma_f32_16x16x32_bf16 v[108:111], v[148:151], v[194:197], v[108:111]
	v_mfma_f32_16x16x32_bf16 v[104:107], v[162:165], v[194:197], v[104:107]
	v_mfma_f32_16x16x32_bf16 v[92:95], v[148:151], v[202:205], v[92:95]
	v_mfma_f32_16x16x32_bf16 v[88:91], v[162:165], v[202:205], v[88:91]
	v_mfma_f32_16x16x32_bf16 v[76:79], v[148:151], v[210:213], v[76:79]
	v_mfma_f32_16x16x32_bf16 v[72:75], v[162:165], v[210:213], v[72:75]
	s_setprio 0
	s_setprio 1
	v_mfma_f32_16x16x32_bf16 v[116:119], v[166:169], v[182:185], v[116:119]
	v_mfma_f32_16x16x32_bf16 v[112:115], v[174:177], v[182:185], v[112:115]
	v_mfma_f32_16x16x32_bf16 v[100:103], v[166:169], v[190:193], v[100:103]
	v_mfma_f32_16x16x32_bf16 v[96:99], v[174:177], v[190:193], v[96:99]
	v_mfma_f32_16x16x32_bf16 v[84:87], v[166:169], v[198:201], v[84:87]
	v_mfma_f32_16x16x32_bf16 v[80:83], v[174:177], v[198:201], v[80:83]
	v_mfma_f32_16x16x32_bf16 v[68:71], v[166:169], v[206:209], v[68:71]
	v_mfma_f32_16x16x32_bf16 v[64:67], v[174:177], v[206:209], v[64:67]
	v_mfma_f32_16x16x32_bf16 v[116:119], v[170:173], v[186:189], v[116:119]
	v_mfma_f32_16x16x32_bf16 v[112:115], v[178:181], v[186:189], v[112:115]
	v_mfma_f32_16x16x32_bf16 v[100:103], v[170:173], v[194:197], v[100:103]
	v_mfma_f32_16x16x32_bf16 v[96:99], v[178:181], v[194:197], v[96:99]
	v_mfma_f32_16x16x32_bf16 v[84:87], v[170:173], v[202:205], v[84:87]
	v_mfma_f32_16x16x32_bf16 v[80:83], v[178:181], v[202:205], v[80:83]
	v_mfma_f32_16x16x32_bf16 v[68:71], v[170:173], v[210:213], v[68:71]
	v_mfma_f32_16x16x32_bf16 v[64:67], v[178:181], v[210:213], v[64:67]
	s_setprio 0
	s_barrier
	s_add_i32 s34, s56, s39
	v_lshl_add_u64 v[214:215], v[214:215], 0, s[12:13]
	s_mov_b32 m0, s34
	ds_read_b128 v[182:185], v157 offset:49152
	ds_read_b128 v[186:189], v157 offset:50176
	ds_read_b128 v[190:193], v157 offset:51200
	ds_read_b128 v[194:197], v157 offset:52224
	ds_read_b128 v[198:201], v157 offset:53248
	ds_read_b128 v[202:205], v157 offset:54272
	ds_read_b128 v[206:209], v157 offset:55296
	ds_read_b128 v[210:213], v157 offset:56320
	global_load_lds_dwordx4 v[214:215], off
	s_add_i32 m0, s34, 0x2000
	s_add_u32 s30, s30, 0x20080
	v_lshl_add_u64 v[214:215], v[216:217], 0, s[12:13]
	s_addc_u32 s31, s31, 0
	s_add_i32 s34, s57, s39
	global_load_lds_dwordx4 v[214:215], off
	v_lshl_add_u64 v[214:215], s[30:31], 0, v[130:131]
	s_mov_b32 m0, s34
	s_nop 0
	global_load_lds_dwordx4 v[214:215], off
	v_lshl_add_u64 v[214:215], s[30:31], 0, v[134:135]
	s_add_i32 m0, s34, 0x2000
	s_nop 0
	global_load_lds_dwordx4 v[214:215], off
	v_lshl_add_u64 v[214:215], v[218:219], 0, s[12:13]
	s_mov_b32 m0, s44
	s_nop 0
	global_load_lds_dwordx4 v[214:215], off
	v_lshl_add_u64 v[214:215], v[220:221], 0, s[12:13]
	s_mov_b32 m0, s45
	s_nop 0
	global_load_lds_dwordx4 v[214:215], off
	s_waitcnt vmcnt(8)
	s_waitcnt lgkmcnt(0)
	s_barrier
	s_setprio 1
	s_waitcnt lgkmcnt(0)
	v_mfma_f32_16x16x32_bf16 v[60:63], v[144:147], v[182:185], v[60:63]
	v_mfma_f32_16x16x32_bf16 v[56:59], v[158:161], v[182:185], v[56:59]
	v_mfma_f32_16x16x32_bf16 v[44:47], v[144:147], v[190:193], v[44:47]
	v_mfma_f32_16x16x32_bf16 v[40:43], v[158:161], v[190:193], v[40:43]
	v_mfma_f32_16x16x32_bf16 v[28:31], v[144:147], v[198:201], v[28:31]
	v_mfma_f32_16x16x32_bf16 v[24:27], v[158:161], v[198:201], v[24:27]
	v_mfma_f32_16x16x32_bf16 v[12:15], v[144:147], v[206:209], v[12:15]
	v_mfma_f32_16x16x32_bf16 v[8:11], v[158:161], v[206:209], v[8:11]
	v_mfma_f32_16x16x32_bf16 v[60:63], v[148:151], v[186:189], v[60:63]
	v_mfma_f32_16x16x32_bf16 v[56:59], v[162:165], v[186:189], v[56:59]
	v_mfma_f32_16x16x32_bf16 v[44:47], v[148:151], v[194:197], v[44:47]
	v_mfma_f32_16x16x32_bf16 v[40:43], v[162:165], v[194:197], v[40:43]
	v_mfma_f32_16x16x32_bf16 v[28:31], v[148:151], v[202:205], v[28:31]
	v_mfma_f32_16x16x32_bf16 v[24:27], v[162:165], v[202:205], v[24:27]
	v_mfma_f32_16x16x32_bf16 v[12:15], v[148:151], v[210:213], v[12:15]
	v_mfma_f32_16x16x32_bf16 v[8:11], v[162:165], v[210:213], v[8:11]
	s_setprio 0
	s_setprio 1
	v_mfma_f32_16x16x32_bf16 v[52:55], v[166:169], v[182:185], v[52:55]
	v_mfma_f32_16x16x32_bf16 v[48:51], v[174:177], v[182:185], v[48:51]
	v_mfma_f32_16x16x32_bf16 v[36:39], v[166:169], v[190:193], v[36:39]
	v_mfma_f32_16x16x32_bf16 v[32:35], v[174:177], v[190:193], v[32:35]
	v_mfma_f32_16x16x32_bf16 v[20:23], v[166:169], v[198:201], v[20:23]
	v_mfma_f32_16x16x32_bf16 v[16:19], v[174:177], v[198:201], v[16:19]
	v_mfma_f32_16x16x32_bf16 v[4:7], v[166:169], v[206:209], v[4:7]
	v_mfma_f32_16x16x32_bf16 v[0:3], v[174:177], v[206:209], v[0:3]
	v_mfma_f32_16x16x32_bf16 v[52:55], v[170:173], v[186:189], v[52:55]
	v_mfma_f32_16x16x32_bf16 v[48:51], v[178:181], v[186:189], v[48:51]
	v_mfma_f32_16x16x32_bf16 v[36:39], v[170:173], v[194:197], v[36:39]
	v_mfma_f32_16x16x32_bf16 v[32:35], v[178:181], v[194:197], v[32:35]
	v_mfma_f32_16x16x32_bf16 v[20:23], v[170:173], v[202:205], v[20:23]
	v_mfma_f32_16x16x32_bf16 v[16:19], v[178:181], v[202:205], v[16:19]
	v_mfma_f32_16x16x32_bf16 v[4:7], v[170:173], v[210:213], v[4:7]
	v_mfma_f32_16x16x32_bf16 v[0:3], v[178:181], v[210:213], v[0:3]
	s_setprio 0
	s_barrier
	s_add_i32 s55, s55, 2
	s_add_u32 s28, s28, 0x100
	s_addc_u32 s29, s29, 0
	s_add_u32 s53, s53, 0x100
	s_addc_u32 s54, s54, 0
	s_cmp_gt_u32 s55, 5
	s_cbranch_scc0 .LBB0_1100
	s_branch .Lpeel_exit_P9

.Lpeel_exit_P9:
	s_mov_b32 s98, 0
	s_and_b64 vcc, exec, s[14:15]
	s_cbranch_vccz .LBB0_1103
	s_barrier
.LBB0_1103:
	v_lshl_add_u32 v144, s26, 8, v152
	v_lshl_or_b32 v145, s51, 8, v154
	s_add_u32 s52, s10, s16
	s_addc_u32 s53, s11, s17
	v_lshlrev_b32_e32 v145, 1, v145
	s_add_u32 s54, s52, 0x26000
	s_addc_u32 s55, s53, 0
	s_add_u32 s56, s52, 0x4c000
	s_addc_u32 s57, s53, 0
	s_add_u32 s58, s52, 0x72000
	s_addc_u32 s59, s53, 0
	s_add_u32 s60, s52, 0x130000
	s_addc_u32 s61, s53, 0
	s_add_u32 s62, s52, 0x156000
	s_addc_u32 s63, s53, 0
	s_add_u32 s66, s52, 0x17c000
	s_addc_u32 s67, s53, 0
	s_add_u32 s68, s52, 0x1a2000
	s_addc_u32 s69, s53, 0
	s_add_u32 s70, s8, 0x8000
	s_addc_u32 s71, s9, 0
	s_add_u32 s72, s8, 0x10000
	s_addc_u32 s73, s9, 0
	s_add_u32 s74, s8, 0x18000
	s_addc_u32 s75, s9, 0
	s_add_u32 s76, s8, 0x40000
	s_addc_u32 s77, s9, 0
	s_add_u32 s78, s8, 0x48000
	s_addc_u32 s79, s9, 0
	s_add_u32 s80, s8, 0x50000
	s_addc_u32 s81, s9, 0
	s_add_u32 s82, s8, 0x58000
	s_addc_u32 s83, s9, 0
	v_mad_u32_u24 v146, v144, s50, v145
	v_lshl_add_u32 v147, v144, 11, v145
	s_nop 1
	global_load_dwordx4 v[168:171], v146, s[52:53]
	global_load_dwordx4 v[172:175], v146, s[52:53] offset:256
	global_load_dwordx4 v[176:179], v146, s[54:55]
	global_load_dwordx4 v[180:183], v146, s[54:55] offset:256
	global_load_dwordx4 v[184:187], v146, s[56:57]
	global_load_dwordx4 v[188:191], v146, s[56:57] offset:256
	global_load_dwordx4 v[192:195], v146, s[58:59]
	global_load_dwordx4 v[196:199], v146, s[58:59] offset:256
	global_load_dwordx4 v[200:203], v146, s[60:61]
	global_load_dwordx4 v[204:207], v146, s[60:61] offset:256
	global_load_dwordx4 v[208:211], v146, s[62:63]
	global_load_dwordx4 v[212:215], v146, s[62:63] offset:256
	s_waitcnt vmcnt(8)
	v_lshlrev_b32_e32 v158, 16, v168
	v_and_b32_e32 v159, 0xffff0000, v168
	v_lshlrev_b32_e32 v160, 16, v169
	v_and_b32_e32 v161, 0xffff0000, v169
	v_lshlrev_b32_e32 v162, 16, v170
	v_and_b32_e32 v163, 0xffff0000, v170
	v_lshlrev_b32_e32 v164, 16, v171
	v_and_b32_e32 v165, 0xffff0000, v171
	v_mul_f32_e32 v158, 0xbfb8aa3b, v158
	v_mul_f32_e32 v159, 0xbfb8aa3b, v159
	v_mul_f32_e32 v160, 0xbfb8aa3b, v160
	v_mul_f32_e32 v161, 0xbfb8aa3b, v161
	v_mul_f32_e32 v162, 0xbfb8aa3b, v162
	v_mul_f32_e32 v163, 0xbfb8aa3b, v163
	v_mul_f32_e32 v164, 0xbfb8aa3b, v164
	v_mul_f32_e32 v165, 0xbfb8aa3b, v165
	v_exp_f32_e32 v158, v158
	v_exp_f32_e32 v159, v159
	v_exp_f32_e32 v160, v160
	v_exp_f32_e32 v161, v161
	v_exp_f32_e32 v162, v162
	v_exp_f32_e32 v163, v163
	v_exp_f32_e32 v164, v164
	v_exp_f32_e32 v165, v165
	v_add_f32_e32 v158, 1.0, v158
	v_add_f32_e32 v159, 1.0, v159
	v_add_f32_e32 v160, 1.0, v160
	v_add_f32_e32 v161, 1.0, v161
	v_add_f32_e32 v162, 1.0, v162
	v_add_f32_e32 v163, 1.0, v163
	v_add_f32_e32 v164, 1.0, v164
	v_add_f32_e32 v165, 1.0, v165
	v_rcp_f32_e32 v158, v158
	v_rcp_f32_e32 v159, v159
	v_rcp_f32_e32 v160, v160
	v_rcp_f32_e32 v161, v161
	v_rcp_f32_e32 v162, v162
	v_rcp_f32_e32 v163, v163
	v_rcp_f32_e32 v164, v164
	v_rcp_f32_e32 v165, v165
	s_nop 0
	v_pk_mul_f32 v[124:125], v[124:125], v[158:159]
	v_pk_mul_f32 v[126:127], v[126:127], v[160:161]
	v_pk_mul_f32 v[120:121], v[120:121], v[162:163]
	v_pk_mul_f32 v[122:123], v[122:123], v[164:165]
	v_cvt_pk_bf16_f32 v168, v124, v125
	v_cvt_pk_bf16_f32 v169, v126, v127
	v_cvt_pk_bf16_f32 v170, v120, v121
	v_cvt_pk_bf16_f32 v171, v122, v123
	global_store_dwordx4 v147, v[168:171], s[8:9]
	v_lshlrev_b32_e32 v158, 16, v172
	v_and_b32_e32 v159, 0xffff0000, v172
	v_lshlrev_b32_e32 v160, 16, v173
	v_and_b32_e32 v161, 0xffff0000, v173
	v_lshlrev_b32_e32 v162, 16, v174
	v_and_b32_e32 v163, 0xffff0000, v174
	v_lshlrev_b32_e32 v164, 16, v175
	v_and_b32_e32 v165, 0xffff0000, v175
	v_mul_f32_e32 v158, 0xbfb8aa3b, v158
	v_mul_f32_e32 v159, 0xbfb8aa3b, v159
	v_mul_f32_e32 v160, 0xbfb8aa3b, v160
	v_mul_f32_e32 v161, 0xbfb8aa3b, v161
	v_mul_f32_e32 v162, 0xbfb8aa3b, v162
	v_mul_f32_e32 v163, 0xbfb8aa3b, v163
	v_mul_f32_e32 v164, 0xbfb8aa3b, v164
	v_mul_f32_e32 v165, 0xbfb8aa3b, v165
	v_exp_f32_e32 v158, v158
	v_exp_f32_e32 v159, v159
	v_exp_f32_e32 v160, v160
	v_exp_f32_e32 v161, v161
	v_exp_f32_e32 v162, v162
	v_exp_f32_e32 v163, v163
	v_exp_f32_e32 v164, v164
	v_exp_f32_e32 v165, v165
	v_add_f32_e32 v158, 1.0, v158
	v_add_f32_e32 v159, 1.0, v159
	v_add_f32_e32 v160, 1.0, v160
	v_add_f32_e32 v161, 1.0, v161
	v_add_f32_e32 v162, 1.0, v162
	v_add_f32_e32 v163, 1.0, v163
	v_add_f32_e32 v164, 1.0, v164
	v_add_f32_e32 v165, 1.0, v165
	v_rcp_f32_e32 v158, v158
	v_rcp_f32_e32 v159, v159
	v_rcp_f32_e32 v160, v160
	v_rcp_f32_e32 v161, v161
	v_rcp_f32_e32 v162, v162
	v_rcp_f32_e32 v163, v163
	v_rcp_f32_e32 v164, v164
	v_rcp_f32_e32 v165, v165
	s_nop 0
	v_pk_mul_f32 v[116:117], v[116:117], v[158:159]
	v_pk_mul_f32 v[118:119], v[118:119], v[160:161]
	v_pk_mul_f32 v[112:113], v[112:113], v[162:163]
	v_pk_mul_f32 v[114:115], v[114:115], v[164:165]
	v_cvt_pk_bf16_f32 v172, v116, v117
	v_cvt_pk_bf16_f32 v173, v118, v119
	v_cvt_pk_bf16_f32 v174, v112, v113
	v_cvt_pk_bf16_f32 v175, v114, v115
	global_store_dwordx4 v147, v[172:175], s[8:9] offset:256
	v_lshlrev_b32_e32 v158, 16, v176
	v_and_b32_e32 v159, 0xffff0000, v176
	v_lshlrev_b32_e32 v160, 16, v177
	v_and_b32_e32 v161, 0xffff0000, v177
	v_lshlrev_b32_e32 v162, 16, v178
	v_and_b32_e32 v163, 0xffff0000, v178
	v_lshlrev_b32_e32 v164, 16, v179
	v_and_b32_e32 v165, 0xffff0000, v179
	v_mul_f32_e32 v158, 0xbfb8aa3b, v158
	v_mul_f32_e32 v159, 0xbfb8aa3b, v159
	v_mul_f32_e32 v160, 0xbfb8aa3b, v160
	v_mul_f32_e32 v161, 0xbfb8aa3b, v161
	v_mul_f32_e32 v162, 0xbfb8aa3b, v162
	v_mul_f32_e32 v163, 0xbfb8aa3b, v163
	v_mul_f32_e32 v164, 0xbfb8aa3b, v164
	v_mul_f32_e32 v165, 0xbfb8aa3b, v165
	v_exp_f32_e32 v158, v158
	v_exp_f32_e32 v159, v159
	v_exp_f32_e32 v160, v160
	v_exp_f32_e32 v161, v161
	v_exp_f32_e32 v162, v162
	v_exp_f32_e32 v163, v163
	v_exp_f32_e32 v164, v164
	v_exp_f32_e32 v165, v165
	v_add_f32_e32 v158, 1.0, v158
	v_add_f32_e32 v159, 1.0, v159
	v_add_f32_e32 v160, 1.0, v160
	v_add_f32_e32 v161, 1.0, v161
	v_add_f32_e32 v162, 1.0, v162
	v_add_f32_e32 v163, 1.0, v163
	v_add_f32_e32 v164, 1.0, v164
	v_add_f32_e32 v165, 1.0, v165
	v_rcp_f32_e32 v158, v158
	v_rcp_f32_e32 v159, v159
	v_rcp_f32_e32 v160, v160
	v_rcp_f32_e32 v161, v161
	v_rcp_f32_e32 v162, v162
	v_rcp_f32_e32 v163, v163
	v_rcp_f32_e32 v164, v164
	v_rcp_f32_e32 v165, v165
	s_nop 0
	v_pk_mul_f32 v[108:109], v[108:109], v[158:159]
	v_pk_mul_f32 v[110:111], v[110:111], v[160:161]
	v_pk_mul_f32 v[104:105], v[104:105], v[162:163]
	v_pk_mul_f32 v[106:107], v[106:107], v[164:165]
	v_cvt_pk_bf16_f32 v176, v108, v109
	v_cvt_pk_bf16_f32 v177, v110, v111
	v_cvt_pk_bf16_f32 v178, v104, v105
	v_cvt_pk_bf16_f32 v179, v106, v107
	global_store_dwordx4 v147, v[176:179], s[70:71]
	v_lshlrev_b32_e32 v158, 16, v180
	v_and_b32_e32 v159, 0xffff0000, v180
	v_lshlrev_b32_e32 v160, 16, v181
	v_and_b32_e32 v161, 0xffff0000, v181
	v_lshlrev_b32_e32 v162, 16, v182
	v_and_b32_e32 v163, 0xffff0000, v182
	v_lshlrev_b32_e32 v164, 16, v183
	v_and_b32_e32 v165, 0xffff0000, v183
	v_mul_f32_e32 v158, 0xbfb8aa3b, v158
	v_mul_f32_e32 v159, 0xbfb8aa3b, v159
	v_mul_f32_e32 v160, 0xbfb8aa3b, v160
	v_mul_f32_e32 v161, 0xbfb8aa3b, v161
	v_mul_f32_e32 v162, 0xbfb8aa3b, v162
	v_mul_f32_e32 v163, 0xbfb8aa3b, v163
	v_mul_f32_e32 v164, 0xbfb8aa3b, v164
	v_mul_f32_e32 v165, 0xbfb8aa3b, v165
	v_exp_f32_e32 v158, v158
	v_exp_f32_e32 v159, v159
	v_exp_f32_e32 v160, v160
	v_exp_f32_e32 v161, v161
	v_exp_f32_e32 v162, v162
	v_exp_f32_e32 v163, v163
	v_exp_f32_e32 v164, v164
	v_exp_f32_e32 v165, v165
	v_add_f32_e32 v158, 1.0, v158
	v_add_f32_e32 v159, 1.0, v159
	v_add_f32_e32 v160, 1.0, v160
	v_add_f32_e32 v161, 1.0, v161
	v_add_f32_e32 v162, 1.0, v162
	v_add_f32_e32 v163, 1.0, v163
	v_add_f32_e32 v164, 1.0, v164
	v_add_f32_e32 v165, 1.0, v165
	v_rcp_f32_e32 v158, v158
	v_rcp_f32_e32 v159, v159
	v_rcp_f32_e32 v160, v160
	v_rcp_f32_e32 v161, v161
	v_rcp_f32_e32 v162, v162
	v_rcp_f32_e32 v163, v163
	v_rcp_f32_e32 v164, v164
	v_rcp_f32_e32 v165, v165
	s_nop 0
	v_pk_mul_f32 v[100:101], v[100:101], v[158:159]
	v_pk_mul_f32 v[102:103], v[102:103], v[160:161]
	v_pk_mul_f32 v[96:97], v[96:97], v[162:163]
	v_pk_mul_f32 v[98:99], v[98:99], v[164:165]
	v_cvt_pk_bf16_f32 v180, v100, v101
	v_cvt_pk_bf16_f32 v181, v102, v103
	v_cvt_pk_bf16_f32 v182, v96, v97
	v_cvt_pk_bf16_f32 v183, v98, v99
	global_store_dwordx4 v147, v[180:183], s[70:71] offset:256
	s_nop 1
	global_load_dwordx4 v[168:171], v146, s[66:67]
	global_load_dwordx4 v[172:175], v146, s[66:67] offset:256
	global_load_dwordx4 v[176:179], v146, s[68:69]
	global_load_dwordx4 v[180:183], v146, s[68:69] offset:256
	s_waitcnt vmcnt(12)
	v_lshlrev_b32_e32 v158, 16, v184
	v_and_b32_e32 v159, 0xffff0000, v184
	v_lshlrev_b32_e32 v160, 16, v185
	v_and_b32_e32 v161, 0xffff0000, v185
	v_lshlrev_b32_e32 v162, 16, v186
	v_and_b32_e32 v163, 0xffff0000, v186
	v_lshlrev_b32_e32 v164, 16, v187
	v_and_b32_e32 v165, 0xffff0000, v187
	v_mul_f32_e32 v158, 0xbfb8aa3b, v158
	v_mul_f32_e32 v159, 0xbfb8aa3b, v159
	v_mul_f32_e32 v160, 0xbfb8aa3b, v160
	v_mul_f32_e32 v161, 0xbfb8aa3b, v161
	v_mul_f32_e32 v162, 0xbfb8aa3b, v162
	v_mul_f32_e32 v163, 0xbfb8aa3b, v163
	v_mul_f32_e32 v164, 0xbfb8aa3b, v164
	v_mul_f32_e32 v165, 0xbfb8aa3b, v165
	v_exp_f32_e32 v158, v158
	v_exp_f32_e32 v159, v159
	v_exp_f32_e32 v160, v160
	v_exp_f32_e32 v161, v161
	v_exp_f32_e32 v162, v162
	v_exp_f32_e32 v163, v163
	v_exp_f32_e32 v164, v164
	v_exp_f32_e32 v165, v165
	v_add_f32_e32 v158, 1.0, v158
	v_add_f32_e32 v159, 1.0, v159
	v_add_f32_e32 v160, 1.0, v160
	v_add_f32_e32 v161, 1.0, v161
	v_add_f32_e32 v162, 1.0, v162
	v_add_f32_e32 v163, 1.0, v163
	v_add_f32_e32 v164, 1.0, v164
	v_add_f32_e32 v165, 1.0, v165
	v_rcp_f32_e32 v158, v158
	v_rcp_f32_e32 v159, v159
	v_rcp_f32_e32 v160, v160
	v_rcp_f32_e32 v161, v161
	v_rcp_f32_e32 v162, v162
	v_rcp_f32_e32 v163, v163
	v_rcp_f32_e32 v164, v164
	v_rcp_f32_e32 v165, v165
	s_nop 0
	v_pk_mul_f32 v[92:93], v[92:93], v[158:159]
	v_pk_mul_f32 v[94:95], v[94:95], v[160:161]
	v_pk_mul_f32 v[88:89], v[88:89], v[162:163]
	v_pk_mul_f32 v[90:91], v[90:91], v[164:165]
	v_cvt_pk_bf16_f32 v184, v92, v93
	v_cvt_pk_bf16_f32 v185, v94, v95
	v_cvt_pk_bf16_f32 v186, v88, v89
	v_cvt_pk_bf16_f32 v187, v90, v91
	global_store_dwordx4 v147, v[184:187], s[72:73]
	v_lshlrev_b32_e32 v158, 16, v188
	v_and_b32_e32 v159, 0xffff0000, v188
	v_lshlrev_b32_e32 v160, 16, v189
	v_and_b32_e32 v161, 0xffff0000, v189
	v_lshlrev_b32_e32 v162, 16, v190
	v_and_b32_e32 v163, 0xffff0000, v190
	v_lshlrev_b32_e32 v164, 16, v191
	v_and_b32_e32 v165, 0xffff0000, v191
	v_mul_f32_e32 v158, 0xbfb8aa3b, v158
	v_mul_f32_e32 v159, 0xbfb8aa3b, v159
	v_mul_f32_e32 v160, 0xbfb8aa3b, v160
	v_mul_f32_e32 v161, 0xbfb8aa3b, v161
	v_mul_f32_e32 v162, 0xbfb8aa3b, v162
	v_mul_f32_e32 v163, 0xbfb8aa3b, v163
	v_mul_f32_e32 v164, 0xbfb8aa3b, v164
	v_mul_f32_e32 v165, 0xbfb8aa3b, v165
	v_exp_f32_e32 v158, v158
	v_exp_f32_e32 v159, v159
	v_exp_f32_e32 v160, v160
	v_exp_f32_e32 v161, v161
	v_exp_f32_e32 v162, v162
	v_exp_f32_e32 v163, v163
	v_exp_f32_e32 v164, v164
	v_exp_f32_e32 v165, v165
	v_add_f32_e32 v158, 1.0, v158
	v_add_f32_e32 v159, 1.0, v159
	v_add_f32_e32 v160, 1.0, v160
	v_add_f32_e32 v161, 1.0, v161
	v_add_f32_e32 v162, 1.0, v162
	v_add_f32_e32 v163, 1.0, v163
	v_add_f32_e32 v164, 1.0, v164
	v_add_f32_e32 v165, 1.0, v165
	v_rcp_f32_e32 v158, v158
	v_rcp_f32_e32 v159, v159
	v_rcp_f32_e32 v160, v160
	v_rcp_f32_e32 v161, v161
	v_rcp_f32_e32 v162, v162
	v_rcp_f32_e32 v163, v163
	v_rcp_f32_e32 v164, v164
	v_rcp_f32_e32 v165, v165
	s_nop 0
	v_pk_mul_f32 v[84:85], v[84:85], v[158:159]
	v_pk_mul_f32 v[86:87], v[86:87], v[160:161]
	v_pk_mul_f32 v[80:81], v[80:81], v[162:163]
	v_pk_mul_f32 v[82:83], v[82:83], v[164:165]
	v_cvt_pk_bf16_f32 v188, v84, v85
	v_cvt_pk_bf16_f32 v189, v86, v87
	v_cvt_pk_bf16_f32 v190, v80, v81
	v_cvt_pk_bf16_f32 v191, v82, v83
	global_store_dwordx4 v147, v[188:191], s[72:73] offset:256
	v_lshlrev_b32_e32 v158, 16, v192
	v_and_b32_e32 v159, 0xffff0000, v192
	v_lshlrev_b32_e32 v160, 16, v193
	v_and_b32_e32 v161, 0xffff0000, v193
	v_lshlrev_b32_e32 v162, 16, v194
	v_and_b32_e32 v163, 0xffff0000, v194
	v_lshlrev_b32_e32 v164, 16, v195
	v_and_b32_e32 v165, 0xffff0000, v195
	v_mul_f32_e32 v158, 0xbfb8aa3b, v158
	v_mul_f32_e32 v159, 0xbfb8aa3b, v159
	v_mul_f32_e32 v160, 0xbfb8aa3b, v160
	v_mul_f32_e32 v161, 0xbfb8aa3b, v161
	v_mul_f32_e32 v162, 0xbfb8aa3b, v162
	v_mul_f32_e32 v163, 0xbfb8aa3b, v163
	v_mul_f32_e32 v164, 0xbfb8aa3b, v164
	v_mul_f32_e32 v165, 0xbfb8aa3b, v165
	v_exp_f32_e32 v158, v158
	v_exp_f32_e32 v159, v159
	v_exp_f32_e32 v160, v160
	v_exp_f32_e32 v161, v161
	v_exp_f32_e32 v162, v162
	v_exp_f32_e32 v163, v163
	v_exp_f32_e32 v164, v164
	v_exp_f32_e32 v165, v165
	v_add_f32_e32 v158, 1.0, v158
	v_add_f32_e32 v159, 1.0, v159
	v_add_f32_e32 v160, 1.0, v160
	v_add_f32_e32 v161, 1.0, v161
	v_add_f32_e32 v162, 1.0, v162
	v_add_f32_e32 v163, 1.0, v163
	v_add_f32_e32 v164, 1.0, v164
	v_add_f32_e32 v165, 1.0, v165
	v_rcp_f32_e32 v158, v158
	v_rcp_f32_e32 v159, v159
	v_rcp_f32_e32 v160, v160
	v_rcp_f32_e32 v161, v161
	v_rcp_f32_e32 v162, v162
	v_rcp_f32_e32 v163, v163
	v_rcp_f32_e32 v164, v164
	v_rcp_f32_e32 v165, v165
	s_nop 0
	v_pk_mul_f32 v[76:77], v[76:77], v[158:159]
	v_pk_mul_f32 v[78:79], v[78:79], v[160:161]
	v_pk_mul_f32 v[72:73], v[72:73], v[162:163]
	v_pk_mul_f32 v[74:75], v[74:75], v[164:165]
	v_cvt_pk_bf16_f32 v192, v76, v77
	v_cvt_pk_bf16_f32 v193, v78, v79
	v_cvt_pk_bf16_f32 v194, v72, v73
	v_cvt_pk_bf16_f32 v195, v74, v75
	global_store_dwordx4 v147, v[192:195], s[74:75]
	v_lshlrev_b32_e32 v158, 16, v196
	v_and_b32_e32 v159, 0xffff0000, v196
	v_lshlrev_b32_e32 v160, 16, v197
	v_and_b32_e32 v161, 0xffff0000, v197
	v_lshlrev_b32_e32 v162, 16, v198
	v_and_b32_e32 v163, 0xffff0000, v198
	v_lshlrev_b32_e32 v164, 16, v199
	v_and_b32_e32 v165, 0xffff0000, v199
	v_mul_f32_e32 v158, 0xbfb8aa3b, v158
	v_mul_f32_e32 v159, 0xbfb8aa3b, v159
	v_mul_f32_e32 v160, 0xbfb8aa3b, v160
	v_mul_f32_e32 v161, 0xbfb8aa3b, v161
	v_mul_f32_e32 v162, 0xbfb8aa3b, v162
	v_mul_f32_e32 v163, 0xbfb8aa3b, v163
	v_mul_f32_e32 v164, 0xbfb8aa3b, v164
	v_mul_f32_e32 v165, 0xbfb8aa3b, v165
	v_exp_f32_e32 v158, v158
	v_exp_f32_e32 v159, v159
	v_exp_f32_e32 v160, v160
	v_exp_f32_e32 v161, v161
	v_exp_f32_e32 v162, v162
	v_exp_f32_e32 v163, v163
	v_exp_f32_e32 v164, v164
	v_exp_f32_e32 v165, v165
	v_add_f32_e32 v158, 1.0, v158
	v_add_f32_e32 v159, 1.0, v159
	v_add_f32_e32 v160, 1.0, v160
	v_add_f32_e32 v161, 1.0, v161
	v_add_f32_e32 v162, 1.0, v162
	v_add_f32_e32 v163, 1.0, v163
	v_add_f32_e32 v164, 1.0, v164
	v_add_f32_e32 v165, 1.0, v165
	v_rcp_f32_e32 v158, v158
	v_rcp_f32_e32 v159, v159
	v_rcp_f32_e32 v160, v160
	v_rcp_f32_e32 v161, v161
	v_rcp_f32_e32 v162, v162
	v_rcp_f32_e32 v163, v163
	v_rcp_f32_e32 v164, v164
	v_rcp_f32_e32 v165, v165
	s_nop 0
	v_pk_mul_f32 v[68:69], v[68:69], v[158:159]
	v_pk_mul_f32 v[70:71], v[70:71], v[160:161]
	v_pk_mul_f32 v[64:65], v[64:65], v[162:163]
	v_pk_mul_f32 v[66:67], v[66:67], v[164:165]
	v_cvt_pk_bf16_f32 v196, v68, v69
	v_cvt_pk_bf16_f32 v197, v70, v71
	v_cvt_pk_bf16_f32 v198, v64, v65
	v_cvt_pk_bf16_f32 v199, v66, v67
	global_store_dwordx4 v147, v[196:199], s[74:75] offset:256
	s_waitcnt vmcnt(12)
	v_lshlrev_b32_e32 v158, 16, v200
	v_and_b32_e32 v159, 0xffff0000, v200
	v_lshlrev_b32_e32 v160, 16, v201
	v_and_b32_e32 v161, 0xffff0000, v201
	v_lshlrev_b32_e32 v162, 16, v202
	v_and_b32_e32 v163, 0xffff0000, v202
	v_lshlrev_b32_e32 v164, 16, v203
	v_and_b32_e32 v165, 0xffff0000, v203
	v_mul_f32_e32 v158, 0xbfb8aa3b, v158
	v_mul_f32_e32 v159, 0xbfb8aa3b, v159
	v_mul_f32_e32 v160, 0xbfb8aa3b, v160
	v_mul_f32_e32 v161, 0xbfb8aa3b, v161
	v_mul_f32_e32 v162, 0xbfb8aa3b, v162
	v_mul_f32_e32 v163, 0xbfb8aa3b, v163
	v_mul_f32_e32 v164, 0xbfb8aa3b, v164
	v_mul_f32_e32 v165, 0xbfb8aa3b, v165
	v_exp_f32_e32 v158, v158
	v_exp_f32_e32 v159, v159
	v_exp_f32_e32 v160, v160
	v_exp_f32_e32 v161, v161
	v_exp_f32_e32 v162, v162
	v_exp_f32_e32 v163, v163
	v_exp_f32_e32 v164, v164
	v_exp_f32_e32 v165, v165
	v_add_f32_e32 v158, 1.0, v158
	v_add_f32_e32 v159, 1.0, v159
	v_add_f32_e32 v160, 1.0, v160
	v_add_f32_e32 v161, 1.0, v161
	v_add_f32_e32 v162, 1.0, v162
	v_add_f32_e32 v163, 1.0, v163
	v_add_f32_e32 v164, 1.0, v164
	v_add_f32_e32 v165, 1.0, v165
	v_rcp_f32_e32 v158, v158
	v_rcp_f32_e32 v159, v159
	v_rcp_f32_e32 v160, v160
	v_rcp_f32_e32 v161, v161
	v_rcp_f32_e32 v162, v162
	v_rcp_f32_e32 v163, v163
	v_rcp_f32_e32 v164, v164
	v_rcp_f32_e32 v165, v165
	s_nop 0
	v_pk_mul_f32 v[60:61], v[60:61], v[158:159]
	v_pk_mul_f32 v[62:63], v[62:63], v[160:161]
	v_pk_mul_f32 v[56:57], v[56:57], v[162:163]
	v_pk_mul_f32 v[58:59], v[58:59], v[164:165]
	v_cvt_pk_bf16_f32 v200, v60, v61
	v_cvt_pk_bf16_f32 v201, v62, v63
	v_cvt_pk_bf16_f32 v202, v56, v57
	v_cvt_pk_bf16_f32 v203, v58, v59
	global_store_dwordx4 v147, v[200:203], s[76:77]
	v_lshlrev_b32_e32 v158, 16, v204
	v_and_b32_e32 v159, 0xffff0000, v204
	v_lshlrev_b32_e32 v160, 16, v205
	v_and_b32_e32 v161, 0xffff0000, v205
	v_lshlrev_b32_e32 v162, 16, v206
	v_and_b32_e32 v163, 0xffff0000, v206
	v_lshlrev_b32_e32 v164, 16, v207
	v_and_b32_e32 v165, 0xffff0000, v207
	v_mul_f32_e32 v158, 0xbfb8aa3b, v158
	v_mul_f32_e32 v159, 0xbfb8aa3b, v159
	v_mul_f32_e32 v160, 0xbfb8aa3b, v160
	v_mul_f32_e32 v161, 0xbfb8aa3b, v161
	v_mul_f32_e32 v162, 0xbfb8aa3b, v162
	v_mul_f32_e32 v163, 0xbfb8aa3b, v163
	v_mul_f32_e32 v164, 0xbfb8aa3b, v164
	v_mul_f32_e32 v165, 0xbfb8aa3b, v165
	v_exp_f32_e32 v158, v158
	v_exp_f32_e32 v159, v159
	v_exp_f32_e32 v160, v160
	v_exp_f32_e32 v161, v161
	v_exp_f32_e32 v162, v162
	v_exp_f32_e32 v163, v163
	v_exp_f32_e32 v164, v164
	v_exp_f32_e32 v165, v165
	v_add_f32_e32 v158, 1.0, v158
	v_add_f32_e32 v159, 1.0, v159
	v_add_f32_e32 v160, 1.0, v160
	v_add_f32_e32 v161, 1.0, v161
	v_add_f32_e32 v162, 1.0, v162
	v_add_f32_e32 v163, 1.0, v163
	v_add_f32_e32 v164, 1.0, v164
	v_add_f32_e32 v165, 1.0, v165
	v_rcp_f32_e32 v158, v158
	v_rcp_f32_e32 v159, v159
	v_rcp_f32_e32 v160, v160
	v_rcp_f32_e32 v161, v161
	v_rcp_f32_e32 v162, v162
	v_rcp_f32_e32 v163, v163
	v_rcp_f32_e32 v164, v164
	v_rcp_f32_e32 v165, v165
	s_nop 0
	v_pk_mul_f32 v[52:53], v[52:53], v[158:159]
	v_pk_mul_f32 v[54:55], v[54:55], v[160:161]
	v_pk_mul_f32 v[48:49], v[48:49], v[162:163]
	v_pk_mul_f32 v[50:51], v[50:51], v[164:165]
	v_cvt_pk_bf16_f32 v204, v52, v53
	v_cvt_pk_bf16_f32 v205, v54, v55
	v_cvt_pk_bf16_f32 v206, v48, v49
	v_cvt_pk_bf16_f32 v207, v50, v51
	global_store_dwordx4 v147, v[204:207], s[76:77] offset:256
	v_lshlrev_b32_e32 v158, 16, v208
	v_and_b32_e32 v159, 0xffff0000, v208
	v_lshlrev_b32_e32 v160, 16, v209
	v_and_b32_e32 v161, 0xffff0000, v209
	v_lshlrev_b32_e32 v162, 16, v210
	v_and_b32_e32 v163, 0xffff0000, v210
	v_lshlrev_b32_e32 v164, 16, v211
	v_and_b32_e32 v165, 0xffff0000, v211
	v_mul_f32_e32 v158, 0xbfb8aa3b, v158
	v_mul_f32_e32 v159, 0xbfb8aa3b, v159
	v_mul_f32_e32 v160, 0xbfb8aa3b, v160
	v_mul_f32_e32 v161, 0xbfb8aa3b, v161
	v_mul_f32_e32 v162, 0xbfb8aa3b, v162
	v_mul_f32_e32 v163, 0xbfb8aa3b, v163
	v_mul_f32_e32 v164, 0xbfb8aa3b, v164
	v_mul_f32_e32 v165, 0xbfb8aa3b, v165
	v_exp_f32_e32 v158, v158
	v_exp_f32_e32 v159, v159
	v_exp_f32_e32 v160, v160
	v_exp_f32_e32 v161, v161
	v_exp_f32_e32 v162, v162
	v_exp_f32_e32 v163, v163
	v_exp_f32_e32 v164, v164
	v_exp_f32_e32 v165, v165
	v_add_f32_e32 v158, 1.0, v158
	v_add_f32_e32 v159, 1.0, v159
	v_add_f32_e32 v160, 1.0, v160
	v_add_f32_e32 v161, 1.0, v161
	v_add_f32_e32 v162, 1.0, v162
	v_add_f32_e32 v163, 1.0, v163
	v_add_f32_e32 v164, 1.0, v164
	v_add_f32_e32 v165, 1.0, v165
	v_rcp_f32_e32 v158, v158
	v_rcp_f32_e32 v159, v159
	v_rcp_f32_e32 v160, v160
	v_rcp_f32_e32 v161, v161
	v_rcp_f32_e32 v162, v162
	v_rcp_f32_e32 v163, v163
	v_rcp_f32_e32 v164, v164
	v_rcp_f32_e32 v165, v165
	s_nop 0
	v_pk_mul_f32 v[44:45], v[44:45], v[158:159]
	v_pk_mul_f32 v[46:47], v[46:47], v[160:161]
	v_pk_mul_f32 v[40:41], v[40:41], v[162:163]
	v_pk_mul_f32 v[42:43], v[42:43], v[164:165]
	v_cvt_pk_bf16_f32 v208, v44, v45
	v_cvt_pk_bf16_f32 v209, v46, v47
	v_cvt_pk_bf16_f32 v210, v40, v41
	v_cvt_pk_bf16_f32 v211, v42, v43
	global_store_dwordx4 v147, v[208:211], s[78:79]
	v_lshlrev_b32_e32 v158, 16, v212
	v_and_b32_e32 v159, 0xffff0000, v212
	v_lshlrev_b32_e32 v160, 16, v213
	v_and_b32_e32 v161, 0xffff0000, v213
	v_lshlrev_b32_e32 v162, 16, v214
	v_and_b32_e32 v163, 0xffff0000, v214
	v_lshlrev_b32_e32 v164, 16, v215
	v_and_b32_e32 v165, 0xffff0000, v215
	v_mul_f32_e32 v158, 0xbfb8aa3b, v158
	v_mul_f32_e32 v159, 0xbfb8aa3b, v159
	v_mul_f32_e32 v160, 0xbfb8aa3b, v160
	v_mul_f32_e32 v161, 0xbfb8aa3b, v161
	v_mul_f32_e32 v162, 0xbfb8aa3b, v162
	v_mul_f32_e32 v163, 0xbfb8aa3b, v163
	v_mul_f32_e32 v164, 0xbfb8aa3b, v164
	v_mul_f32_e32 v165, 0xbfb8aa3b, v165
	v_exp_f32_e32 v158, v158
	v_exp_f32_e32 v159, v159
	v_exp_f32_e32 v160, v160
	v_exp_f32_e32 v161, v161
	v_exp_f32_e32 v162, v162
	v_exp_f32_e32 v163, v163
	v_exp_f32_e32 v164, v164
	v_exp_f32_e32 v165, v165
	v_add_f32_e32 v158, 1.0, v158
	v_add_f32_e32 v159, 1.0, v159
	v_add_f32_e32 v160, 1.0, v160
	v_add_f32_e32 v161, 1.0, v161
	v_add_f32_e32 v162, 1.0, v162
	v_add_f32_e32 v163, 1.0, v163
	v_add_f32_e32 v164, 1.0, v164
	v_add_f32_e32 v165, 1.0, v165
	v_rcp_f32_e32 v158, v158
	v_rcp_f32_e32 v159, v159
	v_rcp_f32_e32 v160, v160
	v_rcp_f32_e32 v161, v161
	v_rcp_f32_e32 v162, v162
	v_rcp_f32_e32 v163, v163
	v_rcp_f32_e32 v164, v164
	v_rcp_f32_e32 v165, v165
	s_nop 0
	v_pk_mul_f32 v[36:37], v[36:37], v[158:159]
	v_pk_mul_f32 v[38:39], v[38:39], v[160:161]
	v_pk_mul_f32 v[32:33], v[32:33], v[162:163]
	v_pk_mul_f32 v[34:35], v[34:35], v[164:165]
	v_cvt_pk_bf16_f32 v212, v36, v37
	v_cvt_pk_bf16_f32 v213, v38, v39
	v_cvt_pk_bf16_f32 v214, v32, v33
	v_cvt_pk_bf16_f32 v215, v34, v35
	global_store_dwordx4 v147, v[212:215], s[78:79] offset:256
	s_waitcnt vmcnt(8)
	v_lshlrev_b32_e32 v158, 16, v168
	v_and_b32_e32 v159, 0xffff0000, v168
	v_lshlrev_b32_e32 v160, 16, v169
	v_and_b32_e32 v161, 0xffff0000, v169
	v_lshlrev_b32_e32 v162, 16, v170
	v_and_b32_e32 v163, 0xffff0000, v170
	v_lshlrev_b32_e32 v164, 16, v171
	v_and_b32_e32 v165, 0xffff0000, v171
	v_mul_f32_e32 v158, 0xbfb8aa3b, v158
	v_mul_f32_e32 v159, 0xbfb8aa3b, v159
	v_mul_f32_e32 v160, 0xbfb8aa3b, v160
	v_mul_f32_e32 v161, 0xbfb8aa3b, v161
	v_mul_f32_e32 v162, 0xbfb8aa3b, v162
	v_mul_f32_e32 v163, 0xbfb8aa3b, v163
	v_mul_f32_e32 v164, 0xbfb8aa3b, v164
	v_mul_f32_e32 v165, 0xbfb8aa3b, v165
	v_exp_f32_e32 v158, v158
	v_exp_f32_e32 v159, v159
	v_exp_f32_e32 v160, v160
	v_exp_f32_e32 v161, v161
	v_exp_f32_e32 v162, v162
	v_exp_f32_e32 v163, v163
	v_exp_f32_e32 v164, v164
	v_exp_f32_e32 v165, v165
	v_add_f32_e32 v158, 1.0, v158
	v_add_f32_e32 v159, 1.0, v159
	v_add_f32_e32 v160, 1.0, v160
	v_add_f32_e32 v161, 1.0, v161
	v_add_f32_e32 v162, 1.0, v162
	v_add_f32_e32 v163, 1.0, v163
	v_add_f32_e32 v164, 1.0, v164
	v_add_f32_e32 v165, 1.0, v165
	v_rcp_f32_e32 v158, v158
	v_rcp_f32_e32 v159, v159
	v_rcp_f32_e32 v160, v160
	v_rcp_f32_e32 v161, v161
	v_rcp_f32_e32 v162, v162
	v_rcp_f32_e32 v163, v163
	v_rcp_f32_e32 v164, v164
	v_rcp_f32_e32 v165, v165
	s_nop 0
	v_pk_mul_f32 v[28:29], v[28:29], v[158:159]
	v_pk_mul_f32 v[30:31], v[30:31], v[160:161]
	v_pk_mul_f32 v[24:25], v[24:25], v[162:163]
	v_pk_mul_f32 v[26:27], v[26:27], v[164:165]
	v_cvt_pk_bf16_f32 v168, v28, v29
	v_cvt_pk_bf16_f32 v169, v30, v31
	v_cvt_pk_bf16_f32 v170, v24, v25
	v_cvt_pk_bf16_f32 v171, v26, v27
	global_store_dwordx4 v147, v[168:171], s[80:81]
	v_lshlrev_b32_e32 v158, 16, v172
	v_and_b32_e32 v159, 0xffff0000, v172
	v_lshlrev_b32_e32 v160, 16, v173
	v_and_b32_e32 v161, 0xffff0000, v173
	v_lshlrev_b32_e32 v162, 16, v174
	v_and_b32_e32 v163, 0xffff0000, v174
	v_lshlrev_b32_e32 v164, 16, v175
	v_and_b32_e32 v165, 0xffff0000, v175
	v_mul_f32_e32 v158, 0xbfb8aa3b, v158
	v_mul_f32_e32 v159, 0xbfb8aa3b, v159
	v_mul_f32_e32 v160, 0xbfb8aa3b, v160
	v_mul_f32_e32 v161, 0xbfb8aa3b, v161
	v_mul_f32_e32 v162, 0xbfb8aa3b, v162
	v_mul_f32_e32 v163, 0xbfb8aa3b, v163
	v_mul_f32_e32 v164, 0xbfb8aa3b, v164
	v_mul_f32_e32 v165, 0xbfb8aa3b, v165
	v_exp_f32_e32 v158, v158
	v_exp_f32_e32 v159, v159
	v_exp_f32_e32 v160, v160
	v_exp_f32_e32 v161, v161
	v_exp_f32_e32 v162, v162
	v_exp_f32_e32 v163, v163
	v_exp_f32_e32 v164, v164
	v_exp_f32_e32 v165, v165
	v_add_f32_e32 v158, 1.0, v158
	v_add_f32_e32 v159, 1.0, v159
	v_add_f32_e32 v160, 1.0, v160
	v_add_f32_e32 v161, 1.0, v161
	v_add_f32_e32 v162, 1.0, v162
	v_add_f32_e32 v163, 1.0, v163
	v_add_f32_e32 v164, 1.0, v164
	v_add_f32_e32 v165, 1.0, v165
	v_rcp_f32_e32 v158, v158
	v_rcp_f32_e32 v159, v159
	v_rcp_f32_e32 v160, v160
	v_rcp_f32_e32 v161, v161
	v_rcp_f32_e32 v162, v162
	v_rcp_f32_e32 v163, v163
	v_rcp_f32_e32 v164, v164
	v_rcp_f32_e32 v165, v165
	s_nop 0
	v_pk_mul_f32 v[20:21], v[20:21], v[158:159]
	v_pk_mul_f32 v[22:23], v[22:23], v[160:161]
	v_pk_mul_f32 v[16:17], v[16:17], v[162:163]
	v_pk_mul_f32 v[18:19], v[18:19], v[164:165]
	v_cvt_pk_bf16_f32 v172, v20, v21
	v_cvt_pk_bf16_f32 v173, v22, v23
	v_cvt_pk_bf16_f32 v174, v16, v17
	v_cvt_pk_bf16_f32 v175, v18, v19
	global_store_dwordx4 v147, v[172:175], s[80:81] offset:256
	v_lshlrev_b32_e32 v158, 16, v176
	v_and_b32_e32 v159, 0xffff0000, v176
	v_lshlrev_b32_e32 v160, 16, v177
	v_and_b32_e32 v161, 0xffff0000, v177
	v_lshlrev_b32_e32 v162, 16, v178
	v_and_b32_e32 v163, 0xffff0000, v178
	v_lshlrev_b32_e32 v164, 16, v179
	v_and_b32_e32 v165, 0xffff0000, v179
	v_mul_f32_e32 v158, 0xbfb8aa3b, v158
	v_mul_f32_e32 v159, 0xbfb8aa3b, v159
	v_mul_f32_e32 v160, 0xbfb8aa3b, v160
	v_mul_f32_e32 v161, 0xbfb8aa3b, v161
	v_mul_f32_e32 v162, 0xbfb8aa3b, v162
	v_mul_f32_e32 v163, 0xbfb8aa3b, v163
	v_mul_f32_e32 v164, 0xbfb8aa3b, v164
	v_mul_f32_e32 v165, 0xbfb8aa3b, v165
	v_exp_f32_e32 v158, v158
	v_exp_f32_e32 v159, v159
	v_exp_f32_e32 v160, v160
	v_exp_f32_e32 v161, v161
	v_exp_f32_e32 v162, v162
	v_exp_f32_e32 v163, v163
	v_exp_f32_e32 v164, v164
	v_exp_f32_e32 v165, v165
	v_add_f32_e32 v158, 1.0, v158
	v_add_f32_e32 v159, 1.0, v159
	v_add_f32_e32 v160, 1.0, v160
	v_add_f32_e32 v161, 1.0, v161
	v_add_f32_e32 v162, 1.0, v162
	v_add_f32_e32 v163, 1.0, v163
	v_add_f32_e32 v164, 1.0, v164
	v_add_f32_e32 v165, 1.0, v165
	v_rcp_f32_e32 v158, v158
	v_rcp_f32_e32 v159, v159
	v_rcp_f32_e32 v160, v160
	v_rcp_f32_e32 v161, v161
	v_rcp_f32_e32 v162, v162
	v_rcp_f32_e32 v163, v163
	v_rcp_f32_e32 v164, v164
	v_rcp_f32_e32 v165, v165
	s_nop 0
	v_pk_mul_f32 v[12:13], v[12:13], v[158:159]
	v_pk_mul_f32 v[14:15], v[14:15], v[160:161]
	v_pk_mul_f32 v[8:9], v[8:9], v[162:163]
	v_pk_mul_f32 v[10:11], v[10:11], v[164:165]
	v_cvt_pk_bf16_f32 v176, v12, v13
	v_cvt_pk_bf16_f32 v177, v14, v15
	v_cvt_pk_bf16_f32 v178, v8, v9
	v_cvt_pk_bf16_f32 v179, v10, v11
	global_store_dwordx4 v147, v[176:179], s[82:83]
	v_lshlrev_b32_e32 v158, 16, v180
	v_and_b32_e32 v159, 0xffff0000, v180
	v_lshlrev_b32_e32 v160, 16, v181
	v_and_b32_e32 v161, 0xffff0000, v181
	v_lshlrev_b32_e32 v162, 16, v182
	v_and_b32_e32 v163, 0xffff0000, v182
	v_lshlrev_b32_e32 v164, 16, v183
	v_and_b32_e32 v165, 0xffff0000, v183
	v_mul_f32_e32 v158, 0xbfb8aa3b, v158
	v_mul_f32_e32 v159, 0xbfb8aa3b, v159
	v_mul_f32_e32 v160, 0xbfb8aa3b, v160
	v_mul_f32_e32 v161, 0xbfb8aa3b, v161
	v_mul_f32_e32 v162, 0xbfb8aa3b, v162
	v_mul_f32_e32 v163, 0xbfb8aa3b, v163
	v_mul_f32_e32 v164, 0xbfb8aa3b, v164
	v_mul_f32_e32 v165, 0xbfb8aa3b, v165
	v_exp_f32_e32 v158, v158
	v_exp_f32_e32 v159, v159
	v_exp_f32_e32 v160, v160
	v_exp_f32_e32 v161, v161
	v_exp_f32_e32 v162, v162
	v_exp_f32_e32 v163, v163
	v_exp_f32_e32 v164, v164
	v_exp_f32_e32 v165, v165
	v_add_f32_e32 v158, 1.0, v158
	v_add_f32_e32 v159, 1.0, v159
	v_add_f32_e32 v160, 1.0, v160
	v_add_f32_e32 v161, 1.0, v161
	v_add_f32_e32 v162, 1.0, v162
	v_add_f32_e32 v163, 1.0, v163
	v_add_f32_e32 v164, 1.0, v164
	v_add_f32_e32 v165, 1.0, v165
	v_rcp_f32_e32 v158, v158
	v_rcp_f32_e32 v159, v159
	v_rcp_f32_e32 v160, v160
	v_rcp_f32_e32 v161, v161
	v_rcp_f32_e32 v162, v162
	v_rcp_f32_e32 v163, v163
	v_rcp_f32_e32 v164, v164
	v_rcp_f32_e32 v165, v165
	s_nop 0
	v_pk_mul_f32 v[4:5], v[4:5], v[158:159]
	v_pk_mul_f32 v[6:7], v[6:7], v[160:161]
	v_pk_mul_f32 v[0:1], v[0:1], v[162:163]
	v_pk_mul_f32 v[2:3], v[2:3], v[164:165]
	v_cvt_pk_bf16_f32 v180, v4, v5
	v_cvt_pk_bf16_f32 v181, v6, v7
	v_cvt_pk_bf16_f32 v182, v0, v1
	v_cvt_pk_bf16_f32 v183, v2, v3
	global_store_dwordx4 v147, v[180:183], s[82:83] offset:256
	s_andn2_b64 vcc, exec, s[6:7]
	s_mov_b64 s[6:7], -1
	s_mov_b32 s98, 1
	s_cbranch_vccnz .LBB0_1092
	s_andn2_b64 vcc, exec, s[0:1]
	s_cbranch_vccnz .LBB0_1091
	s_barrier
	s_branch .LBB0_1091

.LBB0_1114:
	s_add_u32 s8, s6, 0x86a0000
	s_addc_u32 s9, s7, 0
	s_add_u32 s10, s6, 0x186a0000
	s_addc_u32 s11, s7, 0
	s_lshl_b32 s6, s12, 5
	s_mov_b64 s[12:13], 0x80
	s_and_b32 s17, s6, 0x60
	s_add_i32 m0, s27, 0x18000
	v_lshl_add_u64 v[6:7], v[6:7], 0, s[12:13]
	s_lshl_b32 s16, s15, 13
	s_lshl_b32 s18, s17, 7
	s_waitcnt vmcnt(2)
	s_barrier
	global_load_lds_dwordx4 v[6:7], off
	v_lshl_add_u64 v[4:5], v[4:5], 0, s[12:13]
	s_add_i32 m0, s27, 0x1a000
	s_add_i32 s44, s27, 0x8000
	s_add_i32 s45, s27, 0xa000
	global_load_lds_dwordx4 v[4:5], off
	v_lshl_add_u64 v[0:1], v[0:1], 0, s[12:13]
	s_mov_b32 m0, s44
	s_add_u32 s6, s30, 0x20080
	global_load_lds_dwordx4 v[0:1], off
	v_lshl_add_u64 v[0:1], v[2:3], 0, s[12:13]
	s_mov_b32 m0, s45
	s_addc_u32 s7, s31, 0
	global_load_lds_dwordx4 v[0:1], off
	s_add_i32 m0, s27, 0x1c000
	v_lshl_add_u64 v[0:1], s[6:7], 0, v[134:135]
	global_load_lds_dwordx4 v[0:1], off
	v_lshl_add_u64 v[0:1], s[6:7], 0, v[138:139]
	s_add_i32 m0, s27, 0x1e000
	s_cmpk_lt_u32 s2, 0x100
	global_load_lds_dwordx4 v[0:1], off
	v_lshrrev_b32_e32 v1, 1, v8
	v_and_b32_e32 v1, 24, v1
	v_and_b32_e32 v0, 15, v8
	v_lshlrev_b32_e32 v2, 1, v1
	v_lshl_or_b32 v160, s15, 6, v0
	v_lshl_or_b32 v0, v0, 6, v2
	v_lshlrev_b32_e32 v2, 2, v8
	v_and_b32_e32 v2, 32, v2
	v_bitop3_b32 v3, v0, s16, v2 bitop3:0xde
	v_bitop3_b32 v161, v0, s18, v2 bitop3:0xde
	v_lshlrev_b32_e32 v0, 13, v9
	v_and_b32_e32 v0, 0xffffc000, v0
	v_or_b32_e32 v162, s17, v1
	v_lshl_add_u32 v0, v10, 10, v0
	v_and_b32_e32 v1, 1, v9
	v_lshl_or_b32 v0, v1, 6, v0
	v_lshl_add_u32 v140, v11, 1, v0
	v_lshlrev_b32_e32 v0, 13, v12
	v_and_b32_e32 v0, 0xffffc000, v0
	s_waitcnt vmcnt(6)
	v_lshl_add_u32 v0, v13, 10, v0
	v_and_b32_e32 v1, 1, v12
	s_sext_i32_i8 s51, s14
	s_cselect_b64 s[14:15], -1, 0
	v_lshl_or_b32 v0, v1, 6, v0
	s_add_i32 s48, 0, 0x10000
	s_add_i32 s49, 0, 0x14000
	s_ashr_i32 s46, s90, 31
	s_mov_b32 s47, s90
	v_mov_b32_e32 v141, v135
	v_lshl_add_u32 v142, v14, 1, v0
	v_mov_b32_e32 v143, v135
	v_mov_b64_e32 v[144:145], 0x400
	v_mov_b64_e32 v[146:147], 0x3ff
	v_add_u32_e32 v163, s48, v161
	v_add_u32_e32 v164, s49, v161
	v_add_u32_e32 v165, 0, v3
	s_movk_i32 s50, 0x2600
	s_mov_b64 s[16:17], 0x1e00
	s_barrier
	s_mov_b32 s98, 0
	s_branch .LBB0_1117

.LBB0_1123:
	s_ashr_i32 s21, s20, 31
	s_lshl_b64 s[22:23], s[20:21], 18
	s_add_u32 s22, s33, s22
	s_addc_u32 s23, s36, s23
	s_and_b64 s[24:25], s[6:7], exec
	s_cselect_b32 s2, s23, s29
	s_cselect_b32 s21, s22, s28
	s_ashr_i32 s19, s18, 31
	s_lshl_b64 s[24:25], s[18:19], 18
	s_add_u32 s24, s37, s24
	s_addc_u32 s25, s38, s25
	s_and_b64 s[34:35], s[6:7], exec
	s_cselect_b32 s19, s25, s31
	s_cselect_b32 s52, s24, s30
	s_add_u32 s28, s28, 0x20080
	s_addc_u32 s29, s29, 0
	s_add_u32 s53, s30, 0x100
	v_mov_b32_e32 v0, 0
	s_addc_u32 s54, s31, 0
	s_mov_b32 s55, -2
	v_mov_b32_e32 v1, v0
	v_mov_b32_e32 v2, v0
	v_mov_b32_e32 v3, v0
	v_mov_b32_e32 v4, v0
	v_mov_b32_e32 v5, v0
	v_mov_b32_e32 v6, v0
	v_mov_b32_e32 v7, v0
	v_mov_b32_e32 v16, v0
	v_mov_b32_e32 v17, v0
	v_mov_b32_e32 v18, v0
	v_mov_b32_e32 v19, v0
	v_mov_b32_e32 v20, v0
	v_mov_b32_e32 v21, v0
	v_mov_b32_e32 v22, v0
	v_mov_b32_e32 v23, v0
	v_mov_b32_e32 v32, v0
	v_mov_b32_e32 v33, v0
	v_mov_b32_e32 v34, v0
	v_mov_b32_e32 v35, v0
	v_mov_b32_e32 v36, v0
	v_mov_b32_e32 v37, v0
	v_mov_b32_e32 v38, v0
	v_mov_b32_e32 v39, v0
	v_mov_b32_e32 v48, v0
	v_mov_b32_e32 v49, v0
	v_mov_b32_e32 v50, v0
	v_mov_b32_e32 v51, v0
	v_mov_b32_e32 v52, v0
	v_mov_b32_e32 v53, v0
	v_mov_b32_e32 v54, v0
	v_mov_b32_e32 v55, v0
	v_mov_b32_e32 v8, v0
	v_mov_b32_e32 v9, v0
	v_mov_b32_e32 v10, v0
	v_mov_b32_e32 v11, v0
	v_mov_b32_e32 v12, v0
	v_mov_b32_e32 v13, v0
	v_mov_b32_e32 v14, v0
	v_mov_b32_e32 v15, v0
	v_mov_b32_e32 v24, v0
	v_mov_b32_e32 v25, v0
	v_mov_b32_e32 v26, v0
	v_mov_b32_e32 v27, v0
	v_mov_b32_e32 v28, v0
	v_mov_b32_e32 v29, v0
	v_mov_b32_e32 v30, v0
	v_mov_b32_e32 v31, v0
	v_mov_b32_e32 v40, v0
	v_mov_b32_e32 v41, v0
	v_mov_b32_e32 v42, v0
	v_mov_b32_e32 v43, v0
	v_mov_b32_e32 v44, v0
	v_mov_b32_e32 v45, v0
	v_mov_b32_e32 v46, v0
	v_mov_b32_e32 v47, v0
	v_mov_b32_e32 v56, v0
	v_mov_b32_e32 v57, v0
	v_mov_b32_e32 v58, v0
	v_mov_b32_e32 v59, v0
	v_mov_b32_e32 v60, v0
	v_mov_b32_e32 v61, v0
	v_mov_b32_e32 v62, v0
	v_mov_b32_e32 v63, v0
	v_mov_b32_e32 v64, v0
	v_mov_b32_e32 v65, v0
	v_mov_b32_e32 v66, v0
	v_mov_b32_e32 v67, v0
	v_mov_b32_e32 v68, v0
	v_mov_b32_e32 v69, v0
	v_mov_b32_e32 v70, v0
	v_mov_b32_e32 v71, v0
	v_mov_b32_e32 v80, v0
	v_mov_b32_e32 v81, v0
	v_mov_b32_e32 v82, v0
	v_mov_b32_e32 v83, v0
	v_mov_b32_e32 v84, v0
	v_mov_b32_e32 v85, v0
	v_mov_b32_e32 v86, v0
	v_mov_b32_e32 v87, v0
	v_mov_b32_e32 v96, v0
	v_mov_b32_e32 v97, v0
	v_mov_b32_e32 v98, v0
	v_mov_b32_e32 v99, v0
	v_mov_b32_e32 v100, v0
	v_mov_b32_e32 v101, v0
	v_mov_b32_e32 v102, v0
	v_mov_b32_e32 v103, v0
	v_mov_b32_e32 v112, v0
	v_mov_b32_e32 v113, v0
	v_mov_b32_e32 v114, v0
	v_mov_b32_e32 v115, v0
	v_mov_b32_e32 v116, v0
	v_mov_b32_e32 v117, v0
	v_mov_b32_e32 v118, v0
	v_mov_b32_e32 v119, v0
	v_mov_b32_e32 v72, v0
	v_mov_b32_e32 v73, v0
	v_mov_b32_e32 v74, v0
	v_mov_b32_e32 v75, v0
	v_mov_b32_e32 v76, v0
	v_mov_b32_e32 v77, v0
	v_mov_b32_e32 v78, v0
	v_mov_b32_e32 v79, v0
	v_mov_b32_e32 v88, v0
	v_mov_b32_e32 v89, v0
	v_mov_b32_e32 v90, v0
	v_mov_b32_e32 v91, v0
	v_mov_b32_e32 v92, v0
	v_mov_b32_e32 v93, v0
	v_mov_b32_e32 v94, v0
	v_mov_b32_e32 v95, v0
	v_mov_b32_e32 v104, v0
	v_mov_b32_e32 v105, v0
	v_mov_b32_e32 v106, v0
	v_mov_b32_e32 v107, v0
	v_mov_b32_e32 v108, v0
	v_mov_b32_e32 v109, v0
	v_mov_b32_e32 v110, v0
	v_mov_b32_e32 v111, v0
	v_mov_b32_e32 v120, v0
	v_mov_b32_e32 v121, v0
	v_mov_b32_e32 v122, v0
	v_mov_b32_e32 v123, v0
	v_mov_b32_e32 v124, v0
	v_mov_b32_e32 v125, v0
	v_mov_b32_e32 v126, v0
	v_mov_b32_e32 v127, v0
	s_cmp_eq_u32 s98, 0
	s_cbranch_scc1 .LBB0_1124
	ds_read_b128 v[128:131], v163
	ds_read_b128 v[148:151], v163 offset:1024
	ds_read_b128 v[152:155], v163 offset:2048
	ds_read_b128 v[156:159], v163 offset:3072
	ds_read_b128 v[166:169], v164
	ds_read_b128 v[170:173], v164 offset:1024
	ds_read_b128 v[174:177], v164 offset:2048
	ds_read_b128 v[178:181], v164 offset:3072
	s_add_u32 s30, s28, 0xfffe0080
	s_addc_u32 s31, s29, -1
	s_cmp_eq_u32 s55, 4
	s_cselect_b32 s35, s2, s31
	s_cselect_b32 s34, s21, s30
	s_cselect_b32 s31, s19, s54
	s_cselect_b32 s30, s52, s53
	v_lshl_add_u64 v[214:215], s[28:29], 0, v[140:141]
	s_add_i32 m0, s27, 0xc000
	ds_read_b128 v[182:185], v165
	ds_read_b128 v[186:189], v165 offset:1024
	ds_read_b128 v[190:193], v165 offset:2048
	ds_read_b128 v[194:197], v165 offset:3072
	ds_read_b128 v[198:201], v165 offset:4096
	ds_read_b128 v[202:205], v165 offset:5120
	ds_read_b128 v[206:209], v165 offset:6144
	ds_read_b128 v[210:213], v165 offset:7168
	global_load_lds_dwordx4 v[214:215], off
	v_lshl_add_u64 v[214:215], s[28:29], 0, v[142:143]
	s_add_i32 m0, s27, 0xe000
	s_nop 0
	global_load_lds_dwordx4 v[214:215], off
	s_waitcnt vmcnt(30)
	s_waitcnt lgkmcnt(0)
	s_barrier
	s_setprio 1
	s_waitcnt lgkmcnt(0)
	v_mfma_f32_16x16x32_bf16 v[124:127], v[128:131], v[182:185], v[124:127]
	v_mfma_f32_16x16x32_bf16 v[120:123], v[152:155], v[182:185], v[120:123]
	v_mfma_f32_16x16x32_bf16 v[108:111], v[128:131], v[190:193], v[108:111]
	v_mfma_f32_16x16x32_bf16 v[104:107], v[152:155], v[190:193], v[104:107]
	v_mfma_f32_16x16x32_bf16 v[92:95], v[128:131], v[198:201], v[92:95]
	v_mfma_f32_16x16x32_bf16 v[88:91], v[152:155], v[198:201], v[88:91]
	v_mfma_f32_16x16x32_bf16 v[76:79], v[128:131], v[206:209], v[76:79]
	v_mfma_f32_16x16x32_bf16 v[72:75], v[152:155], v[206:209], v[72:75]
	v_mfma_f32_16x16x32_bf16 v[124:127], v[148:151], v[186:189], v[124:127]
	v_mfma_f32_16x16x32_bf16 v[120:123], v[156:159], v[186:189], v[120:123]
	v_mfma_f32_16x16x32_bf16 v[108:111], v[148:151], v[194:197], v[108:111]
	v_mfma_f32_16x16x32_bf16 v[104:107], v[156:159], v[194:197], v[104:107]
	v_mfma_f32_16x16x32_bf16 v[92:95], v[148:151], v[202:205], v[92:95]
	v_mfma_f32_16x16x32_bf16 v[88:91], v[156:159], v[202:205], v[88:91]
	v_mfma_f32_16x16x32_bf16 v[76:79], v[148:151], v[210:213], v[76:79]
	v_mfma_f32_16x16x32_bf16 v[72:75], v[156:159], v[210:213], v[72:75]
	s_setprio 0
	s_setprio 1
	v_mfma_f32_16x16x32_bf16 v[116:119], v[166:169], v[182:185], v[116:119]
	v_mfma_f32_16x16x32_bf16 v[112:115], v[174:177], v[182:185], v[112:115]
	v_mfma_f32_16x16x32_bf16 v[100:103], v[166:169], v[190:193], v[100:103]
	v_mfma_f32_16x16x32_bf16 v[96:99], v[174:177], v[190:193], v[96:99]
	v_mfma_f32_16x16x32_bf16 v[84:87], v[166:169], v[198:201], v[84:87]
	v_mfma_f32_16x16x32_bf16 v[80:83], v[174:177], v[198:201], v[80:83]
	v_mfma_f32_16x16x32_bf16 v[68:71], v[166:169], v[206:209], v[68:71]
	v_mfma_f32_16x16x32_bf16 v[64:67], v[174:177], v[206:209], v[64:67]
	v_mfma_f32_16x16x32_bf16 v[116:119], v[170:173], v[186:189], v[116:119]
	v_mfma_f32_16x16x32_bf16 v[112:115], v[178:181], v[186:189], v[112:115]
	v_mfma_f32_16x16x32_bf16 v[100:103], v[170:173], v[194:197], v[100:103]
	v_mfma_f32_16x16x32_bf16 v[96:99], v[178:181], v[194:197], v[96:99]
	v_mfma_f32_16x16x32_bf16 v[84:87], v[170:173], v[202:205], v[84:87]
	v_mfma_f32_16x16x32_bf16 v[80:83], v[178:181], v[202:205], v[80:83]
	v_mfma_f32_16x16x32_bf16 v[68:71], v[170:173], v[210:213], v[68:71]
	v_mfma_f32_16x16x32_bf16 v[64:67], v[178:181], v[210:213], v[64:67]
	s_setprio 0
	s_barrier
	s_add_i32 s56, s48, s39
	v_lshl_add_u64 v[214:215], s[30:31], 0, v[134:135]
	s_mov_b32 m0, s56
	ds_read_b128 v[182:185], v165 offset:16384
	ds_read_b128 v[186:189], v165 offset:17408
	ds_read_b128 v[190:193], v165 offset:18432
	ds_read_b128 v[194:197], v165 offset:19456
	ds_read_b128 v[198:201], v165 offset:20480
	ds_read_b128 v[202:205], v165 offset:21504
	ds_read_b128 v[206:209], v165 offset:22528
	ds_read_b128 v[210:213], v165 offset:23552
	global_load_lds_dwordx4 v[214:215], off
	s_add_i32 m0, s56, 0x2000
	s_add_u32 s56, s30, 0x20000
	v_lshl_add_u64 v[216:217], s[30:31], 0, v[138:139]
	s_addc_u32 s57, s31, 0
	s_add_i32 s58, s49, s39
	global_load_lds_dwordx4 v[216:217], off
	v_lshl_add_u64 v[218:219], s[56:57], 0, v[134:135]
	s_mov_b32 m0, s58
	v_lshl_add_u64 v[220:221], s[34:35], 0, v[136:137]
	global_load_lds_dwordx4 v[218:219], off
	v_lshl_add_u64 v[218:219], s[56:57], 0, v[138:139]
	s_add_i32 m0, s58, 0x2000
	s_nop 0
	global_load_lds_dwordx4 v[218:219], off
	v_lshl_add_u64 v[218:219], s[34:35], 0, v[132:133]
	s_mov_b32 m0, s27
	s_nop 0
	global_load_lds_dwordx4 v[218:219], off
	s_mov_b32 m0, s40
	s_nop 0
	global_load_lds_dwordx4 v[220:221], off
	s_waitcnt vmcnt(30)
	s_waitcnt lgkmcnt(0)
	s_barrier
	s_setprio 1
	s_waitcnt lgkmcnt(0)
	v_mfma_f32_16x16x32_bf16 v[60:63], v[128:131], v[182:185], v[60:63]
	v_mfma_f32_16x16x32_bf16 v[56:59], v[152:155], v[182:185], v[56:59]
	v_mfma_f32_16x16x32_bf16 v[44:47], v[128:131], v[190:193], v[44:47]
	v_mfma_f32_16x16x32_bf16 v[40:43], v[152:155], v[190:193], v[40:43]
	v_mfma_f32_16x16x32_bf16 v[28:31], v[128:131], v[198:201], v[28:31]
	v_mfma_f32_16x16x32_bf16 v[24:27], v[152:155], v[198:201], v[24:27]
	v_mfma_f32_16x16x32_bf16 v[12:15], v[128:131], v[206:209], v[12:15]
	v_mfma_f32_16x16x32_bf16 v[8:11], v[152:155], v[206:209], v[8:11]
	v_mfma_f32_16x16x32_bf16 v[60:63], v[148:151], v[186:189], v[60:63]
	v_mfma_f32_16x16x32_bf16 v[56:59], v[156:159], v[186:189], v[56:59]
	v_mfma_f32_16x16x32_bf16 v[44:47], v[148:151], v[194:197], v[44:47]
	v_mfma_f32_16x16x32_bf16 v[40:43], v[156:159], v[194:197], v[40:43]
	v_mfma_f32_16x16x32_bf16 v[28:31], v[148:151], v[202:205], v[28:31]
	v_mfma_f32_16x16x32_bf16 v[24:27], v[156:159], v[202:205], v[24:27]
	v_mfma_f32_16x16x32_bf16 v[12:15], v[148:151], v[210:213], v[12:15]
	v_mfma_f32_16x16x32_bf16 v[8:11], v[156:159], v[210:213], v[8:11]
	s_setprio 0
	s_setprio 1
	v_mfma_f32_16x16x32_bf16 v[52:55], v[166:169], v[182:185], v[52:55]
	v_mfma_f32_16x16x32_bf16 v[48:51], v[174:177], v[182:185], v[48:51]
	v_mfma_f32_16x16x32_bf16 v[36:39], v[166:169], v[190:193], v[36:39]
	v_mfma_f32_16x16x32_bf16 v[32:35], v[174:177], v[190:193], v[32:35]
	v_mfma_f32_16x16x32_bf16 v[20:23], v[166:169], v[198:201], v[20:23]
	v_mfma_f32_16x16x32_bf16 v[16:19], v[174:177], v[198:201], v[16:19]
	v_mfma_f32_16x16x32_bf16 v[4:7], v[166:169], v[206:209], v[4:7]
	v_mfma_f32_16x16x32_bf16 v[0:3], v[174:177], v[206:209], v[0:3]
	v_mfma_f32_16x16x32_bf16 v[52:55], v[170:173], v[186:189], v[52:55]
	v_mfma_f32_16x16x32_bf16 v[48:51], v[178:181], v[186:189], v[48:51]
	v_mfma_f32_16x16x32_bf16 v[36:39], v[170:173], v[194:197], v[36:39]
	v_mfma_f32_16x16x32_bf16 v[32:35], v[178:181], v[194:197], v[32:35]
	v_mfma_f32_16x16x32_bf16 v[20:23], v[170:173], v[202:205], v[20:23]
	v_mfma_f32_16x16x32_bf16 v[16:19], v[178:181], v[202:205], v[16:19]
	v_mfma_f32_16x16x32_bf16 v[4:7], v[170:173], v[210:213], v[4:7]
	v_mfma_f32_16x16x32_bf16 v[0:3], v[178:181], v[210:213], v[0:3]
	s_setprio 0
	s_barrier
	s_add_i32 s56, 0, 0x18000
	s_add_i32 s57, 0, 0x1c000
	v_add_u32_e32 v156, s56, v161
	v_add_u32_e32 v178, s57, v161
	ds_read_b128 v[128:131], v156
	ds_read_b128 v[148:151], v156 offset:1024
	ds_read_b128 v[152:155], v156 offset:2048
	ds_read_b128 v[156:159], v156 offset:3072
	ds_read_b128 v[166:169], v178
	ds_read_b128 v[170:173], v178 offset:1024
	ds_read_b128 v[174:177], v178 offset:2048
	ds_read_b128 v[178:181], v178 offset:3072
	s_add_u32 s34, s34, 0x20000
	s_addc_u32 s35, s35, 0
	s_mov_b32 m0, s41
	v_lshl_add_u64 v[222:223], s[34:35], 0, v[132:133]
	ds_read_b128 v[182:185], v165 offset:32768
	ds_read_b128 v[186:189], v165 offset:33792
	ds_read_b128 v[190:193], v165 offset:34816
	ds_read_b128 v[194:197], v165 offset:35840
	ds_read_b128 v[198:201], v165 offset:36864
	ds_read_b128 v[202:205], v165 offset:37888
	ds_read_b128 v[206:209], v165 offset:38912
	ds_read_b128 v[210:213], v165 offset:39936
	global_load_lds_dwordx4 v[222:223], off
	v_lshl_add_u64 v[222:223], s[34:35], 0, v[136:137]
	s_mov_b32 m0, s42
	s_nop 0
	global_load_lds_dwordx4 v[222:223], off
	s_waitcnt vmcnt(8)
	s_waitcnt lgkmcnt(0)
	s_barrier
	s_setprio 1
	s_waitcnt lgkmcnt(0)
	v_mfma_f32_16x16x32_bf16 v[124:127], v[128:131], v[182:185], v[124:127]
	v_mfma_f32_16x16x32_bf16 v[120:123], v[152:155], v[182:185], v[120:123]
	v_mfma_f32_16x16x32_bf16 v[108:111], v[128:131], v[190:193], v[108:111]
	v_mfma_f32_16x16x32_bf16 v[104:107], v[152:155], v[190:193], v[104:107]
	v_mfma_f32_16x16x32_bf16 v[92:95], v[128:131], v[198:201], v[92:95]
	v_mfma_f32_16x16x32_bf16 v[88:91], v[152:155], v[198:201], v[88:91]
	v_mfma_f32_16x16x32_bf16 v[76:79], v[128:131], v[206:209], v[76:79]
	v_mfma_f32_16x16x32_bf16 v[72:75], v[152:155], v[206:209], v[72:75]
	v_mfma_f32_16x16x32_bf16 v[124:127], v[148:151], v[186:189], v[124:127]
	v_mfma_f32_16x16x32_bf16 v[120:123], v[156:159], v[186:189], v[120:123]
	v_mfma_f32_16x16x32_bf16 v[108:111], v[148:151], v[194:197], v[108:111]
	v_mfma_f32_16x16x32_bf16 v[104:107], v[156:159], v[194:197], v[104:107]
	v_mfma_f32_16x16x32_bf16 v[92:95], v[148:151], v[202:205], v[92:95]
	v_mfma_f32_16x16x32_bf16 v[88:91], v[156:159], v[202:205], v[88:91]
	v_mfma_f32_16x16x32_bf16 v[76:79], v[148:151], v[210:213], v[76:79]
	v_mfma_f32_16x16x32_bf16 v[72:75], v[156:159], v[210:213], v[72:75]
	s_setprio 0
	s_setprio 1
	v_mfma_f32_16x16x32_bf16 v[116:119], v[166:169], v[182:185], v[116:119]
	v_mfma_f32_16x16x32_bf16 v[112:115], v[174:177], v[182:185], v[112:115]
	v_mfma_f32_16x16x32_bf16 v[100:103], v[166:169], v[190:193], v[100:103]
	v_mfma_f32_16x16x32_bf16 v[96:99], v[174:177], v[190:193], v[96:99]
	v_mfma_f32_16x16x32_bf16 v[84:87], v[166:169], v[198:201], v[84:87]
	v_mfma_f32_16x16x32_bf16 v[80:83], v[174:177], v[198:201], v[80:83]
	v_mfma_f32_16x16x32_bf16 v[68:71], v[166:169], v[206:209], v[68:71]
	v_mfma_f32_16x16x32_bf16 v[64:67], v[174:177], v[206:209], v[64:67]
	v_mfma_f32_16x16x32_bf16 v[116:119], v[170:173], v[186:189], v[116:119]
	v_mfma_f32_16x16x32_bf16 v[112:115], v[178:181], v[186:189], v[112:115]
	v_mfma_f32_16x16x32_bf16 v[100:103], v[170:173], v[194:197], v[100:103]
	v_mfma_f32_16x16x32_bf16 v[96:99], v[178:181], v[194:197], v[96:99]
	v_mfma_f32_16x16x32_bf16 v[84:87], v[170:173], v[202:205], v[84:87]
	v_mfma_f32_16x16x32_bf16 v[80:83], v[178:181], v[202:205], v[80:83]
	v_mfma_f32_16x16x32_bf16 v[68:71], v[170:173], v[210:213], v[68:71]
	v_mfma_f32_16x16x32_bf16 v[64:67], v[178:181], v[210:213], v[64:67]
	s_setprio 0
	s_barrier
	s_add_i32 s34, s56, s39
	v_lshl_add_u64 v[214:215], v[214:215], 0, s[12:13]
	s_mov_b32 m0, s34
	ds_read_b128 v[182:185], v165 offset:49152
	ds_read_b128 v[186:189], v165 offset:50176
	ds_read_b128 v[190:193], v165 offset:51200
	ds_read_b128 v[194:197], v165 offset:52224
	ds_read_b128 v[198:201], v165 offset:53248
	ds_read_b128 v[202:205], v165 offset:54272
	ds_read_b128 v[206:209], v165 offset:55296
	ds_read_b128 v[210:213], v165 offset:56320
	global_load_lds_dwordx4 v[214:215], off
	s_add_i32 m0, s34, 0x2000
	s_add_u32 s30, s30, 0x20080
	v_lshl_add_u64 v[214:215], v[216:217], 0, s[12:13]
	s_addc_u32 s31, s31, 0
	s_add_i32 s34, s57, s39
	global_load_lds_dwordx4 v[214:215], off
	v_lshl_add_u64 v[214:215], s[30:31], 0, v[134:135]
	s_mov_b32 m0, s34
	s_nop 0
	global_load_lds_dwordx4 v[214:215], off
	v_lshl_add_u64 v[214:215], s[30:31], 0, v[138:139]
	s_add_i32 m0, s34, 0x2000
	s_nop 0
	global_load_lds_dwordx4 v[214:215], off
	v_lshl_add_u64 v[214:215], v[218:219], 0, s[12:13]
	s_mov_b32 m0, s44
	s_nop 0
	global_load_lds_dwordx4 v[214:215], off
	v_lshl_add_u64 v[214:215], v[220:221], 0, s[12:13]
	s_mov_b32 m0, s45
	s_nop 0
	global_load_lds_dwordx4 v[214:215], off
	s_waitcnt vmcnt(8)
	s_waitcnt lgkmcnt(0)
	s_barrier
	s_setprio 1
	s_waitcnt lgkmcnt(0)
	v_mfma_f32_16x16x32_bf16 v[60:63], v[128:131], v[182:185], v[60:63]
	v_mfma_f32_16x16x32_bf16 v[56:59], v[152:155], v[182:185], v[56:59]
	v_mfma_f32_16x16x32_bf16 v[44:47], v[128:131], v[190:193], v[44:47]
	v_mfma_f32_16x16x32_bf16 v[40:43], v[152:155], v[190:193], v[40:43]
	v_mfma_f32_16x16x32_bf16 v[28:31], v[128:131], v[198:201], v[28:31]
	v_mfma_f32_16x16x32_bf16 v[24:27], v[152:155], v[198:201], v[24:27]
	v_mfma_f32_16x16x32_bf16 v[12:15], v[128:131], v[206:209], v[12:15]
	v_mfma_f32_16x16x32_bf16 v[8:11], v[152:155], v[206:209], v[8:11]
	v_mfma_f32_16x16x32_bf16 v[60:63], v[148:151], v[186:189], v[60:63]
	v_mfma_f32_16x16x32_bf16 v[56:59], v[156:159], v[186:189], v[56:59]
	v_mfma_f32_16x16x32_bf16 v[44:47], v[148:151], v[194:197], v[44:47]
	v_mfma_f32_16x16x32_bf16 v[40:43], v[156:159], v[194:197], v[40:43]
	v_mfma_f32_16x16x32_bf16 v[28:31], v[148:151], v[202:205], v[28:31]
	v_mfma_f32_16x16x32_bf16 v[24:27], v[156:159], v[202:205], v[24:27]
	v_mfma_f32_16x16x32_bf16 v[12:15], v[148:151], v[210:213], v[12:15]
	v_mfma_f32_16x16x32_bf16 v[8:11], v[156:159], v[210:213], v[8:11]
	s_setprio 0
	s_setprio 1
	v_mfma_f32_16x16x32_bf16 v[52:55], v[166:169], v[182:185], v[52:55]
	v_mfma_f32_16x16x32_bf16 v[48:51], v[174:177], v[182:185], v[48:51]
	v_mfma_f32_16x16x32_bf16 v[36:39], v[166:169], v[190:193], v[36:39]
	v_mfma_f32_16x16x32_bf16 v[32:35], v[174:177], v[190:193], v[32:35]
	v_mfma_f32_16x16x32_bf16 v[20:23], v[166:169], v[198:201], v[20:23]
	v_mfma_f32_16x16x32_bf16 v[16:19], v[174:177], v[198:201], v[16:19]
	v_mfma_f32_16x16x32_bf16 v[4:7], v[166:169], v[206:209], v[4:7]
	v_mfma_f32_16x16x32_bf16 v[0:3], v[174:177], v[206:209], v[0:3]
	v_mfma_f32_16x16x32_bf16 v[52:55], v[170:173], v[186:189], v[52:55]
	v_mfma_f32_16x16x32_bf16 v[48:51], v[178:181], v[186:189], v[48:51]
	v_mfma_f32_16x16x32_bf16 v[36:39], v[170:173], v[194:197], v[36:39]
	v_mfma_f32_16x16x32_bf16 v[32:35], v[178:181], v[194:197], v[32:35]
	v_mfma_f32_16x16x32_bf16 v[20:23], v[170:173], v[202:205], v[20:23]
	v_mfma_f32_16x16x32_bf16 v[16:19], v[178:181], v[202:205], v[16:19]
	v_mfma_f32_16x16x32_bf16 v[4:7], v[170:173], v[210:213], v[4:7]
	v_mfma_f32_16x16x32_bf16 v[0:3], v[178:181], v[210:213], v[0:3]
	s_setprio 0
	s_barrier
	s_add_i32 s55, s55, 2
	s_add_u32 s28, s28, 0x100
	s_addc_u32 s29, s29, 0
	s_add_u32 s53, s53, 0x100
	s_addc_u32 s54, s54, 0
	s_cmp_gt_u32 s55, 5
	s_cbranch_scc0 .LBB0_1124
	s_branch .Lpeel_exit_P10

.LBB0_1127:
	v_lshl_add_u32 v128, s26, 8, v160
	v_lshl_or_b32 v129, s51, 8, v162
	s_add_u32 s52, s10, s16
	s_addc_u32 s53, s11, s17
	v_lshlrev_b32_e32 v129, 1, v129
	s_add_u32 s54, s52, 0x26000
	s_addc_u32 s55, s53, 0
	s_add_u32 s56, s52, 0x4c000
	s_addc_u32 s57, s53, 0
	s_add_u32 s58, s52, 0x72000
	s_addc_u32 s59, s53, 0
	s_add_u32 s60, s52, 0x130000
	s_addc_u32 s61, s53, 0
	s_add_u32 s62, s52, 0x156000
	s_addc_u32 s63, s53, 0
	s_add_u32 s66, s52, 0x17c000
	s_addc_u32 s67, s53, 0
	s_add_u32 s68, s52, 0x1a2000
	s_addc_u32 s69, s53, 0
	s_add_u32 s70, s8, 0x8000
	s_addc_u32 s71, s9, 0
	s_add_u32 s72, s8, 0x10000
	s_addc_u32 s73, s9, 0
	s_add_u32 s74, s8, 0x18000
	s_addc_u32 s75, s9, 0
	s_add_u32 s76, s8, 0x40000
	s_addc_u32 s77, s9, 0
	s_add_u32 s78, s8, 0x48000
	s_addc_u32 s79, s9, 0
	s_add_u32 s80, s8, 0x50000
	s_addc_u32 s81, s9, 0
	s_add_u32 s82, s8, 0x58000
	s_addc_u32 s83, s9, 0
	v_mad_u32_u24 v130, v128, s50, v129
	v_lshl_add_u32 v131, v128, 11, v129
	s_nop 1
	global_load_dwordx4 v[166:169], v130, s[52:53]
	global_load_dwordx4 v[170:173], v130, s[52:53] offset:256
	global_load_dwordx4 v[174:177], v130, s[54:55]
	global_load_dwordx4 v[178:181], v130, s[54:55] offset:256
	global_load_dwordx4 v[214:217], v131, s[8:9]
	global_load_dwordx4 v[218:221], v131, s[8:9] offset:256
	global_load_dwordx4 v[222:225], v131, s[70:71]
	global_load_dwordx4 v[226:229], v131, s[70:71] offset:256
	global_load_dwordx4 v[182:185], v130, s[56:57]
	global_load_dwordx4 v[186:189], v130, s[56:57] offset:256
	global_load_dwordx4 v[190:193], v130, s[58:59]
	global_load_dwordx4 v[194:197], v130, s[58:59] offset:256
	global_load_dwordx4 v[240:243], v131, s[72:73]
	global_load_dwordx4 v[244:247], v131, s[72:73] offset:256
	global_load_dwordx4 v[248:251], v131, s[74:75]
	global_load_dwordx4 v[156:159], v131, s[74:75] offset:256
	global_load_dwordx4 v[198:201], v130, s[60:61]
	global_load_dwordx4 v[202:205], v130, s[60:61] offset:256
	global_load_dwordx4 v[206:209], v130, s[62:63]
	global_load_dwordx4 v[210:213], v130, s[62:63] offset:256
	s_waitcnt vmcnt(12)
	v_lshlrev_b32_e32 v148, 16, v166
	v_and_b32_e32 v149, 0xffff0000, v166
	v_lshlrev_b32_e32 v150, 16, v167
	v_and_b32_e32 v151, 0xffff0000, v167
	v_lshlrev_b32_e32 v152, 16, v168
	v_and_b32_e32 v153, 0xffff0000, v168
	v_lshlrev_b32_e32 v154, 16, v169
	v_and_b32_e32 v155, 0xffff0000, v169
	v_mul_f32_e32 v148, 0xbfb8aa3b, v148
	v_mul_f32_e32 v149, 0xbfb8aa3b, v149
	v_mul_f32_e32 v150, 0xbfb8aa3b, v150
	v_mul_f32_e32 v151, 0xbfb8aa3b, v151
	v_mul_f32_e32 v152, 0xbfb8aa3b, v152
	v_mul_f32_e32 v153, 0xbfb8aa3b, v153
	v_mul_f32_e32 v154, 0xbfb8aa3b, v154
	v_mul_f32_e32 v155, 0xbfb8aa3b, v155
	v_exp_f32_e32 v148, v148
	v_exp_f32_e32 v149, v149
	v_exp_f32_e32 v150, v150
	v_exp_f32_e32 v151, v151
	v_exp_f32_e32 v152, v152
	v_exp_f32_e32 v153, v153
	v_exp_f32_e32 v154, v154
	v_exp_f32_e32 v155, v155
	v_lshlrev_b32_e32 v232, 16, v214
	v_and_b32_e32 v233, 0xffff0000, v214
	v_lshlrev_b32_e32 v234, 16, v215
	v_and_b32_e32 v235, 0xffff0000, v215
	v_lshlrev_b32_e32 v236, 16, v216
	v_and_b32_e32 v237, 0xffff0000, v216
	v_lshlrev_b32_e32 v238, 16, v217
	v_and_b32_e32 v239, 0xffff0000, v217
	v_add_f32_e32 v148, 1.0, v148
	v_add_f32_e32 v149, 1.0, v149
	v_add_f32_e32 v150, 1.0, v150
	v_add_f32_e32 v151, 1.0, v151
	v_add_f32_e32 v152, 1.0, v152
	v_add_f32_e32 v153, 1.0, v153
	v_add_f32_e32 v154, 1.0, v154
	v_add_f32_e32 v155, 1.0, v155
	v_rcp_f32_e32 v148, v148
	v_rcp_f32_e32 v149, v149
	v_rcp_f32_e32 v150, v150
	v_rcp_f32_e32 v151, v151
	v_rcp_f32_e32 v152, v152
	v_rcp_f32_e32 v153, v153
	v_rcp_f32_e32 v154, v154
	v_rcp_f32_e32 v155, v155
	s_nop 0
	v_pk_fma_f32 v[124:125], v[124:125], v[148:149], v[232:233]
	v_pk_fma_f32 v[126:127], v[126:127], v[150:151], v[234:235]
	v_pk_fma_f32 v[120:121], v[120:121], v[152:153], v[236:237]
	v_pk_fma_f32 v[122:123], v[122:123], v[154:155], v[238:239]
	v_cvt_pk_bf16_f32 v166, v124, v125
	v_cvt_pk_bf16_f32 v167, v126, v127
	v_cvt_pk_bf16_f32 v168, v120, v121
	v_cvt_pk_bf16_f32 v169, v122, v123
	global_store_dwordx4 v131, v[166:169], s[8:9]
	v_lshlrev_b32_e32 v148, 16, v170
	v_and_b32_e32 v149, 0xffff0000, v170
	v_lshlrev_b32_e32 v150, 16, v171
	v_and_b32_e32 v151, 0xffff0000, v171
	v_lshlrev_b32_e32 v152, 16, v172
	v_and_b32_e32 v153, 0xffff0000, v172
	v_lshlrev_b32_e32 v154, 16, v173
	v_and_b32_e32 v155, 0xffff0000, v173
	v_mul_f32_e32 v148, 0xbfb8aa3b, v148
	v_mul_f32_e32 v149, 0xbfb8aa3b, v149
	v_mul_f32_e32 v150, 0xbfb8aa3b, v150
	v_mul_f32_e32 v151, 0xbfb8aa3b, v151
	v_mul_f32_e32 v152, 0xbfb8aa3b, v152
	v_mul_f32_e32 v153, 0xbfb8aa3b, v153
	v_mul_f32_e32 v154, 0xbfb8aa3b, v154
	v_mul_f32_e32 v155, 0xbfb8aa3b, v155
	v_exp_f32_e32 v148, v148
	v_exp_f32_e32 v149, v149
	v_exp_f32_e32 v150, v150
	v_exp_f32_e32 v151, v151
	v_exp_f32_e32 v152, v152
	v_exp_f32_e32 v153, v153
	v_exp_f32_e32 v154, v154
	v_exp_f32_e32 v155, v155
	v_lshlrev_b32_e32 v232, 16, v218
	v_and_b32_e32 v233, 0xffff0000, v218
	v_lshlrev_b32_e32 v234, 16, v219
	v_and_b32_e32 v235, 0xffff0000, v219
	v_lshlrev_b32_e32 v236, 16, v220
	v_and_b32_e32 v237, 0xffff0000, v220
	v_lshlrev_b32_e32 v238, 16, v221
	v_and_b32_e32 v239, 0xffff0000, v221
	v_add_f32_e32 v148, 1.0, v148
	v_add_f32_e32 v149, 1.0, v149
	v_add_f32_e32 v150, 1.0, v150
	v_add_f32_e32 v151, 1.0, v151
	v_add_f32_e32 v152, 1.0, v152
	v_add_f32_e32 v153, 1.0, v153
	v_add_f32_e32 v154, 1.0, v154
	v_add_f32_e32 v155, 1.0, v155
	v_rcp_f32_e32 v148, v148
	v_rcp_f32_e32 v149, v149
	v_rcp_f32_e32 v150, v150
	v_rcp_f32_e32 v151, v151
	v_rcp_f32_e32 v152, v152
	v_rcp_f32_e32 v153, v153
	v_rcp_f32_e32 v154, v154
	v_rcp_f32_e32 v155, v155
	s_nop 0
	v_pk_fma_f32 v[116:117], v[116:117], v[148:149], v[232:233]
	v_pk_fma_f32 v[118:119], v[118:119], v[150:151], v[234:235]
	v_pk_fma_f32 v[112:113], v[112:113], v[152:153], v[236:237]
	v_pk_fma_f32 v[114:115], v[114:115], v[154:155], v[238:239]
	v_cvt_pk_bf16_f32 v170, v116, v117
	v_cvt_pk_bf16_f32 v171, v118, v119
	v_cvt_pk_bf16_f32 v172, v112, v113
	v_cvt_pk_bf16_f32 v173, v114, v115
	global_store_dwordx4 v131, v[170:173], s[8:9] offset:256
	v_lshlrev_b32_e32 v148, 16, v174
	v_and_b32_e32 v149, 0xffff0000, v174
	v_lshlrev_b32_e32 v150, 16, v175
	v_and_b32_e32 v151, 0xffff0000, v175
	v_lshlrev_b32_e32 v152, 16, v176
	v_and_b32_e32 v153, 0xffff0000, v176
	v_lshlrev_b32_e32 v154, 16, v177
	v_and_b32_e32 v155, 0xffff0000, v177
	v_mul_f32_e32 v148, 0xbfb8aa3b, v148
	v_mul_f32_e32 v149, 0xbfb8aa3b, v149
	v_mul_f32_e32 v150, 0xbfb8aa3b, v150
	v_mul_f32_e32 v151, 0xbfb8aa3b, v151
	v_mul_f32_e32 v152, 0xbfb8aa3b, v152
	v_mul_f32_e32 v153, 0xbfb8aa3b, v153
	v_mul_f32_e32 v154, 0xbfb8aa3b, v154
	v_mul_f32_e32 v155, 0xbfb8aa3b, v155
	v_exp_f32_e32 v148, v148
	v_exp_f32_e32 v149, v149
	v_exp_f32_e32 v150, v150
	v_exp_f32_e32 v151, v151
	v_exp_f32_e32 v152, v152
	v_exp_f32_e32 v153, v153
	v_exp_f32_e32 v154, v154
	v_exp_f32_e32 v155, v155
	v_lshlrev_b32_e32 v232, 16, v222
	v_and_b32_e32 v233, 0xffff0000, v222
	v_lshlrev_b32_e32 v234, 16, v223
	v_and_b32_e32 v235, 0xffff0000, v223
	v_lshlrev_b32_e32 v236, 16, v224
	v_and_b32_e32 v237, 0xffff0000, v224
	v_lshlrev_b32_e32 v238, 16, v225
	v_and_b32_e32 v239, 0xffff0000, v225
	v_add_f32_e32 v148, 1.0, v148
	v_add_f32_e32 v149, 1.0, v149
	v_add_f32_e32 v150, 1.0, v150
	v_add_f32_e32 v151, 1.0, v151
	v_add_f32_e32 v152, 1.0, v152
	v_add_f32_e32 v153, 1.0, v153
	v_add_f32_e32 v154, 1.0, v154
	v_add_f32_e32 v155, 1.0, v155
	v_rcp_f32_e32 v148, v148
	v_rcp_f32_e32 v149, v149
	v_rcp_f32_e32 v150, v150
	v_rcp_f32_e32 v151, v151
	v_rcp_f32_e32 v152, v152
	v_rcp_f32_e32 v153, v153
	v_rcp_f32_e32 v154, v154
	v_rcp_f32_e32 v155, v155
	s_nop 0
	v_pk_fma_f32 v[108:109], v[108:109], v[148:149], v[232:233]
	v_pk_fma_f32 v[110:111], v[110:111], v[150:151], v[234:235]
	v_pk_fma_f32 v[104:105], v[104:105], v[152:153], v[236:237]
	v_pk_fma_f32 v[106:107], v[106:107], v[154:155], v[238:239]
	v_cvt_pk_bf16_f32 v174, v108, v109
	v_cvt_pk_bf16_f32 v175, v110, v111
	v_cvt_pk_bf16_f32 v176, v104, v105
	v_cvt_pk_bf16_f32 v177, v106, v107
	global_store_dwordx4 v131, v[174:177], s[70:71]
	v_lshlrev_b32_e32 v148, 16, v178
	v_and_b32_e32 v149, 0xffff0000, v178
	v_lshlrev_b32_e32 v150, 16, v179
	v_and_b32_e32 v151, 0xffff0000, v179
	v_lshlrev_b32_e32 v152, 16, v180
	v_and_b32_e32 v153, 0xffff0000, v180
	v_lshlrev_b32_e32 v154, 16, v181
	v_and_b32_e32 v155, 0xffff0000, v181
	v_mul_f32_e32 v148, 0xbfb8aa3b, v148
	v_mul_f32_e32 v149, 0xbfb8aa3b, v149
	v_mul_f32_e32 v150, 0xbfb8aa3b, v150
	v_mul_f32_e32 v151, 0xbfb8aa3b, v151
	v_mul_f32_e32 v152, 0xbfb8aa3b, v152
	v_mul_f32_e32 v153, 0xbfb8aa3b, v153
	v_mul_f32_e32 v154, 0xbfb8aa3b, v154
	v_mul_f32_e32 v155, 0xbfb8aa3b, v155
	v_exp_f32_e32 v148, v148
	v_exp_f32_e32 v149, v149
	v_exp_f32_e32 v150, v150
	v_exp_f32_e32 v151, v151
	v_exp_f32_e32 v152, v152
	v_exp_f32_e32 v153, v153
	v_exp_f32_e32 v154, v154
	v_exp_f32_e32 v155, v155
	v_lshlrev_b32_e32 v232, 16, v226
	v_and_b32_e32 v233, 0xffff0000, v226
	v_lshlrev_b32_e32 v234, 16, v227
	v_and_b32_e32 v235, 0xffff0000, v227
	v_lshlrev_b32_e32 v236, 16, v228
	v_and_b32_e32 v237, 0xffff0000, v228
	v_lshlrev_b32_e32 v238, 16, v229
	v_and_b32_e32 v239, 0xffff0000, v229
	v_add_f32_e32 v148, 1.0, v148
	v_add_f32_e32 v149, 1.0, v149
	v_add_f32_e32 v150, 1.0, v150
	v_add_f32_e32 v151, 1.0, v151
	v_add_f32_e32 v152, 1.0, v152
	v_add_f32_e32 v153, 1.0, v153
	v_add_f32_e32 v154, 1.0, v154
	v_add_f32_e32 v155, 1.0, v155
	v_rcp_f32_e32 v148, v148
	v_rcp_f32_e32 v149, v149
	v_rcp_f32_e32 v150, v150
	v_rcp_f32_e32 v151, v151
	v_rcp_f32_e32 v152, v152
	v_rcp_f32_e32 v153, v153
	v_rcp_f32_e32 v154, v154
	v_rcp_f32_e32 v155, v155
	s_nop 0
	v_pk_fma_f32 v[100:101], v[100:101], v[148:149], v[232:233]
	v_pk_fma_f32 v[102:103], v[102:103], v[150:151], v[234:235]
	v_pk_fma_f32 v[96:97], v[96:97], v[152:153], v[236:237]
	v_pk_fma_f32 v[98:99], v[98:99], v[154:155], v[238:239]
	v_cvt_pk_bf16_f32 v178, v100, v101
	v_cvt_pk_bf16_f32 v179, v102, v103
	v_cvt_pk_bf16_f32 v180, v96, v97
	v_cvt_pk_bf16_f32 v181, v98, v99
	global_store_dwordx4 v131, v[178:181], s[70:71] offset:256
	s_nop 1
	global_load_dwordx4 v[214:217], v131, s[76:77]
	global_load_dwordx4 v[218:221], v131, s[76:77] offset:256
	global_load_dwordx4 v[222:225], v131, s[78:79]
	global_load_dwordx4 v[226:229], v131, s[78:79] offset:256
	global_load_dwordx4 v[166:169], v130, s[66:67]
	global_load_dwordx4 v[170:173], v130, s[66:67] offset:256
	global_load_dwordx4 v[174:177], v130, s[68:69]
	global_load_dwordx4 v[178:181], v130, s[68:69] offset:256
	s_waitcnt vmcnt(16)
	v_lshlrev_b32_e32 v148, 16, v182
	v_and_b32_e32 v149, 0xffff0000, v182
	v_lshlrev_b32_e32 v150, 16, v183
	v_and_b32_e32 v151, 0xffff0000, v183
	v_lshlrev_b32_e32 v152, 16, v184
	v_and_b32_e32 v153, 0xffff0000, v184
	v_lshlrev_b32_e32 v154, 16, v185
	v_and_b32_e32 v155, 0xffff0000, v185
	v_mul_f32_e32 v148, 0xbfb8aa3b, v148
	v_mul_f32_e32 v149, 0xbfb8aa3b, v149
	v_mul_f32_e32 v150, 0xbfb8aa3b, v150
	v_mul_f32_e32 v151, 0xbfb8aa3b, v151
	v_mul_f32_e32 v152, 0xbfb8aa3b, v152
	v_mul_f32_e32 v153, 0xbfb8aa3b, v153
	v_mul_f32_e32 v154, 0xbfb8aa3b, v154
	v_mul_f32_e32 v155, 0xbfb8aa3b, v155
	v_exp_f32_e32 v148, v148
	v_exp_f32_e32 v149, v149
	v_exp_f32_e32 v150, v150
	v_exp_f32_e32 v151, v151
	v_exp_f32_e32 v152, v152
	v_exp_f32_e32 v153, v153
	v_exp_f32_e32 v154, v154
	v_exp_f32_e32 v155, v155
	v_lshlrev_b32_e32 v232, 16, v240
	v_and_b32_e32 v233, 0xffff0000, v240
	v_lshlrev_b32_e32 v234, 16, v241
	v_and_b32_e32 v235, 0xffff0000, v241
	v_lshlrev_b32_e32 v236, 16, v242
	v_and_b32_e32 v237, 0xffff0000, v242
	v_lshlrev_b32_e32 v238, 16, v243
	v_and_b32_e32 v239, 0xffff0000, v243
	v_add_f32_e32 v148, 1.0, v148
	v_add_f32_e32 v149, 1.0, v149
	v_add_f32_e32 v150, 1.0, v150
	v_add_f32_e32 v151, 1.0, v151
	v_add_f32_e32 v152, 1.0, v152
	v_add_f32_e32 v153, 1.0, v153
	v_add_f32_e32 v154, 1.0, v154
	v_add_f32_e32 v155, 1.0, v155
	v_rcp_f32_e32 v148, v148
	v_rcp_f32_e32 v149, v149
	v_rcp_f32_e32 v150, v150
	v_rcp_f32_e32 v151, v151
	v_rcp_f32_e32 v152, v152
	v_rcp_f32_e32 v153, v153
	v_rcp_f32_e32 v154, v154
	v_rcp_f32_e32 v155, v155
	s_nop 0
	v_pk_fma_f32 v[92:93], v[92:93], v[148:149], v[232:233]
	v_pk_fma_f32 v[94:95], v[94:95], v[150:151], v[234:235]
	v_pk_fma_f32 v[88:89], v[88:89], v[152:153], v[236:237]
	v_pk_fma_f32 v[90:91], v[90:91], v[154:155], v[238:239]
	v_cvt_pk_bf16_f32 v182, v92, v93
	v_cvt_pk_bf16_f32 v183, v94, v95
	v_cvt_pk_bf16_f32 v184, v88, v89
	v_cvt_pk_bf16_f32 v185, v90, v91
	global_store_dwordx4 v131, v[182:185], s[72:73]
	v_lshlrev_b32_e32 v148, 16, v186
	v_and_b32_e32 v149, 0xffff0000, v186
	v_lshlrev_b32_e32 v150, 16, v187
	v_and_b32_e32 v151, 0xffff0000, v187
	v_lshlrev_b32_e32 v152, 16, v188
	v_and_b32_e32 v153, 0xffff0000, v188
	v_lshlrev_b32_e32 v154, 16, v189
	v_and_b32_e32 v155, 0xffff0000, v189
	v_mul_f32_e32 v148, 0xbfb8aa3b, v148
	v_mul_f32_e32 v149, 0xbfb8aa3b, v149
	v_mul_f32_e32 v150, 0xbfb8aa3b, v150
	v_mul_f32_e32 v151, 0xbfb8aa3b, v151
	v_mul_f32_e32 v152, 0xbfb8aa3b, v152
	v_mul_f32_e32 v153, 0xbfb8aa3b, v153
	v_mul_f32_e32 v154, 0xbfb8aa3b, v154
	v_mul_f32_e32 v155, 0xbfb8aa3b, v155
	v_exp_f32_e32 v148, v148
	v_exp_f32_e32 v149, v149
	v_exp_f32_e32 v150, v150
	v_exp_f32_e32 v151, v151
	v_exp_f32_e32 v152, v152
	v_exp_f32_e32 v153, v153
	v_exp_f32_e32 v154, v154
	v_exp_f32_e32 v155, v155
	v_lshlrev_b32_e32 v232, 16, v244
	v_and_b32_e32 v233, 0xffff0000, v244
	v_lshlrev_b32_e32 v234, 16, v245
	v_and_b32_e32 v235, 0xffff0000, v245
	v_lshlrev_b32_e32 v236, 16, v246
	v_and_b32_e32 v237, 0xffff0000, v246
	v_lshlrev_b32_e32 v238, 16, v247
	v_and_b32_e32 v239, 0xffff0000, v247
	v_add_f32_e32 v148, 1.0, v148
	v_add_f32_e32 v149, 1.0, v149
	v_add_f32_e32 v150, 1.0, v150
	v_add_f32_e32 v151, 1.0, v151
	v_add_f32_e32 v152, 1.0, v152
	v_add_f32_e32 v153, 1.0, v153
	v_add_f32_e32 v154, 1.0, v154
	v_add_f32_e32 v155, 1.0, v155
	v_rcp_f32_e32 v148, v148
	v_rcp_f32_e32 v149, v149
	v_rcp_f32_e32 v150, v150
	v_rcp_f32_e32 v151, v151
	v_rcp_f32_e32 v152, v152
	v_rcp_f32_e32 v153, v153
	v_rcp_f32_e32 v154, v154
	v_rcp_f32_e32 v155, v155
	s_nop 0
	v_pk_fma_f32 v[84:85], v[84:85], v[148:149], v[232:233]
	v_pk_fma_f32 v[86:87], v[86:87], v[150:151], v[234:235]
	v_pk_fma_f32 v[80:81], v[80:81], v[152:153], v[236:237]
	v_pk_fma_f32 v[82:83], v[82:83], v[154:155], v[238:239]
	v_cvt_pk_bf16_f32 v186, v84, v85
	v_cvt_pk_bf16_f32 v187, v86, v87
	v_cvt_pk_bf16_f32 v188, v80, v81
	v_cvt_pk_bf16_f32 v189, v82, v83
	global_store_dwordx4 v131, v[186:189], s[72:73] offset:256
	v_lshlrev_b32_e32 v148, 16, v190
	v_and_b32_e32 v149, 0xffff0000, v190
	v_lshlrev_b32_e32 v150, 16, v191
	v_and_b32_e32 v151, 0xffff0000, v191
	v_lshlrev_b32_e32 v152, 16, v192
	v_and_b32_e32 v153, 0xffff0000, v192
	v_lshlrev_b32_e32 v154, 16, v193
	v_and_b32_e32 v155, 0xffff0000, v193
	v_mul_f32_e32 v148, 0xbfb8aa3b, v148
	v_mul_f32_e32 v149, 0xbfb8aa3b, v149
	v_mul_f32_e32 v150, 0xbfb8aa3b, v150
	v_mul_f32_e32 v151, 0xbfb8aa3b, v151
	v_mul_f32_e32 v152, 0xbfb8aa3b, v152
	v_mul_f32_e32 v153, 0xbfb8aa3b, v153
	v_mul_f32_e32 v154, 0xbfb8aa3b, v154
	v_mul_f32_e32 v155, 0xbfb8aa3b, v155
	v_exp_f32_e32 v148, v148
	v_exp_f32_e32 v149, v149
	v_exp_f32_e32 v150, v150
	v_exp_f32_e32 v151, v151
	v_exp_f32_e32 v152, v152
	v_exp_f32_e32 v153, v153
	v_exp_f32_e32 v154, v154
	v_exp_f32_e32 v155, v155
	v_lshlrev_b32_e32 v232, 16, v248
	v_and_b32_e32 v233, 0xffff0000, v248
	v_lshlrev_b32_e32 v234, 16, v249
	v_and_b32_e32 v235, 0xffff0000, v249
	v_lshlrev_b32_e32 v236, 16, v250
	v_and_b32_e32 v237, 0xffff0000, v250
	v_lshlrev_b32_e32 v238, 16, v251
	v_and_b32_e32 v239, 0xffff0000, v251
	v_add_f32_e32 v148, 1.0, v148
	v_add_f32_e32 v149, 1.0, v149
	v_add_f32_e32 v150, 1.0, v150
	v_add_f32_e32 v151, 1.0, v151
	v_add_f32_e32 v152, 1.0, v152
	v_add_f32_e32 v153, 1.0, v153
	v_add_f32_e32 v154, 1.0, v154
	v_add_f32_e32 v155, 1.0, v155
	v_rcp_f32_e32 v148, v148
	v_rcp_f32_e32 v149, v149
	v_rcp_f32_e32 v150, v150
	v_rcp_f32_e32 v151, v151
	v_rcp_f32_e32 v152, v152
	v_rcp_f32_e32 v153, v153
	v_rcp_f32_e32 v154, v154
	v_rcp_f32_e32 v155, v155
	s_nop 0
	v_pk_fma_f32 v[76:77], v[76:77], v[148:149], v[232:233]
	v_pk_fma_f32 v[78:79], v[78:79], v[150:151], v[234:235]
	v_pk_fma_f32 v[72:73], v[72:73], v[152:153], v[236:237]
	v_pk_fma_f32 v[74:75], v[74:75], v[154:155], v[238:239]
	v_cvt_pk_bf16_f32 v190, v76, v77
	v_cvt_pk_bf16_f32 v191, v78, v79
	v_cvt_pk_bf16_f32 v192, v72, v73
	v_cvt_pk_bf16_f32 v193, v74, v75
	global_store_dwordx4 v131, v[190:193], s[74:75]
	v_lshlrev_b32_e32 v148, 16, v194
	v_and_b32_e32 v149, 0xffff0000, v194
	v_lshlrev_b32_e32 v150, 16, v195
	v_and_b32_e32 v151, 0xffff0000, v195
	v_lshlrev_b32_e32 v152, 16, v196
	v_and_b32_e32 v153, 0xffff0000, v196
	v_lshlrev_b32_e32 v154, 16, v197
	v_and_b32_e32 v155, 0xffff0000, v197
	v_mul_f32_e32 v148, 0xbfb8aa3b, v148
	v_mul_f32_e32 v149, 0xbfb8aa3b, v149
	v_mul_f32_e32 v150, 0xbfb8aa3b, v150
	v_mul_f32_e32 v151, 0xbfb8aa3b, v151
	v_mul_f32_e32 v152, 0xbfb8aa3b, v152
	v_mul_f32_e32 v153, 0xbfb8aa3b, v153
	v_mul_f32_e32 v154, 0xbfb8aa3b, v154
	v_mul_f32_e32 v155, 0xbfb8aa3b, v155
	v_exp_f32_e32 v148, v148
	v_exp_f32_e32 v149, v149
	v_exp_f32_e32 v150, v150
	v_exp_f32_e32 v151, v151
	v_exp_f32_e32 v152, v152
	v_exp_f32_e32 v153, v153
	v_exp_f32_e32 v154, v154
	v_exp_f32_e32 v155, v155
	v_lshlrev_b32_e32 v232, 16, v156
	v_and_b32_e32 v233, 0xffff0000, v156
	v_lshlrev_b32_e32 v234, 16, v157
	v_and_b32_e32 v235, 0xffff0000, v157
	v_lshlrev_b32_e32 v236, 16, v158
	v_and_b32_e32 v237, 0xffff0000, v158
	v_lshlrev_b32_e32 v238, 16, v159
	v_and_b32_e32 v239, 0xffff0000, v159
	v_add_f32_e32 v148, 1.0, v148
	v_add_f32_e32 v149, 1.0, v149
	v_add_f32_e32 v150, 1.0, v150
	v_add_f32_e32 v151, 1.0, v151
	v_add_f32_e32 v152, 1.0, v152
	v_add_f32_e32 v153, 1.0, v153
	v_add_f32_e32 v154, 1.0, v154
	v_add_f32_e32 v155, 1.0, v155
	v_rcp_f32_e32 v148, v148
	v_rcp_f32_e32 v149, v149
	v_rcp_f32_e32 v150, v150
	v_rcp_f32_e32 v151, v151
	v_rcp_f32_e32 v152, v152
	v_rcp_f32_e32 v153, v153
	v_rcp_f32_e32 v154, v154
	v_rcp_f32_e32 v155, v155
	s_nop 0
	v_pk_fma_f32 v[68:69], v[68:69], v[148:149], v[232:233]
	v_pk_fma_f32 v[70:71], v[70:71], v[150:151], v[234:235]
	v_pk_fma_f32 v[64:65], v[64:65], v[152:153], v[236:237]
	v_pk_fma_f32 v[66:67], v[66:67], v[154:155], v[238:239]
	v_cvt_pk_bf16_f32 v194, v68, v69
	v_cvt_pk_bf16_f32 v195, v70, v71
	v_cvt_pk_bf16_f32 v196, v64, v65
	v_cvt_pk_bf16_f32 v197, v66, v67
	global_store_dwordx4 v131, v[194:197], s[74:75] offset:256
	s_nop 1
	global_load_dwordx4 v[240:243], v131, s[80:81]
	global_load_dwordx4 v[244:247], v131, s[80:81] offset:256
	global_load_dwordx4 v[248:251], v131, s[82:83]
	global_load_dwordx4 v[156:159], v131, s[82:83] offset:256
	s_waitcnt vmcnt(12)
	v_lshlrev_b32_e32 v148, 16, v198
	v_and_b32_e32 v149, 0xffff0000, v198
	v_lshlrev_b32_e32 v150, 16, v199
	v_and_b32_e32 v151, 0xffff0000, v199
	v_lshlrev_b32_e32 v152, 16, v200
	v_and_b32_e32 v153, 0xffff0000, v200
	v_lshlrev_b32_e32 v154, 16, v201
	v_and_b32_e32 v155, 0xffff0000, v201
	v_mul_f32_e32 v148, 0xbfb8aa3b, v148
	v_mul_f32_e32 v149, 0xbfb8aa3b, v149
	v_mul_f32_e32 v150, 0xbfb8aa3b, v150
	v_mul_f32_e32 v151, 0xbfb8aa3b, v151
	v_mul_f32_e32 v152, 0xbfb8aa3b, v152
	v_mul_f32_e32 v153, 0xbfb8aa3b, v153
	v_mul_f32_e32 v154, 0xbfb8aa3b, v154
	v_mul_f32_e32 v155, 0xbfb8aa3b, v155
	v_exp_f32_e32 v148, v148
	v_exp_f32_e32 v149, v149
	v_exp_f32_e32 v150, v150
	v_exp_f32_e32 v151, v151
	v_exp_f32_e32 v152, v152
	v_exp_f32_e32 v153, v153
	v_exp_f32_e32 v154, v154
	v_exp_f32_e32 v155, v155
	v_lshlrev_b32_e32 v232, 16, v214
	v_and_b32_e32 v233, 0xffff0000, v214
	v_lshlrev_b32_e32 v234, 16, v215
	v_and_b32_e32 v235, 0xffff0000, v215
	v_lshlrev_b32_e32 v236, 16, v216
	v_and_b32_e32 v237, 0xffff0000, v216
	v_lshlrev_b32_e32 v238, 16, v217
	v_and_b32_e32 v239, 0xffff0000, v217
	v_add_f32_e32 v148, 1.0, v148
	v_add_f32_e32 v149, 1.0, v149
	v_add_f32_e32 v150, 1.0, v150
	v_add_f32_e32 v151, 1.0, v151
	v_add_f32_e32 v152, 1.0, v152
	v_add_f32_e32 v153, 1.0, v153
	v_add_f32_e32 v154, 1.0, v154
	v_add_f32_e32 v155, 1.0, v155
	v_rcp_f32_e32 v148, v148
	v_rcp_f32_e32 v149, v149
	v_rcp_f32_e32 v150, v150
	v_rcp_f32_e32 v151, v151
	v_rcp_f32_e32 v152, v152
	v_rcp_f32_e32 v153, v153
	v_rcp_f32_e32 v154, v154
	v_rcp_f32_e32 v155, v155
	s_nop 0
	v_pk_fma_f32 v[60:61], v[60:61], v[148:149], v[232:233]
	v_pk_fma_f32 v[62:63], v[62:63], v[150:151], v[234:235]
	v_pk_fma_f32 v[56:57], v[56:57], v[152:153], v[236:237]
	v_pk_fma_f32 v[58:59], v[58:59], v[154:155], v[238:239]
	v_cvt_pk_bf16_f32 v198, v60, v61
	v_cvt_pk_bf16_f32 v199, v62, v63
	v_cvt_pk_bf16_f32 v200, v56, v57
	v_cvt_pk_bf16_f32 v201, v58, v59
	global_store_dwordx4 v131, v[198:201], s[76:77]
	v_lshlrev_b32_e32 v148, 16, v202
	v_and_b32_e32 v149, 0xffff0000, v202
	v_lshlrev_b32_e32 v150, 16, v203
	v_and_b32_e32 v151, 0xffff0000, v203
	v_lshlrev_b32_e32 v152, 16, v204
	v_and_b32_e32 v153, 0xffff0000, v204
	v_lshlrev_b32_e32 v154, 16, v205
	v_and_b32_e32 v155, 0xffff0000, v205
	v_mul_f32_e32 v148, 0xbfb8aa3b, v148
	v_mul_f32_e32 v149, 0xbfb8aa3b, v149
	v_mul_f32_e32 v150, 0xbfb8aa3b, v150
	v_mul_f32_e32 v151, 0xbfb8aa3b, v151
	v_mul_f32_e32 v152, 0xbfb8aa3b, v152
	v_mul_f32_e32 v153, 0xbfb8aa3b, v153
	v_mul_f32_e32 v154, 0xbfb8aa3b, v154
	v_mul_f32_e32 v155, 0xbfb8aa3b, v155
	v_exp_f32_e32 v148, v148
	v_exp_f32_e32 v149, v149
	v_exp_f32_e32 v150, v150
	v_exp_f32_e32 v151, v151
	v_exp_f32_e32 v152, v152
	v_exp_f32_e32 v153, v153
	v_exp_f32_e32 v154, v154
	v_exp_f32_e32 v155, v155
	v_lshlrev_b32_e32 v232, 16, v218
	v_and_b32_e32 v233, 0xffff0000, v218
	v_lshlrev_b32_e32 v234, 16, v219
	v_and_b32_e32 v235, 0xffff0000, v219
	v_lshlrev_b32_e32 v236, 16, v220
	v_and_b32_e32 v237, 0xffff0000, v220
	v_lshlrev_b32_e32 v238, 16, v221
	v_and_b32_e32 v239, 0xffff0000, v221
	v_add_f32_e32 v148, 1.0, v148
	v_add_f32_e32 v149, 1.0, v149
	v_add_f32_e32 v150, 1.0, v150
	v_add_f32_e32 v151, 1.0, v151
	v_add_f32_e32 v152, 1.0, v152
	v_add_f32_e32 v153, 1.0, v153
	v_add_f32_e32 v154, 1.0, v154
	v_add_f32_e32 v155, 1.0, v155
	v_rcp_f32_e32 v148, v148
	v_rcp_f32_e32 v149, v149
	v_rcp_f32_e32 v150, v150
	v_rcp_f32_e32 v151, v151
	v_rcp_f32_e32 v152, v152
	v_rcp_f32_e32 v153, v153
	v_rcp_f32_e32 v154, v154
	v_rcp_f32_e32 v155, v155
	s_nop 0
	v_pk_fma_f32 v[52:53], v[52:53], v[148:149], v[232:233]
	v_pk_fma_f32 v[54:55], v[54:55], v[150:151], v[234:235]
	v_pk_fma_f32 v[48:49], v[48:49], v[152:153], v[236:237]
	v_pk_fma_f32 v[50:51], v[50:51], v[154:155], v[238:239]
	v_cvt_pk_bf16_f32 v202, v52, v53
	v_cvt_pk_bf16_f32 v203, v54, v55
	v_cvt_pk_bf16_f32 v204, v48, v49
	v_cvt_pk_bf16_f32 v205, v50, v51
	global_store_dwordx4 v131, v[202:205], s[76:77] offset:256
	v_lshlrev_b32_e32 v148, 16, v206
	v_and_b32_e32 v149, 0xffff0000, v206
	v_lshlrev_b32_e32 v150, 16, v207
	v_and_b32_e32 v151, 0xffff0000, v207
	v_lshlrev_b32_e32 v152, 16, v208
	v_and_b32_e32 v153, 0xffff0000, v208
	v_lshlrev_b32_e32 v154, 16, v209
	v_and_b32_e32 v155, 0xffff0000, v209
	v_mul_f32_e32 v148, 0xbfb8aa3b, v148
	v_mul_f32_e32 v149, 0xbfb8aa3b, v149
	v_mul_f32_e32 v150, 0xbfb8aa3b, v150
	v_mul_f32_e32 v151, 0xbfb8aa3b, v151
	v_mul_f32_e32 v152, 0xbfb8aa3b, v152
	v_mul_f32_e32 v153, 0xbfb8aa3b, v153
	v_mul_f32_e32 v154, 0xbfb8aa3b, v154
	v_mul_f32_e32 v155, 0xbfb8aa3b, v155
	v_exp_f32_e32 v148, v148
	v_exp_f32_e32 v149, v149
	v_exp_f32_e32 v150, v150
	v_exp_f32_e32 v151, v151
	v_exp_f32_e32 v152, v152
	v_exp_f32_e32 v153, v153
	v_exp_f32_e32 v154, v154
	v_exp_f32_e32 v155, v155
	v_lshlrev_b32_e32 v232, 16, v222
	v_and_b32_e32 v233, 0xffff0000, v222
	v_lshlrev_b32_e32 v234, 16, v223
	v_and_b32_e32 v235, 0xffff0000, v223
	v_lshlrev_b32_e32 v236, 16, v224
	v_and_b32_e32 v237, 0xffff0000, v224
	v_lshlrev_b32_e32 v238, 16, v225
	v_and_b32_e32 v239, 0xffff0000, v225
	v_add_f32_e32 v148, 1.0, v148
	v_add_f32_e32 v149, 1.0, v149
	v_add_f32_e32 v150, 1.0, v150
	v_add_f32_e32 v151, 1.0, v151
	v_add_f32_e32 v152, 1.0, v152
	v_add_f32_e32 v153, 1.0, v153
	v_add_f32_e32 v154, 1.0, v154
	v_add_f32_e32 v155, 1.0, v155
	v_rcp_f32_e32 v148, v148
	v_rcp_f32_e32 v149, v149
	v_rcp_f32_e32 v150, v150
	v_rcp_f32_e32 v151, v151
	v_rcp_f32_e32 v152, v152
	v_rcp_f32_e32 v153, v153
	v_rcp_f32_e32 v154, v154
	v_rcp_f32_e32 v155, v155
	s_nop 0
	v_pk_fma_f32 v[44:45], v[44:45], v[148:149], v[232:233]
	v_pk_fma_f32 v[46:47], v[46:47], v[150:151], v[234:235]
	v_pk_fma_f32 v[40:41], v[40:41], v[152:153], v[236:237]
	v_pk_fma_f32 v[42:43], v[42:43], v[154:155], v[238:239]
	v_cvt_pk_bf16_f32 v206, v44, v45
	v_cvt_pk_bf16_f32 v207, v46, v47
	v_cvt_pk_bf16_f32 v208, v40, v41
	v_cvt_pk_bf16_f32 v209, v42, v43
	global_store_dwordx4 v131, v[206:209], s[78:79]
	v_lshlrev_b32_e32 v148, 16, v210
	v_and_b32_e32 v149, 0xffff0000, v210
	v_lshlrev_b32_e32 v150, 16, v211
	v_and_b32_e32 v151, 0xffff0000, v211
	v_lshlrev_b32_e32 v152, 16, v212
	v_and_b32_e32 v153, 0xffff0000, v212
	v_lshlrev_b32_e32 v154, 16, v213
	v_and_b32_e32 v155, 0xffff0000, v213
	v_mul_f32_e32 v148, 0xbfb8aa3b, v148
	v_mul_f32_e32 v149, 0xbfb8aa3b, v149
	v_mul_f32_e32 v150, 0xbfb8aa3b, v150
	v_mul_f32_e32 v151, 0xbfb8aa3b, v151
	v_mul_f32_e32 v152, 0xbfb8aa3b, v152
	v_mul_f32_e32 v153, 0xbfb8aa3b, v153
	v_mul_f32_e32 v154, 0xbfb8aa3b, v154
	v_mul_f32_e32 v155, 0xbfb8aa3b, v155
	v_exp_f32_e32 v148, v148
	v_exp_f32_e32 v149, v149
	v_exp_f32_e32 v150, v150
	v_exp_f32_e32 v151, v151
	v_exp_f32_e32 v152, v152
	v_exp_f32_e32 v153, v153
	v_exp_f32_e32 v154, v154
	v_exp_f32_e32 v155, v155
	v_lshlrev_b32_e32 v232, 16, v226
	v_and_b32_e32 v233, 0xffff0000, v226
	v_lshlrev_b32_e32 v234, 16, v227
	v_and_b32_e32 v235, 0xffff0000, v227
	v_lshlrev_b32_e32 v236, 16, v228
	v_and_b32_e32 v237, 0xffff0000, v228
	v_lshlrev_b32_e32 v238, 16, v229
	v_and_b32_e32 v239, 0xffff0000, v229
	v_add_f32_e32 v148, 1.0, v148
	v_add_f32_e32 v149, 1.0, v149
	v_add_f32_e32 v150, 1.0, v150
	v_add_f32_e32 v151, 1.0, v151
	v_add_f32_e32 v152, 1.0, v152
	v_add_f32_e32 v153, 1.0, v153
	v_add_f32_e32 v154, 1.0, v154
	v_add_f32_e32 v155, 1.0, v155
	v_rcp_f32_e32 v148, v148
	v_rcp_f32_e32 v149, v149
	v_rcp_f32_e32 v150, v150
	v_rcp_f32_e32 v151, v151
	v_rcp_f32_e32 v152, v152
	v_rcp_f32_e32 v153, v153
	v_rcp_f32_e32 v154, v154
	v_rcp_f32_e32 v155, v155
	s_nop 0
	v_pk_fma_f32 v[36:37], v[36:37], v[148:149], v[232:233]
	v_pk_fma_f32 v[38:39], v[38:39], v[150:151], v[234:235]
	v_pk_fma_f32 v[32:33], v[32:33], v[152:153], v[236:237]
	v_pk_fma_f32 v[34:35], v[34:35], v[154:155], v[238:239]
	v_cvt_pk_bf16_f32 v210, v36, v37
	v_cvt_pk_bf16_f32 v211, v38, v39
	v_cvt_pk_bf16_f32 v212, v32, v33
	v_cvt_pk_bf16_f32 v213, v34, v35
	global_store_dwordx4 v131, v[210:213], s[78:79] offset:256
	s_waitcnt vmcnt(4)
	v_lshlrev_b32_e32 v148, 16, v166
	v_and_b32_e32 v149, 0xffff0000, v166
	v_lshlrev_b32_e32 v150, 16, v167
	v_and_b32_e32 v151, 0xffff0000, v167
	v_lshlrev_b32_e32 v152, 16, v168
	v_and_b32_e32 v153, 0xffff0000, v168
	v_lshlrev_b32_e32 v154, 16, v169
	v_and_b32_e32 v155, 0xffff0000, v169
	v_mul_f32_e32 v148, 0xbfb8aa3b, v148
	v_mul_f32_e32 v149, 0xbfb8aa3b, v149
	v_mul_f32_e32 v150, 0xbfb8aa3b, v150
	v_mul_f32_e32 v151, 0xbfb8aa3b, v151
	v_mul_f32_e32 v152, 0xbfb8aa3b, v152
	v_mul_f32_e32 v153, 0xbfb8aa3b, v153
	v_mul_f32_e32 v154, 0xbfb8aa3b, v154
	v_mul_f32_e32 v155, 0xbfb8aa3b, v155
	v_exp_f32_e32 v148, v148
	v_exp_f32_e32 v149, v149
	v_exp_f32_e32 v150, v150
	v_exp_f32_e32 v151, v151
	v_exp_f32_e32 v152, v152
	v_exp_f32_e32 v153, v153
	v_exp_f32_e32 v154, v154
	v_exp_f32_e32 v155, v155
	v_lshlrev_b32_e32 v232, 16, v240
	v_and_b32_e32 v233, 0xffff0000, v240
	v_lshlrev_b32_e32 v234, 16, v241
	v_and_b32_e32 v235, 0xffff0000, v241
	v_lshlrev_b32_e32 v236, 16, v242
	v_and_b32_e32 v237, 0xffff0000, v242
	v_lshlrev_b32_e32 v238, 16, v243
	v_and_b32_e32 v239, 0xffff0000, v243
	v_add_f32_e32 v148, 1.0, v148
	v_add_f32_e32 v149, 1.0, v149
	v_add_f32_e32 v150, 1.0, v150
	v_add_f32_e32 v151, 1.0, v151
	v_add_f32_e32 v152, 1.0, v152
	v_add_f32_e32 v153, 1.0, v153
	v_add_f32_e32 v154, 1.0, v154
	v_add_f32_e32 v155, 1.0, v155
	v_rcp_f32_e32 v148, v148
	v_rcp_f32_e32 v149, v149
	v_rcp_f32_e32 v150, v150
	v_rcp_f32_e32 v151, v151
	v_rcp_f32_e32 v152, v152
	v_rcp_f32_e32 v153, v153
	v_rcp_f32_e32 v154, v154
	v_rcp_f32_e32 v155, v155
	s_nop 0
	v_pk_fma_f32 v[28:29], v[28:29], v[148:149], v[232:233]
	v_pk_fma_f32 v[30:31], v[30:31], v[150:151], v[234:235]
	v_pk_fma_f32 v[24:25], v[24:25], v[152:153], v[236:237]
	v_pk_fma_f32 v[26:27], v[26:27], v[154:155], v[238:239]
	v_cvt_pk_bf16_f32 v166, v28, v29
	v_cvt_pk_bf16_f32 v167, v30, v31
	v_cvt_pk_bf16_f32 v168, v24, v25
	v_cvt_pk_bf16_f32 v169, v26, v27
	global_store_dwordx4 v131, v[166:169], s[80:81]
	v_lshlrev_b32_e32 v148, 16, v170
	v_and_b32_e32 v149, 0xffff0000, v170
	v_lshlrev_b32_e32 v150, 16, v171
	v_and_b32_e32 v151, 0xffff0000, v171
	v_lshlrev_b32_e32 v152, 16, v172
	v_and_b32_e32 v153, 0xffff0000, v172
	v_lshlrev_b32_e32 v154, 16, v173
	v_and_b32_e32 v155, 0xffff0000, v173
	v_mul_f32_e32 v148, 0xbfb8aa3b, v148
	v_mul_f32_e32 v149, 0xbfb8aa3b, v149
	v_mul_f32_e32 v150, 0xbfb8aa3b, v150
	v_mul_f32_e32 v151, 0xbfb8aa3b, v151
	v_mul_f32_e32 v152, 0xbfb8aa3b, v152
	v_mul_f32_e32 v153, 0xbfb8aa3b, v153
	v_mul_f32_e32 v154, 0xbfb8aa3b, v154
	v_mul_f32_e32 v155, 0xbfb8aa3b, v155
	v_exp_f32_e32 v148, v148
	v_exp_f32_e32 v149, v149
	v_exp_f32_e32 v150, v150
	v_exp_f32_e32 v151, v151
	v_exp_f32_e32 v152, v152
	v_exp_f32_e32 v153, v153
	v_exp_f32_e32 v154, v154
	v_exp_f32_e32 v155, v155
	v_lshlrev_b32_e32 v232, 16, v244
	v_and_b32_e32 v233, 0xffff0000, v244
	v_lshlrev_b32_e32 v234, 16, v245
	v_and_b32_e32 v235, 0xffff0000, v245
	v_lshlrev_b32_e32 v236, 16, v246
	v_and_b32_e32 v237, 0xffff0000, v246
	v_lshlrev_b32_e32 v238, 16, v247
	v_and_b32_e32 v239, 0xffff0000, v247
	v_add_f32_e32 v148, 1.0, v148
	v_add_f32_e32 v149, 1.0, v149
	v_add_f32_e32 v150, 1.0, v150
	v_add_f32_e32 v151, 1.0, v151
	v_add_f32_e32 v152, 1.0, v152
	v_add_f32_e32 v153, 1.0, v153
	v_add_f32_e32 v154, 1.0, v154
	v_add_f32_e32 v155, 1.0, v155
	v_rcp_f32_e32 v148, v148
	v_rcp_f32_e32 v149, v149
	v_rcp_f32_e32 v150, v150
	v_rcp_f32_e32 v151, v151
	v_rcp_f32_e32 v152, v152
	v_rcp_f32_e32 v153, v153
	v_rcp_f32_e32 v154, v154
	v_rcp_f32_e32 v155, v155
	s_nop 0
	v_pk_fma_f32 v[20:21], v[20:21], v[148:149], v[232:233]
	v_pk_fma_f32 v[22:23], v[22:23], v[150:151], v[234:235]
	v_pk_fma_f32 v[16:17], v[16:17], v[152:153], v[236:237]
	v_pk_fma_f32 v[18:19], v[18:19], v[154:155], v[238:239]
	v_cvt_pk_bf16_f32 v170, v20, v21
	v_cvt_pk_bf16_f32 v171, v22, v23
	v_cvt_pk_bf16_f32 v172, v16, v17
	v_cvt_pk_bf16_f32 v173, v18, v19
	global_store_dwordx4 v131, v[170:173], s[80:81] offset:256
	v_lshlrev_b32_e32 v148, 16, v174
	v_and_b32_e32 v149, 0xffff0000, v174
	v_lshlrev_b32_e32 v150, 16, v175
	v_and_b32_e32 v151, 0xffff0000, v175
	v_lshlrev_b32_e32 v152, 16, v176
	v_and_b32_e32 v153, 0xffff0000, v176
	v_lshlrev_b32_e32 v154, 16, v177
	v_and_b32_e32 v155, 0xffff0000, v177
	v_mul_f32_e32 v148, 0xbfb8aa3b, v148
	v_mul_f32_e32 v149, 0xbfb8aa3b, v149
	v_mul_f32_e32 v150, 0xbfb8aa3b, v150
	v_mul_f32_e32 v151, 0xbfb8aa3b, v151
	v_mul_f32_e32 v152, 0xbfb8aa3b, v152
	v_mul_f32_e32 v153, 0xbfb8aa3b, v153
	v_mul_f32_e32 v154, 0xbfb8aa3b, v154
	v_mul_f32_e32 v155, 0xbfb8aa3b, v155
	v_exp_f32_e32 v148, v148
	v_exp_f32_e32 v149, v149
	v_exp_f32_e32 v150, v150
	v_exp_f32_e32 v151, v151
	v_exp_f32_e32 v152, v152
	v_exp_f32_e32 v153, v153
	v_exp_f32_e32 v154, v154
	v_exp_f32_e32 v155, v155
	v_lshlrev_b32_e32 v232, 16, v248
	v_and_b32_e32 v233, 0xffff0000, v248
	v_lshlrev_b32_e32 v234, 16, v249
	v_and_b32_e32 v235, 0xffff0000, v249
	v_lshlrev_b32_e32 v236, 16, v250
	v_and_b32_e32 v237, 0xffff0000, v250
	v_lshlrev_b32_e32 v238, 16, v251
	v_and_b32_e32 v239, 0xffff0000, v251
	v_add_f32_e32 v148, 1.0, v148
	v_add_f32_e32 v149, 1.0, v149
	v_add_f32_e32 v150, 1.0, v150
	v_add_f32_e32 v151, 1.0, v151
	v_add_f32_e32 v152, 1.0, v152
	v_add_f32_e32 v153, 1.0, v153
	v_add_f32_e32 v154, 1.0, v154
	v_add_f32_e32 v155, 1.0, v155
	v_rcp_f32_e32 v148, v148
	v_rcp_f32_e32 v149, v149
	v_rcp_f32_e32 v150, v150
	v_rcp_f32_e32 v151, v151
	v_rcp_f32_e32 v152, v152
	v_rcp_f32_e32 v153, v153
	v_rcp_f32_e32 v154, v154
	v_rcp_f32_e32 v155, v155
	s_nop 0
	v_pk_fma_f32 v[12:13], v[12:13], v[148:149], v[232:233]
	v_pk_fma_f32 v[14:15], v[14:15], v[150:151], v[234:235]
	v_pk_fma_f32 v[8:9], v[8:9], v[152:153], v[236:237]
	v_pk_fma_f32 v[10:11], v[10:11], v[154:155], v[238:239]
	v_cvt_pk_bf16_f32 v174, v12, v13
	v_cvt_pk_bf16_f32 v175, v14, v15
	v_cvt_pk_bf16_f32 v176, v8, v9
	v_cvt_pk_bf16_f32 v177, v10, v11
	global_store_dwordx4 v131, v[174:177], s[82:83]
	v_lshlrev_b32_e32 v148, 16, v178
	v_and_b32_e32 v149, 0xffff0000, v178
	v_lshlrev_b32_e32 v150, 16, v179
	v_and_b32_e32 v151, 0xffff0000, v179
	v_lshlrev_b32_e32 v152, 16, v180
	v_and_b32_e32 v153, 0xffff0000, v180
	v_lshlrev_b32_e32 v154, 16, v181
	v_and_b32_e32 v155, 0xffff0000, v181
	v_mul_f32_e32 v148, 0xbfb8aa3b, v148
	v_mul_f32_e32 v149, 0xbfb8aa3b, v149
	v_mul_f32_e32 v150, 0xbfb8aa3b, v150
	v_mul_f32_e32 v151, 0xbfb8aa3b, v151
	v_mul_f32_e32 v152, 0xbfb8aa3b, v152
	v_mul_f32_e32 v153, 0xbfb8aa3b, v153
	v_mul_f32_e32 v154, 0xbfb8aa3b, v154
	v_mul_f32_e32 v155, 0xbfb8aa3b, v155
	v_exp_f32_e32 v148, v148
	v_exp_f32_e32 v149, v149
	v_exp_f32_e32 v150, v150
	v_exp_f32_e32 v151, v151
	v_exp_f32_e32 v152, v152
	v_exp_f32_e32 v153, v153
	v_exp_f32_e32 v154, v154
	v_exp_f32_e32 v155, v155
	v_lshlrev_b32_e32 v232, 16, v156
	v_and_b32_e32 v233, 0xffff0000, v156
	v_lshlrev_b32_e32 v234, 16, v157
	v_and_b32_e32 v235, 0xffff0000, v157
	v_lshlrev_b32_e32 v236, 16, v158
	v_and_b32_e32 v237, 0xffff0000, v158
	v_lshlrev_b32_e32 v238, 16, v159
	v_and_b32_e32 v239, 0xffff0000, v159
	v_add_f32_e32 v148, 1.0, v148
	v_add_f32_e32 v149, 1.0, v149
	v_add_f32_e32 v150, 1.0, v150
	v_add_f32_e32 v151, 1.0, v151
	v_add_f32_e32 v152, 1.0, v152
	v_add_f32_e32 v153, 1.0, v153
	v_add_f32_e32 v154, 1.0, v154
	v_add_f32_e32 v155, 1.0, v155
	v_rcp_f32_e32 v148, v148
	v_rcp_f32_e32 v149, v149
	v_rcp_f32_e32 v150, v150
	v_rcp_f32_e32 v151, v151
	v_rcp_f32_e32 v152, v152
	v_rcp_f32_e32 v153, v153
	v_rcp_f32_e32 v154, v154
	v_rcp_f32_e32 v155, v155
	s_nop 0
	v_pk_fma_f32 v[4:5], v[4:5], v[148:149], v[232:233]
	v_pk_fma_f32 v[6:7], v[6:7], v[150:151], v[234:235]
	v_pk_fma_f32 v[0:1], v[0:1], v[152:153], v[236:237]
	v_pk_fma_f32 v[2:3], v[2:3], v[154:155], v[238:239]
	v_cvt_pk_bf16_f32 v178, v4, v5
	v_cvt_pk_bf16_f32 v179, v6, v7
	v_cvt_pk_bf16_f32 v180, v0, v1
	v_cvt_pk_bf16_f32 v181, v2, v3
	global_store_dwordx4 v131, v[178:181], s[82:83] offset:256
	s_andn2_b64 vcc, exec, s[6:7]
	s_mov_b64 s[6:7], -1
	s_mov_b32 s98, 1
	s_cbranch_vccnz .LBB0_1116
	s_andn2_b64 vcc, exec, s[0:1]
	s_cbranch_vccnz .LBB0_1115
	s_barrier
	s_branch .LBB0_1115

.LBB0_1190:
	s_add_u32 s58, s10, 0x3015000
	s_addc_u32 s59, s11, 0
	s_lshl_b32 s10, s12, 5
	s_and_b32 s15, s10, 0x60
	s_mov_b64 s[10:11], 0x80
	s_add_i32 m0, s52, 0x18000
	v_lshl_add_u64 v[6:7], v[6:7], 0, s[10:11]
	s_lshl_b32 s14, s7, 13
	s_lshl_b32 s16, s15, 7
	s_waitcnt vmcnt(2)
	s_barrier
	global_load_lds_dwordx4 v[6:7], off
	v_lshl_add_u64 v[4:5], v[4:5], 0, s[10:11]
	s_add_i32 m0, s52, 0x1a000
	s_add_i32 s60, s52, 0x8000
	s_add_i32 s61, s52, 0xa000
	global_load_lds_dwordx4 v[4:5], off
	v_lshl_add_u64 v[0:1], v[0:1], 0, s[10:11]
	s_mov_b32 m0, s60
	s_add_u32 s12, s42, 0x40080
	global_load_lds_dwordx4 v[0:1], off
	v_lshl_add_u64 v[0:1], v[2:3], 0, s[10:11]
	s_mov_b32 m0, s61
	s_addc_u32 s13, s43, 0
	global_load_lds_dwordx4 v[0:1], off
	s_add_i32 m0, s52, 0x1c000
	v_lshl_add_u64 v[0:1], s[12:13], 0, v[168:169]
	global_load_lds_dwordx4 v[0:1], off
	v_lshl_add_u64 v[0:1], s[12:13], 0, v[170:171]
	s_add_i32 m0, s52, 0x1e000
	s_sext_i32_i8 s39, s6
	global_load_lds_dwordx4 v[0:1], off
	v_bfe_u32 v0, v8, 4, 2
	v_lshlrev_b32_e32 v2, 4, v0
	v_lshl_or_b32 v208, v0, 2, s15
	v_lshlrev_b32_e32 v0, 13, v9
	v_and_b32_e32 v1, 15, v8
	v_and_b32_e32 v0, 0x7fffc000, v0
	v_lshl_or_b32 v206, s7, 6, v1
	v_lshl_or_b32 v1, v1, 6, v2
	v_lshlrev_b32_e32 v2, 2, v8
	v_lshl_add_u32 v0, v10, 10, v0
	v_and_b32_e32 v2, 32, v2
	v_or_b32_e32 v0, v0, v11
	v_bitop3_b32 v3, v1, s14, v2 bitop3:0xde
	v_bitop3_b32 v207, v1, s16, v2 bitop3:0xde
	s_mov_b64 s[6:7], 0x40080
	v_add_lshl_u32 v0, v0, v12, 1
	v_mov_b32_e32 v1, v169
	v_lshl_add_u64 v[172:173], v[0:1], 0, s[6:7]
	v_lshlrev_b32_e32 v0, 13, v13
	v_and_b32_e32 v0, 0x7fffc000, v0
	v_lshl_add_u32 v0, v14, 10, v0
	s_waitcnt vmcnt(6)
	s_cmpk_lt_u32 s2, 0x100
	v_or_b32_e32 v0, v0, v15
	s_cselect_b64 s[12:13], -1, 0
	v_add_lshl_u32 v0, v0, v16, 1
	s_add_i32 s64, 0, 0x10000
	s_add_i32 s65, 0, 0x14000
	s_ashr_i32 s62, s90, 31
	s_mov_b32 s63, s90
	v_lshl_add_u64 v[174:175], v[0:1], 0, s[6:7]
	v_mov_b64_e32 v[176:177], 0x400
	v_mov_b64_e32 v[178:179], 0x3ff
	v_add_u32_e32 v209, s64, v207
	v_add_u32_e32 v210, s65, v207
	v_add_u32_e32 v211, 0, v3
	s_mov_b32 s66, 0x20000
	s_mov_b32 s67, 0x30000
	s_mov_b32 s68, 0x80000
	s_mov_b32 s69, 0x90000
	s_mov_b32 s70, 0xa0000
	s_mov_b32 s71, 0xb0000
	s_mov_b64 s[14:15], 0x10000
	s_mov_b64 s[16:17], 0x20000
	s_mov_b64 s[18:19], 0x30000
	s_mov_b64 s[20:21], 0x80000
	s_mov_b64 s[22:23], 0x90000
	s_mov_b64 s[24:25], 0xa0000
	s_mov_b64 s[26:27], 0xb0000
	s_barrier
	s_mov_b32 s98, 0
	s_branch .LBB0_1193

.LBB0_1199:
	s_ashr_i32 s31, s30, 31
	s_lshl_b64 s[34:35], s[30:31], 19
	s_add_u32 s34, s33, s34
	s_addc_u32 s35, s48, s35
	s_and_b64 s[36:37], s[6:7], exec
	s_cselect_b32 s2, s35, s41
	s_cselect_b32 s31, s34, s40
	s_ashr_i32 s29, s28, 31
	s_lshl_b64 s[36:37], s[28:29], 19
	s_add_u32 s36, s49, s36
	s_addc_u32 s37, s50, s37
	s_and_b64 s[44:45], s[6:7], exec
	s_cselect_b32 s29, s37, s43
	s_cselect_b32 s72, s36, s42
	s_add_u32 s73, s42, 0x100
	v_mov_b32_e32 v0, 0
	s_addc_u32 s74, s43, 0
	s_mov_b32 s75, -2
	v_mov_b32_e32 v1, v0
	v_mov_b32_e32 v2, v0
	v_mov_b32_e32 v3, v0
	v_mov_b32_e32 v16, v0
	v_mov_b32_e32 v17, v0
	v_mov_b32_e32 v18, v0
	v_mov_b32_e32 v19, v0
	v_mov_b32_e32 v4, v0
	v_mov_b32_e32 v5, v0
	v_mov_b32_e32 v6, v0
	v_mov_b32_e32 v7, v0
	v_mov_b32_e32 v24, v0
	v_mov_b32_e32 v25, v0
	v_mov_b32_e32 v26, v0
	v_mov_b32_e32 v27, v0
	v_mov_b32_e32 v8, v0
	v_mov_b32_e32 v9, v0
	v_mov_b32_e32 v10, v0
	v_mov_b32_e32 v11, v0
	v_mov_b32_e32 v32, v0
	v_mov_b32_e32 v33, v0
	v_mov_b32_e32 v34, v0
	v_mov_b32_e32 v35, v0
	v_mov_b32_e32 v12, v0
	v_mov_b32_e32 v13, v0
	v_mov_b32_e32 v14, v0
	v_mov_b32_e32 v15, v0
	v_mov_b32_e32 v40, v0
	v_mov_b32_e32 v41, v0
	v_mov_b32_e32 v42, v0
	v_mov_b32_e32 v43, v0
	v_mov_b32_e32 v56, v0
	v_mov_b32_e32 v57, v0
	v_mov_b32_e32 v58, v0
	v_mov_b32_e32 v59, v0
	v_mov_b32_e32 v84, v0
	v_mov_b32_e32 v85, v0
	v_mov_b32_e32 v86, v0
	v_mov_b32_e32 v87, v0
	v_mov_b32_e32 v60, v0
	v_mov_b32_e32 v61, v0
	v_mov_b32_e32 v62, v0
	v_mov_b32_e32 v63, v0
	v_mov_b32_e32 v92, v0
	v_mov_b32_e32 v93, v0
	v_mov_b32_e32 v94, v0
	v_mov_b32_e32 v95, v0
	v_mov_b32_e32 v72, v0
	v_mov_b32_e32 v73, v0
	v_mov_b32_e32 v74, v0
	v_mov_b32_e32 v75, v0
	v_mov_b32_e32 v104, v0
	v_mov_b32_e32 v105, v0
	v_mov_b32_e32 v106, v0
	v_mov_b32_e32 v107, v0
	v_mov_b32_e32 v76, v0
	v_mov_b32_e32 v77, v0
	v_mov_b32_e32 v78, v0
	v_mov_b32_e32 v79, v0
	v_mov_b32_e32 v108, v0
	v_mov_b32_e32 v109, v0
	v_mov_b32_e32 v110, v0
	v_mov_b32_e32 v111, v0
	v_mov_b32_e32 v20, v0
	v_mov_b32_e32 v21, v0
	v_mov_b32_e32 v22, v0
	v_mov_b32_e32 v23, v0
	v_mov_b32_e32 v48, v0
	v_mov_b32_e32 v49, v0
	v_mov_b32_e32 v50, v0
	v_mov_b32_e32 v51, v0
	v_mov_b32_e32 v28, v0
	v_mov_b32_e32 v29, v0
	v_mov_b32_e32 v30, v0
	v_mov_b32_e32 v31, v0
	v_mov_b32_e32 v52, v0
	v_mov_b32_e32 v53, v0
	v_mov_b32_e32 v54, v0
	v_mov_b32_e32 v55, v0
	v_mov_b32_e32 v36, v0
	v_mov_b32_e32 v37, v0
	v_mov_b32_e32 v38, v0
	v_mov_b32_e32 v39, v0
	v_mov_b32_e32 v64, v0
	v_mov_b32_e32 v65, v0
	v_mov_b32_e32 v66, v0
	v_mov_b32_e32 v67, v0
	v_mov_b32_e32 v44, v0
	v_mov_b32_e32 v45, v0
	v_mov_b32_e32 v46, v0
	v_mov_b32_e32 v47, v0
	v_mov_b32_e32 v68, v0
	v_mov_b32_e32 v69, v0
	v_mov_b32_e32 v70, v0
	v_mov_b32_e32 v71, v0
	v_mov_b32_e32 v80, v0
	v_mov_b32_e32 v81, v0
	v_mov_b32_e32 v82, v0
	v_mov_b32_e32 v83, v0
	v_mov_b32_e32 v112, v0
	v_mov_b32_e32 v113, v0
	v_mov_b32_e32 v114, v0
	v_mov_b32_e32 v115, v0
	v_mov_b32_e32 v88, v0
	v_mov_b32_e32 v89, v0
	v_mov_b32_e32 v90, v0
	v_mov_b32_e32 v91, v0
	v_mov_b32_e32 v116, v0
	v_mov_b32_e32 v117, v0
	v_mov_b32_e32 v118, v0
	v_mov_b32_e32 v119, v0
	v_mov_b32_e32 v96, v0
	v_mov_b32_e32 v97, v0
	v_mov_b32_e32 v98, v0
	v_mov_b32_e32 v99, v0
	v_mov_b32_e32 v120, v0
	v_mov_b32_e32 v121, v0
	v_mov_b32_e32 v122, v0
	v_mov_b32_e32 v123, v0
	v_mov_b32_e32 v100, v0
	v_mov_b32_e32 v101, v0
	v_mov_b32_e32 v102, v0
	v_mov_b32_e32 v103, v0
	v_mov_b32_e32 v124, v0
	v_mov_b32_e32 v125, v0
	v_mov_b32_e32 v126, v0
	v_mov_b32_e32 v127, v0
	s_cmp_eq_u32 s98, 0
	s_cbranch_scc1 .LBB0_1200
	ds_read_b128 v[128:131], v209
	ds_read_b128 v[132:135], v209 offset:1024
	ds_read_b128 v[136:139], v209 offset:2048
	ds_read_b128 v[140:143], v209 offset:3072
	ds_read_b128 v[144:147], v210
	ds_read_b128 v[148:151], v210 offset:1024
	ds_read_b128 v[152:155], v210 offset:2048
	ds_read_b128 v[156:159], v210 offset:3072
	s_add_u32 s42, s40, 0x100
	s_addc_u32 s43, s41, 0
	s_cmp_eq_u32 s75, 12
	s_cselect_b32 s47, s2, s43
	s_cselect_b32 s46, s31, s42
	s_cselect_b32 s45, s29, s74
	s_cselect_b32 s44, s72, s73
	v_lshl_add_u64 v[204:205], s[40:41], 0, v[172:173]
	s_add_i32 m0, s52, 0xc000
	ds_read_b128 v[160:163], v211
	ds_read_b128 v[164:167], v211 offset:1024
	ds_read_b128 v[180:183], v211 offset:2048
	ds_read_b128 v[184:187], v211 offset:3072
	ds_read_b128 v[188:191], v211 offset:4096
	ds_read_b128 v[192:195], v211 offset:5120
	ds_read_b128 v[196:199], v211 offset:6144
	ds_read_b128 v[200:203], v211 offset:7168
	global_load_lds_dwordx4 v[204:205], off
	v_lshl_add_u64 v[204:205], s[40:41], 0, v[174:175]
	s_add_i32 m0, s52, 0xe000
	s_nop 0
	global_load_lds_dwordx4 v[204:205], off
	s_waitcnt vmcnt(30)
	s_waitcnt lgkmcnt(0)
	s_barrier
	s_setprio 1
	s_waitcnt lgkmcnt(0)
	v_mfma_f32_16x16x32_bf16 v[124:127], v[128:131], v[160:163], v[124:127]
	v_mfma_f32_16x16x32_bf16 v[100:103], v[136:139], v[160:163], v[100:103]
	v_mfma_f32_16x16x32_bf16 v[120:123], v[128:131], v[180:183], v[120:123]
	v_mfma_f32_16x16x32_bf16 v[96:99], v[136:139], v[180:183], v[96:99]
	v_mfma_f32_16x16x32_bf16 v[116:119], v[128:131], v[188:191], v[116:119]
	v_mfma_f32_16x16x32_bf16 v[88:91], v[136:139], v[188:191], v[88:91]
	v_mfma_f32_16x16x32_bf16 v[112:115], v[128:131], v[196:199], v[112:115]
	v_mfma_f32_16x16x32_bf16 v[80:83], v[136:139], v[196:199], v[80:83]
	v_mfma_f32_16x16x32_bf16 v[124:127], v[132:135], v[164:167], v[124:127]
	v_mfma_f32_16x16x32_bf16 v[100:103], v[140:143], v[164:167], v[100:103]
	v_mfma_f32_16x16x32_bf16 v[120:123], v[132:135], v[184:187], v[120:123]
	v_mfma_f32_16x16x32_bf16 v[96:99], v[140:143], v[184:187], v[96:99]
	v_mfma_f32_16x16x32_bf16 v[116:119], v[132:135], v[192:195], v[116:119]
	v_mfma_f32_16x16x32_bf16 v[88:91], v[140:143], v[192:195], v[88:91]
	v_mfma_f32_16x16x32_bf16 v[112:115], v[132:135], v[200:203], v[112:115]
	v_mfma_f32_16x16x32_bf16 v[80:83], v[140:143], v[200:203], v[80:83]
	s_setprio 0
	s_setprio 1
	v_mfma_f32_16x16x32_bf16 v[68:71], v[144:147], v[160:163], v[68:71]
	v_mfma_f32_16x16x32_bf16 v[44:47], v[152:155], v[160:163], v[44:47]
	v_mfma_f32_16x16x32_bf16 v[64:67], v[144:147], v[180:183], v[64:67]
	v_mfma_f32_16x16x32_bf16 v[36:39], v[152:155], v[180:183], v[36:39]
	v_mfma_f32_16x16x32_bf16 v[52:55], v[144:147], v[188:191], v[52:55]
	v_mfma_f32_16x16x32_bf16 v[28:31], v[152:155], v[188:191], v[28:31]
	v_mfma_f32_16x16x32_bf16 v[48:51], v[144:147], v[196:199], v[48:51]
	v_mfma_f32_16x16x32_bf16 v[20:23], v[152:155], v[196:199], v[20:23]
	v_mfma_f32_16x16x32_bf16 v[68:71], v[148:151], v[164:167], v[68:71]
	v_mfma_f32_16x16x32_bf16 v[44:47], v[156:159], v[164:167], v[44:47]
	v_mfma_f32_16x16x32_bf16 v[64:67], v[148:151], v[184:187], v[64:67]
	v_mfma_f32_16x16x32_bf16 v[36:39], v[156:159], v[184:187], v[36:39]
	v_mfma_f32_16x16x32_bf16 v[52:55], v[148:151], v[192:195], v[52:55]
	v_mfma_f32_16x16x32_bf16 v[28:31], v[156:159], v[192:195], v[28:31]
	v_mfma_f32_16x16x32_bf16 v[48:51], v[148:151], v[200:203], v[48:51]
	v_mfma_f32_16x16x32_bf16 v[20:23], v[156:159], v[200:203], v[20:23]
	s_setprio 0
	s_barrier
	s_add_i32 s40, s64, s51
	v_lshl_add_u64 v[204:205], s[44:45], 0, v[168:169]
	s_mov_b32 m0, s40
	ds_read_b128 v[160:163], v211 offset:16384
	ds_read_b128 v[164:167], v211 offset:17408
	ds_read_b128 v[180:183], v211 offset:18432
	ds_read_b128 v[184:187], v211 offset:19456
	ds_read_b128 v[188:191], v211 offset:20480
	ds_read_b128 v[192:195], v211 offset:21504
	ds_read_b128 v[196:199], v211 offset:22528
	ds_read_b128 v[200:203], v211 offset:23552
	global_load_lds_dwordx4 v[204:205], off
	s_add_i32 m0, s40, 0x2000
	s_add_u32 s40, s44, 0x40000
	v_lshl_add_u64 v[212:213], s[44:45], 0, v[170:171]
	s_addc_u32 s41, s45, 0
	s_add_i32 s76, s65, s51
	global_load_lds_dwordx4 v[212:213], off
	v_lshl_add_u64 v[214:215], s[40:41], 0, v[168:169]
	s_mov_b32 m0, s76
	v_lshl_add_u64 v[216:217], s[46:47], 0, v[170:171]
	global_load_lds_dwordx4 v[214:215], off
	v_lshl_add_u64 v[214:215], s[40:41], 0, v[170:171]
	s_add_i32 m0, s76, 0x2000
	s_nop 0
	global_load_lds_dwordx4 v[214:215], off
	v_lshl_add_u64 v[214:215], s[46:47], 0, v[168:169]
	s_mov_b32 m0, s52
	s_nop 0
	global_load_lds_dwordx4 v[214:215], off
	s_mov_b32 m0, s53
	s_nop 0
	global_load_lds_dwordx4 v[216:217], off
	s_waitcnt vmcnt(30)
	s_waitcnt lgkmcnt(0)
	s_barrier
	s_setprio 1
	s_waitcnt lgkmcnt(0)
	v_mfma_f32_16x16x32_bf16 v[108:111], v[128:131], v[160:163], v[108:111]
	v_mfma_f32_16x16x32_bf16 v[76:79], v[136:139], v[160:163], v[76:79]
	v_mfma_f32_16x16x32_bf16 v[104:107], v[128:131], v[180:183], v[104:107]
	v_mfma_f32_16x16x32_bf16 v[72:75], v[136:139], v[180:183], v[72:75]
	v_mfma_f32_16x16x32_bf16 v[92:95], v[128:131], v[188:191], v[92:95]
	v_mfma_f32_16x16x32_bf16 v[60:63], v[136:139], v[188:191], v[60:63]
	v_mfma_f32_16x16x32_bf16 v[84:87], v[128:131], v[196:199], v[84:87]
	v_mfma_f32_16x16x32_bf16 v[56:59], v[136:139], v[196:199], v[56:59]
	v_mfma_f32_16x16x32_bf16 v[108:111], v[132:135], v[164:167], v[108:111]
	v_mfma_f32_16x16x32_bf16 v[76:79], v[140:143], v[164:167], v[76:79]
	v_mfma_f32_16x16x32_bf16 v[104:107], v[132:135], v[184:187], v[104:107]
	v_mfma_f32_16x16x32_bf16 v[72:75], v[140:143], v[184:187], v[72:75]
	v_mfma_f32_16x16x32_bf16 v[92:95], v[132:135], v[192:195], v[92:95]
	v_mfma_f32_16x16x32_bf16 v[60:63], v[140:143], v[192:195], v[60:63]
	v_mfma_f32_16x16x32_bf16 v[84:87], v[132:135], v[200:203], v[84:87]
	v_mfma_f32_16x16x32_bf16 v[56:59], v[140:143], v[200:203], v[56:59]
	s_setprio 0
	s_setprio 1
	v_mfma_f32_16x16x32_bf16 v[40:43], v[144:147], v[160:163], v[40:43]
	v_mfma_f32_16x16x32_bf16 v[12:15], v[152:155], v[160:163], v[12:15]
	v_mfma_f32_16x16x32_bf16 v[32:35], v[144:147], v[180:183], v[32:35]
	v_mfma_f32_16x16x32_bf16 v[8:11], v[152:155], v[180:183], v[8:11]
	v_mfma_f32_16x16x32_bf16 v[24:27], v[144:147], v[188:191], v[24:27]
	v_mfma_f32_16x16x32_bf16 v[4:7], v[152:155], v[188:191], v[4:7]
	v_mfma_f32_16x16x32_bf16 v[16:19], v[144:147], v[196:199], v[16:19]
	v_mfma_f32_16x16x32_bf16 v[0:3], v[152:155], v[196:199], v[0:3]
	v_mfma_f32_16x16x32_bf16 v[40:43], v[148:151], v[164:167], v[40:43]
	v_mfma_f32_16x16x32_bf16 v[12:15], v[156:159], v[164:167], v[12:15]
	v_mfma_f32_16x16x32_bf16 v[32:35], v[148:151], v[184:187], v[32:35]
	v_mfma_f32_16x16x32_bf16 v[8:11], v[156:159], v[184:187], v[8:11]
	v_mfma_f32_16x16x32_bf16 v[24:27], v[148:151], v[192:195], v[24:27]
	v_mfma_f32_16x16x32_bf16 v[4:7], v[156:159], v[192:195], v[4:7]
	v_mfma_f32_16x16x32_bf16 v[16:19], v[148:151], v[200:203], v[16:19]
	v_mfma_f32_16x16x32_bf16 v[0:3], v[156:159], v[200:203], v[0:3]
	s_setprio 0
	s_barrier
	s_add_i32 s76, 0, 0x18000
	s_add_i32 s77, 0, 0x1c000
	v_add_u32_e32 v140, s76, v207
	v_add_u32_e32 v156, s77, v207
	ds_read_b128 v[128:131], v140
	ds_read_b128 v[132:135], v140 offset:1024
	ds_read_b128 v[136:139], v140 offset:2048
	ds_read_b128 v[140:143], v140 offset:3072
	ds_read_b128 v[144:147], v156
	ds_read_b128 v[148:151], v156 offset:1024
	ds_read_b128 v[152:155], v156 offset:2048
	ds_read_b128 v[156:159], v156 offset:3072
	s_add_u32 s40, s46, 0x40000
	s_addc_u32 s41, s47, 0
	s_mov_b32 m0, s54
	v_lshl_add_u64 v[218:219], s[40:41], 0, v[168:169]
	ds_read_b128 v[160:163], v211 offset:32768
	ds_read_b128 v[164:167], v211 offset:33792
	ds_read_b128 v[180:183], v211 offset:34816
	ds_read_b128 v[184:187], v211 offset:35840
	ds_read_b128 v[188:191], v211 offset:36864
	ds_read_b128 v[192:195], v211 offset:37888
	ds_read_b128 v[196:199], v211 offset:38912
	ds_read_b128 v[200:203], v211 offset:39936
	global_load_lds_dwordx4 v[218:219], off
	v_lshl_add_u64 v[218:219], s[40:41], 0, v[170:171]
	s_mov_b32 m0, s55
	s_nop 0
	global_load_lds_dwordx4 v[218:219], off
	s_waitcnt vmcnt(8)
	s_waitcnt lgkmcnt(0)
	s_barrier
	s_setprio 1
	s_waitcnt lgkmcnt(0)
	v_mfma_f32_16x16x32_bf16 v[124:127], v[128:131], v[160:163], v[124:127]
	v_mfma_f32_16x16x32_bf16 v[100:103], v[136:139], v[160:163], v[100:103]
	v_mfma_f32_16x16x32_bf16 v[120:123], v[128:131], v[180:183], v[120:123]
	v_mfma_f32_16x16x32_bf16 v[96:99], v[136:139], v[180:183], v[96:99]
	v_mfma_f32_16x16x32_bf16 v[116:119], v[128:131], v[188:191], v[116:119]
	v_mfma_f32_16x16x32_bf16 v[88:91], v[136:139], v[188:191], v[88:91]
	v_mfma_f32_16x16x32_bf16 v[112:115], v[128:131], v[196:199], v[112:115]
	v_mfma_f32_16x16x32_bf16 v[80:83], v[136:139], v[196:199], v[80:83]
	v_mfma_f32_16x16x32_bf16 v[124:127], v[132:135], v[164:167], v[124:127]
	v_mfma_f32_16x16x32_bf16 v[100:103], v[140:143], v[164:167], v[100:103]
	v_mfma_f32_16x16x32_bf16 v[120:123], v[132:135], v[184:187], v[120:123]
	v_mfma_f32_16x16x32_bf16 v[96:99], v[140:143], v[184:187], v[96:99]
	v_mfma_f32_16x16x32_bf16 v[116:119], v[132:135], v[192:195], v[116:119]
	v_mfma_f32_16x16x32_bf16 v[88:91], v[140:143], v[192:195], v[88:91]
	v_mfma_f32_16x16x32_bf16 v[112:115], v[132:135], v[200:203], v[112:115]
	v_mfma_f32_16x16x32_bf16 v[80:83], v[140:143], v[200:203], v[80:83]
	s_setprio 0
	s_setprio 1
	v_mfma_f32_16x16x32_bf16 v[68:71], v[144:147], v[160:163], v[68:71]
	v_mfma_f32_16x16x32_bf16 v[44:47], v[152:155], v[160:163], v[44:47]
	v_mfma_f32_16x16x32_bf16 v[64:67], v[144:147], v[180:183], v[64:67]
	v_mfma_f32_16x16x32_bf16 v[36:39], v[152:155], v[180:183], v[36:39]
	v_mfma_f32_16x16x32_bf16 v[52:55], v[144:147], v[188:191], v[52:55]
	v_mfma_f32_16x16x32_bf16 v[28:31], v[152:155], v[188:191], v[28:31]
	v_mfma_f32_16x16x32_bf16 v[48:51], v[144:147], v[196:199], v[48:51]
	v_mfma_f32_16x16x32_bf16 v[20:23], v[152:155], v[196:199], v[20:23]
	v_mfma_f32_16x16x32_bf16 v[68:71], v[148:151], v[164:167], v[68:71]
	v_mfma_f32_16x16x32_bf16 v[44:47], v[156:159], v[164:167], v[44:47]
	v_mfma_f32_16x16x32_bf16 v[64:67], v[148:151], v[184:187], v[64:67]
	v_mfma_f32_16x16x32_bf16 v[36:39], v[156:159], v[184:187], v[36:39]
	v_mfma_f32_16x16x32_bf16 v[52:55], v[148:151], v[192:195], v[52:55]
	v_mfma_f32_16x16x32_bf16 v[28:31], v[156:159], v[192:195], v[28:31]
	v_mfma_f32_16x16x32_bf16 v[48:51], v[148:151], v[200:203], v[48:51]
	v_mfma_f32_16x16x32_bf16 v[20:23], v[156:159], v[200:203], v[20:23]
	s_setprio 0
	s_barrier
	s_add_i32 s40, s76, s51
	v_lshl_add_u64 v[204:205], v[204:205], 0, s[10:11]
	s_mov_b32 m0, s40
	ds_read_b128 v[160:163], v211 offset:49152
	ds_read_b128 v[164:167], v211 offset:50176
	ds_read_b128 v[180:183], v211 offset:51200
	ds_read_b128 v[184:187], v211 offset:52224
	ds_read_b128 v[188:191], v211 offset:53248
	ds_read_b128 v[192:195], v211 offset:54272
	ds_read_b128 v[196:199], v211 offset:55296
	ds_read_b128 v[200:203], v211 offset:56320
	global_load_lds_dwordx4 v[204:205], off
	s_add_i32 m0, s40, 0x2000
	s_add_u32 s40, s44, 0x40080
	v_lshl_add_u64 v[204:205], v[212:213], 0, s[10:11]
	s_addc_u32 s41, s45, 0
	s_add_i32 s44, s77, s51
	global_load_lds_dwordx4 v[204:205], off
	v_lshl_add_u64 v[204:205], s[40:41], 0, v[168:169]
	s_mov_b32 m0, s44
	s_nop 0
	global_load_lds_dwordx4 v[204:205], off
	v_lshl_add_u64 v[204:205], s[40:41], 0, v[170:171]
	s_add_i32 m0, s44, 0x2000
	s_nop 0
	global_load_lds_dwordx4 v[204:205], off
	v_lshl_add_u64 v[204:205], v[214:215], 0, s[10:11]
	s_mov_b32 m0, s60
	s_nop 0
	global_load_lds_dwordx4 v[204:205], off
	v_lshl_add_u64 v[204:205], v[216:217], 0, s[10:11]
	s_mov_b32 m0, s61
	s_nop 0
	global_load_lds_dwordx4 v[204:205], off
	s_waitcnt vmcnt(8)
	s_waitcnt lgkmcnt(0)
	s_barrier
	s_setprio 1
	s_waitcnt lgkmcnt(0)
	v_mfma_f32_16x16x32_bf16 v[108:111], v[128:131], v[160:163], v[108:111]
	v_mfma_f32_16x16x32_bf16 v[76:79], v[136:139], v[160:163], v[76:79]
	v_mfma_f32_16x16x32_bf16 v[104:107], v[128:131], v[180:183], v[104:107]
	v_mfma_f32_16x16x32_bf16 v[72:75], v[136:139], v[180:183], v[72:75]
	v_mfma_f32_16x16x32_bf16 v[92:95], v[128:131], v[188:191], v[92:95]
	v_mfma_f32_16x16x32_bf16 v[60:63], v[136:139], v[188:191], v[60:63]
	v_mfma_f32_16x16x32_bf16 v[84:87], v[128:131], v[196:199], v[84:87]
	v_mfma_f32_16x16x32_bf16 v[56:59], v[136:139], v[196:199], v[56:59]
	v_mfma_f32_16x16x32_bf16 v[108:111], v[132:135], v[164:167], v[108:111]
	v_mfma_f32_16x16x32_bf16 v[76:79], v[140:143], v[164:167], v[76:79]
	v_mfma_f32_16x16x32_bf16 v[104:107], v[132:135], v[184:187], v[104:107]
	v_mfma_f32_16x16x32_bf16 v[72:75], v[140:143], v[184:187], v[72:75]
	v_mfma_f32_16x16x32_bf16 v[92:95], v[132:135], v[192:195], v[92:95]
	v_mfma_f32_16x16x32_bf16 v[60:63], v[140:143], v[192:195], v[60:63]
	v_mfma_f32_16x16x32_bf16 v[84:87], v[132:135], v[200:203], v[84:87]
	v_mfma_f32_16x16x32_bf16 v[56:59], v[140:143], v[200:203], v[56:59]
	s_setprio 0
	s_setprio 1
	v_mfma_f32_16x16x32_bf16 v[40:43], v[144:147], v[160:163], v[40:43]
	v_mfma_f32_16x16x32_bf16 v[12:15], v[152:155], v[160:163], v[12:15]
	v_mfma_f32_16x16x32_bf16 v[32:35], v[144:147], v[180:183], v[32:35]
	v_mfma_f32_16x16x32_bf16 v[8:11], v[152:155], v[180:183], v[8:11]
	v_mfma_f32_16x16x32_bf16 v[24:27], v[144:147], v[188:191], v[24:27]
	v_mfma_f32_16x16x32_bf16 v[4:7], v[152:155], v[188:191], v[4:7]
	v_mfma_f32_16x16x32_bf16 v[16:19], v[144:147], v[196:199], v[16:19]
	v_mfma_f32_16x16x32_bf16 v[0:3], v[152:155], v[196:199], v[0:3]
	v_mfma_f32_16x16x32_bf16 v[40:43], v[148:151], v[164:167], v[40:43]
	v_mfma_f32_16x16x32_bf16 v[12:15], v[156:159], v[164:167], v[12:15]
	v_mfma_f32_16x16x32_bf16 v[32:35], v[148:151], v[184:187], v[32:35]
	v_mfma_f32_16x16x32_bf16 v[8:11], v[156:159], v[184:187], v[8:11]
	v_mfma_f32_16x16x32_bf16 v[24:27], v[148:151], v[192:195], v[24:27]
	v_mfma_f32_16x16x32_bf16 v[4:7], v[156:159], v[192:195], v[4:7]
	v_mfma_f32_16x16x32_bf16 v[16:19], v[148:151], v[200:203], v[16:19]
	v_mfma_f32_16x16x32_bf16 v[0:3], v[156:159], v[200:203], v[0:3]
	s_setprio 0
	s_barrier
	s_add_i32 s75, s75, 2
	s_add_u32 s73, s73, 0x100
	s_addc_u32 s74, s74, 0
	s_cmp_gt_u32 s75, 13
	s_mov_b64 s[40:41], s[42:43]
	s_cbranch_scc0 .LBB0_1200
	s_branch .Lpeel_exit_P11

.Lpeel_exit_P11:
	s_mov_b32 s98, 0
	s_and_b64 vcc, exec, s[12:13]
	s_cbranch_vccz .LBB0_1203
	s_barrier
.LBB0_1203:
	v_lshl_add_u32 v128, s38, 8, v206
	v_lshl_or_b32 v136, s39, 8, v208
	s_ashr_i32 s2, s38, 4
	v_lshlrev_b32_e32 v136, 2, v136
	s_mul_hi_i32 s29, s2, 0x9000
	s_mul_i32 s2, s2, 0x9000
	v_lshl_add_u32 v128, v128, 12, v136
	s_add_u32 s38, s58, s2
	s_addc_u32 s39, s59, s29
	v_add_u32_e32 v129, 0x10000, v128
	v_add_u32_e32 v130, 0x20000, v128
	v_add_u32_e32 v131, 0x30000, v128
	v_add_u32_e32 v132, 0x80000, v128
	v_add_u32_e32 v133, 0x90000, v128
	v_add_u32_e32 v134, 0xa0000, v128
	v_add_u32_e32 v135, 0xb0000, v128
	global_load_dwordx4 v[140:143], v136, s[38:39]
	global_load_dwordx4 v[144:147], v136, s[38:39] offset:64
	global_load_dwordx4 v[148:151], v136, s[38:39] offset:512
	global_load_dwordx4 v[152:155], v136, s[38:39] offset:576
	global_load_dwordx4 v[180:183], v128, s[8:9]
	global_load_dwordx4 v[184:187], v128, s[8:9] offset:64
	global_load_dwordx4 v[188:191], v128, s[8:9] offset:512
	global_load_dwordx4 v[192:195], v128, s[8:9] offset:576
	global_load_dwordx4 v[196:199], v129, s[8:9]
	global_load_dwordx4 v[200:203], v129, s[8:9] offset:64
	global_load_dwordx4 v[212:215], v129, s[8:9] offset:512
	global_load_dwordx4 v[216:219], v129, s[8:9] offset:576
	global_load_dwordx4 v[220:223], v130, s[8:9]
	global_load_dwordx4 v[224:227], v130, s[8:9] offset:64
	global_load_dwordx4 v[232:235], v130, s[8:9] offset:512
	global_load_dwordx4 v[236:239], v130, s[8:9] offset:576
	global_load_dwordx4 v[240:243], v131, s[8:9]
	global_load_dwordx4 v[244:247], v131, s[8:9] offset:64
	global_load_dwordx4 v[248:251], v131, s[8:9] offset:512
	global_load_dwordx4 v[156:159], v131, s[8:9] offset:576
	s_waitcnt vmcnt(8)
	v_pk_fma_f32 v[180:181], v[124:125], v[140:141], v[180:181]
	v_pk_fma_f32 v[182:183], v[126:127], v[142:143], v[182:183]
	v_pk_fma_f32 v[184:185], v[100:101], v[144:145], v[184:185]
	v_pk_fma_f32 v[186:187], v[102:103], v[146:147], v[186:187]
	v_pk_fma_f32 v[188:189], v[68:69], v[148:149], v[188:189]
	v_pk_fma_f32 v[190:191], v[70:71], v[150:151], v[190:191]
	v_pk_fma_f32 v[192:193], v[44:45], v[152:153], v[192:193]
	v_pk_fma_f32 v[194:195], v[46:47], v[154:155], v[194:195]
	global_store_dwordx4 v128, v[180:183], s[8:9]
	global_store_dwordx4 v128, v[184:187], s[8:9] offset:64
	global_store_dwordx4 v128, v[188:191], s[8:9] offset:512
	global_store_dwordx4 v128, v[192:195], s[8:9] offset:576
	v_pk_fma_f32 v[196:197], v[120:121], v[140:141], v[196:197]
	v_pk_fma_f32 v[198:199], v[122:123], v[142:143], v[198:199]
	v_pk_fma_f32 v[200:201], v[96:97], v[144:145], v[200:201]
	v_pk_fma_f32 v[202:203], v[98:99], v[146:147], v[202:203]
	v_pk_fma_f32 v[212:213], v[64:65], v[148:149], v[212:213]
	v_pk_fma_f32 v[214:215], v[66:67], v[150:151], v[214:215]
	v_pk_fma_f32 v[216:217], v[36:37], v[152:153], v[216:217]
	v_pk_fma_f32 v[218:219], v[38:39], v[154:155], v[218:219]
	global_store_dwordx4 v129, v[196:199], s[8:9]
	global_store_dwordx4 v129, v[200:203], s[8:9] offset:64
	global_store_dwordx4 v129, v[212:215], s[8:9] offset:512
	global_store_dwordx4 v129, v[216:219], s[8:9] offset:576
	s_nop 1
	global_load_dwordx4 v[180:183], v132, s[8:9]
	global_load_dwordx4 v[184:187], v132, s[8:9] offset:64
	global_load_dwordx4 v[188:191], v132, s[8:9] offset:512
	global_load_dwordx4 v[192:195], v132, s[8:9] offset:576
	global_load_dwordx4 v[196:199], v133, s[8:9]
	global_load_dwordx4 v[200:203], v133, s[8:9] offset:64
	global_load_dwordx4 v[212:215], v133, s[8:9] offset:512
	global_load_dwordx4 v[216:219], v133, s[8:9] offset:576
	s_waitcnt vmcnt(16)
	v_pk_fma_f32 v[220:221], v[116:117], v[140:141], v[220:221]
	v_pk_fma_f32 v[222:223], v[118:119], v[142:143], v[222:223]
	v_pk_fma_f32 v[224:225], v[88:89], v[144:145], v[224:225]
	v_pk_fma_f32 v[226:227], v[90:91], v[146:147], v[226:227]
	v_pk_fma_f32 v[232:233], v[52:53], v[148:149], v[232:233]
	v_pk_fma_f32 v[234:235], v[54:55], v[150:151], v[234:235]
	v_pk_fma_f32 v[236:237], v[28:29], v[152:153], v[236:237]
	v_pk_fma_f32 v[238:239], v[30:31], v[154:155], v[238:239]
	global_store_dwordx4 v130, v[220:223], s[8:9]
	global_store_dwordx4 v130, v[224:227], s[8:9] offset:64
	global_store_dwordx4 v130, v[232:235], s[8:9] offset:512
	global_store_dwordx4 v130, v[236:239], s[8:9] offset:576
	v_pk_fma_f32 v[240:241], v[112:113], v[140:141], v[240:241]
	v_pk_fma_f32 v[242:243], v[114:115], v[142:143], v[242:243]
	v_pk_fma_f32 v[244:245], v[80:81], v[144:145], v[244:245]
	v_pk_fma_f32 v[246:247], v[82:83], v[146:147], v[246:247]
	v_pk_fma_f32 v[248:249], v[48:49], v[148:149], v[248:249]
	v_pk_fma_f32 v[250:251], v[50:51], v[150:151], v[250:251]
	v_pk_fma_f32 v[156:157], v[20:21], v[152:153], v[156:157]
	v_pk_fma_f32 v[158:159], v[22:23], v[154:155], v[158:159]
	global_store_dwordx4 v131, v[240:243], s[8:9]
	global_store_dwordx4 v131, v[244:247], s[8:9] offset:64
	global_store_dwordx4 v131, v[248:251], s[8:9] offset:512
	global_store_dwordx4 v131, v[156:159], s[8:9] offset:576
	s_nop 1
	global_load_dwordx4 v[220:223], v134, s[8:9]
	global_load_dwordx4 v[224:227], v134, s[8:9] offset:64
	global_load_dwordx4 v[232:235], v134, s[8:9] offset:512
	global_load_dwordx4 v[236:239], v134, s[8:9] offset:576
	global_load_dwordx4 v[240:243], v135, s[8:9]
	global_load_dwordx4 v[244:247], v135, s[8:9] offset:64
	global_load_dwordx4 v[248:251], v135, s[8:9] offset:512
	global_load_dwordx4 v[156:159], v135, s[8:9] offset:576
	s_waitcnt vmcnt(16)
	v_pk_fma_f32 v[180:181], v[108:109], v[140:141], v[180:181]
	v_pk_fma_f32 v[182:183], v[110:111], v[142:143], v[182:183]
	v_pk_fma_f32 v[184:185], v[76:77], v[144:145], v[184:185]
	v_pk_fma_f32 v[186:187], v[78:79], v[146:147], v[186:187]
	v_pk_fma_f32 v[188:189], v[40:41], v[148:149], v[188:189]
	v_pk_fma_f32 v[190:191], v[42:43], v[150:151], v[190:191]
	v_pk_fma_f32 v[192:193], v[12:13], v[152:153], v[192:193]
	v_pk_fma_f32 v[194:195], v[14:15], v[154:155], v[194:195]
	global_store_dwordx4 v132, v[180:183], s[8:9]
	global_store_dwordx4 v132, v[184:187], s[8:9] offset:64
	global_store_dwordx4 v132, v[188:191], s[8:9] offset:512
	global_store_dwordx4 v132, v[192:195], s[8:9] offset:576
	v_pk_fma_f32 v[196:197], v[104:105], v[140:141], v[196:197]
	v_pk_fma_f32 v[198:199], v[106:107], v[142:143], v[198:199]
	v_pk_fma_f32 v[200:201], v[72:73], v[144:145], v[200:201]
	v_pk_fma_f32 v[202:203], v[74:75], v[146:147], v[202:203]
	v_pk_fma_f32 v[212:213], v[32:33], v[148:149], v[212:213]
	v_pk_fma_f32 v[214:215], v[34:35], v[150:151], v[214:215]
	v_pk_fma_f32 v[216:217], v[8:9], v[152:153], v[216:217]
	v_pk_fma_f32 v[218:219], v[10:11], v[154:155], v[218:219]
	global_store_dwordx4 v133, v[196:199], s[8:9]
	global_store_dwordx4 v133, v[200:203], s[8:9] offset:64
	global_store_dwordx4 v133, v[212:215], s[8:9] offset:512
	global_store_dwordx4 v133, v[216:219], s[8:9] offset:576
	s_waitcnt vmcnt(8)
	v_pk_fma_f32 v[220:221], v[92:93], v[140:141], v[220:221]
	v_pk_fma_f32 v[222:223], v[94:95], v[142:143], v[222:223]
	v_pk_fma_f32 v[224:225], v[60:61], v[144:145], v[224:225]
	v_pk_fma_f32 v[226:227], v[62:63], v[146:147], v[226:227]
	v_pk_fma_f32 v[232:233], v[24:25], v[148:149], v[232:233]
	v_pk_fma_f32 v[234:235], v[26:27], v[150:151], v[234:235]
	v_pk_fma_f32 v[236:237], v[4:5], v[152:153], v[236:237]
	v_pk_fma_f32 v[238:239], v[6:7], v[154:155], v[238:239]
	global_store_dwordx4 v134, v[220:223], s[8:9]
	global_store_dwordx4 v134, v[224:227], s[8:9] offset:64
	global_store_dwordx4 v134, v[232:235], s[8:9] offset:512
	global_store_dwordx4 v134, v[236:239], s[8:9] offset:576
	v_pk_fma_f32 v[240:241], v[84:85], v[140:141], v[240:241]
	v_pk_fma_f32 v[242:243], v[86:87], v[142:143], v[242:243]
	v_pk_fma_f32 v[244:245], v[56:57], v[144:145], v[244:245]
	v_pk_fma_f32 v[246:247], v[58:59], v[146:147], v[246:247]
	v_pk_fma_f32 v[248:249], v[16:17], v[148:149], v[248:249]
	v_pk_fma_f32 v[250:251], v[18:19], v[150:151], v[250:251]
	v_pk_fma_f32 v[156:157], v[0:1], v[152:153], v[156:157]
	v_pk_fma_f32 v[158:159], v[2:3], v[154:155], v[158:159]
	global_store_dwordx4 v135, v[240:243], s[8:9]
	global_store_dwordx4 v135, v[244:247], s[8:9] offset:64
	global_store_dwordx4 v135, v[248:251], s[8:9] offset:512
	global_store_dwordx4 v135, v[156:159], s[8:9] offset:576
	s_mov_b64 s[38:39], -1
	s_andn2_b64 vcc, exec, s[6:7]
	s_mov_b32 s98, 1
	s_cbranch_vccnz .LBB0_1192
	s_andn2_b64 vcc, exec, s[0:1]
	s_cbranch_vccnz .LBB0_1191
	s_barrier
	s_branch .LBB0_1191

.LBB0_1325:
	s_add_u32 s8, s6, 0x186a0000
	s_addc_u32 s9, s7, 0
	s_lshl_b32 s2, s2, 5
	s_mov_b64 s[10:11], 0x80
	s_and_b32 s16, s2, 0x60
	s_add_i32 m0, s23, 0x18000
	v_lshl_add_u64 v[6:7], v[6:7], 0, s[10:11]
	s_lshl_b32 s15, s14, 13
	s_lshl_b32 s17, s16, 7
	s_waitcnt vmcnt(2)
	s_barrier
	global_load_lds_dwordx4 v[6:7], off
	v_lshl_add_u64 v[4:5], v[4:5], 0, s[10:11]
	s_add_i32 m0, s23, 0x1a000
	s_add_i32 s41, s23, 0x8000
	s_add_i32 s42, s23, 0xa000
	global_load_lds_dwordx4 v[4:5], off
	v_lshl_add_u64 v[0:1], v[0:1], 0, s[10:11]
	s_mov_b32 m0, s41
	s_add_u32 s6, s26, 0x40080
	global_load_lds_dwordx4 v[0:1], off
	v_lshl_add_u64 v[0:1], v[2:3], 0, s[10:11]
	s_mov_b32 m0, s42
	s_addc_u32 s7, s27, 0
	global_load_lds_dwordx4 v[0:1], off
	s_add_i32 m0, s23, 0x1c000
	v_lshl_add_u64 v[0:1], s[6:7], 0, v[132:133]
	global_load_lds_dwordx4 v[0:1], off
	v_lshl_add_u64 v[0:1], s[6:7], 0, v[128:129]
	s_add_i32 m0, s23, 0x1e000
	s_cmpk_lt_u32 s13, 0x100
	global_load_lds_dwordx4 v[0:1], off
	v_lshrrev_b32_e32 v1, 1, v8
	v_and_b32_e32 v1, 24, v1
	v_and_b32_e32 v0, 15, v8
	v_lshlrev_b32_e32 v2, 1, v1
	s_waitcnt vmcnt(0)
	v_lshl_or_b32 v146, s14, 6, v0
	v_lshl_or_b32 v0, v0, 6, v2
	v_lshlrev_b32_e32 v2, 2, v8
	v_and_b32_e32 v2, 32, v2
	v_bitop3_b32 v3, v0, s15, v2 bitop3:0xde
	v_bitop3_b32 v147, v0, s17, v2 bitop3:0xde
	v_lshlrev_b32_e32 v0, 14, v13
	v_and_b32_e32 v0, 0xffff8000, v0
	v_or_b32_e32 v148, s16, v1
	v_lshl_add_u32 v0, v12, 11, v0
	v_and_b32_e32 v1, 1, v13
	v_lshl_or_b32 v0, v1, 6, v0
	v_lshl_add_u32 v136, v14, 1, v0
	v_lshlrev_b32_e32 v0, 14, v9
	v_and_b32_e32 v0, 0xffff8000, v0
	s_waitcnt vmcnt(6)
	v_lshl_add_u32 v0, v10, 11, v0
	v_and_b32_e32 v1, 1, v9
	s_sext_i32_i16 s2, s12
	s_cselect_b64 s[12:13], -1, 0
	v_lshl_or_b32 v0, v1, 6, v0
	s_add_i32 s45, 0, 0x10000
	s_add_i32 s46, 0, 0x14000
	s_ashr_i32 s43, s90, 31
	s_mov_b32 s44, s90
	v_mov_b32_e32 v137, v133
	v_lshl_add_u32 v138, v11, 1, v0
	v_mov_b32_e32 v139, v133
	v_mov_b64_e32 v[140:141], 0x1600
	v_mov_b64_e32 v[142:143], 0x15ff
	v_add_u32_e32 v149, s45, v147
	v_add_u32_e32 v150, s46, v147
	v_add_u32_e32 v151, 0, v3
	s_movk_i32 s47, 0x1600
	s_barrier
	s_mov_b32 s98, 0
	s_branch .LBB0_1328

.LBB0_1330:
	s_ashr_i32 s17, s16, 31
	s_lshl_b64 s[18:19], s[16:17], 19
	s_add_u32 s18, s3, s18
	s_addc_u32 s19, s30, s19
	s_and_b64 s[20:21], s[6:7], exec
	s_cselect_b32 s17, s19, s25
	s_cselect_b32 s48, s18, s24
	s_ashr_i32 s15, s14, 31
	s_lshl_b64 s[20:21], s[14:15], 19
	s_add_u32 s20, s31, s20
	s_addc_u32 s21, s33, s21
	s_and_b64 s[28:29], s[6:7], exec
	s_cselect_b32 s15, s21, s27
	s_cselect_b32 s49, s20, s26
	s_add_u32 s24, s24, 0x40080
	s_addc_u32 s25, s25, 0
	s_add_u32 s50, s26, 0x100
	v_mov_b32_e32 v0, 0
	s_addc_u32 s51, s27, 0
	s_mov_b32 s52, -2
	v_mov_b32_e32 v1, v0
	v_mov_b32_e32 v2, v0
	v_mov_b32_e32 v3, v0
	v_mov_b32_e32 v4, v0
	v_mov_b32_e32 v5, v0
	v_mov_b32_e32 v6, v0
	v_mov_b32_e32 v7, v0
	v_mov_b32_e32 v16, v0
	v_mov_b32_e32 v17, v0
	v_mov_b32_e32 v18, v0
	v_mov_b32_e32 v19, v0
	v_mov_b32_e32 v20, v0
	v_mov_b32_e32 v21, v0
	v_mov_b32_e32 v22, v0
	v_mov_b32_e32 v23, v0
	v_mov_b32_e32 v32, v0
	v_mov_b32_e32 v33, v0
	v_mov_b32_e32 v34, v0
	v_mov_b32_e32 v35, v0
	v_mov_b32_e32 v36, v0
	v_mov_b32_e32 v37, v0
	v_mov_b32_e32 v38, v0
	v_mov_b32_e32 v39, v0
	v_mov_b32_e32 v48, v0
	v_mov_b32_e32 v49, v0
	v_mov_b32_e32 v50, v0
	v_mov_b32_e32 v51, v0
	v_mov_b32_e32 v52, v0
	v_mov_b32_e32 v53, v0
	v_mov_b32_e32 v54, v0
	v_mov_b32_e32 v55, v0
	v_mov_b32_e32 v8, v0
	v_mov_b32_e32 v9, v0
	v_mov_b32_e32 v10, v0
	v_mov_b32_e32 v11, v0
	v_mov_b32_e32 v12, v0
	v_mov_b32_e32 v13, v0
	v_mov_b32_e32 v14, v0
	v_mov_b32_e32 v15, v0
	v_mov_b32_e32 v24, v0
	v_mov_b32_e32 v25, v0
	v_mov_b32_e32 v26, v0
	v_mov_b32_e32 v27, v0
	v_mov_b32_e32 v28, v0
	v_mov_b32_e32 v29, v0
	v_mov_b32_e32 v30, v0
	v_mov_b32_e32 v31, v0
	v_mov_b32_e32 v40, v0
	v_mov_b32_e32 v41, v0
	v_mov_b32_e32 v42, v0
	v_mov_b32_e32 v43, v0
	v_mov_b32_e32 v44, v0
	v_mov_b32_e32 v45, v0
	v_mov_b32_e32 v46, v0
	v_mov_b32_e32 v47, v0
	v_mov_b32_e32 v56, v0
	v_mov_b32_e32 v57, v0
	v_mov_b32_e32 v58, v0
	v_mov_b32_e32 v59, v0
	v_mov_b32_e32 v60, v0
	v_mov_b32_e32 v61, v0
	v_mov_b32_e32 v62, v0
	v_mov_b32_e32 v63, v0
	v_mov_b32_e32 v64, v0
	v_mov_b32_e32 v65, v0
	v_mov_b32_e32 v66, v0
	v_mov_b32_e32 v67, v0
	v_mov_b32_e32 v68, v0
	v_mov_b32_e32 v69, v0
	v_mov_b32_e32 v70, v0
	v_mov_b32_e32 v71, v0
	v_mov_b32_e32 v80, v0
	v_mov_b32_e32 v81, v0
	v_mov_b32_e32 v82, v0
	v_mov_b32_e32 v83, v0
	v_mov_b32_e32 v84, v0
	v_mov_b32_e32 v85, v0
	v_mov_b32_e32 v86, v0
	v_mov_b32_e32 v87, v0
	v_mov_b32_e32 v96, v0
	v_mov_b32_e32 v97, v0
	v_mov_b32_e32 v98, v0
	v_mov_b32_e32 v99, v0
	v_mov_b32_e32 v100, v0
	v_mov_b32_e32 v101, v0
	v_mov_b32_e32 v102, v0
	v_mov_b32_e32 v103, v0
	v_mov_b32_e32 v112, v0
	v_mov_b32_e32 v113, v0
	v_mov_b32_e32 v114, v0
	v_mov_b32_e32 v115, v0
	v_mov_b32_e32 v116, v0
	v_mov_b32_e32 v117, v0
	v_mov_b32_e32 v118, v0
	v_mov_b32_e32 v119, v0
	v_mov_b32_e32 v72, v0
	v_mov_b32_e32 v73, v0
	v_mov_b32_e32 v74, v0
	v_mov_b32_e32 v75, v0
	v_mov_b32_e32 v76, v0
	v_mov_b32_e32 v77, v0
	v_mov_b32_e32 v78, v0
	v_mov_b32_e32 v79, v0
	v_mov_b32_e32 v88, v0
	v_mov_b32_e32 v89, v0
	v_mov_b32_e32 v90, v0
	v_mov_b32_e32 v91, v0
	v_mov_b32_e32 v92, v0
	v_mov_b32_e32 v93, v0
	v_mov_b32_e32 v94, v0
	v_mov_b32_e32 v95, v0
	v_mov_b32_e32 v104, v0
	v_mov_b32_e32 v105, v0
	v_mov_b32_e32 v106, v0
	v_mov_b32_e32 v107, v0
	v_mov_b32_e32 v108, v0
	v_mov_b32_e32 v109, v0
	v_mov_b32_e32 v110, v0
	v_mov_b32_e32 v111, v0
	v_mov_b32_e32 v120, v0
	v_mov_b32_e32 v121, v0
	v_mov_b32_e32 v122, v0
	v_mov_b32_e32 v123, v0
	v_mov_b32_e32 v124, v0
	v_mov_b32_e32 v125, v0
	v_mov_b32_e32 v126, v0
	v_mov_b32_e32 v127, v0
	s_cmp_eq_u32 s98, 0
	s_cbranch_scc1 .LBB0_1331
	ds_read_b128 v[152:155], v149
	ds_read_b128 v[156:159], v149 offset:1024
	ds_read_b128 v[160:163], v149 offset:2048
	ds_read_b128 v[164:167], v149 offset:3072
	ds_read_b128 v[168:171], v150
	ds_read_b128 v[172:175], v150 offset:1024
	ds_read_b128 v[176:179], v150 offset:2048
	ds_read_b128 v[180:183], v150 offset:3072
	s_add_u32 s26, s24, 0xfffc0080
	s_addc_u32 s27, s25, -1
	s_cmp_eq_u32 s52, 12
	s_cselect_b32 s29, s17, s27
	s_cselect_b32 s28, s48, s26
	s_cselect_b32 s27, s15, s51
	s_cselect_b32 s26, s49, s50
	v_lshl_add_u64 v[144:145], s[24:25], 0, v[136:137]
	s_add_i32 m0, s23, 0xc000
	ds_read_b128 v[184:187], v151
	ds_read_b128 v[188:191], v151 offset:1024
	ds_read_b128 v[192:195], v151 offset:2048
	ds_read_b128 v[196:199], v151 offset:3072
	ds_read_b128 v[200:203], v151 offset:4096
	ds_read_b128 v[204:207], v151 offset:5120
	ds_read_b128 v[208:211], v151 offset:6144
	ds_read_b128 v[212:215], v151 offset:7168
	global_load_lds_dwordx4 v[144:145], off
	v_lshl_add_u64 v[144:145], s[24:25], 0, v[138:139]
	s_add_i32 m0, s23, 0xe000
	s_nop 0
	global_load_lds_dwordx4 v[144:145], off
	s_waitcnt vmcnt(16)
	s_waitcnt lgkmcnt(0)
	s_barrier
	s_setprio 1
	s_waitcnt lgkmcnt(0)
	v_mfma_f32_16x16x32_bf16 v[124:127], v[152:155], v[184:187], v[124:127]
	v_mfma_f32_16x16x32_bf16 v[120:123], v[160:163], v[184:187], v[120:123]
	v_mfma_f32_16x16x32_bf16 v[108:111], v[152:155], v[192:195], v[108:111]
	v_mfma_f32_16x16x32_bf16 v[104:107], v[160:163], v[192:195], v[104:107]
	v_mfma_f32_16x16x32_bf16 v[92:95], v[152:155], v[200:203], v[92:95]
	v_mfma_f32_16x16x32_bf16 v[88:91], v[160:163], v[200:203], v[88:91]
	v_mfma_f32_16x16x32_bf16 v[76:79], v[152:155], v[208:211], v[76:79]
	v_mfma_f32_16x16x32_bf16 v[72:75], v[160:163], v[208:211], v[72:75]
	v_mfma_f32_16x16x32_bf16 v[124:127], v[156:159], v[188:191], v[124:127]
	v_mfma_f32_16x16x32_bf16 v[120:123], v[164:167], v[188:191], v[120:123]
	v_mfma_f32_16x16x32_bf16 v[108:111], v[156:159], v[196:199], v[108:111]
	v_mfma_f32_16x16x32_bf16 v[104:107], v[164:167], v[196:199], v[104:107]
	v_mfma_f32_16x16x32_bf16 v[92:95], v[156:159], v[204:207], v[92:95]
	v_mfma_f32_16x16x32_bf16 v[88:91], v[164:167], v[204:207], v[88:91]
	v_mfma_f32_16x16x32_bf16 v[76:79], v[156:159], v[212:215], v[76:79]
	v_mfma_f32_16x16x32_bf16 v[72:75], v[164:167], v[212:215], v[72:75]
	s_setprio 0
	s_setprio 1
	v_mfma_f32_16x16x32_bf16 v[116:119], v[168:171], v[184:187], v[116:119]
	v_mfma_f32_16x16x32_bf16 v[112:115], v[176:179], v[184:187], v[112:115]
	v_mfma_f32_16x16x32_bf16 v[100:103], v[168:171], v[192:195], v[100:103]
	v_mfma_f32_16x16x32_bf16 v[96:99], v[176:179], v[192:195], v[96:99]
	v_mfma_f32_16x16x32_bf16 v[84:87], v[168:171], v[200:203], v[84:87]
	v_mfma_f32_16x16x32_bf16 v[80:83], v[176:179], v[200:203], v[80:83]
	v_mfma_f32_16x16x32_bf16 v[68:71], v[168:171], v[208:211], v[68:71]
	v_mfma_f32_16x16x32_bf16 v[64:67], v[176:179], v[208:211], v[64:67]
	v_mfma_f32_16x16x32_bf16 v[116:119], v[172:175], v[188:191], v[116:119]
	v_mfma_f32_16x16x32_bf16 v[112:115], v[180:183], v[188:191], v[112:115]
	v_mfma_f32_16x16x32_bf16 v[100:103], v[172:175], v[196:199], v[100:103]
	v_mfma_f32_16x16x32_bf16 v[96:99], v[180:183], v[196:199], v[96:99]
	v_mfma_f32_16x16x32_bf16 v[84:87], v[172:175], v[204:207], v[84:87]
	v_mfma_f32_16x16x32_bf16 v[80:83], v[180:183], v[204:207], v[80:83]
	v_mfma_f32_16x16x32_bf16 v[68:71], v[172:175], v[212:215], v[68:71]
	v_mfma_f32_16x16x32_bf16 v[64:67], v[180:183], v[212:215], v[64:67]
	s_setprio 0
	s_barrier
	s_add_i32 s53, s45, s34
	v_lshl_add_u64 v[144:145], s[26:27], 0, v[132:133]
	s_mov_b32 m0, s53
	ds_read_b128 v[184:187], v151 offset:16384
	ds_read_b128 v[188:191], v151 offset:17408
	ds_read_b128 v[192:195], v151 offset:18432
	ds_read_b128 v[196:199], v151 offset:19456
	ds_read_b128 v[200:203], v151 offset:20480
	ds_read_b128 v[204:207], v151 offset:21504
	ds_read_b128 v[208:211], v151 offset:22528
	ds_read_b128 v[212:215], v151 offset:23552
	global_load_lds_dwordx4 v[144:145], off
	s_add_i32 m0, s53, 0x2000
	s_add_u32 s54, s26, 0x40000
	v_lshl_add_u64 v[216:217], s[26:27], 0, v[128:129]
	s_addc_u32 s55, s27, 0
	s_add_i32 s53, s46, s34
	global_load_lds_dwordx4 v[216:217], off
	v_lshl_add_u64 v[218:219], s[54:55], 0, v[132:133]
	s_mov_b32 m0, s53
	v_lshl_add_u64 v[220:221], s[28:29], 0, v[130:131]
	global_load_lds_dwordx4 v[218:219], off
	v_lshl_add_u64 v[218:219], s[54:55], 0, v[128:129]
	s_add_i32 m0, s53, 0x2000
	s_nop 0
	global_load_lds_dwordx4 v[218:219], off
	v_lshl_add_u64 v[218:219], s[28:29], 0, v[134:135]
	s_mov_b32 m0, s23
	s_nop 0
	global_load_lds_dwordx4 v[218:219], off
	s_mov_b32 m0, s37
	s_nop 0
	global_load_lds_dwordx4 v[220:221], off
	s_waitcnt vmcnt(16)
	s_waitcnt lgkmcnt(0)
	s_barrier
	s_setprio 1
	s_waitcnt lgkmcnt(0)
	v_mfma_f32_16x16x32_bf16 v[60:63], v[152:155], v[184:187], v[60:63]
	v_mfma_f32_16x16x32_bf16 v[56:59], v[160:163], v[184:187], v[56:59]
	v_mfma_f32_16x16x32_bf16 v[44:47], v[152:155], v[192:195], v[44:47]
	v_mfma_f32_16x16x32_bf16 v[40:43], v[160:163], v[192:195], v[40:43]
	v_mfma_f32_16x16x32_bf16 v[28:31], v[152:155], v[200:203], v[28:31]
	v_mfma_f32_16x16x32_bf16 v[24:27], v[160:163], v[200:203], v[24:27]
	v_mfma_f32_16x16x32_bf16 v[12:15], v[152:155], v[208:211], v[12:15]
	v_mfma_f32_16x16x32_bf16 v[8:11], v[160:163], v[208:211], v[8:11]
	v_mfma_f32_16x16x32_bf16 v[60:63], v[156:159], v[188:191], v[60:63]
	v_mfma_f32_16x16x32_bf16 v[56:59], v[164:167], v[188:191], v[56:59]
	v_mfma_f32_16x16x32_bf16 v[44:47], v[156:159], v[196:199], v[44:47]
	v_mfma_f32_16x16x32_bf16 v[40:43], v[164:167], v[196:199], v[40:43]
	v_mfma_f32_16x16x32_bf16 v[28:31], v[156:159], v[204:207], v[28:31]
	v_mfma_f32_16x16x32_bf16 v[24:27], v[164:167], v[204:207], v[24:27]
	v_mfma_f32_16x16x32_bf16 v[12:15], v[156:159], v[212:215], v[12:15]
	v_mfma_f32_16x16x32_bf16 v[8:11], v[164:167], v[212:215], v[8:11]
	s_setprio 0
	s_setprio 1
	v_mfma_f32_16x16x32_bf16 v[52:55], v[168:171], v[184:187], v[52:55]
	v_mfma_f32_16x16x32_bf16 v[48:51], v[176:179], v[184:187], v[48:51]
	v_mfma_f32_16x16x32_bf16 v[36:39], v[168:171], v[192:195], v[36:39]
	v_mfma_f32_16x16x32_bf16 v[32:35], v[176:179], v[192:195], v[32:35]
	v_mfma_f32_16x16x32_bf16 v[20:23], v[168:171], v[200:203], v[20:23]
	v_mfma_f32_16x16x32_bf16 v[16:19], v[176:179], v[200:203], v[16:19]
	v_mfma_f32_16x16x32_bf16 v[4:7], v[168:171], v[208:211], v[4:7]
	v_mfma_f32_16x16x32_bf16 v[0:3], v[176:179], v[208:211], v[0:3]
	v_mfma_f32_16x16x32_bf16 v[52:55], v[172:175], v[188:191], v[52:55]
	v_mfma_f32_16x16x32_bf16 v[48:51], v[180:183], v[188:191], v[48:51]
	v_mfma_f32_16x16x32_bf16 v[36:39], v[172:175], v[196:199], v[36:39]
	v_mfma_f32_16x16x32_bf16 v[32:35], v[180:183], v[196:199], v[32:35]
	v_mfma_f32_16x16x32_bf16 v[20:23], v[172:175], v[204:207], v[20:23]
	v_mfma_f32_16x16x32_bf16 v[16:19], v[180:183], v[204:207], v[16:19]
	v_mfma_f32_16x16x32_bf16 v[4:7], v[172:175], v[212:215], v[4:7]
	v_mfma_f32_16x16x32_bf16 v[0:3], v[180:183], v[212:215], v[0:3]
	s_setprio 0
	s_barrier
	s_add_i32 s53, 0, 0x18000
	s_add_i32 s54, 0, 0x1c000
	v_add_u32_e32 v164, s53, v147
	v_add_u32_e32 v180, s54, v147
	ds_read_b128 v[152:155], v164
	ds_read_b128 v[156:159], v164 offset:1024
	ds_read_b128 v[160:163], v164 offset:2048
	ds_read_b128 v[164:167], v164 offset:3072
	ds_read_b128 v[168:171], v180
	ds_read_b128 v[172:175], v180 offset:1024
	ds_read_b128 v[176:179], v180 offset:2048
	ds_read_b128 v[180:183], v180 offset:3072
	s_add_u32 s28, s28, 0x40000
	s_addc_u32 s29, s29, 0
	s_mov_b32 m0, s38
	v_lshl_add_u64 v[222:223], s[28:29], 0, v[134:135]
	ds_read_b128 v[184:187], v151 offset:32768
	ds_read_b128 v[188:191], v151 offset:33792
	ds_read_b128 v[192:195], v151 offset:34816
	ds_read_b128 v[196:199], v151 offset:35840
	ds_read_b128 v[200:203], v151 offset:36864
	ds_read_b128 v[204:207], v151 offset:37888
	ds_read_b128 v[208:211], v151 offset:38912
	ds_read_b128 v[212:215], v151 offset:39936
	global_load_lds_dwordx4 v[222:223], off
	v_lshl_add_u64 v[222:223], s[28:29], 0, v[130:131]
	s_mov_b32 m0, s39
	s_nop 0
	global_load_lds_dwordx4 v[222:223], off
	s_waitcnt vmcnt(8)
	s_waitcnt lgkmcnt(0)
	s_barrier
	s_setprio 1
	s_waitcnt lgkmcnt(0)
	v_mfma_f32_16x16x32_bf16 v[124:127], v[152:155], v[184:187], v[124:127]
	v_mfma_f32_16x16x32_bf16 v[120:123], v[160:163], v[184:187], v[120:123]
	v_mfma_f32_16x16x32_bf16 v[108:111], v[152:155], v[192:195], v[108:111]
	v_mfma_f32_16x16x32_bf16 v[104:107], v[160:163], v[192:195], v[104:107]
	v_mfma_f32_16x16x32_bf16 v[92:95], v[152:155], v[200:203], v[92:95]
	v_mfma_f32_16x16x32_bf16 v[88:91], v[160:163], v[200:203], v[88:91]
	v_mfma_f32_16x16x32_bf16 v[76:79], v[152:155], v[208:211], v[76:79]
	v_mfma_f32_16x16x32_bf16 v[72:75], v[160:163], v[208:211], v[72:75]
	v_mfma_f32_16x16x32_bf16 v[124:127], v[156:159], v[188:191], v[124:127]
	v_mfma_f32_16x16x32_bf16 v[120:123], v[164:167], v[188:191], v[120:123]
	v_mfma_f32_16x16x32_bf16 v[108:111], v[156:159], v[196:199], v[108:111]
	v_mfma_f32_16x16x32_bf16 v[104:107], v[164:167], v[196:199], v[104:107]
	v_mfma_f32_16x16x32_bf16 v[92:95], v[156:159], v[204:207], v[92:95]
	v_mfma_f32_16x16x32_bf16 v[88:91], v[164:167], v[204:207], v[88:91]
	v_mfma_f32_16x16x32_bf16 v[76:79], v[156:159], v[212:215], v[76:79]
	v_mfma_f32_16x16x32_bf16 v[72:75], v[164:167], v[212:215], v[72:75]
	s_setprio 0
	s_setprio 1
	v_mfma_f32_16x16x32_bf16 v[116:119], v[168:171], v[184:187], v[116:119]
	v_mfma_f32_16x16x32_bf16 v[112:115], v[176:179], v[184:187], v[112:115]
	v_mfma_f32_16x16x32_bf16 v[100:103], v[168:171], v[192:195], v[100:103]
	v_mfma_f32_16x16x32_bf16 v[96:99], v[176:179], v[192:195], v[96:99]
	v_mfma_f32_16x16x32_bf16 v[84:87], v[168:171], v[200:203], v[84:87]
	v_mfma_f32_16x16x32_bf16 v[80:83], v[176:179], v[200:203], v[80:83]
	v_mfma_f32_16x16x32_bf16 v[68:71], v[168:171], v[208:211], v[68:71]
	v_mfma_f32_16x16x32_bf16 v[64:67], v[176:179], v[208:211], v[64:67]
	v_mfma_f32_16x16x32_bf16 v[116:119], v[172:175], v[188:191], v[116:119]
	v_mfma_f32_16x16x32_bf16 v[112:115], v[180:183], v[188:191], v[112:115]
	v_mfma_f32_16x16x32_bf16 v[100:103], v[172:175], v[196:199], v[100:103]
	v_mfma_f32_16x16x32_bf16 v[96:99], v[180:183], v[196:199], v[96:99]
	v_mfma_f32_16x16x32_bf16 v[84:87], v[172:175], v[204:207], v[84:87]
	v_mfma_f32_16x16x32_bf16 v[80:83], v[180:183], v[204:207], v[80:83]
	v_mfma_f32_16x16x32_bf16 v[68:71], v[172:175], v[212:215], v[68:71]
	v_mfma_f32_16x16x32_bf16 v[64:67], v[180:183], v[212:215], v[64:67]
	s_setprio 0
	s_barrier
	s_add_i32 s28, s53, s34
	v_lshl_add_u64 v[144:145], v[144:145], 0, s[10:11]
	s_mov_b32 m0, s28
	ds_read_b128 v[184:187], v151 offset:49152
	ds_read_b128 v[188:191], v151 offset:50176
	ds_read_b128 v[192:195], v151 offset:51200
	ds_read_b128 v[196:199], v151 offset:52224
	ds_read_b128 v[200:203], v151 offset:53248
	ds_read_b128 v[204:207], v151 offset:54272
	ds_read_b128 v[208:211], v151 offset:55296
	ds_read_b128 v[212:215], v151 offset:56320
	global_load_lds_dwordx4 v[144:145], off
	s_add_i32 m0, s28, 0x2000
	s_add_u32 s26, s26, 0x40080
	v_lshl_add_u64 v[144:145], v[216:217], 0, s[10:11]
	s_addc_u32 s27, s27, 0
	s_add_i32 s28, s54, s34
	global_load_lds_dwordx4 v[144:145], off
	v_lshl_add_u64 v[144:145], s[26:27], 0, v[132:133]
	s_mov_b32 m0, s28
	s_nop 0
	global_load_lds_dwordx4 v[144:145], off
	v_lshl_add_u64 v[144:145], s[26:27], 0, v[128:129]
	s_add_i32 m0, s28, 0x2000
	s_nop 0
	global_load_lds_dwordx4 v[144:145], off
	v_lshl_add_u64 v[144:145], v[218:219], 0, s[10:11]
	s_mov_b32 m0, s41
	s_nop 0
	global_load_lds_dwordx4 v[144:145], off
	v_lshl_add_u64 v[144:145], v[220:221], 0, s[10:11]
	s_mov_b32 m0, s42
	s_nop 0
	global_load_lds_dwordx4 v[144:145], off
	s_waitcnt vmcnt(8)
	s_waitcnt lgkmcnt(0)
	s_barrier
	s_setprio 1
	s_waitcnt lgkmcnt(0)
	v_mfma_f32_16x16x32_bf16 v[60:63], v[152:155], v[184:187], v[60:63]
	v_mfma_f32_16x16x32_bf16 v[56:59], v[160:163], v[184:187], v[56:59]
	v_mfma_f32_16x16x32_bf16 v[44:47], v[152:155], v[192:195], v[44:47]
	v_mfma_f32_16x16x32_bf16 v[40:43], v[160:163], v[192:195], v[40:43]
	v_mfma_f32_16x16x32_bf16 v[28:31], v[152:155], v[200:203], v[28:31]
	v_mfma_f32_16x16x32_bf16 v[24:27], v[160:163], v[200:203], v[24:27]
	v_mfma_f32_16x16x32_bf16 v[12:15], v[152:155], v[208:211], v[12:15]
	v_mfma_f32_16x16x32_bf16 v[8:11], v[160:163], v[208:211], v[8:11]
	v_mfma_f32_16x16x32_bf16 v[60:63], v[156:159], v[188:191], v[60:63]
	v_mfma_f32_16x16x32_bf16 v[56:59], v[164:167], v[188:191], v[56:59]
	v_mfma_f32_16x16x32_bf16 v[44:47], v[156:159], v[196:199], v[44:47]
	v_mfma_f32_16x16x32_bf16 v[40:43], v[164:167], v[196:199], v[40:43]
	v_mfma_f32_16x16x32_bf16 v[28:31], v[156:159], v[204:207], v[28:31]
	v_mfma_f32_16x16x32_bf16 v[24:27], v[164:167], v[204:207], v[24:27]
	v_mfma_f32_16x16x32_bf16 v[12:15], v[156:159], v[212:215], v[12:15]
	v_mfma_f32_16x16x32_bf16 v[8:11], v[164:167], v[212:215], v[8:11]
	s_setprio 0
	s_setprio 1
	v_mfma_f32_16x16x32_bf16 v[52:55], v[168:171], v[184:187], v[52:55]
	v_mfma_f32_16x16x32_bf16 v[48:51], v[176:179], v[184:187], v[48:51]
	v_mfma_f32_16x16x32_bf16 v[36:39], v[168:171], v[192:195], v[36:39]
	v_mfma_f32_16x16x32_bf16 v[32:35], v[176:179], v[192:195], v[32:35]
	v_mfma_f32_16x16x32_bf16 v[20:23], v[168:171], v[200:203], v[20:23]
	v_mfma_f32_16x16x32_bf16 v[16:19], v[176:179], v[200:203], v[16:19]
	v_mfma_f32_16x16x32_bf16 v[4:7], v[168:171], v[208:211], v[4:7]
	v_mfma_f32_16x16x32_bf16 v[0:3], v[176:179], v[208:211], v[0:3]
	v_mfma_f32_16x16x32_bf16 v[52:55], v[172:175], v[188:191], v[52:55]
	v_mfma_f32_16x16x32_bf16 v[48:51], v[180:183], v[188:191], v[48:51]
	v_mfma_f32_16x16x32_bf16 v[36:39], v[172:175], v[196:199], v[36:39]
	v_mfma_f32_16x16x32_bf16 v[32:35], v[180:183], v[196:199], v[32:35]
	v_mfma_f32_16x16x32_bf16 v[20:23], v[172:175], v[204:207], v[20:23]
	v_mfma_f32_16x16x32_bf16 v[16:19], v[180:183], v[204:207], v[16:19]
	v_mfma_f32_16x16x32_bf16 v[4:7], v[172:175], v[212:215], v[4:7]
	v_mfma_f32_16x16x32_bf16 v[0:3], v[180:183], v[212:215], v[0:3]
	s_setprio 0
	s_barrier
	s_add_i32 s52, s52, 2
	s_add_u32 s24, s24, 0x100
	s_addc_u32 s25, s25, 0
	s_add_u32 s50, s50, 0x100
	s_addc_u32 s51, s51, 0
	s_cmp_gt_u32 s52, 13
	s_cbranch_scc0 .LBB0_1331
	s_branch .Lpeel_exit_P13

.LBB0_1334:
	v_mul_f32_e32 v144, 0xbfb8aa3b, v124
	v_exp_f32_e32 v144, v144
	v_mul_f32_e32 v145, 0xbfb8aa3b, v125
	v_exp_f32_e32 v145, v145
	v_mul_f32_e32 v153, 0xbfb8aa3b, v126
	v_add_f32_e32 v144, 1.0, v144
	v_rcp_f32_e32 v156, v144
	v_add_f32_e32 v144, 1.0, v145
	v_rcp_f32_e32 v157, v144
	v_exp_f32_e32 v153, v153
	v_lshl_or_b32 v154, s2, 7, v148
	v_lshl_add_u32 v152, s22, 8, v146
	v_pk_mul_f32 v[124:125], v[124:125], v[156:157]
	v_mul_f32_e32 v156, 0xbfb8aa3b, v127
	v_exp_f32_e32 v156, v156
	v_pk_mul_f32 v[116:117], v[124:125], v[116:117]
	v_add_f32_e32 v124, 1.0, v153
	v_mul_f32_e32 v153, 0xbfb8aa3b, v120
	v_add_f32_e32 v125, 1.0, v156
	v_rcp_f32_e32 v124, v124
	v_rcp_f32_e32 v125, v125
	v_exp_f32_e32 v153, v153
	v_mul_f32_e32 v156, 0xbfb8aa3b, v121
	v_exp_f32_e32 v156, v156
	v_pk_mul_f32 v[124:125], v[126:127], v[124:125]
	v_add_f32_e32 v126, 1.0, v153
	v_mul_f32_e32 v153, 0xbfb8aa3b, v122
	v_add_f32_e32 v127, 1.0, v156
	v_exp_f32_e32 v153, v153
	v_mul_f32_e32 v156, 0xbfb8aa3b, v123
	v_exp_f32_e32 v157, v156
	v_rcp_f32_e32 v126, v126
	v_add_f32_e32 v153, 1.0, v153
	v_rcp_f32_e32 v127, v127
	v_rcp_f32_e32 v156, v153
	v_add_f32_e32 v153, 1.0, v157
	v_rcp_f32_e32 v157, v153
	v_pk_mul_f32 v[120:121], v[120:121], v[126:127]
	v_pk_mul_f32 v[118:119], v[124:125], v[118:119]
	v_pk_mul_f32 v[120:121], v[120:121], v[112:113]
	v_pk_mul_f32 v[112:113], v[122:123], v[156:157]
	v_ashrrev_i32_e32 v155, 31, v154
	v_pk_mul_f32 v[122:123], v[112:113], v[114:115]
	v_cvt_pk_bf16_f32 v115, v118, v119
	v_mul_f32_e32 v118, 0xbfb8aa3b, v108
	v_mul_f32_e32 v119, 0xbfb8aa3b, v109
	v_exp_f32_e32 v118, v118
	v_exp_f32_e32 v119, v119
	v_mov_b64_e32 v[144:145], s[8:9]
	v_mad_i64_i32 v[158:159], s[24:25], v152, s47, v[144:145]
	v_lshlrev_b64 v[112:113], 1, v[154:155]
	v_lshl_add_u64 v[124:125], v[158:159], 0, v[112:113]
	v_cvt_pk_bf16_f32 v114, v116, v117
	v_cvt_pk_bf16_f32 v116, v120, v121
	v_cvt_pk_bf16_f32 v117, v122, v123
	global_store_dwordx4 v[124:125], v[114:117], off
	s_andn2_b64 vcc, exec, s[6:7]
	s_mov_b64 s[6:7], -1
	v_add_f32_e32 v114, 1.0, v118
	v_add_f32_e32 v115, 1.0, v119
	v_rcp_f32_e32 v114, v114
	v_rcp_f32_e32 v115, v115
	v_or_b32_e32 v116, 16, v152
	v_mad_i64_i32 v[116:117], s[24:25], v116, s47, v[144:145]
	v_pk_mul_f32 v[108:109], v[108:109], v[114:115]
	v_mul_f32_e32 v114, 0xbfb8aa3b, v110
	v_mul_f32_e32 v115, 0xbfb8aa3b, v111
	v_exp_f32_e32 v114, v114
	v_exp_f32_e32 v115, v115
	v_pk_mul_f32 v[100:101], v[108:109], v[100:101]
	v_add_f32_e32 v108, 1.0, v114
	v_add_f32_e32 v109, 1.0, v115
	v_mul_f32_e32 v114, 0xbfb8aa3b, v104
	v_mul_f32_e32 v115, 0xbfb8aa3b, v105
	v_rcp_f32_e32 v108, v108
	v_rcp_f32_e32 v109, v109
	v_exp_f32_e32 v114, v114
	v_exp_f32_e32 v115, v115
	v_pk_mul_f32 v[108:109], v[110:111], v[108:109]
	v_add_f32_e32 v110, 1.0, v114
	v_add_f32_e32 v111, 1.0, v115
	v_mul_f32_e32 v114, 0xbfb8aa3b, v106
	v_mul_f32_e32 v115, 0xbfb8aa3b, v107
	v_exp_f32_e32 v114, v114
	v_exp_f32_e32 v115, v115
	v_rcp_f32_e32 v110, v110
	v_rcp_f32_e32 v111, v111
	v_add_f32_e32 v114, 1.0, v114
	v_add_f32_e32 v115, 1.0, v115
	v_rcp_f32_e32 v114, v114
	v_rcp_f32_e32 v115, v115
	v_pk_mul_f32 v[104:105], v[104:105], v[110:111]
	v_pk_mul_f32 v[102:103], v[108:109], v[102:103]
	v_pk_mul_f32 v[104:105], v[104:105], v[96:97]
	v_pk_mul_f32 v[96:97], v[106:107], v[114:115]
	v_lshl_add_u64 v[108:109], v[116:117], 0, v[112:113]
	v_pk_mul_f32 v[106:107], v[96:97], v[98:99]
	v_cvt_pk_bf16_f32 v96, v100, v101
	v_mul_f32_e32 v100, 0xbfb8aa3b, v92
	v_mul_f32_e32 v101, 0xbfb8aa3b, v93
	v_exp_f32_e32 v100, v100
	v_exp_f32_e32 v101, v101
	v_cvt_pk_bf16_f32 v97, v102, v103
	v_cvt_pk_bf16_f32 v98, v104, v105
	v_cvt_pk_bf16_f32 v99, v106, v107
	global_store_dwordx4 v[108:109], v[96:99], off
	s_nop 1
	v_add_f32_e32 v96, 1.0, v100
	v_add_f32_e32 v97, 1.0, v101
	v_rcp_f32_e32 v96, v96
	v_rcp_f32_e32 v97, v97
	v_or_b32_e32 v98, 32, v152
	v_mad_i64_i32 v[98:99], s[24:25], v98, s47, v[144:145]
	v_pk_mul_f32 v[92:93], v[92:93], v[96:97]
	v_mul_f32_e32 v96, 0xbfb8aa3b, v94
	v_mul_f32_e32 v97, 0xbfb8aa3b, v95
	v_exp_f32_e32 v96, v96
	v_exp_f32_e32 v97, v97
	v_pk_mul_f32 v[84:85], v[92:93], v[84:85]
	v_add_f32_e32 v92, 1.0, v96
	v_add_f32_e32 v93, 1.0, v97
	v_mul_f32_e32 v96, 0xbfb8aa3b, v88
	v_mul_f32_e32 v97, 0xbfb8aa3b, v89
	v_rcp_f32_e32 v92, v92
	v_rcp_f32_e32 v93, v93
	v_exp_f32_e32 v96, v96
	v_exp_f32_e32 v97, v97
	v_pk_mul_f32 v[92:93], v[94:95], v[92:93]
	v_add_f32_e32 v94, 1.0, v96
	v_add_f32_e32 v95, 1.0, v97
	v_mul_f32_e32 v96, 0xbfb8aa3b, v90
	v_mul_f32_e32 v97, 0xbfb8aa3b, v91
	v_exp_f32_e32 v96, v96
	v_exp_f32_e32 v97, v97
	v_rcp_f32_e32 v94, v94
	v_rcp_f32_e32 v95, v95
	v_add_f32_e32 v96, 1.0, v96
	v_add_f32_e32 v97, 1.0, v97
	v_rcp_f32_e32 v96, v96
	v_rcp_f32_e32 v97, v97
	v_pk_mul_f32 v[88:89], v[88:89], v[94:95]
	v_pk_mul_f32 v[86:87], v[92:93], v[86:87]
	v_pk_mul_f32 v[88:89], v[88:89], v[80:81]
	v_pk_mul_f32 v[80:81], v[90:91], v[96:97]
	v_lshl_add_u64 v[92:93], v[98:99], 0, v[112:113]
	v_pk_mul_f32 v[90:91], v[80:81], v[82:83]
	v_cvt_pk_bf16_f32 v80, v84, v85
	v_mul_f32_e32 v84, 0xbfb8aa3b, v76
	v_mul_f32_e32 v85, 0xbfb8aa3b, v77
	v_exp_f32_e32 v84, v84
	v_exp_f32_e32 v85, v85
	v_cvt_pk_bf16_f32 v81, v86, v87
	v_cvt_pk_bf16_f32 v82, v88, v89
	v_cvt_pk_bf16_f32 v83, v90, v91
	global_store_dwordx4 v[92:93], v[80:83], off
	s_nop 1
	v_add_f32_e32 v80, 1.0, v84
	v_add_f32_e32 v81, 1.0, v85
	v_rcp_f32_e32 v80, v80
	v_rcp_f32_e32 v81, v81
	v_or_b32_e32 v82, 48, v152
	v_mad_i64_i32 v[82:83], s[24:25], v82, s47, v[144:145]
	v_pk_mul_f32 v[76:77], v[76:77], v[80:81]
	v_mul_f32_e32 v80, 0xbfb8aa3b, v78
	v_mul_f32_e32 v81, 0xbfb8aa3b, v79
	v_exp_f32_e32 v80, v80
	v_exp_f32_e32 v81, v81
	v_pk_mul_f32 v[68:69], v[76:77], v[68:69]
	v_add_f32_e32 v76, 1.0, v80
	v_add_f32_e32 v77, 1.0, v81
	v_mul_f32_e32 v80, 0xbfb8aa3b, v72
	v_mul_f32_e32 v81, 0xbfb8aa3b, v73
	v_rcp_f32_e32 v76, v76
	v_rcp_f32_e32 v77, v77
	v_exp_f32_e32 v80, v80
	v_exp_f32_e32 v81, v81
	v_pk_mul_f32 v[76:77], v[78:79], v[76:77]
	v_add_f32_e32 v78, 1.0, v80
	v_add_f32_e32 v79, 1.0, v81
	v_mul_f32_e32 v80, 0xbfb8aa3b, v74
	v_mul_f32_e32 v81, 0xbfb8aa3b, v75
	v_exp_f32_e32 v80, v80
	v_exp_f32_e32 v81, v81
	v_rcp_f32_e32 v78, v78
	v_rcp_f32_e32 v79, v79
	v_add_f32_e32 v80, 1.0, v80
	v_add_f32_e32 v81, 1.0, v81
	v_rcp_f32_e32 v80, v80
	v_rcp_f32_e32 v81, v81
	v_pk_mul_f32 v[72:73], v[72:73], v[78:79]
	v_pk_mul_f32 v[70:71], v[76:77], v[70:71]
	v_pk_mul_f32 v[72:73], v[72:73], v[64:65]
	v_pk_mul_f32 v[64:65], v[74:75], v[80:81]
	v_lshl_add_u64 v[76:77], v[82:83], 0, v[112:113]
	v_pk_mul_f32 v[74:75], v[64:65], v[66:67]
	v_cvt_pk_bf16_f32 v64, v68, v69
	v_mul_f32_e32 v68, 0xbfb8aa3b, v60
	v_mul_f32_e32 v69, 0xbfb8aa3b, v61
	v_exp_f32_e32 v68, v68
	v_exp_f32_e32 v69, v69
	v_cvt_pk_bf16_f32 v65, v70, v71
	v_cvt_pk_bf16_f32 v66, v72, v73
	v_cvt_pk_bf16_f32 v67, v74, v75
	global_store_dwordx4 v[76:77], v[64:67], off
	s_nop 1
	v_add_f32_e32 v64, 1.0, v68
	v_add_f32_e32 v65, 1.0, v69
	v_rcp_f32_e32 v64, v64
	v_rcp_f32_e32 v65, v65
	v_add_u32_e32 v66, 0x80, v152
	v_mad_i64_i32 v[66:67], s[24:25], v66, s47, v[144:145]
	v_pk_mul_f32 v[60:61], v[60:61], v[64:65]
	v_mul_f32_e32 v64, 0xbfb8aa3b, v62
	v_mul_f32_e32 v65, 0xbfb8aa3b, v63
	v_exp_f32_e32 v64, v64
	v_exp_f32_e32 v65, v65
	v_pk_mul_f32 v[52:53], v[60:61], v[52:53]
	v_add_f32_e32 v60, 1.0, v64
	v_add_f32_e32 v61, 1.0, v65
	v_mul_f32_e32 v64, 0xbfb8aa3b, v56
	v_mul_f32_e32 v65, 0xbfb8aa3b, v57
	v_rcp_f32_e32 v60, v60
	v_rcp_f32_e32 v61, v61
	v_exp_f32_e32 v64, v64
	v_exp_f32_e32 v65, v65
	v_pk_mul_f32 v[60:61], v[62:63], v[60:61]
	v_add_f32_e32 v62, 1.0, v64
	v_add_f32_e32 v63, 1.0, v65
	v_mul_f32_e32 v64, 0xbfb8aa3b, v58
	v_mul_f32_e32 v65, 0xbfb8aa3b, v59
	v_exp_f32_e32 v64, v64
	v_exp_f32_e32 v65, v65
	v_rcp_f32_e32 v62, v62
	v_rcp_f32_e32 v63, v63
	v_add_f32_e32 v64, 1.0, v64
	v_add_f32_e32 v65, 1.0, v65
	v_rcp_f32_e32 v64, v64
	v_rcp_f32_e32 v65, v65
	v_pk_mul_f32 v[56:57], v[56:57], v[62:63]
	v_pk_mul_f32 v[54:55], v[60:61], v[54:55]
	v_pk_mul_f32 v[56:57], v[56:57], v[48:49]
	v_pk_mul_f32 v[48:49], v[58:59], v[64:65]
	v_lshl_add_u64 v[60:61], v[66:67], 0, v[112:113]
	v_pk_mul_f32 v[58:59], v[48:49], v[50:51]
	v_cvt_pk_bf16_f32 v48, v52, v53
	v_mul_f32_e32 v52, 0xbfb8aa3b, v44
	v_mul_f32_e32 v53, 0xbfb8aa3b, v45
	v_exp_f32_e32 v52, v52
	v_exp_f32_e32 v53, v53
	v_cvt_pk_bf16_f32 v49, v54, v55
	v_cvt_pk_bf16_f32 v50, v56, v57
	v_cvt_pk_bf16_f32 v51, v58, v59
	global_store_dwordx4 v[60:61], v[48:51], off
	s_nop 1
	v_add_f32_e32 v48, 1.0, v52
	v_add_f32_e32 v49, 1.0, v53
	v_rcp_f32_e32 v48, v48
	v_rcp_f32_e32 v49, v49
	v_add_u32_e32 v50, 0x90, v152
	v_mad_i64_i32 v[50:51], s[24:25], v50, s47, v[144:145]
	v_pk_mul_f32 v[44:45], v[44:45], v[48:49]
	v_mul_f32_e32 v48, 0xbfb8aa3b, v46
	v_mul_f32_e32 v49, 0xbfb8aa3b, v47
	v_exp_f32_e32 v48, v48
	v_exp_f32_e32 v49, v49
	v_pk_mul_f32 v[36:37], v[44:45], v[36:37]
	v_add_f32_e32 v44, 1.0, v48
	v_add_f32_e32 v45, 1.0, v49
	v_mul_f32_e32 v48, 0xbfb8aa3b, v40
	v_mul_f32_e32 v49, 0xbfb8aa3b, v41
	v_rcp_f32_e32 v44, v44
	v_rcp_f32_e32 v45, v45
	v_exp_f32_e32 v48, v48
	v_exp_f32_e32 v49, v49
	v_pk_mul_f32 v[44:45], v[46:47], v[44:45]
	v_add_f32_e32 v46, 1.0, v48
	v_add_f32_e32 v47, 1.0, v49
	v_mul_f32_e32 v48, 0xbfb8aa3b, v42
	v_mul_f32_e32 v49, 0xbfb8aa3b, v43
	v_exp_f32_e32 v48, v48
	v_exp_f32_e32 v49, v49
	v_rcp_f32_e32 v46, v46
	v_rcp_f32_e32 v47, v47
	v_add_f32_e32 v48, 1.0, v48
	v_add_f32_e32 v49, 1.0, v49
	v_rcp_f32_e32 v48, v48
	v_rcp_f32_e32 v49, v49
	v_pk_mul_f32 v[40:41], v[40:41], v[46:47]
	v_pk_mul_f32 v[38:39], v[44:45], v[38:39]
	v_pk_mul_f32 v[40:41], v[40:41], v[32:33]
	v_pk_mul_f32 v[32:33], v[42:43], v[48:49]
	v_lshl_add_u64 v[44:45], v[50:51], 0, v[112:113]
	v_pk_mul_f32 v[42:43], v[32:33], v[34:35]
	v_cvt_pk_bf16_f32 v32, v36, v37
	v_mul_f32_e32 v36, 0xbfb8aa3b, v28
	v_mul_f32_e32 v37, 0xbfb8aa3b, v29
	v_exp_f32_e32 v36, v36
	v_exp_f32_e32 v37, v37
	v_cvt_pk_bf16_f32 v33, v38, v39
	v_cvt_pk_bf16_f32 v34, v40, v41
	v_cvt_pk_bf16_f32 v35, v42, v43
	global_store_dwordx4 v[44:45], v[32:35], off
	s_nop 1
	v_add_f32_e32 v32, 1.0, v36
	v_add_f32_e32 v33, 1.0, v37
	v_rcp_f32_e32 v32, v32
	v_rcp_f32_e32 v33, v33
	v_add_u32_e32 v34, 0xa0, v152
	v_mad_i64_i32 v[34:35], s[24:25], v34, s47, v[144:145]
	v_pk_mul_f32 v[28:29], v[28:29], v[32:33]
	v_mul_f32_e32 v32, 0xbfb8aa3b, v30
	v_mul_f32_e32 v33, 0xbfb8aa3b, v31
	v_exp_f32_e32 v32, v32
	v_exp_f32_e32 v33, v33
	v_pk_mul_f32 v[20:21], v[28:29], v[20:21]
	v_add_f32_e32 v28, 1.0, v32
	v_add_f32_e32 v29, 1.0, v33
	v_mul_f32_e32 v32, 0xbfb8aa3b, v24
	v_mul_f32_e32 v33, 0xbfb8aa3b, v25
	v_rcp_f32_e32 v28, v28
	v_rcp_f32_e32 v29, v29
	v_exp_f32_e32 v32, v32
	v_exp_f32_e32 v33, v33
	v_pk_mul_f32 v[28:29], v[30:31], v[28:29]
	v_add_f32_e32 v30, 1.0, v32
	v_add_f32_e32 v31, 1.0, v33
	v_mul_f32_e32 v32, 0xbfb8aa3b, v26
	v_mul_f32_e32 v33, 0xbfb8aa3b, v27
	v_exp_f32_e32 v32, v32
	v_exp_f32_e32 v33, v33
	v_rcp_f32_e32 v30, v30
	v_rcp_f32_e32 v31, v31
	v_add_f32_e32 v32, 1.0, v32
	v_add_f32_e32 v33, 1.0, v33
	v_rcp_f32_e32 v32, v32
	v_rcp_f32_e32 v33, v33
	v_pk_mul_f32 v[24:25], v[24:25], v[30:31]
	v_pk_mul_f32 v[22:23], v[28:29], v[22:23]
	v_pk_mul_f32 v[24:25], v[24:25], v[16:17]
	v_pk_mul_f32 v[16:17], v[26:27], v[32:33]
	v_lshl_add_u64 v[28:29], v[34:35], 0, v[112:113]
	v_pk_mul_f32 v[26:27], v[16:17], v[18:19]
	v_cvt_pk_bf16_f32 v16, v20, v21
	v_mul_f32_e32 v20, 0xbfb8aa3b, v12
	v_mul_f32_e32 v21, 0xbfb8aa3b, v13
	v_exp_f32_e32 v20, v20
	v_exp_f32_e32 v21, v21
	v_cvt_pk_bf16_f32 v17, v22, v23
	v_cvt_pk_bf16_f32 v18, v24, v25
	v_cvt_pk_bf16_f32 v19, v26, v27
	global_store_dwordx4 v[28:29], v[16:19], off
	s_nop 1
	v_add_f32_e32 v16, 1.0, v20
	v_add_f32_e32 v17, 1.0, v21
	v_rcp_f32_e32 v16, v16
	v_rcp_f32_e32 v17, v17
	v_add_u32_e32 v18, 0xb0, v152
	v_mad_i64_i32 v[18:19], s[24:25], v18, s47, v[144:145]
	v_pk_mul_f32 v[12:13], v[12:13], v[16:17]
	v_mul_f32_e32 v16, 0xbfb8aa3b, v14
	v_mul_f32_e32 v17, 0xbfb8aa3b, v15
	v_exp_f32_e32 v16, v16
	v_exp_f32_e32 v17, v17
	v_pk_mul_f32 v[4:5], v[12:13], v[4:5]
	v_add_f32_e32 v12, 1.0, v16
	v_add_f32_e32 v13, 1.0, v17
	v_mul_f32_e32 v16, 0xbfb8aa3b, v8
	v_mul_f32_e32 v17, 0xbfb8aa3b, v9
	v_rcp_f32_e32 v12, v12
	v_rcp_f32_e32 v13, v13
	v_exp_f32_e32 v16, v16
	v_exp_f32_e32 v17, v17
	v_pk_mul_f32 v[12:13], v[14:15], v[12:13]
	v_add_f32_e32 v14, 1.0, v16
	v_add_f32_e32 v15, 1.0, v17
	v_mul_f32_e32 v16, 0xbfb8aa3b, v10
	v_mul_f32_e32 v17, 0xbfb8aa3b, v11
	v_exp_f32_e32 v16, v16
	v_exp_f32_e32 v17, v17
	v_rcp_f32_e32 v14, v14
	v_rcp_f32_e32 v15, v15
	v_add_f32_e32 v16, 1.0, v16
	v_add_f32_e32 v17, 1.0, v17
	v_rcp_f32_e32 v16, v16
	v_rcp_f32_e32 v17, v17
	v_pk_mul_f32 v[8:9], v[8:9], v[14:15]
	v_pk_mul_f32 v[6:7], v[12:13], v[6:7]
	v_pk_mul_f32 v[8:9], v[8:9], v[0:1]
	v_pk_mul_f32 v[0:1], v[10:11], v[16:17]
	v_lshl_add_u64 v[12:13], v[18:19], 0, v[112:113]
	v_pk_mul_f32 v[10:11], v[0:1], v[2:3]
	v_cvt_pk_bf16_f32 v0, v4, v5
	v_cvt_pk_bf16_f32 v1, v6, v7
	v_cvt_pk_bf16_f32 v2, v8, v9
	v_cvt_pk_bf16_f32 v3, v10, v11
	global_store_dwordx4 v[12:13], v[0:3], off
	s_mov_b32 s98, 1
	s_cbranch_vccnz .LBB0_1327
	s_andn2_b64 vcc, exec, s[0:1]
	s_cbranch_vccnz .LBB0_1326
	s_barrier
	s_branch .LBB0_1326

.LBB0_1397:
	s_add_u32 s50, s10, 0x3018000
	s_addc_u32 s51, s11, 0
	s_lshl_b32 s7, s7, 5
	s_mov_b64 s[10:11], 0x80
	s_and_b32 s17, s7, 0x60
	s_add_i32 m0, s44, 0x18000
	v_lshl_add_u64 v[6:7], v[6:7], 0, s[10:11]
	s_lshl_b32 s16, s5, 13
	s_lshl_b32 s7, s17, 7
	s_waitcnt vmcnt(2)
	s_barrier
	global_load_lds_dwordx4 v[6:7], off
	v_lshl_add_u64 v[4:5], v[4:5], 0, s[10:11]
	s_add_i32 m0, s44, 0x1a000
	s_add_i32 s52, s44, 0x8000
	s_add_i32 s53, s44, 0xa000
	global_load_lds_dwordx4 v[4:5], off
	v_lshl_add_u64 v[0:1], v[0:1], 0, s[10:11]
	s_mov_b32 m0, s52
	s_add_u32 s14, s34, 0xb0080
	global_load_lds_dwordx4 v[0:1], off
	v_lshl_add_u64 v[0:1], v[2:3], 0, s[10:11]
	s_mov_b32 m0, s53
	s_addc_u32 s15, s35, 0
	global_load_lds_dwordx4 v[0:1], off
	s_add_i32 m0, s44, 0x1c000
	v_lshl_add_u64 v[0:1], s[14:15], 0, v[172:173]
	global_load_lds_dwordx4 v[0:1], off
	v_lshl_add_u64 v[0:1], s[14:15], 0, v[174:175]
	s_add_i32 m0, s44, 0x1e000
	s_cmpk_lt_u32 s2, 0x100
	global_load_lds_dwordx4 v[0:1], off
	v_bfe_u32 v0, v8, 4, 2
	v_and_b32_e32 v1, 15, v8
	v_lshlrev_b32_e32 v2, 4, v0
	v_lshl_or_b32 v218, s5, 6, v1
	v_lshl_or_b32 v1, v1, 6, v2
	v_lshlrev_b32_e32 v2, 2, v8
	v_and_b32_e32 v2, 32, v2
	v_bitop3_b32 v3, v1, s16, v2 bitop3:0xde
	v_bitop3_b32 v219, v1, s7, v2 bitop3:0xde
	v_lshl_or_b32 v220, v0, 2, s17
	v_lshrrev_b32_e32 v1, 1, v9
	v_mul_lo_u32 v0, v11, s4
	s_mov_b32 s2, 0xb000
	v_mad_u64_u32 v[0:1], s[16:17], v1, s2, v[0:1]
	v_or_b32_e32 v0, v0, v10
	s_sext_i32_i8 s67, s6
	s_mov_b64 s[6:7], 0xb0080
	v_add_lshl_u32 v0, v0, v12, 1
	v_mov_b32_e32 v1, v173
	v_lshl_add_u64 v[176:177], v[0:1], 0, s[6:7]
	v_lshrrev_b32_e32 v1, 1, v13
	v_mul_lo_u32 v0, v14, s4
	v_mad_u64_u32 v[0:1], s[4:5], v1, s2, v[0:1]
	s_waitcnt vmcnt(6)
	v_or_b32_e32 v0, v0, v15
	s_cselect_b64 s[14:15], -1, 0
	v_add_lshl_u32 v0, v0, v16, 1
	v_mov_b32_e32 v1, v173
	s_add_i32 s56, 0, 0x10000
	s_add_i32 s57, 0, 0x14000
	s_ashr_i32 s54, s90, 31
	s_mov_b32 s55, s90
	v_lshl_add_u64 v[178:179], v[0:1], 0, s[6:7]
	v_mov_b64_e32 v[180:181], 0x400
	v_mov_b64_e32 v[182:183], 0x3ff
	v_add_u32_e32 v221, s56, v219
	v_add_u32_e32 v222, s57, v219
	v_add_u32_e32 v223, 0, v3
	s_mov_b32 s58, 0x20000
	s_mov_b32 s59, 0x30000
	s_mov_b32 s60, 0x80000
	s_mov_b32 s61, 0x90000
	s_mov_b32 s62, 0xa0000
	s_mov_b32 s63, 0xb0000
	s_mov_b64 s[16:17], 0x10000
	s_mov_b64 s[18:19], 0x20000
	s_mov_b64 s[20:21], 0x30000
	s_mov_b64 s[22:23], 0x80000
	s_mov_b64 s[24:25], 0x90000
	s_mov_b64 s[26:27], 0xa0000
	s_barrier
	s_mov_b32 s98, 0
	s_branch .LBB0_1400

.LBB0_1410:
	s_add_u32 s2, s34, 0x100
	v_mov_b32_e32 v0, 0
	s_addc_u32 s68, s35, 0
	s_mov_b32 s69, -2
	v_mov_b32_e32 v1, v0
	v_mov_b32_e32 v2, v0
	v_mov_b32_e32 v3, v0
	v_mov_b32_e32 v16, v0
	v_mov_b32_e32 v17, v0
	v_mov_b32_e32 v18, v0
	v_mov_b32_e32 v19, v0
	v_mov_b32_e32 v4, v0
	v_mov_b32_e32 v5, v0
	v_mov_b32_e32 v6, v0
	v_mov_b32_e32 v7, v0
	v_mov_b32_e32 v24, v0
	v_mov_b32_e32 v25, v0
	v_mov_b32_e32 v26, v0
	v_mov_b32_e32 v27, v0
	v_mov_b32_e32 v8, v0
	v_mov_b32_e32 v9, v0
	v_mov_b32_e32 v10, v0
	v_mov_b32_e32 v11, v0
	v_mov_b32_e32 v32, v0
	v_mov_b32_e32 v33, v0
	v_mov_b32_e32 v34, v0
	v_mov_b32_e32 v35, v0
	v_mov_b32_e32 v12, v0
	v_mov_b32_e32 v13, v0
	v_mov_b32_e32 v14, v0
	v_mov_b32_e32 v15, v0
	v_mov_b32_e32 v40, v0
	v_mov_b32_e32 v41, v0
	v_mov_b32_e32 v42, v0
	v_mov_b32_e32 v43, v0
	v_mov_b32_e32 v60, v0
	v_mov_b32_e32 v61, v0
	v_mov_b32_e32 v62, v0
	v_mov_b32_e32 v63, v0
	v_mov_b32_e32 v92, v0
	v_mov_b32_e32 v93, v0
	v_mov_b32_e32 v94, v0
	v_mov_b32_e32 v95, v0
	v_mov_b32_e32 v68, v0
	v_mov_b32_e32 v69, v0
	v_mov_b32_e32 v70, v0
	v_mov_b32_e32 v71, v0
	v_mov_b32_e32 v100, v0
	v_mov_b32_e32 v101, v0
	v_mov_b32_e32 v102, v0
	v_mov_b32_e32 v103, v0
	v_mov_b32_e32 v72, v0
	v_mov_b32_e32 v73, v0
	v_mov_b32_e32 v74, v0
	v_mov_b32_e32 v75, v0
	v_mov_b32_e32 v104, v0
	v_mov_b32_e32 v105, v0
	v_mov_b32_e32 v106, v0
	v_mov_b32_e32 v107, v0
	v_mov_b32_e32 v76, v0
	v_mov_b32_e32 v77, v0
	v_mov_b32_e32 v78, v0
	v_mov_b32_e32 v79, v0
	v_mov_b32_e32 v108, v0
	v_mov_b32_e32 v109, v0
	v_mov_b32_e32 v110, v0
	v_mov_b32_e32 v111, v0
	v_mov_b32_e32 v20, v0
	v_mov_b32_e32 v21, v0
	v_mov_b32_e32 v22, v0
	v_mov_b32_e32 v23, v0
	v_mov_b32_e32 v48, v0
	v_mov_b32_e32 v49, v0
	v_mov_b32_e32 v50, v0
	v_mov_b32_e32 v51, v0
	v_mov_b32_e32 v28, v0
	v_mov_b32_e32 v29, v0
	v_mov_b32_e32 v30, v0
	v_mov_b32_e32 v31, v0
	v_mov_b32_e32 v52, v0
	v_mov_b32_e32 v53, v0
	v_mov_b32_e32 v54, v0
	v_mov_b32_e32 v55, v0
	v_mov_b32_e32 v36, v0
	v_mov_b32_e32 v37, v0
	v_mov_b32_e32 v38, v0
	v_mov_b32_e32 v39, v0
	v_mov_b32_e32 v56, v0
	v_mov_b32_e32 v57, v0
	v_mov_b32_e32 v58, v0
	v_mov_b32_e32 v59, v0
	v_mov_b32_e32 v44, v0
	v_mov_b32_e32 v45, v0
	v_mov_b32_e32 v46, v0
	v_mov_b32_e32 v47, v0
	v_mov_b32_e32 v64, v0
	v_mov_b32_e32 v65, v0
	v_mov_b32_e32 v66, v0
	v_mov_b32_e32 v67, v0
	v_mov_b32_e32 v80, v0
	v_mov_b32_e32 v81, v0
	v_mov_b32_e32 v82, v0
	v_mov_b32_e32 v83, v0
	v_mov_b32_e32 v112, v0
	v_mov_b32_e32 v113, v0
	v_mov_b32_e32 v114, v0
	v_mov_b32_e32 v115, v0
	v_mov_b32_e32 v84, v0
	v_mov_b32_e32 v85, v0
	v_mov_b32_e32 v86, v0
	v_mov_b32_e32 v87, v0
	v_mov_b32_e32 v116, v0
	v_mov_b32_e32 v117, v0
	v_mov_b32_e32 v118, v0
	v_mov_b32_e32 v119, v0
	v_mov_b32_e32 v88, v0
	v_mov_b32_e32 v89, v0
	v_mov_b32_e32 v90, v0
	v_mov_b32_e32 v91, v0
	v_mov_b32_e32 v120, v0
	v_mov_b32_e32 v121, v0
	v_mov_b32_e32 v122, v0
	v_mov_b32_e32 v123, v0
	v_mov_b32_e32 v96, v0
	v_mov_b32_e32 v97, v0
	v_mov_b32_e32 v98, v0
	v_mov_b32_e32 v99, v0
	v_mov_b32_e32 v124, v0
	v_mov_b32_e32 v125, v0
	v_mov_b32_e32 v126, v0
	v_mov_b32_e32 v127, v0
	s_cmp_eq_u32 s98, 0
	s_cbranch_scc1 .LBB0_1411
	ds_read_b128 v[128:131], v221
	ds_read_b128 v[132:135], v221 offset:1024
	ds_read_b128 v[136:139], v221 offset:2048
	ds_read_b128 v[140:143], v221 offset:3072
	ds_read_b128 v[144:147], v222
	ds_read_b128 v[148:151], v222 offset:1024
	ds_read_b128 v[152:155], v222 offset:2048
	ds_read_b128 v[156:159], v222 offset:3072
	s_add_u32 s34, s30, 0x100
	s_addc_u32 s35, s31, 0
	s_cmp_eq_u32 s69, 40
	s_cselect_b32 s39, s7, s35
	s_cselect_b32 s38, s6, s34
	s_cselect_b32 s37, s29, s68
	s_cselect_b32 s36, s28, s2
	v_lshl_add_u64 v[204:205], s[30:31], 0, v[176:177]
	s_add_i32 m0, s44, 0xc000
	ds_read_b128 v[160:163], v223
	ds_read_b128 v[164:167], v223 offset:1024
	ds_read_b128 v[168:171], v223 offset:2048
	ds_read_b128 v[184:187], v223 offset:3072
	ds_read_b128 v[188:191], v223 offset:4096
	ds_read_b128 v[192:195], v223 offset:5120
	ds_read_b128 v[196:199], v223 offset:6144
	ds_read_b128 v[200:203], v223 offset:7168
	global_load_lds_dwordx4 v[204:205], off
	v_lshl_add_u64 v[204:205], s[30:31], 0, v[178:179]
	s_add_i32 m0, s44, 0xe000
	s_nop 0
	global_load_lds_dwordx4 v[204:205], off
	s_waitcnt vmcnt(30)
	s_waitcnt lgkmcnt(0)
	s_barrier
	s_setprio 1
	s_waitcnt lgkmcnt(0)
	v_mfma_f32_16x16x32_bf16 v[124:127], v[128:131], v[160:163], v[124:127]
	v_mfma_f32_16x16x32_bf16 v[96:99], v[136:139], v[160:163], v[96:99]
	v_mfma_f32_16x16x32_bf16 v[120:123], v[128:131], v[168:171], v[120:123]
	v_mfma_f32_16x16x32_bf16 v[88:91], v[136:139], v[168:171], v[88:91]
	v_mfma_f32_16x16x32_bf16 v[116:119], v[128:131], v[188:191], v[116:119]
	v_mfma_f32_16x16x32_bf16 v[84:87], v[136:139], v[188:191], v[84:87]
	v_mfma_f32_16x16x32_bf16 v[112:115], v[128:131], v[196:199], v[112:115]
	v_mfma_f32_16x16x32_bf16 v[80:83], v[136:139], v[196:199], v[80:83]
	v_mfma_f32_16x16x32_bf16 v[124:127], v[132:135], v[164:167], v[124:127]
	v_mfma_f32_16x16x32_bf16 v[96:99], v[140:143], v[164:167], v[96:99]
	v_mfma_f32_16x16x32_bf16 v[120:123], v[132:135], v[184:187], v[120:123]
	v_mfma_f32_16x16x32_bf16 v[88:91], v[140:143], v[184:187], v[88:91]
	v_mfma_f32_16x16x32_bf16 v[116:119], v[132:135], v[192:195], v[116:119]
	v_mfma_f32_16x16x32_bf16 v[84:87], v[140:143], v[192:195], v[84:87]
	v_mfma_f32_16x16x32_bf16 v[112:115], v[132:135], v[200:203], v[112:115]
	v_mfma_f32_16x16x32_bf16 v[80:83], v[140:143], v[200:203], v[80:83]
	s_setprio 0
	s_setprio 1
	v_mfma_f32_16x16x32_bf16 v[64:67], v[144:147], v[160:163], v[64:67]
	v_mfma_f32_16x16x32_bf16 v[44:47], v[152:155], v[160:163], v[44:47]
	v_mfma_f32_16x16x32_bf16 v[56:59], v[144:147], v[168:171], v[56:59]
	v_mfma_f32_16x16x32_bf16 v[36:39], v[152:155], v[168:171], v[36:39]
	v_mfma_f32_16x16x32_bf16 v[52:55], v[144:147], v[188:191], v[52:55]
	v_mfma_f32_16x16x32_bf16 v[28:31], v[152:155], v[188:191], v[28:31]
	v_mfma_f32_16x16x32_bf16 v[48:51], v[144:147], v[196:199], v[48:51]
	v_mfma_f32_16x16x32_bf16 v[20:23], v[152:155], v[196:199], v[20:23]
	v_mfma_f32_16x16x32_bf16 v[64:67], v[148:151], v[164:167], v[64:67]
	v_mfma_f32_16x16x32_bf16 v[44:47], v[156:159], v[164:167], v[44:47]
	v_mfma_f32_16x16x32_bf16 v[56:59], v[148:151], v[184:187], v[56:59]
	v_mfma_f32_16x16x32_bf16 v[36:39], v[156:159], v[184:187], v[36:39]
	v_mfma_f32_16x16x32_bf16 v[52:55], v[148:151], v[192:195], v[52:55]
	v_mfma_f32_16x16x32_bf16 v[28:31], v[156:159], v[192:195], v[28:31]
	v_mfma_f32_16x16x32_bf16 v[48:51], v[148:151], v[200:203], v[48:51]
	v_mfma_f32_16x16x32_bf16 v[20:23], v[156:159], v[200:203], v[20:23]
	s_setprio 0
	s_barrier
	s_add_i32 s30, s56, s43
	v_lshl_add_u64 v[204:205], s[36:37], 0, v[172:173]
	s_mov_b32 m0, s30
	ds_read_b128 v[160:163], v223 offset:16384
	ds_read_b128 v[164:167], v223 offset:17408
	ds_read_b128 v[168:171], v223 offset:18432
	ds_read_b128 v[184:187], v223 offset:19456
	ds_read_b128 v[188:191], v223 offset:20480
	ds_read_b128 v[192:195], v223 offset:21504
	ds_read_b128 v[196:199], v223 offset:22528
	ds_read_b128 v[200:203], v223 offset:23552
	global_load_lds_dwordx4 v[204:205], off
	s_add_i32 m0, s30, 0x2000
	s_add_u32 s30, s36, 0xb0000
	v_lshl_add_u64 v[206:207], s[36:37], 0, v[174:175]
	s_addc_u32 s31, s37, 0
	s_add_i32 s70, s57, s43
	global_load_lds_dwordx4 v[206:207], off
	v_lshl_add_u64 v[208:209], s[30:31], 0, v[172:173]
	s_mov_b32 m0, s70
	v_lshl_add_u64 v[210:211], s[38:39], 0, v[174:175]
	global_load_lds_dwordx4 v[208:209], off
	v_lshl_add_u64 v[208:209], s[30:31], 0, v[174:175]
	s_add_i32 m0, s70, 0x2000
	s_nop 0
	global_load_lds_dwordx4 v[208:209], off
	v_lshl_add_u64 v[208:209], s[38:39], 0, v[172:173]
	s_mov_b32 m0, s44
	s_nop 0
	global_load_lds_dwordx4 v[208:209], off
	s_mov_b32 m0, s45
	s_nop 0
	global_load_lds_dwordx4 v[210:211], off
	s_waitcnt vmcnt(30)
	s_waitcnt lgkmcnt(0)
	s_barrier
	s_setprio 1
	s_waitcnt lgkmcnt(0)
	v_mfma_f32_16x16x32_bf16 v[108:111], v[128:131], v[160:163], v[108:111]
	v_mfma_f32_16x16x32_bf16 v[76:79], v[136:139], v[160:163], v[76:79]
	v_mfma_f32_16x16x32_bf16 v[104:107], v[128:131], v[168:171], v[104:107]
	v_mfma_f32_16x16x32_bf16 v[72:75], v[136:139], v[168:171], v[72:75]
	v_mfma_f32_16x16x32_bf16 v[100:103], v[128:131], v[188:191], v[100:103]
	v_mfma_f32_16x16x32_bf16 v[68:71], v[136:139], v[188:191], v[68:71]
	v_mfma_f32_16x16x32_bf16 v[92:95], v[128:131], v[196:199], v[92:95]
	v_mfma_f32_16x16x32_bf16 v[60:63], v[136:139], v[196:199], v[60:63]
	v_mfma_f32_16x16x32_bf16 v[108:111], v[132:135], v[164:167], v[108:111]
	v_mfma_f32_16x16x32_bf16 v[76:79], v[140:143], v[164:167], v[76:79]
	v_mfma_f32_16x16x32_bf16 v[104:107], v[132:135], v[184:187], v[104:107]
	v_mfma_f32_16x16x32_bf16 v[72:75], v[140:143], v[184:187], v[72:75]
	v_mfma_f32_16x16x32_bf16 v[100:103], v[132:135], v[192:195], v[100:103]
	v_mfma_f32_16x16x32_bf16 v[68:71], v[140:143], v[192:195], v[68:71]
	v_mfma_f32_16x16x32_bf16 v[92:95], v[132:135], v[200:203], v[92:95]
	v_mfma_f32_16x16x32_bf16 v[60:63], v[140:143], v[200:203], v[60:63]
	s_setprio 0
	s_setprio 1
	v_mfma_f32_16x16x32_bf16 v[40:43], v[144:147], v[160:163], v[40:43]
	v_mfma_f32_16x16x32_bf16 v[12:15], v[152:155], v[160:163], v[12:15]
	v_mfma_f32_16x16x32_bf16 v[32:35], v[144:147], v[168:171], v[32:35]
	v_mfma_f32_16x16x32_bf16 v[8:11], v[152:155], v[168:171], v[8:11]
	v_mfma_f32_16x16x32_bf16 v[24:27], v[144:147], v[188:191], v[24:27]
	v_mfma_f32_16x16x32_bf16 v[4:7], v[152:155], v[188:191], v[4:7]
	v_mfma_f32_16x16x32_bf16 v[16:19], v[144:147], v[196:199], v[16:19]
	v_mfma_f32_16x16x32_bf16 v[0:3], v[152:155], v[196:199], v[0:3]
	v_mfma_f32_16x16x32_bf16 v[40:43], v[148:151], v[164:167], v[40:43]
	v_mfma_f32_16x16x32_bf16 v[12:15], v[156:159], v[164:167], v[12:15]
	v_mfma_f32_16x16x32_bf16 v[32:35], v[148:151], v[184:187], v[32:35]
	v_mfma_f32_16x16x32_bf16 v[8:11], v[156:159], v[184:187], v[8:11]
	v_mfma_f32_16x16x32_bf16 v[24:27], v[148:151], v[192:195], v[24:27]
	v_mfma_f32_16x16x32_bf16 v[4:7], v[156:159], v[192:195], v[4:7]
	v_mfma_f32_16x16x32_bf16 v[16:19], v[148:151], v[200:203], v[16:19]
	v_mfma_f32_16x16x32_bf16 v[0:3], v[156:159], v[200:203], v[0:3]
	s_setprio 0
	s_barrier
	s_add_i32 s70, 0, 0x18000
	s_add_i32 s71, 0, 0x1c000
	v_add_u32_e32 v140, s70, v219
	v_add_u32_e32 v156, s71, v219
	ds_read_b128 v[128:131], v140
	ds_read_b128 v[132:135], v140 offset:1024
	ds_read_b128 v[136:139], v140 offset:2048
	ds_read_b128 v[140:143], v140 offset:3072
	ds_read_b128 v[144:147], v156
	ds_read_b128 v[148:151], v156 offset:1024
	ds_read_b128 v[152:155], v156 offset:2048
	ds_read_b128 v[156:159], v156 offset:3072
	s_add_u32 s30, s38, 0xb0000
	s_addc_u32 s31, s39, 0
	s_mov_b32 m0, s46
	v_lshl_add_u64 v[212:213], s[30:31], 0, v[172:173]
	ds_read_b128 v[160:163], v223 offset:32768
	ds_read_b128 v[164:167], v223 offset:33792
	ds_read_b128 v[168:171], v223 offset:34816
	ds_read_b128 v[184:187], v223 offset:35840
	ds_read_b128 v[188:191], v223 offset:36864
	ds_read_b128 v[192:195], v223 offset:37888
	ds_read_b128 v[196:199], v223 offset:38912
	ds_read_b128 v[200:203], v223 offset:39936
	global_load_lds_dwordx4 v[212:213], off
	v_lshl_add_u64 v[212:213], s[30:31], 0, v[174:175]
	s_mov_b32 m0, s47
	s_nop 0
	global_load_lds_dwordx4 v[212:213], off
	s_waitcnt vmcnt(8)
	s_waitcnt lgkmcnt(0)
	s_barrier
	s_setprio 1
	s_waitcnt lgkmcnt(0)
	v_mfma_f32_16x16x32_bf16 v[124:127], v[128:131], v[160:163], v[124:127]
	v_mfma_f32_16x16x32_bf16 v[96:99], v[136:139], v[160:163], v[96:99]
	v_mfma_f32_16x16x32_bf16 v[120:123], v[128:131], v[168:171], v[120:123]
	v_mfma_f32_16x16x32_bf16 v[88:91], v[136:139], v[168:171], v[88:91]
	v_mfma_f32_16x16x32_bf16 v[116:119], v[128:131], v[188:191], v[116:119]
	v_mfma_f32_16x16x32_bf16 v[84:87], v[136:139], v[188:191], v[84:87]
	v_mfma_f32_16x16x32_bf16 v[112:115], v[128:131], v[196:199], v[112:115]
	v_mfma_f32_16x16x32_bf16 v[80:83], v[136:139], v[196:199], v[80:83]
	v_mfma_f32_16x16x32_bf16 v[124:127], v[132:135], v[164:167], v[124:127]
	v_mfma_f32_16x16x32_bf16 v[96:99], v[140:143], v[164:167], v[96:99]
	v_mfma_f32_16x16x32_bf16 v[120:123], v[132:135], v[184:187], v[120:123]
	v_mfma_f32_16x16x32_bf16 v[88:91], v[140:143], v[184:187], v[88:91]
	v_mfma_f32_16x16x32_bf16 v[116:119], v[132:135], v[192:195], v[116:119]
	v_mfma_f32_16x16x32_bf16 v[84:87], v[140:143], v[192:195], v[84:87]
	v_mfma_f32_16x16x32_bf16 v[112:115], v[132:135], v[200:203], v[112:115]
	v_mfma_f32_16x16x32_bf16 v[80:83], v[140:143], v[200:203], v[80:83]
	s_setprio 0
	s_setprio 1
	v_mfma_f32_16x16x32_bf16 v[64:67], v[144:147], v[160:163], v[64:67]
	v_mfma_f32_16x16x32_bf16 v[44:47], v[152:155], v[160:163], v[44:47]
	v_mfma_f32_16x16x32_bf16 v[56:59], v[144:147], v[168:171], v[56:59]
	v_mfma_f32_16x16x32_bf16 v[36:39], v[152:155], v[168:171], v[36:39]
	v_mfma_f32_16x16x32_bf16 v[52:55], v[144:147], v[188:191], v[52:55]
	v_mfma_f32_16x16x32_bf16 v[28:31], v[152:155], v[188:191], v[28:31]
	v_mfma_f32_16x16x32_bf16 v[48:51], v[144:147], v[196:199], v[48:51]
	v_mfma_f32_16x16x32_bf16 v[20:23], v[152:155], v[196:199], v[20:23]
	v_mfma_f32_16x16x32_bf16 v[64:67], v[148:151], v[164:167], v[64:67]
	v_mfma_f32_16x16x32_bf16 v[44:47], v[156:159], v[164:167], v[44:47]
	v_mfma_f32_16x16x32_bf16 v[56:59], v[148:151], v[184:187], v[56:59]
	v_mfma_f32_16x16x32_bf16 v[36:39], v[156:159], v[184:187], v[36:39]
	v_mfma_f32_16x16x32_bf16 v[52:55], v[148:151], v[192:195], v[52:55]
	v_mfma_f32_16x16x32_bf16 v[28:31], v[156:159], v[192:195], v[28:31]
	v_mfma_f32_16x16x32_bf16 v[48:51], v[148:151], v[200:203], v[48:51]
	v_mfma_f32_16x16x32_bf16 v[20:23], v[156:159], v[200:203], v[20:23]
	s_setprio 0
	s_barrier
	s_add_i32 s30, s70, s43
	v_lshl_add_u64 v[204:205], v[204:205], 0, s[10:11]
	s_mov_b32 m0, s30
	ds_read_b128 v[160:163], v223 offset:49152
	ds_read_b128 v[164:167], v223 offset:50176
	ds_read_b128 v[168:171], v223 offset:51200
	ds_read_b128 v[184:187], v223 offset:52224
	ds_read_b128 v[188:191], v223 offset:53248
	ds_read_b128 v[192:195], v223 offset:54272
	ds_read_b128 v[196:199], v223 offset:55296
	ds_read_b128 v[200:203], v223 offset:56320
	global_load_lds_dwordx4 v[204:205], off
	s_add_i32 m0, s30, 0x2000
	s_add_u32 s30, s36, 0xb0080
	v_lshl_add_u64 v[204:205], v[206:207], 0, s[10:11]
	s_addc_u32 s31, s37, 0
	s_add_i32 s36, s71, s43
	global_load_lds_dwordx4 v[204:205], off
	v_lshl_add_u64 v[204:205], s[30:31], 0, v[172:173]
	s_mov_b32 m0, s36
	s_nop 0
	global_load_lds_dwordx4 v[204:205], off
	v_lshl_add_u64 v[204:205], s[30:31], 0, v[174:175]
	s_add_i32 m0, s36, 0x2000
	s_nop 0
	global_load_lds_dwordx4 v[204:205], off
	v_lshl_add_u64 v[204:205], v[208:209], 0, s[10:11]
	s_mov_b32 m0, s52
	s_nop 0
	global_load_lds_dwordx4 v[204:205], off
	v_lshl_add_u64 v[204:205], v[210:211], 0, s[10:11]
	s_mov_b32 m0, s53
	s_nop 0
	global_load_lds_dwordx4 v[204:205], off
	s_waitcnt vmcnt(8)
	s_waitcnt lgkmcnt(0)
	s_barrier
	s_setprio 1
	s_waitcnt lgkmcnt(0)
	v_mfma_f32_16x16x32_bf16 v[108:111], v[128:131], v[160:163], v[108:111]
	v_mfma_f32_16x16x32_bf16 v[76:79], v[136:139], v[160:163], v[76:79]
	v_mfma_f32_16x16x32_bf16 v[104:107], v[128:131], v[168:171], v[104:107]
	v_mfma_f32_16x16x32_bf16 v[72:75], v[136:139], v[168:171], v[72:75]
	v_mfma_f32_16x16x32_bf16 v[100:103], v[128:131], v[188:191], v[100:103]
	v_mfma_f32_16x16x32_bf16 v[68:71], v[136:139], v[188:191], v[68:71]
	v_mfma_f32_16x16x32_bf16 v[92:95], v[128:131], v[196:199], v[92:95]
	v_mfma_f32_16x16x32_bf16 v[60:63], v[136:139], v[196:199], v[60:63]
	v_mfma_f32_16x16x32_bf16 v[108:111], v[132:135], v[164:167], v[108:111]
	v_mfma_f32_16x16x32_bf16 v[76:79], v[140:143], v[164:167], v[76:79]
	v_mfma_f32_16x16x32_bf16 v[104:107], v[132:135], v[184:187], v[104:107]
	v_mfma_f32_16x16x32_bf16 v[72:75], v[140:143], v[184:187], v[72:75]
	v_mfma_f32_16x16x32_bf16 v[100:103], v[132:135], v[192:195], v[100:103]
	v_mfma_f32_16x16x32_bf16 v[68:71], v[140:143], v[192:195], v[68:71]
	v_mfma_f32_16x16x32_bf16 v[92:95], v[132:135], v[200:203], v[92:95]
	v_mfma_f32_16x16x32_bf16 v[60:63], v[140:143], v[200:203], v[60:63]
	s_setprio 0
	s_setprio 1
	v_mfma_f32_16x16x32_bf16 v[40:43], v[144:147], v[160:163], v[40:43]
	v_mfma_f32_16x16x32_bf16 v[12:15], v[152:155], v[160:163], v[12:15]
	v_mfma_f32_16x16x32_bf16 v[32:35], v[144:147], v[168:171], v[32:35]
	v_mfma_f32_16x16x32_bf16 v[8:11], v[152:155], v[168:171], v[8:11]
	v_mfma_f32_16x16x32_bf16 v[24:27], v[144:147], v[188:191], v[24:27]
	v_mfma_f32_16x16x32_bf16 v[4:7], v[152:155], v[188:191], v[4:7]
	v_mfma_f32_16x16x32_bf16 v[16:19], v[144:147], v[196:199], v[16:19]
	v_mfma_f32_16x16x32_bf16 v[0:3], v[152:155], v[196:199], v[0:3]
	v_mfma_f32_16x16x32_bf16 v[40:43], v[148:151], v[164:167], v[40:43]
	v_mfma_f32_16x16x32_bf16 v[12:15], v[156:159], v[164:167], v[12:15]
	v_mfma_f32_16x16x32_bf16 v[32:35], v[148:151], v[184:187], v[32:35]
	v_mfma_f32_16x16x32_bf16 v[8:11], v[156:159], v[184:187], v[8:11]
	v_mfma_f32_16x16x32_bf16 v[24:27], v[148:151], v[192:195], v[24:27]
	v_mfma_f32_16x16x32_bf16 v[4:7], v[156:159], v[192:195], v[4:7]
	v_mfma_f32_16x16x32_bf16 v[16:19], v[148:151], v[200:203], v[16:19]
	v_mfma_f32_16x16x32_bf16 v[0:3], v[156:159], v[200:203], v[0:3]
	s_setprio 0
	s_barrier
	s_add_i32 s69, s69, 2
	s_add_u32 s2, s2, 0x100
	s_addc_u32 s68, s68, 0
	s_cmp_gt_u32 s69, 41
	s_mov_b64 s[30:31], s[34:35]
	s_cbranch_scc0 .LBB0_1411
	s_branch .Lpeel_exit_P14

.LBB0_1414:
	v_lshl_add_u32 v128, s66, 8, v218
	v_lshl_or_b32 v136, s67, 8, v220
	s_ashr_i32 s2, s66, 4
	v_lshlrev_b32_e32 v136, 2, v136
	s_mul_hi_i32 s31, s2, 0x9000
	s_mul_i32 s2, s2, 0x9000
	v_lshl_add_u32 v128, v128, 12, v136
	s_add_u32 s30, s50, s2
	s_addc_u32 s31, s51, s31
	v_add_u32_e32 v129, 0x10000, v128
	v_add_u32_e32 v130, 0x20000, v128
	v_add_u32_e32 v131, 0x30000, v128
	v_add_u32_e32 v132, 0x80000, v128
	v_add_u32_e32 v133, 0x90000, v128
	v_add_u32_e32 v134, 0xa0000, v128
	v_add_u32_e32 v135, 0xb0000, v128
	global_load_dwordx4 v[140:143], v136, s[30:31]
	global_load_dwordx4 v[144:147], v136, s[30:31] offset:64
	global_load_dwordx4 v[148:151], v136, s[30:31] offset:512
	global_load_dwordx4 v[152:155], v136, s[30:31] offset:576
	global_load_dwordx4 v[184:187], v128, s[8:9]
	global_load_dwordx4 v[188:191], v128, s[8:9] offset:64
	global_load_dwordx4 v[192:195], v128, s[8:9] offset:512
	global_load_dwordx4 v[196:199], v128, s[8:9] offset:576
	global_load_dwordx4 v[200:203], v129, s[8:9]
	global_load_dwordx4 v[204:207], v129, s[8:9] offset:64
	global_load_dwordx4 v[208:211], v129, s[8:9] offset:512
	global_load_dwordx4 v[212:215], v129, s[8:9] offset:576
	global_load_dwordx4 v[156:159], v130, s[8:9]
	global_load_dwordx4 v[160:163], v130, s[8:9] offset:64
	global_load_dwordx4 v[164:167], v130, s[8:9] offset:512
	global_load_dwordx4 v[168:171], v130, s[8:9] offset:576
	global_load_dwordx4 v[232:235], v131, s[8:9]
	global_load_dwordx4 v[236:239], v131, s[8:9] offset:64
	global_load_dwordx4 v[240:243], v131, s[8:9] offset:512
	global_load_dwordx4 v[244:247], v131, s[8:9] offset:576
	s_waitcnt vmcnt(8)
	v_pk_mul_f32 v[140:141], v[140:141], 0.5 op_sel_hi:[1,0]
	v_pk_mul_f32 v[142:143], v[142:143], 0.5 op_sel_hi:[1,0]
	v_pk_mul_f32 v[144:145], v[144:145], 0.5 op_sel_hi:[1,0]
	v_pk_mul_f32 v[146:147], v[146:147], 0.5 op_sel_hi:[1,0]
	v_pk_mul_f32 v[148:149], v[148:149], 0.5 op_sel_hi:[1,0]
	v_pk_mul_f32 v[150:151], v[150:151], 0.5 op_sel_hi:[1,0]
	v_pk_mul_f32 v[152:153], v[152:153], 0.5 op_sel_hi:[1,0]
	v_pk_mul_f32 v[154:155], v[154:155], 0.5 op_sel_hi:[1,0]
	v_pk_fma_f32 v[184:185], v[124:125], v[140:141], v[184:185]
	v_pk_fma_f32 v[186:187], v[126:127], v[142:143], v[186:187]
	v_pk_fma_f32 v[188:189], v[96:97], v[144:145], v[188:189]
	v_pk_fma_f32 v[190:191], v[98:99], v[146:147], v[190:191]
	v_pk_fma_f32 v[192:193], v[64:65], v[148:149], v[192:193]
	v_pk_fma_f32 v[194:195], v[66:67], v[150:151], v[194:195]
	v_pk_fma_f32 v[196:197], v[44:45], v[152:153], v[196:197]
	v_pk_fma_f32 v[198:199], v[46:47], v[154:155], v[198:199]
	global_store_dwordx4 v128, v[184:187], s[8:9]
	global_store_dwordx4 v128, v[188:191], s[8:9] offset:64
	global_store_dwordx4 v128, v[192:195], s[8:9] offset:512
	global_store_dwordx4 v128, v[196:199], s[8:9] offset:576
	v_pk_fma_f32 v[200:201], v[120:121], v[140:141], v[200:201]
	v_pk_fma_f32 v[202:203], v[122:123], v[142:143], v[202:203]
	v_pk_fma_f32 v[204:205], v[88:89], v[144:145], v[204:205]
	v_pk_fma_f32 v[206:207], v[90:91], v[146:147], v[206:207]
	v_pk_fma_f32 v[208:209], v[56:57], v[148:149], v[208:209]
	v_pk_fma_f32 v[210:211], v[58:59], v[150:151], v[210:211]
	v_pk_fma_f32 v[212:213], v[36:37], v[152:153], v[212:213]
	v_pk_fma_f32 v[214:215], v[38:39], v[154:155], v[214:215]
	global_store_dwordx4 v129, v[200:203], s[8:9]
	global_store_dwordx4 v129, v[204:207], s[8:9] offset:64
	global_store_dwordx4 v129, v[208:211], s[8:9] offset:512
	global_store_dwordx4 v129, v[212:215], s[8:9] offset:576
	s_nop 1
	global_load_dwordx4 v[184:187], v132, s[8:9]
	global_load_dwordx4 v[188:191], v132, s[8:9] offset:64
	global_load_dwordx4 v[192:195], v132, s[8:9] offset:512
	global_load_dwordx4 v[196:199], v132, s[8:9] offset:576
	global_load_dwordx4 v[200:203], v133, s[8:9]
	global_load_dwordx4 v[204:207], v133, s[8:9] offset:64
	global_load_dwordx4 v[208:211], v133, s[8:9] offset:512
	global_load_dwordx4 v[212:215], v133, s[8:9] offset:576
	s_waitcnt vmcnt(16)
	v_pk_fma_f32 v[156:157], v[116:117], v[140:141], v[156:157]
	v_pk_fma_f32 v[158:159], v[118:119], v[142:143], v[158:159]
	v_pk_fma_f32 v[160:161], v[84:85], v[144:145], v[160:161]
	v_pk_fma_f32 v[162:163], v[86:87], v[146:147], v[162:163]
	v_pk_fma_f32 v[164:165], v[52:53], v[148:149], v[164:165]
	v_pk_fma_f32 v[166:167], v[54:55], v[150:151], v[166:167]
	v_pk_fma_f32 v[168:169], v[28:29], v[152:153], v[168:169]
	v_pk_fma_f32 v[170:171], v[30:31], v[154:155], v[170:171]
	global_store_dwordx4 v130, v[156:159], s[8:9]
	global_store_dwordx4 v130, v[160:163], s[8:9] offset:64
	global_store_dwordx4 v130, v[164:167], s[8:9] offset:512
	global_store_dwordx4 v130, v[168:171], s[8:9] offset:576
	v_pk_fma_f32 v[232:233], v[112:113], v[140:141], v[232:233]
	v_pk_fma_f32 v[234:235], v[114:115], v[142:143], v[234:235]
	v_pk_fma_f32 v[236:237], v[80:81], v[144:145], v[236:237]
	v_pk_fma_f32 v[238:239], v[82:83], v[146:147], v[238:239]
	v_pk_fma_f32 v[240:241], v[48:49], v[148:149], v[240:241]
	v_pk_fma_f32 v[242:243], v[50:51], v[150:151], v[242:243]
	v_pk_fma_f32 v[244:245], v[20:21], v[152:153], v[244:245]
	v_pk_fma_f32 v[246:247], v[22:23], v[154:155], v[246:247]
	global_store_dwordx4 v131, v[232:235], s[8:9]
	global_store_dwordx4 v131, v[236:239], s[8:9] offset:64
	global_store_dwordx4 v131, v[240:243], s[8:9] offset:512
	global_store_dwordx4 v131, v[244:247], s[8:9] offset:576
	s_nop 1
	global_load_dwordx4 v[156:159], v134, s[8:9]
	global_load_dwordx4 v[160:163], v134, s[8:9] offset:64
	global_load_dwordx4 v[164:167], v134, s[8:9] offset:512
	global_load_dwordx4 v[168:171], v134, s[8:9] offset:576
	global_load_dwordx4 v[232:235], v135, s[8:9]
	global_load_dwordx4 v[236:239], v135, s[8:9] offset:64
	global_load_dwordx4 v[240:243], v135, s[8:9] offset:512
	global_load_dwordx4 v[244:247], v135, s[8:9] offset:576
	s_waitcnt vmcnt(16)
	v_pk_fma_f32 v[184:185], v[108:109], v[140:141], v[184:185]
	v_pk_fma_f32 v[186:187], v[110:111], v[142:143], v[186:187]
	v_pk_fma_f32 v[188:189], v[76:77], v[144:145], v[188:189]
	v_pk_fma_f32 v[190:191], v[78:79], v[146:147], v[190:191]
	v_pk_fma_f32 v[192:193], v[40:41], v[148:149], v[192:193]
	v_pk_fma_f32 v[194:195], v[42:43], v[150:151], v[194:195]
	v_pk_fma_f32 v[196:197], v[12:13], v[152:153], v[196:197]
	v_pk_fma_f32 v[198:199], v[14:15], v[154:155], v[198:199]
	global_store_dwordx4 v132, v[184:187], s[8:9]
	global_store_dwordx4 v132, v[188:191], s[8:9] offset:64
	global_store_dwordx4 v132, v[192:195], s[8:9] offset:512
	global_store_dwordx4 v132, v[196:199], s[8:9] offset:576
	v_pk_fma_f32 v[200:201], v[104:105], v[140:141], v[200:201]
	v_pk_fma_f32 v[202:203], v[106:107], v[142:143], v[202:203]
	v_pk_fma_f32 v[204:205], v[72:73], v[144:145], v[204:205]
	v_pk_fma_f32 v[206:207], v[74:75], v[146:147], v[206:207]
	v_pk_fma_f32 v[208:209], v[32:33], v[148:149], v[208:209]
	v_pk_fma_f32 v[210:211], v[34:35], v[150:151], v[210:211]
	v_pk_fma_f32 v[212:213], v[8:9], v[152:153], v[212:213]
	v_pk_fma_f32 v[214:215], v[10:11], v[154:155], v[214:215]
	global_store_dwordx4 v133, v[200:203], s[8:9]
	global_store_dwordx4 v133, v[204:207], s[8:9] offset:64
	global_store_dwordx4 v133, v[208:211], s[8:9] offset:512
	global_store_dwordx4 v133, v[212:215], s[8:9] offset:576
	s_waitcnt vmcnt(8)
	v_pk_fma_f32 v[156:157], v[100:101], v[140:141], v[156:157]
	v_pk_fma_f32 v[158:159], v[102:103], v[142:143], v[158:159]
	v_pk_fma_f32 v[160:161], v[68:69], v[144:145], v[160:161]
	v_pk_fma_f32 v[162:163], v[70:71], v[146:147], v[162:163]
	v_pk_fma_f32 v[164:165], v[24:25], v[148:149], v[164:165]
	v_pk_fma_f32 v[166:167], v[26:27], v[150:151], v[166:167]
	v_pk_fma_f32 v[168:169], v[4:5], v[152:153], v[168:169]
	v_pk_fma_f32 v[170:171], v[6:7], v[154:155], v[170:171]
	global_store_dwordx4 v134, v[156:159], s[8:9]
	global_store_dwordx4 v134, v[160:163], s[8:9] offset:64
	global_store_dwordx4 v134, v[164:167], s[8:9] offset:512
	global_store_dwordx4 v134, v[168:171], s[8:9] offset:576
	v_pk_fma_f32 v[232:233], v[92:93], v[140:141], v[232:233]
	v_pk_fma_f32 v[234:235], v[94:95], v[142:143], v[234:235]
	v_pk_fma_f32 v[236:237], v[60:61], v[144:145], v[236:237]
	v_pk_fma_f32 v[238:239], v[62:63], v[146:147], v[238:239]
	v_pk_fma_f32 v[240:241], v[16:17], v[148:149], v[240:241]
	v_pk_fma_f32 v[242:243], v[18:19], v[150:151], v[242:243]
	v_pk_fma_f32 v[244:245], v[0:1], v[152:153], v[244:245]
	v_pk_fma_f32 v[246:247], v[2:3], v[154:155], v[246:247]
	global_store_dwordx4 v135, v[232:235], s[8:9]
	global_store_dwordx4 v135, v[236:239], s[8:9] offset:64
	global_store_dwordx4 v135, v[240:243], s[8:9] offset:512
	global_store_dwordx4 v135, v[244:247], s[8:9] offset:576
	s_mov_b64 s[30:31], -1
	s_and_b64 vcc, exec, s[4:5]
	s_mov_b32 s98, 1
	s_cbranch_vccnz .LBB0_1399
	s_andn2_b64 vcc, exec, s[12:13]
	s_cbranch_vccnz .LBB0_1398
	s_barrier
	s_branch .LBB0_1398

	.amdhsa_kernel _Z8mega_fwd6Params
		.amdhsa_group_segment_fixed_size 0
		.amdhsa_private_segment_fixed_size 0
		.amdhsa_kernarg_size 480
		.amdhsa_user_sgpr_count 2
		.amdhsa_user_sgpr_dispatch_ptr 0
		.amdhsa_user_sgpr_queue_ptr 0
		.amdhsa_user_sgpr_kernarg_segment_ptr 1
		.amdhsa_user_sgpr_dispatch_id 0
		.amdhsa_user_sgpr_kernarg_preload_length 0
		.amdhsa_user_sgpr_kernarg_preload_offset 0
		.amdhsa_user_sgpr_private_segment_size 0
		.amdhsa_uses_dynamic_stack 0
		.amdhsa_enable_private_segment 0
		.amdhsa_system_sgpr_workgroup_id_x 1
		.amdhsa_system_sgpr_workgroup_id_y 0
		.amdhsa_system_sgpr_workgroup_id_z 0
		.amdhsa_system_sgpr_workgroup_info 0
		.amdhsa_system_vgpr_workitem_id 2
		.amdhsa_next_free_vgpr 253
		.amdhsa_next_free_sgpr 102
		.amdhsa_accum_offset 256
		.amdhsa_reserve_vcc 1
		.amdhsa_float_round_mode_32 0
		.amdhsa_float_round_mode_16_64 0
		.amdhsa_float_denorm_mode_32 3
		.amdhsa_float_denorm_mode_16_64 3
		.amdhsa_dx10_clamp 1
		.amdhsa_ieee_mode 1
		.amdhsa_fp16_overflow 0
		.amdhsa_tg_split 0
		.amdhsa_exception_fp_ieee_invalid_op 0
		.amdhsa_exception_fp_denorm_src 0
		.amdhsa_exception_fp_ieee_div_zero 0
		.amdhsa_exception_fp_ieee_overflow 0
		.amdhsa_exception_fp_ieee_underflow 0
		.amdhsa_exception_fp_ieee_inexact 0
		.amdhsa_exception_int_div_zero 0
	.end_amdhsa_kernel

amdhsa.kernels:
  - .agpr_count:     0
    .args:
      - .offset:         0
        .size:           224
        .value_kind:     by_value
      - .offset:         224
        .size:           4
        .value_kind:     hidden_block_count_x
      - .offset:         228
        .size:           4
        .value_kind:     hidden_block_count_y
      - .offset:         232
        .size:           4
        .value_kind:     hidden_block_count_z
      - .offset:         236
        .size:           2
        .value_kind:     hidden_group_size_x
      - .offset:         238
        .size:           2
        .value_kind:     hidden_group_size_y
      - .offset:         240
        .size:           2
        .value_kind:     hidden_group_size_z
      - .offset:         242
        .size:           2
        .value_kind:     hidden_remainder_x
      - .offset:         244
        .size:           2
        .value_kind:     hidden_remainder_y
      - .offset:         246
        .size:           2
        .value_kind:     hidden_remainder_z
      - .offset:         264
        .size:           8
        .value_kind:     hidden_global_offset_x
      - .offset:         272
        .size:           8
        .value_kind:     hidden_global_offset_y
      - .offset:         280
        .size:           8
        .value_kind:     hidden_global_offset_z
      - .offset:         288
        .size:           2
        .value_kind:     hidden_grid_dims
      - .offset:         312
        .size:           8
        .value_kind:     hidden_multigrid_sync_arg
      - .offset:         344
        .size:           4
        .value_kind:     hidden_dynamic_lds_size
    .group_segment_fixed_size: 0
    .kernarg_segment_align: 8
    .kernarg_segment_size: 480
    .language:       OpenCL C
    .language_version:
      - 2
      - 0
    .max_flat_workgroup_size: 512
    .name:           _Z8mega_fwd6Params
    .private_segment_fixed_size: 0
    .sgpr_count:     108
    .sgpr_spill_count: 36
    .symbol:         _Z8mega_fwd6Params.kd
    .uniform_work_group_size: 1
    .uses_dynamic_stack: false
    .vgpr_count:     253
    .vgpr_spill_count: 0
    .wavefront_size: 64
